# speedup vs baseline: 1.0244x; 1.0100x over previous
; #define STAGE(P, BASE, br, kt) do { const char* _g = (const char*)((BASE) + (size_t)(br) * K + (size_t)(kt) * G_BK); \
;     _Pragma("unroll") for (int _i = 0; _i < 2; ++_i) { \
;       __builtin_amdgcn_global_load_lds((const unsigned*)(_g + (size_t)_i * 128 * K + sg_off), (unsigned*)((char*)(P) + wid * 1024 + _i * 8192), 16, 0, 0); } } while (0)
; #define LDA(dst, b, h) _Pragma("unroll") for (int m = 0; m < 4; ++m) _Pragma("unroll") for (int k = 0; k < 2; ++k) \
;     dst[m][k] = *reinterpret_cast<const bf16x8*>((const char*)shm + aoff + (((b) * 2 + (h)) * 16384 + m * 2048 + k * 1024))
; #define LDB(dst, b, h) _Pragma("unroll") for (int n = 0; n < 2; ++n) _Pragma("unroll") for (int k = 0; k < 2; ++k) \
;     dst[n][k] = *reinterpret_cast<const bf16x8*>((const char*)shm + boff + (((b) * 2 + (h)) * 16384 + n * 2048 + k * 1024))
; #define MMA(ai, bj, At, Bt_) do { __builtin_amdgcn_s_setprio(1); \
;     _Pragma("unroll") for (int m = 0; m < 4; ++m) _Pragma("unroll") for (int n = 0; n < 2; ++n) _Pragma("unroll") for (int k = 0; k < 2; ++k) \
;       acc[ai][bj][m][n] = mfma16(At[m][k], Bt_[n][k], acc[ai][bj][m][n]); \
;     __builtin_amdgcn_s_setprio(0); } while (0)
; #define WAIT_V(n) asm volatile("s_waitcnt vmcnt(" #n ")" ::: "memory")
; #define WAIT_L(n) asm volatile("s_waitcnt lgkmcnt(" #n ")" ::: "memory")
; #define BAR __builtin_amdgcn_s_barrier()
; #define SCHED __builtin_amdgcn_sched_barrier(0)
; template <class Epi>
; __device__ __forceinline__ void gemm_phase(const bfr* __restrict__ A, int lda, const bfr* __restrict__ Bt, int K,
;                                            int nM, int nN, const Epi& epi, bfr* shm, int wv, int nMfull, int ksplit) {
;     ...
;     f32x4 acc[2][2][4][2];
; #pragma unroll
;     for (int a = 0; a < 2; a++)
; #pragma unroll
;       for (int b = 0; b < 2; b++)
; #pragma unroll
;         for (int m = 0; m < 4; m++)
; #pragma unroll
;           for (int n = 0; n < 2; n++) acc[a][b][m][n] = f32x4{0.f, 0.f, 0.f, 0.f};
;     bf16x8 At[4][2], B0[2][2], B1[2][2];
;     if (wr == 1) BAR;
;     WAIT_V(10); BAR;
;     WAIT_V(6); BAR;
;     for (int t = 0; t < nt - 2; t += 2) {
;       LDB(B0, 0, 0); SCHED; LDA(At, 0, 0); STAGE(SA(1, 1), Ak, brow + G_HALF, t + 1);
;       WAIT_L(8); BAR; WAIT_L(0); MMA(0, 0, At, B0); BAR; SCHED;
;       LDB(B1, 0, 1); STAGE(SB(0, 0), Bk, bcol, t + 2);
.LBB0_193:
	s_waitcnt vmcnt(8)
	s_barrier
	s_waitcnt vmcnt(6)
	v_mov_b32_e32 v127, 0
	s_cmp_lt_u32 s30, 3
	v_mov_b32_e32 v126, v127
	v_mov_b32_e32 v125, v127
	v_mov_b32_e32 v124, v127
	v_mov_b32_e32 v123, v127
	v_mov_b32_e32 v122, v127
	v_mov_b32_e32 v121, v127
	v_mov_b32_e32 v120, v127
	v_mov_b32_e32 v119, v127
	v_mov_b32_e32 v118, v127
	v_mov_b32_e32 v117, v127
	v_mov_b32_e32 v116, v127
	v_mov_b32_e32 v115, v127
	v_mov_b32_e32 v114, v127
	v_mov_b32_e32 v113, v127
	v_mov_b32_e32 v112, v127
	v_mov_b32_e32 v111, v127
	v_mov_b32_e32 v110, v127
	v_mov_b32_e32 v109, v127
	v_mov_b32_e32 v108, v127
	v_mov_b32_e32 v107, v127
	v_mov_b32_e32 v106, v127
	v_mov_b32_e32 v105, v127
	v_mov_b32_e32 v104, v127
	v_mov_b32_e32 v103, v127
	v_mov_b32_e32 v102, v127
	v_mov_b32_e32 v101, v127
	v_mov_b32_e32 v100, v127
	v_mov_b32_e32 v99, v127
	v_mov_b32_e32 v98, v127
	v_mov_b32_e32 v97, v127
	v_mov_b32_e32 v96, v127
	v_mov_b32_e32 v95, v127
	v_mov_b32_e32 v94, v127
	v_mov_b32_e32 v93, v127
	v_mov_b32_e32 v92, v127
	v_mov_b32_e32 v91, v127
	v_mov_b32_e32 v90, v127
	v_mov_b32_e32 v89, v127
	v_mov_b32_e32 v88, v127
	v_mov_b32_e32 v87, v127
	v_mov_b32_e32 v86, v127
	v_mov_b32_e32 v85, v127
	v_mov_b32_e32 v84, v127
	v_mov_b32_e32 v83, v127
	v_mov_b32_e32 v82, v127
	v_mov_b32_e32 v81, v127
	v_mov_b32_e32 v80, v127
	v_mov_b32_e32 v79, v127
	v_mov_b32_e32 v78, v127
	v_mov_b32_e32 v77, v127
	v_mov_b32_e32 v76, v127
	v_mov_b32_e32 v75, v127
	v_mov_b32_e32 v74, v127
	v_mov_b32_e32 v73, v127
	v_mov_b32_e32 v72, v127
	v_mov_b32_e32 v71, v127
	v_mov_b32_e32 v70, v127
	v_mov_b32_e32 v69, v127
	v_mov_b32_e32 v68, v127
	v_mov_b32_e32 v67, v127
	v_mov_b32_e32 v66, v127
	v_mov_b32_e32 v65, v127
	v_mov_b32_e32 v64, v127
	v_mov_b32_e32 v63, v127
	v_mov_b32_e32 v62, v127
	v_mov_b32_e32 v61, v127
	v_mov_b32_e32 v60, v127
	v_mov_b32_e32 v59, v127
	v_mov_b32_e32 v58, v127
	v_mov_b32_e32 v57, v127
	v_mov_b32_e32 v56, v127
	v_mov_b32_e32 v55, v127
	v_mov_b32_e32 v54, v127
	v_mov_b32_e32 v53, v127
	v_mov_b32_e32 v52, v127
	v_mov_b32_e32 v51, v127
	v_mov_b32_e32 v50, v127
	v_mov_b32_e32 v49, v127
	v_mov_b32_e32 v48, v127
	v_mov_b32_e32 v47, v127
	v_mov_b32_e32 v46, v127
	v_mov_b32_e32 v45, v127
	v_mov_b32_e32 v44, v127
	v_mov_b32_e32 v43, v127
	v_mov_b32_e32 v42, v127
	v_mov_b32_e32 v41, v127
	v_mov_b32_e32 v40, v127
	v_mov_b32_e32 v39, v127
	v_mov_b32_e32 v38, v127
	v_mov_b32_e32 v37, v127
	v_mov_b32_e32 v36, v127
	v_mov_b32_e32 v35, v127
	v_mov_b32_e32 v34, v127
	v_mov_b32_e32 v33, v127
	v_mov_b32_e32 v32, v127
	v_mov_b32_e32 v31, v127
	v_mov_b32_e32 v30, v127
	v_mov_b32_e32 v29, v127
	v_mov_b32_e32 v28, v127
	v_mov_b32_e32 v27, v127
	v_mov_b32_e32 v26, v127
	v_mov_b32_e32 v25, v127
	v_mov_b32_e32 v24, v127
	v_mov_b32_e32 v23, v127
	v_mov_b32_e32 v22, v127
	v_mov_b32_e32 v21, v127
	v_mov_b32_e32 v20, v127
	v_mov_b32_e32 v19, v127
	v_mov_b32_e32 v18, v127
	v_mov_b32_e32 v17, v127
	v_mov_b32_e32 v16, v127
	v_mov_b32_e32 v15, v127
	v_mov_b32_e32 v14, v127
	v_mov_b32_e32 v13, v127
	v_mov_b32_e32 v12, v127
	v_mov_b32_e32 v11, v127
	v_mov_b32_e32 v10, v127
	v_mov_b32_e32 v9, v127
	v_mov_b32_e32 v8, v127
	v_mov_b32_e32 v7, v127
	v_mov_b32_e32 v6, v127
	v_mov_b32_e32 v5, v127
	v_mov_b32_e32 v4, v127
	v_mov_b32_e32 v3, v127
	v_mov_b32_e32 v2, v127
	v_mov_b32_e32 v1, v127
	v_mov_b32_e32 v0, v127
	s_barrier
	s_cbranch_scc1 .LBB0_196
	s_ashr_i32 s43, s42, 31
	s_ashr_i32 s45, s44, 31
	v_readlane_b32 s60, v254, 54
	s_add_i32 s31, s30, -2
	s_lshl_b64 s[36:37], s[42:43], 11
	s_lshl_b64 s[38:39], s[44:45], 11
	v_readlane_b32 s62, v254, 56
	v_readlane_b32 s63, v254, 57
	s_add_u32 s36, s62, s36
	s_addc_u32 s37, s63, s37
	s_add_u32 s38, s80, s38
	v_mov_b32_e32 v0, 0
	s_addc_u32 s39, s81, s39
	s_mov_b32 s40, 0
	v_readlane_b32 s61, v254, 55
	v_readlane_b32 s64, v254, 58
	v_readlane_b32 s65, v254, 59
	v_readlane_b32 s66, v254, 60
	v_readlane_b32 s67, v254, 61
	v_readlane_b32 s68, v254, 62
	v_readlane_b32 s69, v254, 63
	v_readlane_b32 s70, v255, 0
	v_readlane_b32 s71, v255, 1
	v_readlane_b32 s72, v255, 2
	v_readlane_b32 s73, v255, 3
	v_readlane_b32 s74, v255, 4
	v_readlane_b32 s75, v255, 5
.LBB0_195:
	ds_read_b128 v[142:145], v139
	ds_read_b128 v[146:149], v139 offset:1024
	ds_read_b128 v[150:153], v139 offset:2048
	ds_read_b128 v[154:157], v139 offset:3072
	ds_read_b128 v[158:161], v138
	ds_read_b128 v[162:165], v138 offset:1024
	ds_read_b128 v[166:169], v138 offset:2048
	ds_read_b128 v[170:173], v138 offset:3072
	ds_read_b128 v[174:177], v138 offset:4096
	ds_read_b128 v[178:181], v138 offset:5120
	ds_read_b128 v[182:185], v138 offset:6144
	ds_read_b128 v[186:189], v138 offset:7168
	ds_read_b128 v[190:193], v139 offset:16384
	ds_read_b128 v[194:197], v139 offset:17408
	ds_read_b128 v[198:201], v139 offset:18432
	ds_read_b128 v[202:205], v139 offset:19456
	v_lshl_add_u64 v[136:137], s[38:39], 0, v[134:135]
	v_lshl_add_u64 v[206:207], s[36:37], 0, v[134:135]
	s_mov_b32 m0, s54
	s_mov_b64 s[46:47], 0x40080
	v_lshl_add_u64 v[210:211], v[136:137], 0, s[46:47]
	global_load_lds_dwordx4 v[210:211], off
	s_mov_b32 m0, s55
	s_mov_b64 s[46:47], 0x60080
	v_lshl_add_u64 v[212:213], v[136:137], 0, s[46:47]
	global_load_lds_dwordx4 v[212:213], off
	s_waitcnt lgkmcnt(0)
	s_barrier
; #define STAGE(P, BASE, br, kt) do { const char* _g = (const char*)((BASE) + (size_t)(br) * K + (size_t)(kt) * G_BK); \
;     _Pragma("unroll") for (int _i = 0; _i < 2; ++_i) { \
;       __builtin_amdgcn_global_load_lds((const unsigned*)(_g + (size_t)_i * 128 * K + sg_off), (unsigned*)((char*)(P) + wid * 1024 + _i * 8192), 16, 0, 0); } } while (0)
; #define LDA(dst, b, h) _Pragma("unroll") for (int m = 0; m < 4; ++m) _Pragma("unroll") for (int k = 0; k < 2; ++k) \
;     dst[m][k] = *reinterpret_cast<const bf16x8*>((const char*)shm + aoff + (((b) * 2 + (h)) * 16384 + m * 2048 + k * 1024))
; #define LDB(dst, b, h) _Pragma("unroll") for (int n = 0; n < 2; ++n) _Pragma("unroll") for (int k = 0; k < 2; ++k) \
;     dst[n][k] = *reinterpret_cast<const bf16x8*>((const char*)shm + boff + (((b) * 2 + (h)) * 16384 + n * 2048 + k * 1024))
; #define MMA(ai, bj, At, Bt_) do { __builtin_amdgcn_s_setprio(1); \
;     _Pragma("unroll") for (int m = 0; m < 4; ++m) _Pragma("unroll") for (int n = 0; n < 2; ++n) _Pragma("unroll") for (int k = 0; k < 2; ++k) \
;       acc[ai][bj][m][n] = mfma16(At[m][k], Bt_[n][k], acc[ai][bj][m][n]); \
;     __builtin_amdgcn_s_setprio(0); } while (0)
; #define WAIT_V(n) asm volatile("s_waitcnt vmcnt(" #n ")" ::: "memory")
; #define WAIT_L(n) asm volatile("s_waitcnt lgkmcnt(" #n ")" ::: "memory")
; #define BAR __builtin_amdgcn_s_barrier()
; #define SCHED __builtin_amdgcn_sched_barrier(0)
; template <class Epi>
; __device__ __forceinline__ void gemm_phase(const bfr* __restrict__ A, int lda, const bfr* __restrict__ Bt, int K,
;                                            int nM, int nN, const Epi& epi, bfr* shm, int wv, int nMfull, int ksplit) {
;     ...
;       WAIT_L(8); BAR; WAIT_L(0); MMA(0, 0, At, B0); BAR; SCHED;
;       LDB(B1, 0, 1); STAGE(SB(0, 0), Bk, bcol, t + 2);
;       BAR; WAIT_L(0); MMA(0, 1, At, B1); BAR;
;       LDA(At, 0, 1); STAGE(SA(0, 0), Ak, brow, t + 2);
;       BAR; WAIT_L(0); MMA(1, 0, At, B0); BAR; SCHED;
;       STAGE(SB(0, 1), Bk, bcol + G_HALF, t + 2);
;       WAIT_V(6); BAR; MMA(1, 1, At, B1); BAR;
	s_setprio 1
	v_mfma_f32_16x16x32_bf16 v[124:127], v[158:161], v[142:145], v[124:127]
	v_mfma_f32_16x16x32_bf16 v[120:123], v[158:161], v[150:153], v[120:123]
	v_mfma_f32_16x16x32_bf16 v[116:119], v[166:169], v[142:145], v[116:119]
	v_mfma_f32_16x16x32_bf16 v[112:115], v[166:169], v[150:153], v[112:115]
	v_mfma_f32_16x16x32_bf16 v[108:111], v[174:177], v[142:145], v[108:111]
	v_mfma_f32_16x16x32_bf16 v[104:107], v[174:177], v[150:153], v[104:107]
	v_mfma_f32_16x16x32_bf16 v[100:103], v[182:185], v[142:145], v[100:103]
	v_mfma_f32_16x16x32_bf16 v[96:99], v[182:185], v[150:153], v[96:99]
	v_mfma_f32_16x16x32_bf16 v[124:127], v[162:165], v[146:149], v[124:127]
	v_mfma_f32_16x16x32_bf16 v[120:123], v[162:165], v[154:157], v[120:123]
	v_mfma_f32_16x16x32_bf16 v[116:119], v[170:173], v[146:149], v[116:119]
	v_mfma_f32_16x16x32_bf16 v[112:115], v[170:173], v[154:157], v[112:115]
	v_mfma_f32_16x16x32_bf16 v[108:111], v[178:181], v[146:149], v[108:111]
	v_mfma_f32_16x16x32_bf16 v[104:107], v[178:181], v[154:157], v[104:107]
	v_mfma_f32_16x16x32_bf16 v[100:103], v[186:189], v[146:149], v[100:103]
	v_mfma_f32_16x16x32_bf16 v[96:99], v[186:189], v[154:157], v[96:99]
	v_mfma_f32_16x16x32_bf16 v[92:95], v[158:161], v[190:193], v[92:95]
	v_mfma_f32_16x16x32_bf16 v[88:91], v[158:161], v[198:201], v[88:91]
	v_mfma_f32_16x16x32_bf16 v[84:87], v[166:169], v[190:193], v[84:87]
	v_mfma_f32_16x16x32_bf16 v[80:83], v[166:169], v[198:201], v[80:83]
	v_mfma_f32_16x16x32_bf16 v[76:79], v[174:177], v[190:193], v[76:79]
	v_mfma_f32_16x16x32_bf16 v[72:75], v[174:177], v[198:201], v[72:75]
	v_mfma_f32_16x16x32_bf16 v[68:71], v[182:185], v[190:193], v[68:71]
	v_mfma_f32_16x16x32_bf16 v[64:67], v[182:185], v[198:201], v[64:67]
	v_mfma_f32_16x16x32_bf16 v[92:95], v[162:165], v[194:197], v[92:95]
	v_mfma_f32_16x16x32_bf16 v[88:91], v[162:165], v[202:205], v[88:91]
	v_mfma_f32_16x16x32_bf16 v[84:87], v[170:173], v[194:197], v[84:87]
	v_mfma_f32_16x16x32_bf16 v[80:83], v[170:173], v[202:205], v[80:83]
	v_mfma_f32_16x16x32_bf16 v[76:79], v[178:181], v[194:197], v[76:79]
	v_mfma_f32_16x16x32_bf16 v[72:75], v[178:181], v[202:205], v[72:75]
	v_mfma_f32_16x16x32_bf16 v[68:71], v[186:189], v[194:197], v[68:71]
	v_mfma_f32_16x16x32_bf16 v[64:67], v[186:189], v[202:205], v[64:67]
	s_setprio 0
	s_barrier
	ds_read_b128 v[158:161], v138 offset:16384
	ds_read_b128 v[162:165], v138 offset:17408
	ds_read_b128 v[166:169], v138 offset:18432
	ds_read_b128 v[170:173], v138 offset:19456
	ds_read_b128 v[174:177], v138 offset:20480
	ds_read_b128 v[178:181], v138 offset:21504
	ds_read_b128 v[182:185], v138 offset:22528
	ds_read_b128 v[186:189], v138 offset:23552
	s_mov_b32 m0, s24
	v_lshl_add_u64 v[214:215], v[206:207], 0, s[10:11]
	global_load_lds_dwordx4 v[214:215], off
	s_mov_b32 m0, s25
	v_lshl_add_u64 v[210:211], v[206:207], 0, s[12:13]
	global_load_lds_dwordx4 v[210:211], off
	s_mov_b32 m0, s23
	v_lshl_add_u64 v[212:213], v[136:137], 0, s[10:11]
	global_load_lds_dwordx4 v[212:213], off
	s_mov_b32 m0, s26
	v_lshl_add_u64 v[214:215], v[136:137], 0, s[12:13]
	global_load_lds_dwordx4 v[214:215], off
	s_waitcnt vmcnt(6)
	s_waitcnt lgkmcnt(0)
	s_barrier
	s_setprio 1
	v_mfma_f32_16x16x32_bf16 v[60:63], v[158:161], v[142:145], v[60:63]
	v_mfma_f32_16x16x32_bf16 v[56:59], v[158:161], v[150:153], v[56:59]
	v_mfma_f32_16x16x32_bf16 v[52:55], v[166:169], v[142:145], v[52:55]
	v_mfma_f32_16x16x32_bf16 v[48:51], v[166:169], v[150:153], v[48:51]
	v_mfma_f32_16x16x32_bf16 v[44:47], v[174:177], v[142:145], v[44:47]
	v_mfma_f32_16x16x32_bf16 v[40:43], v[174:177], v[150:153], v[40:43]
	v_mfma_f32_16x16x32_bf16 v[36:39], v[182:185], v[142:145], v[36:39]
	v_mfma_f32_16x16x32_bf16 v[32:35], v[182:185], v[150:153], v[32:35]
	v_mfma_f32_16x16x32_bf16 v[60:63], v[162:165], v[146:149], v[60:63]
	v_mfma_f32_16x16x32_bf16 v[56:59], v[162:165], v[154:157], v[56:59]
	v_mfma_f32_16x16x32_bf16 v[52:55], v[170:173], v[146:149], v[52:55]
	v_mfma_f32_16x16x32_bf16 v[48:51], v[170:173], v[154:157], v[48:51]
	v_mfma_f32_16x16x32_bf16 v[44:47], v[178:181], v[146:149], v[44:47]
	v_mfma_f32_16x16x32_bf16 v[40:43], v[178:181], v[154:157], v[40:43]
	v_mfma_f32_16x16x32_bf16 v[36:39], v[186:189], v[146:149], v[36:39]
	v_mfma_f32_16x16x32_bf16 v[32:35], v[186:189], v[154:157], v[32:35]
	v_mfma_f32_16x16x32_bf16 v[28:31], v[158:161], v[190:193], v[28:31]
	v_mfma_f32_16x16x32_bf16 v[24:27], v[158:161], v[198:201], v[24:27]
	v_mfma_f32_16x16x32_bf16 v[20:23], v[166:169], v[190:193], v[20:23]
	v_mfma_f32_16x16x32_bf16 v[16:19], v[166:169], v[198:201], v[16:19]
	v_mfma_f32_16x16x32_bf16 v[12:15], v[174:177], v[190:193], v[12:15]
	v_mfma_f32_16x16x32_bf16 v[8:11], v[174:177], v[198:201], v[8:11]
	v_mfma_f32_16x16x32_bf16 v[4:7], v[182:185], v[190:193], v[4:7]
	v_mfma_f32_16x16x32_bf16 v[0:3], v[182:185], v[198:201], v[0:3]
	v_mfma_f32_16x16x32_bf16 v[28:31], v[162:165], v[194:197], v[28:31]
	v_mfma_f32_16x16x32_bf16 v[24:27], v[162:165], v[202:205], v[24:27]
	v_mfma_f32_16x16x32_bf16 v[20:23], v[170:173], v[194:197], v[20:23]
	v_mfma_f32_16x16x32_bf16 v[16:19], v[170:173], v[202:205], v[16:19]
	v_mfma_f32_16x16x32_bf16 v[12:15], v[178:181], v[194:197], v[12:15]
	v_mfma_f32_16x16x32_bf16 v[8:11], v[178:181], v[202:205], v[8:11]
	v_mfma_f32_16x16x32_bf16 v[4:7], v[186:189], v[194:197], v[4:7]
	v_mfma_f32_16x16x32_bf16 v[0:3], v[186:189], v[202:205], v[0:3]
	s_setprio 0
	s_barrier
; #define STAGE(P, BASE, br, kt) do { const char* _g = (const char*)((BASE) + (size_t)(br) * K + (size_t)(kt) * G_BK); \
;     _Pragma("unroll") for (int _i = 0; _i < 2; ++_i) { \
;       __builtin_amdgcn_global_load_lds((const unsigned*)(_g + (size_t)_i * 128 * K + sg_off), (unsigned*)((char*)(P) + wid * 1024 + _i * 8192), 16, 0, 0); } } while (0)
; #define LDA(dst, b, h) _Pragma("unroll") for (int m = 0; m < 4; ++m) _Pragma("unroll") for (int k = 0; k < 2; ++k) \
;     dst[m][k] = *reinterpret_cast<const bf16x8*>((const char*)shm + aoff + (((b) * 2 + (h)) * 16384 + m * 2048 + k * 1024))
; #define LDB(dst, b, h) _Pragma("unroll") for (int n = 0; n < 2; ++n) _Pragma("unroll") for (int k = 0; k < 2; ++k) \
;     dst[n][k] = *reinterpret_cast<const bf16x8*>((const char*)shm + boff + (((b) * 2 + (h)) * 16384 + n * 2048 + k * 1024))
; #define MMA(ai, bj, At, Bt_) do { __builtin_amdgcn_s_setprio(1); \
;     _Pragma("unroll") for (int m = 0; m < 4; ++m) _Pragma("unroll") for (int n = 0; n < 2; ++n) _Pragma("unroll") for (int k = 0; k < 2; ++k) \
;       acc[ai][bj][m][n] = mfma16(At[m][k], Bt_[n][k], acc[ai][bj][m][n]); \
;     __builtin_amdgcn_s_setprio(0); } while (0)
; #define WAIT_V(n) asm volatile("s_waitcnt vmcnt(" #n ")" ::: "memory")
; #define WAIT_L(n) asm volatile("s_waitcnt lgkmcnt(" #n ")" ::: "memory")
; #define BAR __builtin_amdgcn_s_barrier()
; #define SCHED __builtin_amdgcn_sched_barrier(0)
; template <class Epi>
; __device__ __forceinline__ void gemm_phase(const bfr* __restrict__ A, int lda, const bfr* __restrict__ Bt, int K,
;                                            int nM, int nN, const Epi& epi, bfr* shm, int wv, int nMfull, int ksplit) {
;     ...
;       LDB(B0, 1, 0); SCHED; LDA(At, 1, 0); STAGE(SA(0, 1), Ak, brow + G_HALF, t + 2);
;       WAIT_L(8); BAR; WAIT_L(0); MMA(0, 0, At, B0); BAR; SCHED;
;       LDB(B1, 1, 1); STAGE(SB(1, 0), Bk, bcol, t + 3);
;       BAR; WAIT_L(0); MMA(0, 1, At, B1); BAR;
;       LDA(At, 1, 1); STAGE(SA(1, 0), Ak, brow, t + 3);
;       BAR; WAIT_L(0); MMA(1, 0, At, B0); BAR; SCHED;
;       STAGE(SB(1, 1), Bk, bcol + G_HALF, t + 3);
;       WAIT_V(6); BAR; MMA(1, 1, At, B1); BAR;
;     }
	ds_read_b128 v[142:145], v139 offset:32768
	ds_read_b128 v[146:149], v139 offset:33792
	ds_read_b128 v[150:153], v139 offset:34816
	ds_read_b128 v[154:157], v139 offset:35840
	ds_read_b128 v[158:161], v138 offset:32768
	ds_read_b128 v[162:165], v138 offset:33792
	ds_read_b128 v[166:169], v138 offset:34816
	ds_read_b128 v[170:173], v138 offset:35840
	ds_read_b128 v[174:177], v138 offset:36864
	ds_read_b128 v[178:181], v138 offset:37888
	ds_read_b128 v[182:185], v138 offset:38912
	ds_read_b128 v[186:189], v138 offset:39936
	ds_read_b128 v[190:193], v139 offset:49152
	ds_read_b128 v[194:197], v139 offset:50176
	ds_read_b128 v[198:201], v139 offset:51200
	ds_read_b128 v[202:205], v139 offset:52224
	s_mov_b32 m0, s27
	v_lshl_add_u64 v[210:211], v[206:207], 0, s[14:15]
	global_load_lds_dwordx4 v[210:211], off
	s_mov_b32 m0, s28
	v_lshl_add_u64 v[212:213], v[206:207], 0, s[16:17]
	global_load_lds_dwordx4 v[212:213], off
	s_mov_b32 m0, s29
	v_lshl_add_u64 v[214:215], v[136:137], 0, s[14:15]
	global_load_lds_dwordx4 v[214:215], off
	s_mov_b32 m0, s33
	v_lshl_add_u64 v[210:211], v[136:137], 0, s[16:17]
	global_load_lds_dwordx4 v[210:211], off
	s_waitcnt vmcnt(8)
	s_waitcnt lgkmcnt(0)
	s_barrier
	s_setprio 1
	v_mfma_f32_16x16x32_bf16 v[124:127], v[158:161], v[142:145], v[124:127]
	v_mfma_f32_16x16x32_bf16 v[120:123], v[158:161], v[150:153], v[120:123]
	v_mfma_f32_16x16x32_bf16 v[116:119], v[166:169], v[142:145], v[116:119]
	v_mfma_f32_16x16x32_bf16 v[112:115], v[166:169], v[150:153], v[112:115]
	v_mfma_f32_16x16x32_bf16 v[108:111], v[174:177], v[142:145], v[108:111]
	v_mfma_f32_16x16x32_bf16 v[104:107], v[174:177], v[150:153], v[104:107]
	v_mfma_f32_16x16x32_bf16 v[100:103], v[182:185], v[142:145], v[100:103]
	v_mfma_f32_16x16x32_bf16 v[96:99], v[182:185], v[150:153], v[96:99]
	v_mfma_f32_16x16x32_bf16 v[124:127], v[162:165], v[146:149], v[124:127]
	v_mfma_f32_16x16x32_bf16 v[120:123], v[162:165], v[154:157], v[120:123]
	v_mfma_f32_16x16x32_bf16 v[116:119], v[170:173], v[146:149], v[116:119]
	v_mfma_f32_16x16x32_bf16 v[112:115], v[170:173], v[154:157], v[112:115]
	v_mfma_f32_16x16x32_bf16 v[108:111], v[178:181], v[146:149], v[108:111]
	v_mfma_f32_16x16x32_bf16 v[104:107], v[178:181], v[154:157], v[104:107]
	v_mfma_f32_16x16x32_bf16 v[100:103], v[186:189], v[146:149], v[100:103]
	v_mfma_f32_16x16x32_bf16 v[96:99], v[186:189], v[154:157], v[96:99]
	v_mfma_f32_16x16x32_bf16 v[92:95], v[158:161], v[190:193], v[92:95]
	v_mfma_f32_16x16x32_bf16 v[88:91], v[158:161], v[198:201], v[88:91]
	v_mfma_f32_16x16x32_bf16 v[84:87], v[166:169], v[190:193], v[84:87]
	v_mfma_f32_16x16x32_bf16 v[80:83], v[166:169], v[198:201], v[80:83]
	v_mfma_f32_16x16x32_bf16 v[76:79], v[174:177], v[190:193], v[76:79]
	v_mfma_f32_16x16x32_bf16 v[72:75], v[174:177], v[198:201], v[72:75]
	v_mfma_f32_16x16x32_bf16 v[68:71], v[182:185], v[190:193], v[68:71]
	v_mfma_f32_16x16x32_bf16 v[64:67], v[182:185], v[198:201], v[64:67]
	v_mfma_f32_16x16x32_bf16 v[92:95], v[162:165], v[194:197], v[92:95]
	v_mfma_f32_16x16x32_bf16 v[88:91], v[162:165], v[202:205], v[88:91]
	v_mfma_f32_16x16x32_bf16 v[84:87], v[170:173], v[194:197], v[84:87]
	v_mfma_f32_16x16x32_bf16 v[80:83], v[170:173], v[202:205], v[80:83]
	v_mfma_f32_16x16x32_bf16 v[76:79], v[178:181], v[194:197], v[76:79]
	v_mfma_f32_16x16x32_bf16 v[72:75], v[178:181], v[202:205], v[72:75]
	v_mfma_f32_16x16x32_bf16 v[68:71], v[186:189], v[194:197], v[68:71]
	v_mfma_f32_16x16x32_bf16 v[64:67], v[186:189], v[202:205], v[64:67]
	s_setprio 0
	s_barrier
	ds_read_b128 v[158:161], v138 offset:49152
	ds_read_b128 v[162:165], v138 offset:50176
	ds_read_b128 v[166:169], v138 offset:51200
	ds_read_b128 v[170:173], v138 offset:52224
	ds_read_b128 v[174:177], v138 offset:53248
	ds_read_b128 v[178:181], v138 offset:54272
	ds_read_b128 v[182:185], v138 offset:55296
	ds_read_b128 v[186:189], v138 offset:56320
	s_mov_b32 m0, s48
	v_lshl_add_u64 v[212:213], v[206:207], 0, s[18:19]
	global_load_lds_dwordx4 v[212:213], off
	s_mov_b32 m0, s49
	v_lshl_add_u64 v[214:215], v[206:207], 0, s[20:21]
	global_load_lds_dwordx4 v[214:215], off
	s_mov_b32 m0, s50
	v_lshl_add_u64 v[210:211], v[136:137], 0, s[18:19]
	global_load_lds_dwordx4 v[210:211], off
	s_mov_b32 m0, s51
	v_lshl_add_u64 v[212:213], v[136:137], 0, s[20:21]
	global_load_lds_dwordx4 v[212:213], off
	s_mov_b32 m0, s52
	s_mov_b64 s[46:47], 0x40180
	v_lshl_add_u64 v[214:215], v[206:207], 0, s[46:47]
	global_load_lds_dwordx4 v[214:215], off
	s_mov_b32 m0, s53
	s_mov_b64 s[46:47], 0x60180
	v_lshl_add_u64 v[210:211], v[206:207], 0, s[46:47]
	global_load_lds_dwordx4 v[210:211], off
	s_waitcnt vmcnt(6)
	s_waitcnt lgkmcnt(0)
	s_barrier
	s_setprio 1
	v_mfma_f32_16x16x32_bf16 v[60:63], v[158:161], v[142:145], v[60:63]
	v_mfma_f32_16x16x32_bf16 v[56:59], v[158:161], v[150:153], v[56:59]
	v_mfma_f32_16x16x32_bf16 v[52:55], v[166:169], v[142:145], v[52:55]
	v_mfma_f32_16x16x32_bf16 v[48:51], v[166:169], v[150:153], v[48:51]
	v_mfma_f32_16x16x32_bf16 v[44:47], v[174:177], v[142:145], v[44:47]
	v_mfma_f32_16x16x32_bf16 v[40:43], v[174:177], v[150:153], v[40:43]
	v_mfma_f32_16x16x32_bf16 v[36:39], v[182:185], v[142:145], v[36:39]
	v_mfma_f32_16x16x32_bf16 v[32:35], v[182:185], v[150:153], v[32:35]
	v_mfma_f32_16x16x32_bf16 v[60:63], v[162:165], v[146:149], v[60:63]
	v_mfma_f32_16x16x32_bf16 v[56:59], v[162:165], v[154:157], v[56:59]
	v_mfma_f32_16x16x32_bf16 v[52:55], v[170:173], v[146:149], v[52:55]
	v_mfma_f32_16x16x32_bf16 v[48:51], v[170:173], v[154:157], v[48:51]
	v_mfma_f32_16x16x32_bf16 v[44:47], v[178:181], v[146:149], v[44:47]
	v_mfma_f32_16x16x32_bf16 v[40:43], v[178:181], v[154:157], v[40:43]
	v_mfma_f32_16x16x32_bf16 v[36:39], v[186:189], v[146:149], v[36:39]
	v_mfma_f32_16x16x32_bf16 v[32:35], v[186:189], v[154:157], v[32:35]
	v_mfma_f32_16x16x32_bf16 v[28:31], v[158:161], v[190:193], v[28:31]
	v_mfma_f32_16x16x32_bf16 v[24:27], v[158:161], v[198:201], v[24:27]
	v_mfma_f32_16x16x32_bf16 v[20:23], v[166:169], v[190:193], v[20:23]
	v_mfma_f32_16x16x32_bf16 v[16:19], v[166:169], v[198:201], v[16:19]
	v_mfma_f32_16x16x32_bf16 v[12:15], v[174:177], v[190:193], v[12:15]
	v_mfma_f32_16x16x32_bf16 v[8:11], v[174:177], v[198:201], v[8:11]
	v_mfma_f32_16x16x32_bf16 v[4:7], v[182:185], v[190:193], v[4:7]
	v_mfma_f32_16x16x32_bf16 v[0:3], v[182:185], v[198:201], v[0:3]
	v_mfma_f32_16x16x32_bf16 v[28:31], v[162:165], v[194:197], v[28:31]
	v_mfma_f32_16x16x32_bf16 v[24:27], v[162:165], v[202:205], v[24:27]
	v_mfma_f32_16x16x32_bf16 v[20:23], v[170:173], v[194:197], v[20:23]
	v_mfma_f32_16x16x32_bf16 v[16:19], v[170:173], v[202:205], v[16:19]
	v_mfma_f32_16x16x32_bf16 v[12:15], v[178:181], v[194:197], v[12:15]
	v_mfma_f32_16x16x32_bf16 v[8:11], v[178:181], v[202:205], v[8:11]
	v_mfma_f32_16x16x32_bf16 v[4:7], v[186:189], v[194:197], v[4:7]
	v_mfma_f32_16x16x32_bf16 v[0:3], v[186:189], v[202:205], v[0:3]
	s_setprio 0
	s_add_i32 s40, s40, 2
	s_add_u32 s36, s36, 0x100
	s_addc_u32 s37, s37, 0
	s_add_u32 s38, s38, 0x100
	s_addc_u32 s39, s39, 0
	s_cmp_ge_i32 s40, s31
	s_barrier
	s_cbranch_scc0 .LBB0_195

; #define WAIT_V(n) asm volatile("s_waitcnt vmcnt(" #n ")" ::: "memory")
; #define BAR __builtin_amdgcn_s_barrier()
; template <class Epi>
; __device__ __forceinline__ void gemm_phase(const bfr* __restrict__ A, int lda, const bfr* __restrict__ Bt, int K,
;                                            int nM, int nN, const Epi& epi, bfr* shm, int wv, int nMfull, int ksplit) {
;     ...
;     f32x4 acc[2][2][4][2];
; #pragma unroll
;     for (int a = 0; a < 2; a++)
; #pragma unroll
;       for (int b = 0; b < 2; b++)
; #pragma unroll
;         for (int m = 0; m < 4; m++)
; #pragma unroll
;           for (int n = 0; n < 2; n++) acc[a][b][m][n] = f32x4{0.f, 0.f, 0.f, 0.f};
;     bf16x8 At[4][2], B0[2][2], B1[2][2];
;     if (wr == 1) BAR;
;     WAIT_V(10); BAR;
;     WAIT_V(6); BAR;
;     for (int t = 0; t < nt - 2; t += 2) {
.LBB0_240:
	s_lshl_b64 s[38:39], s[6:7], 1
	s_add_u32 s4, s82, s38
	s_waitcnt vmcnt(8)
	s_barrier
	s_waitcnt vmcnt(6)
	s_addc_u32 s5, s83, s39
	v_mov_b32_e32 v127, 0
	s_cmp_lt_u32 s96, 3
	v_mov_b32_e32 v126, v127
	v_mov_b32_e32 v125, v127
	v_mov_b32_e32 v124, v127
	v_mov_b32_e32 v123, v127
	v_mov_b32_e32 v122, v127
	v_mov_b32_e32 v121, v127
	v_mov_b32_e32 v120, v127
	v_mov_b32_e32 v119, v127
	v_mov_b32_e32 v118, v127
	v_mov_b32_e32 v117, v127
	v_mov_b32_e32 v116, v127
	v_mov_b32_e32 v115, v127
	v_mov_b32_e32 v114, v127
	v_mov_b32_e32 v113, v127
	v_mov_b32_e32 v112, v127
	v_mov_b32_e32 v111, v127
	v_mov_b32_e32 v110, v127
	v_mov_b32_e32 v109, v127
	v_mov_b32_e32 v108, v127
	v_mov_b32_e32 v107, v127
	v_mov_b32_e32 v106, v127
	v_mov_b32_e32 v105, v127
	v_mov_b32_e32 v104, v127
	v_mov_b32_e32 v103, v127
	v_mov_b32_e32 v102, v127
	v_mov_b32_e32 v101, v127
	v_mov_b32_e32 v100, v127
	v_mov_b32_e32 v99, v127
	v_mov_b32_e32 v98, v127
	v_mov_b32_e32 v97, v127
	v_mov_b32_e32 v96, v127
	v_mov_b32_e32 v95, v127
	v_mov_b32_e32 v94, v127
	v_mov_b32_e32 v93, v127
	v_mov_b32_e32 v92, v127
	v_mov_b32_e32 v91, v127
	v_mov_b32_e32 v90, v127
	v_mov_b32_e32 v89, v127
	v_mov_b32_e32 v88, v127
	v_mov_b32_e32 v87, v127
	v_mov_b32_e32 v86, v127
	v_mov_b32_e32 v85, v127
	v_mov_b32_e32 v84, v127
	v_mov_b32_e32 v83, v127
	v_mov_b32_e32 v82, v127
	v_mov_b32_e32 v81, v127
	v_mov_b32_e32 v80, v127
	v_mov_b32_e32 v79, v127
	v_mov_b32_e32 v78, v127
	v_mov_b32_e32 v77, v127
	v_mov_b32_e32 v76, v127
	v_mov_b32_e32 v75, v127
	v_mov_b32_e32 v74, v127
	v_mov_b32_e32 v73, v127
	v_mov_b32_e32 v72, v127
	v_mov_b32_e32 v71, v127
	v_mov_b32_e32 v70, v127
	v_mov_b32_e32 v69, v127
	v_mov_b32_e32 v68, v127
	v_mov_b32_e32 v67, v127
	v_mov_b32_e32 v66, v127
	v_mov_b32_e32 v65, v127
	v_mov_b32_e32 v64, v127
	v_mov_b32_e32 v63, v127
	v_mov_b32_e32 v62, v127
	v_mov_b32_e32 v61, v127
	v_mov_b32_e32 v60, v127
	v_mov_b32_e32 v59, v127
	v_mov_b32_e32 v58, v127
	v_mov_b32_e32 v57, v127
	v_mov_b32_e32 v56, v127
	v_mov_b32_e32 v55, v127
	v_mov_b32_e32 v54, v127
	v_mov_b32_e32 v53, v127
	v_mov_b32_e32 v52, v127
	v_mov_b32_e32 v51, v127
	v_mov_b32_e32 v50, v127
	v_mov_b32_e32 v49, v127
	v_mov_b32_e32 v48, v127
	v_mov_b32_e32 v47, v127
	v_mov_b32_e32 v46, v127
	v_mov_b32_e32 v45, v127
	v_mov_b32_e32 v44, v127
	v_mov_b32_e32 v43, v127
	v_mov_b32_e32 v42, v127
	v_mov_b32_e32 v41, v127
	v_mov_b32_e32 v40, v127
	v_mov_b32_e32 v39, v127
	v_mov_b32_e32 v38, v127
	v_mov_b32_e32 v37, v127
	v_mov_b32_e32 v36, v127
	v_mov_b32_e32 v35, v127
	v_mov_b32_e32 v34, v127
	v_mov_b32_e32 v33, v127
	v_mov_b32_e32 v32, v127
	v_mov_b32_e32 v31, v127
	v_mov_b32_e32 v30, v127
	v_mov_b32_e32 v29, v127
	v_mov_b32_e32 v28, v127
	v_mov_b32_e32 v27, v127
	v_mov_b32_e32 v26, v127
	v_mov_b32_e32 v25, v127
	v_mov_b32_e32 v24, v127
	v_mov_b32_e32 v23, v127
	v_mov_b32_e32 v22, v127
	v_mov_b32_e32 v21, v127
	v_mov_b32_e32 v20, v127
	v_mov_b32_e32 v19, v127
	v_mov_b32_e32 v18, v127
	v_mov_b32_e32 v17, v127
	v_mov_b32_e32 v16, v127
	v_mov_b32_e32 v15, v127
	v_mov_b32_e32 v14, v127
	v_mov_b32_e32 v13, v127
	v_mov_b32_e32 v12, v127
	v_mov_b32_e32 v11, v127
	v_mov_b32_e32 v10, v127
	v_mov_b32_e32 v9, v127
	v_mov_b32_e32 v8, v127
	v_mov_b32_e32 v7, v127
	v_mov_b32_e32 v6, v127
	v_mov_b32_e32 v5, v127
	v_mov_b32_e32 v4, v127
	v_mov_b32_e32 v3, v127
	v_mov_b32_e32 v2, v127
	v_mov_b32_e32 v1, v127
	v_mov_b32_e32 v0, v127
	s_barrier
	s_cbranch_scc1 .LBB0_243
	v_readlane_b32 s56, v254, 54
	s_add_i32 s6, s96, -2
	v_readlane_b32 s60, v254, 58
	v_readlane_b32 s61, v254, 59
	s_add_u32 s27, s60, s38
	s_mul_i32 s38, s36, 0xb00
	s_addc_u32 s37, s61, s39
	s_ashr_i32 s39, s38, 31
	s_lshl_b64 s[38:39], s[38:39], 1
	s_add_u32 s38, s27, s38
	s_addc_u32 s39, s37, s39
	s_mul_i32 s37, s13, 0x1600
	s_mul_hi_i32 s27, s13, 0x1600
	s_add_u32 s44, s4, s37
	v_mov_b32_e32 v0, 0
	s_addc_u32 s45, s5, s27
	s_mov_b32 s27, 0
	v_readlane_b32 s57, v254, 55
	v_readlane_b32 s58, v254, 56
	v_readlane_b32 s59, v254, 57
	v_readlane_b32 s62, v254, 60
	v_readlane_b32 s63, v254, 61
	v_readlane_b32 s64, v254, 62
	v_readlane_b32 s65, v254, 63
	v_readlane_b32 s66, v255, 0
	v_readlane_b32 s67, v255, 1
	v_readlane_b32 s68, v255, 2
	v_readlane_b32 s69, v255, 3
	v_readlane_b32 s70, v255, 4
	v_readlane_b32 s71, v255, 5
; #define STAGE(P, BASE, br, kt) do { const char* _g = (const char*)((BASE) + (size_t)(br) * K + (size_t)(kt) * G_BK); \
;     _Pragma("unroll") for (int _i = 0; _i < 2; ++_i) { \
;       __builtin_amdgcn_global_load_lds((const unsigned*)(_g + (size_t)_i * 128 * K + sg_off), (unsigned*)((char*)(P) + wid * 1024 + _i * 8192), 16, 0, 0); } } while (0)
; #define LDA(dst, b, h) _Pragma("unroll") for (int m = 0; m < 4; ++m) _Pragma("unroll") for (int k = 0; k < 2; ++k) \
;     dst[m][k] = *reinterpret_cast<const bf16x8*>((const char*)shm + aoff + (((b) * 2 + (h)) * 16384 + m * 2048 + k * 1024))
; #define LDB(dst, b, h) _Pragma("unroll") for (int n = 0; n < 2; ++n) _Pragma("unroll") for (int k = 0; k < 2; ++k) \
;     dst[n][k] = *reinterpret_cast<const bf16x8*>((const char*)shm + boff + (((b) * 2 + (h)) * 16384 + n * 2048 + k * 1024))
; #define MMA(ai, bj, At, Bt_) do { __builtin_amdgcn_s_setprio(1); \
;     _Pragma("unroll") for (int m = 0; m < 4; ++m) _Pragma("unroll") for (int n = 0; n < 2; ++n) _Pragma("unroll") for (int k = 0; k < 2; ++k) \
;       acc[ai][bj][m][n] = mfma16(At[m][k], Bt_[n][k], acc[ai][bj][m][n]); \
;     __builtin_amdgcn_s_setprio(0); } while (0)
; #define WAIT_V(n) asm volatile("s_waitcnt vmcnt(" #n ")" ::: "memory")
; #define WAIT_L(n) asm volatile("s_waitcnt lgkmcnt(" #n ")" ::: "memory")
; #define BAR __builtin_amdgcn_s_barrier()
; #define SCHED __builtin_amdgcn_sched_barrier(0)
; template <class Epi>
; __device__ __forceinline__ void gemm_phase(const bfr* __restrict__ A, int lda, const bfr* __restrict__ Bt, int K,
;                                            int nM, int nN, const Epi& epi, bfr* shm, int wv, int nMfull, int ksplit) {
;     ...
;       LDB(B0, 0, 0); SCHED; LDA(At, 0, 0); STAGE(SA(1, 1), Ak, brow + G_HALF, t + 1);
;       WAIT_L(8); BAR; WAIT_L(0); MMA(0, 0, At, B0); BAR; SCHED;
;       LDB(B1, 0, 1); STAGE(SB(0, 0), Bk, bcol, t + 2);
;       BAR; WAIT_L(0); MMA(0, 1, At, B1); BAR;
;       LDA(At, 0, 1); STAGE(SA(0, 0), Ak, brow, t + 2);
;       BAR; WAIT_L(0); MMA(1, 0, At, B0); BAR; SCHED;
;       STAGE(SB(0, 1), Bk, bcol + G_HALF, t + 2);
;       WAIT_V(6); BAR; MMA(1, 1, At, B1); BAR;
.LBB0_242:
	ds_read_b128 v[140:143], v178
	ds_read_b128 v[144:147], v178 offset:1024
	ds_read_b128 v[148:151], v178 offset:2048
	ds_read_b128 v[152:155], v178 offset:3072
	ds_read_b128 v[156:159], v129
	ds_read_b128 v[160:163], v129 offset:1024
	ds_read_b128 v[164:167], v129 offset:2048
	ds_read_b128 v[168:171], v129 offset:3072
	ds_read_b128 v[172:175], v129 offset:4096
	ds_read_b128 v[180:183], v129 offset:5120
	ds_read_b128 v[184:187], v129 offset:6144
	ds_read_b128 v[188:191], v129 offset:7168
	ds_read_b128 v[192:195], v178 offset:16384
	ds_read_b128 v[196:199], v178 offset:17408
	ds_read_b128 v[200:203], v178 offset:18432
	ds_read_b128 v[204:207], v178 offset:19456
	v_lshl_add_u64 v[176:177], s[44:45], 0, v[138:139]
	v_lshl_add_u64 v[208:209], s[38:39], 0, v[138:139]
	s_mov_b32 m0, s28
	v_lshl_add_u64 v[212:213], v[176:177], 0, s[16:17]
	global_load_lds_dwordx4 v[212:213], off
	s_mov_b32 m0, s29
	v_lshl_add_u64 v[214:215], v[176:177], 0, s[18:19]
	global_load_lds_dwordx4 v[214:215], off
	s_waitcnt lgkmcnt(0)
	s_barrier
	s_setprio 1
	v_mfma_f32_16x16x32_bf16 v[124:127], v[156:159], v[140:143], v[124:127]
	v_mfma_f32_16x16x32_bf16 v[120:123], v[156:159], v[148:151], v[120:123]
	v_mfma_f32_16x16x32_bf16 v[116:119], v[164:167], v[140:143], v[116:119]
	v_mfma_f32_16x16x32_bf16 v[112:115], v[164:167], v[148:151], v[112:115]
	v_mfma_f32_16x16x32_bf16 v[108:111], v[172:175], v[140:143], v[108:111]
	v_mfma_f32_16x16x32_bf16 v[104:107], v[172:175], v[148:151], v[104:107]
	v_mfma_f32_16x16x32_bf16 v[100:103], v[184:187], v[140:143], v[100:103]
	v_mfma_f32_16x16x32_bf16 v[96:99], v[184:187], v[148:151], v[96:99]
	v_mfma_f32_16x16x32_bf16 v[124:127], v[160:163], v[144:147], v[124:127]
	v_mfma_f32_16x16x32_bf16 v[120:123], v[160:163], v[152:155], v[120:123]
	v_mfma_f32_16x16x32_bf16 v[116:119], v[168:171], v[144:147], v[116:119]
	v_mfma_f32_16x16x32_bf16 v[112:115], v[168:171], v[152:155], v[112:115]
	v_mfma_f32_16x16x32_bf16 v[108:111], v[180:183], v[144:147], v[108:111]
	v_mfma_f32_16x16x32_bf16 v[104:107], v[180:183], v[152:155], v[104:107]
	v_mfma_f32_16x16x32_bf16 v[100:103], v[188:191], v[144:147], v[100:103]
	v_mfma_f32_16x16x32_bf16 v[96:99], v[188:191], v[152:155], v[96:99]
	v_mfma_f32_16x16x32_bf16 v[92:95], v[156:159], v[192:195], v[92:95]
	v_mfma_f32_16x16x32_bf16 v[88:91], v[156:159], v[200:203], v[88:91]
	v_mfma_f32_16x16x32_bf16 v[84:87], v[164:167], v[192:195], v[84:87]
	v_mfma_f32_16x16x32_bf16 v[80:83], v[164:167], v[200:203], v[80:83]
	v_mfma_f32_16x16x32_bf16 v[76:79], v[172:175], v[192:195], v[76:79]
	v_mfma_f32_16x16x32_bf16 v[72:75], v[172:175], v[200:203], v[72:75]
	v_mfma_f32_16x16x32_bf16 v[68:71], v[184:187], v[192:195], v[68:71]
	v_mfma_f32_16x16x32_bf16 v[64:67], v[184:187], v[200:203], v[64:67]
	v_mfma_f32_16x16x32_bf16 v[92:95], v[160:163], v[196:199], v[92:95]
	v_mfma_f32_16x16x32_bf16 v[88:91], v[160:163], v[204:207], v[88:91]
	v_mfma_f32_16x16x32_bf16 v[84:87], v[168:171], v[196:199], v[84:87]
	v_mfma_f32_16x16x32_bf16 v[80:83], v[168:171], v[204:207], v[80:83]
	v_mfma_f32_16x16x32_bf16 v[76:79], v[180:183], v[196:199], v[76:79]
	v_mfma_f32_16x16x32_bf16 v[72:75], v[180:183], v[204:207], v[72:75]
	v_mfma_f32_16x16x32_bf16 v[68:71], v[188:191], v[196:199], v[68:71]
	v_mfma_f32_16x16x32_bf16 v[64:67], v[188:191], v[204:207], v[64:67]
	s_setprio 0
	s_barrier
	ds_read_b128 v[156:159], v129 offset:16384
	ds_read_b128 v[160:163], v129 offset:17408
	ds_read_b128 v[164:167], v129 offset:18432
	ds_read_b128 v[168:171], v129 offset:19456
	ds_read_b128 v[172:175], v129 offset:20480
	ds_read_b128 v[180:183], v129 offset:21504
	ds_read_b128 v[184:187], v129 offset:22528
	ds_read_b128 v[188:191], v129 offset:23552
	s_mov_b32 m0, s33
	v_lshl_add_u64 v[216:217], v[208:209], 0, s[20:21]
	global_load_lds_dwordx4 v[216:217], off
	s_mov_b32 m0, s92
	v_lshl_add_u64 v[212:213], v[208:209], 0, s[30:31]
	global_load_lds_dwordx4 v[212:213], off
	s_mov_b32 m0, s26
	v_lshl_add_u64 v[214:215], v[176:177], 0, s[20:21]
	global_load_lds_dwordx4 v[214:215], off
	s_mov_b32 m0, s93
	v_lshl_add_u64 v[216:217], v[176:177], 0, s[30:31]
	global_load_lds_dwordx4 v[216:217], off
	s_waitcnt vmcnt(6)
	s_waitcnt lgkmcnt(0)
	s_barrier
	s_setprio 1
	v_mfma_f32_16x16x32_bf16 v[60:63], v[156:159], v[140:143], v[60:63]
	v_mfma_f32_16x16x32_bf16 v[56:59], v[156:159], v[148:151], v[56:59]
	v_mfma_f32_16x16x32_bf16 v[52:55], v[164:167], v[140:143], v[52:55]
	v_mfma_f32_16x16x32_bf16 v[48:51], v[164:167], v[148:151], v[48:51]
	v_mfma_f32_16x16x32_bf16 v[44:47], v[172:175], v[140:143], v[44:47]
	v_mfma_f32_16x16x32_bf16 v[40:43], v[172:175], v[148:151], v[40:43]
	v_mfma_f32_16x16x32_bf16 v[36:39], v[184:187], v[140:143], v[36:39]
	v_mfma_f32_16x16x32_bf16 v[32:35], v[184:187], v[148:151], v[32:35]
	v_mfma_f32_16x16x32_bf16 v[60:63], v[160:163], v[144:147], v[60:63]
	v_mfma_f32_16x16x32_bf16 v[56:59], v[160:163], v[152:155], v[56:59]
	v_mfma_f32_16x16x32_bf16 v[52:55], v[168:171], v[144:147], v[52:55]
	v_mfma_f32_16x16x32_bf16 v[48:51], v[168:171], v[152:155], v[48:51]
	v_mfma_f32_16x16x32_bf16 v[44:47], v[180:183], v[144:147], v[44:47]
	v_mfma_f32_16x16x32_bf16 v[40:43], v[180:183], v[152:155], v[40:43]
	v_mfma_f32_16x16x32_bf16 v[36:39], v[188:191], v[144:147], v[36:39]
	v_mfma_f32_16x16x32_bf16 v[32:35], v[188:191], v[152:155], v[32:35]
	v_mfma_f32_16x16x32_bf16 v[28:31], v[156:159], v[192:195], v[28:31]
	v_mfma_f32_16x16x32_bf16 v[24:27], v[156:159], v[200:203], v[24:27]
	v_mfma_f32_16x16x32_bf16 v[20:23], v[164:167], v[192:195], v[20:23]
	v_mfma_f32_16x16x32_bf16 v[16:19], v[164:167], v[200:203], v[16:19]
	v_mfma_f32_16x16x32_bf16 v[12:15], v[172:175], v[192:195], v[12:15]
	v_mfma_f32_16x16x32_bf16 v[8:11], v[172:175], v[200:203], v[8:11]
	v_mfma_f32_16x16x32_bf16 v[4:7], v[184:187], v[192:195], v[4:7]
	v_mfma_f32_16x16x32_bf16 v[0:3], v[184:187], v[200:203], v[0:3]
	v_mfma_f32_16x16x32_bf16 v[28:31], v[160:163], v[196:199], v[28:31]
	v_mfma_f32_16x16x32_bf16 v[24:27], v[160:163], v[204:207], v[24:27]
	v_mfma_f32_16x16x32_bf16 v[20:23], v[168:171], v[196:199], v[20:23]
	v_mfma_f32_16x16x32_bf16 v[16:19], v[168:171], v[204:207], v[16:19]
	v_mfma_f32_16x16x32_bf16 v[12:15], v[180:183], v[196:199], v[12:15]
	v_mfma_f32_16x16x32_bf16 v[8:11], v[180:183], v[204:207], v[8:11]
	v_mfma_f32_16x16x32_bf16 v[4:7], v[188:191], v[196:199], v[4:7]
	v_mfma_f32_16x16x32_bf16 v[0:3], v[188:191], v[204:207], v[0:3]
	s_setprio 0
	s_barrier
; #define STAGE(P, BASE, br, kt) do { const char* _g = (const char*)((BASE) + (size_t)(br) * K + (size_t)(kt) * G_BK); \
;     _Pragma("unroll") for (int _i = 0; _i < 2; ++_i) { \
;       __builtin_amdgcn_global_load_lds((const unsigned*)(_g + (size_t)_i * 128 * K + sg_off), (unsigned*)((char*)(P) + wid * 1024 + _i * 8192), 16, 0, 0); } } while (0)
; #define LDA(dst, b, h) _Pragma("unroll") for (int m = 0; m < 4; ++m) _Pragma("unroll") for (int k = 0; k < 2; ++k) \
;     dst[m][k] = *reinterpret_cast<const bf16x8*>((const char*)shm + aoff + (((b) * 2 + (h)) * 16384 + m * 2048 + k * 1024))
; #define LDB(dst, b, h) _Pragma("unroll") for (int n = 0; n < 2; ++n) _Pragma("unroll") for (int k = 0; k < 2; ++k) \
;     dst[n][k] = *reinterpret_cast<const bf16x8*>((const char*)shm + boff + (((b) * 2 + (h)) * 16384 + n * 2048 + k * 1024))
; #define MMA(ai, bj, At, Bt_) do { __builtin_amdgcn_s_setprio(1); \
;     _Pragma("unroll") for (int m = 0; m < 4; ++m) _Pragma("unroll") for (int n = 0; n < 2; ++n) _Pragma("unroll") for (int k = 0; k < 2; ++k) \
;       acc[ai][bj][m][n] = mfma16(At[m][k], Bt_[n][k], acc[ai][bj][m][n]); \
;     __builtin_amdgcn_s_setprio(0); } while (0)
; #define WAIT_V(n) asm volatile("s_waitcnt vmcnt(" #n ")" ::: "memory")
; #define WAIT_L(n) asm volatile("s_waitcnt lgkmcnt(" #n ")" ::: "memory")
; #define BAR __builtin_amdgcn_s_barrier()
; #define SCHED __builtin_amdgcn_sched_barrier(0)
; template <class Epi>
; __device__ __forceinline__ void gemm_phase(const bfr* __restrict__ A, int lda, const bfr* __restrict__ Bt, int K,
;                                            int nM, int nN, const Epi& epi, bfr* shm, int wv, int nMfull, int ksplit) {
;     ...
;       LDB(B0, 1, 0); SCHED; LDA(At, 1, 0); STAGE(SA(0, 1), Ak, brow + G_HALF, t + 2);
;       WAIT_L(8); BAR; WAIT_L(0); MMA(0, 0, At, B0); BAR; SCHED;
;       LDB(B1, 1, 1); STAGE(SB(1, 0), Bk, bcol, t + 3);
;       BAR; WAIT_L(0); MMA(0, 1, At, B1); BAR;
;       LDA(At, 1, 1); STAGE(SA(1, 0), Ak, brow, t + 3);
;       BAR; WAIT_L(0); MMA(1, 0, At, B0); BAR; SCHED;
;       STAGE(SB(1, 1), Bk, bcol + G_HALF, t + 3);
;       WAIT_V(6); BAR; MMA(1, 1, At, B1); BAR;
;     }
	ds_read_b128 v[140:143], v178 offset:32768
	ds_read_b128 v[144:147], v178 offset:33792
	ds_read_b128 v[148:151], v178 offset:34816
	ds_read_b128 v[152:155], v178 offset:35840
	ds_read_b128 v[156:159], v129 offset:32768
	ds_read_b128 v[160:163], v129 offset:33792
	ds_read_b128 v[164:167], v129 offset:34816
	ds_read_b128 v[168:171], v129 offset:35840
	ds_read_b128 v[172:175], v129 offset:36864
	ds_read_b128 v[180:183], v129 offset:37888
	ds_read_b128 v[184:187], v129 offset:38912
	ds_read_b128 v[188:191], v129 offset:39936
	ds_read_b128 v[192:195], v178 offset:49152
	ds_read_b128 v[196:199], v178 offset:50176
	ds_read_b128 v[200:203], v178 offset:51200
	ds_read_b128 v[204:207], v178 offset:52224
	s_mov_b32 m0, s10
	v_lshl_add_u64 v[212:213], v[208:209], 0, s[40:41]
	global_load_lds_dwordx4 v[212:213], off
	s_mov_b32 m0, s11
	v_lshl_add_u64 v[214:215], v[208:209], 0, s[42:43]
	global_load_lds_dwordx4 v[214:215], off
	s_mov_b32 m0, s94
	v_lshl_add_u64 v[216:217], v[176:177], 0, s[40:41]
	global_load_lds_dwordx4 v[216:217], off
	s_mov_b32 m0, s95
	v_lshl_add_u64 v[212:213], v[176:177], 0, s[42:43]
	global_load_lds_dwordx4 v[212:213], off
	s_waitcnt vmcnt(8)
	s_waitcnt lgkmcnt(0)
	s_barrier
	s_setprio 1
	v_mfma_f32_16x16x32_bf16 v[124:127], v[156:159], v[140:143], v[124:127]
	v_mfma_f32_16x16x32_bf16 v[120:123], v[156:159], v[148:151], v[120:123]
	v_mfma_f32_16x16x32_bf16 v[116:119], v[164:167], v[140:143], v[116:119]
	v_mfma_f32_16x16x32_bf16 v[112:115], v[164:167], v[148:151], v[112:115]
	v_mfma_f32_16x16x32_bf16 v[108:111], v[172:175], v[140:143], v[108:111]
	v_mfma_f32_16x16x32_bf16 v[104:107], v[172:175], v[148:151], v[104:107]
	v_mfma_f32_16x16x32_bf16 v[100:103], v[184:187], v[140:143], v[100:103]
	v_mfma_f32_16x16x32_bf16 v[96:99], v[184:187], v[148:151], v[96:99]
	v_mfma_f32_16x16x32_bf16 v[124:127], v[160:163], v[144:147], v[124:127]
	v_mfma_f32_16x16x32_bf16 v[120:123], v[160:163], v[152:155], v[120:123]
	v_mfma_f32_16x16x32_bf16 v[116:119], v[168:171], v[144:147], v[116:119]
	v_mfma_f32_16x16x32_bf16 v[112:115], v[168:171], v[152:155], v[112:115]
	v_mfma_f32_16x16x32_bf16 v[108:111], v[180:183], v[144:147], v[108:111]
	v_mfma_f32_16x16x32_bf16 v[104:107], v[180:183], v[152:155], v[104:107]
	v_mfma_f32_16x16x32_bf16 v[100:103], v[188:191], v[144:147], v[100:103]
	v_mfma_f32_16x16x32_bf16 v[96:99], v[188:191], v[152:155], v[96:99]
	v_mfma_f32_16x16x32_bf16 v[92:95], v[156:159], v[192:195], v[92:95]
	v_mfma_f32_16x16x32_bf16 v[88:91], v[156:159], v[200:203], v[88:91]
	v_mfma_f32_16x16x32_bf16 v[84:87], v[164:167], v[192:195], v[84:87]
	v_mfma_f32_16x16x32_bf16 v[80:83], v[164:167], v[200:203], v[80:83]
	v_mfma_f32_16x16x32_bf16 v[76:79], v[172:175], v[192:195], v[76:79]
	v_mfma_f32_16x16x32_bf16 v[72:75], v[172:175], v[200:203], v[72:75]
	v_mfma_f32_16x16x32_bf16 v[68:71], v[184:187], v[192:195], v[68:71]
	v_mfma_f32_16x16x32_bf16 v[64:67], v[184:187], v[200:203], v[64:67]
	v_mfma_f32_16x16x32_bf16 v[92:95], v[160:163], v[196:199], v[92:95]
	v_mfma_f32_16x16x32_bf16 v[88:91], v[160:163], v[204:207], v[88:91]
	v_mfma_f32_16x16x32_bf16 v[84:87], v[168:171], v[196:199], v[84:87]
	v_mfma_f32_16x16x32_bf16 v[80:83], v[168:171], v[204:207], v[80:83]
	v_mfma_f32_16x16x32_bf16 v[76:79], v[180:183], v[196:199], v[76:79]
	v_mfma_f32_16x16x32_bf16 v[72:75], v[180:183], v[204:207], v[72:75]
	v_mfma_f32_16x16x32_bf16 v[68:71], v[188:191], v[196:199], v[68:71]
	v_mfma_f32_16x16x32_bf16 v[64:67], v[188:191], v[204:207], v[64:67]
	s_setprio 0
	s_barrier
	ds_read_b128 v[156:159], v129 offset:49152
	ds_read_b128 v[160:163], v129 offset:50176
	ds_read_b128 v[164:167], v129 offset:51200
	ds_read_b128 v[168:171], v129 offset:52224
	ds_read_b128 v[172:175], v129 offset:53248
	ds_read_b128 v[180:183], v129 offset:54272
	ds_read_b128 v[184:187], v129 offset:55296
	ds_read_b128 v[188:191], v129 offset:56320
	s_mov_b32 m0, s8
	v_lshl_add_u64 v[214:215], v[208:209], 0, s[46:47]
	global_load_lds_dwordx4 v[214:215], off
	s_mov_b32 m0, s9
	v_lshl_add_u64 v[216:217], v[208:209], 0, s[48:49]
	global_load_lds_dwordx4 v[216:217], off
	s_mov_b32 m0, s50
	v_lshl_add_u64 v[212:213], v[176:177], 0, s[46:47]
	global_load_lds_dwordx4 v[212:213], off
	s_mov_b32 m0, s51
	v_lshl_add_u64 v[214:215], v[176:177], 0, s[48:49]
	global_load_lds_dwordx4 v[214:215], off
	s_mov_b32 m0, s24
	s_mov_b64 s[54:55], 0xb0180
	v_lshl_add_u64 v[216:217], v[208:209], 0, s[54:55]
	global_load_lds_dwordx4 v[216:217], off
	s_mov_b32 m0, s25
	s_mov_b64 s[54:55], 0x108180
	v_lshl_add_u64 v[212:213], v[208:209], 0, s[54:55]
	global_load_lds_dwordx4 v[212:213], off
	s_waitcnt vmcnt(6)
	s_waitcnt lgkmcnt(0)
	s_barrier
	s_setprio 1
	v_mfma_f32_16x16x32_bf16 v[60:63], v[156:159], v[140:143], v[60:63]
	v_mfma_f32_16x16x32_bf16 v[56:59], v[156:159], v[148:151], v[56:59]
	v_mfma_f32_16x16x32_bf16 v[52:55], v[164:167], v[140:143], v[52:55]
	v_mfma_f32_16x16x32_bf16 v[48:51], v[164:167], v[148:151], v[48:51]
	v_mfma_f32_16x16x32_bf16 v[44:47], v[172:175], v[140:143], v[44:47]
	v_mfma_f32_16x16x32_bf16 v[40:43], v[172:175], v[148:151], v[40:43]
	v_mfma_f32_16x16x32_bf16 v[36:39], v[184:187], v[140:143], v[36:39]
	v_mfma_f32_16x16x32_bf16 v[32:35], v[184:187], v[148:151], v[32:35]
	v_mfma_f32_16x16x32_bf16 v[60:63], v[160:163], v[144:147], v[60:63]
	v_mfma_f32_16x16x32_bf16 v[56:59], v[160:163], v[152:155], v[56:59]
	v_mfma_f32_16x16x32_bf16 v[52:55], v[168:171], v[144:147], v[52:55]
	v_mfma_f32_16x16x32_bf16 v[48:51], v[168:171], v[152:155], v[48:51]
	v_mfma_f32_16x16x32_bf16 v[44:47], v[180:183], v[144:147], v[44:47]
	v_mfma_f32_16x16x32_bf16 v[40:43], v[180:183], v[152:155], v[40:43]
	v_mfma_f32_16x16x32_bf16 v[36:39], v[188:191], v[144:147], v[36:39]
	v_mfma_f32_16x16x32_bf16 v[32:35], v[188:191], v[152:155], v[32:35]
	v_mfma_f32_16x16x32_bf16 v[28:31], v[156:159], v[192:195], v[28:31]
	v_mfma_f32_16x16x32_bf16 v[24:27], v[156:159], v[200:203], v[24:27]
	v_mfma_f32_16x16x32_bf16 v[20:23], v[164:167], v[192:195], v[20:23]
	v_mfma_f32_16x16x32_bf16 v[16:19], v[164:167], v[200:203], v[16:19]
	v_mfma_f32_16x16x32_bf16 v[12:15], v[172:175], v[192:195], v[12:15]
	v_mfma_f32_16x16x32_bf16 v[8:11], v[172:175], v[200:203], v[8:11]
	v_mfma_f32_16x16x32_bf16 v[4:7], v[184:187], v[192:195], v[4:7]
	v_mfma_f32_16x16x32_bf16 v[0:3], v[184:187], v[200:203], v[0:3]
	v_mfma_f32_16x16x32_bf16 v[28:31], v[160:163], v[196:199], v[28:31]
	v_mfma_f32_16x16x32_bf16 v[24:27], v[160:163], v[204:207], v[24:27]
	v_mfma_f32_16x16x32_bf16 v[20:23], v[168:171], v[196:199], v[20:23]
	v_mfma_f32_16x16x32_bf16 v[16:19], v[168:171], v[204:207], v[16:19]
	v_mfma_f32_16x16x32_bf16 v[12:15], v[180:183], v[196:199], v[12:15]
	v_mfma_f32_16x16x32_bf16 v[8:11], v[180:183], v[204:207], v[8:11]
	v_mfma_f32_16x16x32_bf16 v[4:7], v[188:191], v[196:199], v[4:7]
	v_mfma_f32_16x16x32_bf16 v[0:3], v[188:191], v[204:207], v[0:3]
	s_setprio 0
	s_add_i32 s27, s27, 2
	s_add_u32 s38, s38, 0x100
	s_addc_u32 s39, s39, 0
	s_add_u32 s44, s44, 0x100
	s_addc_u32 s45, s45, 0
	s_cmp_ge_i32 s27, s6
	s_barrier
	s_cbranch_scc0 .LBB0_242

; #define STAGE(P, BASE, br, kt) do { const char* _g = (const char*)((BASE) + (size_t)(br) * K + (size_t)(kt) * G_BK); \
;     _Pragma("unroll") for (int _i = 0; _i < 2; ++_i) { \
;       __builtin_amdgcn_global_load_lds((const unsigned*)(_g + (size_t)_i * 128 * K + sg_off), (unsigned*)((char*)(P) + wid * 1024 + _i * 8192), 16, 0, 0); } } while (0)
; #define LDA(dst, b, h) _Pragma("unroll") for (int m = 0; m < 4; ++m) _Pragma("unroll") for (int k = 0; k < 2; ++k) \
;     dst[m][k] = *reinterpret_cast<const bf16x8*>((const char*)shm + aoff + (((b) * 2 + (h)) * 16384 + m * 2048 + k * 1024))
; #define LDB(dst, b, h) _Pragma("unroll") for (int n = 0; n < 2; ++n) _Pragma("unroll") for (int k = 0; k < 2; ++k) \
;     dst[n][k] = *reinterpret_cast<const bf16x8*>((const char*)shm + boff + (((b) * 2 + (h)) * 16384 + n * 2048 + k * 1024))
; #define MMA(ai, bj, At, Bt_) do { __builtin_amdgcn_s_setprio(1); \
;     _Pragma("unroll") for (int m = 0; m < 4; ++m) _Pragma("unroll") for (int n = 0; n < 2; ++n) _Pragma("unroll") for (int k = 0; k < 2; ++k) \
;       acc[ai][bj][m][n] = mfma16(At[m][k], Bt_[n][k], acc[ai][bj][m][n]); \
;     __builtin_amdgcn_s_setprio(0); } while (0)
; #define WAIT_V(n) asm volatile("s_waitcnt vmcnt(" #n ")" ::: "memory")
; #define WAIT_L(n) asm volatile("s_waitcnt lgkmcnt(" #n ")" ::: "memory")
; #define BAR __builtin_amdgcn_s_barrier()
; #define SCHED __builtin_amdgcn_sched_barrier(0)
; template <class Epi>
; __device__ __forceinline__ void gemm_phase(const bfr* __restrict__ A, int lda, const bfr* __restrict__ Bt, int K,
;                                            int nM, int nN, const Epi& epi, bfr* shm, int wv, int nMfull, int ksplit) {
;     ...
;     f32x4 acc[2][2][4][2];
; #pragma unroll
;     for (int a = 0; a < 2; a++)
; #pragma unroll
;       for (int b = 0; b < 2; b++)
; #pragma unroll
;         for (int m = 0; m < 4; m++)
; #pragma unroll
;           for (int n = 0; n < 2; n++) acc[a][b][m][n] = f32x4{0.f, 0.f, 0.f, 0.f};
;     bf16x8 At[4][2], B0[2][2], B1[2][2];
;     if (wr == 1) BAR;
;     WAIT_V(10); BAR;
;     WAIT_V(6); BAR;
;     for (int t = 0; t < nt - 2; t += 2) {
;       LDB(B0, 0, 0); SCHED; LDA(At, 0, 0); STAGE(SA(1, 1), Ak, brow + G_HALF, t + 1);
;       WAIT_L(8); BAR; WAIT_L(0); MMA(0, 0, At, B0); BAR; SCHED;
;       LDB(B1, 0, 1); STAGE(SB(0, 0), Bk, bcol, t + 2);
.LBB0_394:
	s_waitcnt vmcnt(8)
	s_barrier
	s_waitcnt vmcnt(6)
	v_mov_b32_e32 v127, 0
	s_cmp_lt_u32 s0, 3
	v_mov_b32_e32 v126, v127
	v_mov_b32_e32 v125, v127
	v_mov_b32_e32 v124, v127
	v_mov_b32_e32 v123, v127
	v_mov_b32_e32 v122, v127
	v_mov_b32_e32 v121, v127
	v_mov_b32_e32 v120, v127
	v_mov_b32_e32 v119, v127
	v_mov_b32_e32 v118, v127
	v_mov_b32_e32 v117, v127
	v_mov_b32_e32 v116, v127
	v_mov_b32_e32 v115, v127
	v_mov_b32_e32 v114, v127
	v_mov_b32_e32 v113, v127
	v_mov_b32_e32 v112, v127
	v_mov_b32_e32 v111, v127
	v_mov_b32_e32 v110, v127
	v_mov_b32_e32 v109, v127
	v_mov_b32_e32 v108, v127
	v_mov_b32_e32 v107, v127
	v_mov_b32_e32 v106, v127
	v_mov_b32_e32 v105, v127
	v_mov_b32_e32 v104, v127
	v_mov_b32_e32 v103, v127
	v_mov_b32_e32 v102, v127
	v_mov_b32_e32 v101, v127
	v_mov_b32_e32 v100, v127
	v_mov_b32_e32 v99, v127
	v_mov_b32_e32 v98, v127
	v_mov_b32_e32 v97, v127
	v_mov_b32_e32 v96, v127
	v_mov_b32_e32 v95, v127
	v_mov_b32_e32 v94, v127
	v_mov_b32_e32 v93, v127
	v_mov_b32_e32 v92, v127
	v_mov_b32_e32 v91, v127
	v_mov_b32_e32 v90, v127
	v_mov_b32_e32 v89, v127
	v_mov_b32_e32 v88, v127
	v_mov_b32_e32 v87, v127
	v_mov_b32_e32 v86, v127
	v_mov_b32_e32 v85, v127
	v_mov_b32_e32 v84, v127
	v_mov_b32_e32 v83, v127
	v_mov_b32_e32 v82, v127
	v_mov_b32_e32 v81, v127
	v_mov_b32_e32 v80, v127
	v_mov_b32_e32 v79, v127
	v_mov_b32_e32 v78, v127
	v_mov_b32_e32 v77, v127
	v_mov_b32_e32 v76, v127
	v_mov_b32_e32 v75, v127
	v_mov_b32_e32 v74, v127
	v_mov_b32_e32 v73, v127
	v_mov_b32_e32 v72, v127
	v_mov_b32_e32 v71, v127
	v_mov_b32_e32 v70, v127
	v_mov_b32_e32 v69, v127
	v_mov_b32_e32 v68, v127
	v_mov_b32_e32 v67, v127
	v_mov_b32_e32 v66, v127
	v_mov_b32_e32 v65, v127
	v_mov_b32_e32 v64, v127
	v_mov_b32_e32 v63, v127
	v_mov_b32_e32 v62, v127
	v_mov_b32_e32 v61, v127
	v_mov_b32_e32 v60, v127
	v_mov_b32_e32 v59, v127
	v_mov_b32_e32 v58, v127
	v_mov_b32_e32 v57, v127
	v_mov_b32_e32 v56, v127
	v_mov_b32_e32 v55, v127
	v_mov_b32_e32 v54, v127
	v_mov_b32_e32 v53, v127
	v_mov_b32_e32 v52, v127
	v_mov_b32_e32 v51, v127
	v_mov_b32_e32 v50, v127
	v_mov_b32_e32 v49, v127
	v_mov_b32_e32 v48, v127
	v_mov_b32_e32 v47, v127
	v_mov_b32_e32 v46, v127
	v_mov_b32_e32 v45, v127
	v_mov_b32_e32 v44, v127
	v_mov_b32_e32 v43, v127
	v_mov_b32_e32 v42, v127
	v_mov_b32_e32 v41, v127
	v_mov_b32_e32 v40, v127
	v_mov_b32_e32 v39, v127
	v_mov_b32_e32 v38, v127
	v_mov_b32_e32 v37, v127
	v_mov_b32_e32 v36, v127
	v_mov_b32_e32 v35, v127
	v_mov_b32_e32 v34, v127
	v_mov_b32_e32 v33, v127
	v_mov_b32_e32 v32, v127
	v_mov_b32_e32 v31, v127
	v_mov_b32_e32 v30, v127
	v_mov_b32_e32 v29, v127
	v_mov_b32_e32 v28, v127
	v_mov_b32_e32 v27, v127
	v_mov_b32_e32 v26, v127
	v_mov_b32_e32 v25, v127
	v_mov_b32_e32 v24, v127
	v_mov_b32_e32 v23, v127
	v_mov_b32_e32 v22, v127
	v_mov_b32_e32 v21, v127
	v_mov_b32_e32 v20, v127
	v_mov_b32_e32 v19, v127
	v_mov_b32_e32 v18, v127
	v_mov_b32_e32 v17, v127
	v_mov_b32_e32 v16, v127
	v_mov_b32_e32 v15, v127
	v_mov_b32_e32 v14, v127
	v_mov_b32_e32 v13, v127
	v_mov_b32_e32 v12, v127
	v_mov_b32_e32 v11, v127
	v_mov_b32_e32 v10, v127
	v_mov_b32_e32 v9, v127
	v_mov_b32_e32 v8, v127
	v_mov_b32_e32 v7, v127
	v_mov_b32_e32 v6, v127
	v_mov_b32_e32 v5, v127
	v_mov_b32_e32 v4, v127
	v_mov_b32_e32 v3, v127
	v_mov_b32_e32 v2, v127
	v_mov_b32_e32 v1, v127
	v_mov_b32_e32 v0, v127
	s_barrier
	s_cbranch_scc1 .LBB0_398
	s_ashr_i32 s49, s48, 31
	s_ashr_i32 s43, s42, 31
	v_readlane_b32 s60, v254, 54
	s_add_i32 s1, s0, -2
	s_lshl_b64 s[2:3], s[48:49], 11
	s_lshl_b64 s[4:5], s[42:43], 11
	v_readlane_b32 s66, v254, 60
	v_readlane_b32 s67, v254, 61
	s_add_u32 s2, s66, s2
	s_addc_u32 s3, s67, s3
	s_add_u32 s4, s80, s4
	v_mov_b32_e32 v0, 0
	s_addc_u32 s5, s81, s5
	s_mov_b32 s6, 0
	v_readlane_b32 s61, v254, 55
	v_readlane_b32 s62, v254, 56
	v_readlane_b32 s63, v254, 57
	v_readlane_b32 s64, v254, 58
	v_readlane_b32 s65, v254, 59
	v_readlane_b32 s68, v254, 62
	v_readlane_b32 s69, v254, 63
	v_readlane_b32 s70, v255, 0
	v_readlane_b32 s71, v255, 1
	v_readlane_b32 s72, v255, 2
	v_readlane_b32 s73, v255, 3
	v_readlane_b32 s74, v255, 4
	v_readlane_b32 s75, v255, 5
.LBB0_396:
	ds_read_b128 v[128:131], v181
	ds_read_b128 v[136:139], v181 offset:1024
	ds_read_b128 v[142:145], v181 offset:2048
	ds_read_b128 v[146:149], v181 offset:3072
	ds_read_b128 v[150:153], v179
	ds_read_b128 v[154:157], v179 offset:1024
	ds_read_b128 v[158:161], v179 offset:2048
	ds_read_b128 v[162:165], v179 offset:3072
	ds_read_b128 v[166:169], v179 offset:4096
	ds_read_b128 v[182:185], v179 offset:5120
	ds_read_b128 v[186:189], v179 offset:6144
	ds_read_b128 v[190:193], v179 offset:7168
	ds_read_b128 v[194:197], v181 offset:16384
	ds_read_b128 v[198:201], v181 offset:17408
	ds_read_b128 v[202:205], v181 offset:18432
	ds_read_b128 v[206:209], v181 offset:19456
	v_lshl_add_u64 v[132:133], s[4:5], 0, v[140:141]
	v_lshl_add_u64 v[170:171], s[2:3], 0, v[140:141]
	s_mov_b32 m0, s58
	s_mov_b64 s[12:13], 0x40080
	v_lshl_add_u64 v[210:211], v[132:133], 0, s[12:13]
	global_load_lds_dwordx4 v[210:211], off
	s_mov_b32 m0, s59
	s_mov_b64 s[12:13], 0x60080
	v_lshl_add_u64 v[212:213], v[132:133], 0, s[12:13]
	global_load_lds_dwordx4 v[212:213], off
	s_waitcnt lgkmcnt(0)
	s_barrier
; #define STAGE(P, BASE, br, kt) do { const char* _g = (const char*)((BASE) + (size_t)(br) * K + (size_t)(kt) * G_BK); \
;     _Pragma("unroll") for (int _i = 0; _i < 2; ++_i) { \
;       __builtin_amdgcn_global_load_lds((const unsigned*)(_g + (size_t)_i * 128 * K + sg_off), (unsigned*)((char*)(P) + wid * 1024 + _i * 8192), 16, 0, 0); } } while (0)
; #define LDA(dst, b, h) _Pragma("unroll") for (int m = 0; m < 4; ++m) _Pragma("unroll") for (int k = 0; k < 2; ++k) \
;     dst[m][k] = *reinterpret_cast<const bf16x8*>((const char*)shm + aoff + (((b) * 2 + (h)) * 16384 + m * 2048 + k * 1024))
; #define LDB(dst, b, h) _Pragma("unroll") for (int n = 0; n < 2; ++n) _Pragma("unroll") for (int k = 0; k < 2; ++k) \
;     dst[n][k] = *reinterpret_cast<const bf16x8*>((const char*)shm + boff + (((b) * 2 + (h)) * 16384 + n * 2048 + k * 1024))
; #define MMA(ai, bj, At, Bt_) do { __builtin_amdgcn_s_setprio(1); \
;     _Pragma("unroll") for (int m = 0; m < 4; ++m) _Pragma("unroll") for (int n = 0; n < 2; ++n) _Pragma("unroll") for (int k = 0; k < 2; ++k) \
;       acc[ai][bj][m][n] = mfma16(At[m][k], Bt_[n][k], acc[ai][bj][m][n]); \
;     __builtin_amdgcn_s_setprio(0); } while (0)
; #define WAIT_V(n) asm volatile("s_waitcnt vmcnt(" #n ")" ::: "memory")
; #define WAIT_L(n) asm volatile("s_waitcnt lgkmcnt(" #n ")" ::: "memory")
; #define BAR __builtin_amdgcn_s_barrier()
; #define SCHED __builtin_amdgcn_sched_barrier(0)
; template <class Epi>
; __device__ __forceinline__ void gemm_phase(const bfr* __restrict__ A, int lda, const bfr* __restrict__ Bt, int K,
;                                            int nM, int nN, const Epi& epi, bfr* shm, int wv, int nMfull, int ksplit) {
;     ...
;       WAIT_L(8); BAR; WAIT_L(0); MMA(0, 0, At, B0); BAR; SCHED;
;       LDB(B1, 0, 1); STAGE(SB(0, 0), Bk, bcol, t + 2);
;       BAR; WAIT_L(0); MMA(0, 1, At, B1); BAR;
;       LDA(At, 0, 1); STAGE(SA(0, 0), Ak, brow, t + 2);
;       BAR; WAIT_L(0); MMA(1, 0, At, B0); BAR; SCHED;
;       STAGE(SB(0, 1), Bk, bcol + G_HALF, t + 2);
;       WAIT_V(6); BAR; MMA(1, 1, At, B1); BAR;
	s_setprio 1
	v_mfma_f32_16x16x32_bf16 v[124:127], v[150:153], v[128:131], v[124:127]
	v_mfma_f32_16x16x32_bf16 v[120:123], v[150:153], v[142:145], v[120:123]
	v_mfma_f32_16x16x32_bf16 v[116:119], v[158:161], v[128:131], v[116:119]
	v_mfma_f32_16x16x32_bf16 v[112:115], v[158:161], v[142:145], v[112:115]
	v_mfma_f32_16x16x32_bf16 v[108:111], v[166:169], v[128:131], v[108:111]
	v_mfma_f32_16x16x32_bf16 v[104:107], v[166:169], v[142:145], v[104:107]
	v_mfma_f32_16x16x32_bf16 v[100:103], v[186:189], v[128:131], v[100:103]
	v_mfma_f32_16x16x32_bf16 v[96:99], v[186:189], v[142:145], v[96:99]
	v_mfma_f32_16x16x32_bf16 v[124:127], v[154:157], v[136:139], v[124:127]
	v_mfma_f32_16x16x32_bf16 v[120:123], v[154:157], v[146:149], v[120:123]
	v_mfma_f32_16x16x32_bf16 v[116:119], v[162:165], v[136:139], v[116:119]
	v_mfma_f32_16x16x32_bf16 v[112:115], v[162:165], v[146:149], v[112:115]
	v_mfma_f32_16x16x32_bf16 v[108:111], v[182:185], v[136:139], v[108:111]
	v_mfma_f32_16x16x32_bf16 v[104:107], v[182:185], v[146:149], v[104:107]
	v_mfma_f32_16x16x32_bf16 v[100:103], v[190:193], v[136:139], v[100:103]
	v_mfma_f32_16x16x32_bf16 v[96:99], v[190:193], v[146:149], v[96:99]
	v_mfma_f32_16x16x32_bf16 v[92:95], v[150:153], v[194:197], v[92:95]
	v_mfma_f32_16x16x32_bf16 v[88:91], v[150:153], v[202:205], v[88:91]
	v_mfma_f32_16x16x32_bf16 v[84:87], v[158:161], v[194:197], v[84:87]
	v_mfma_f32_16x16x32_bf16 v[80:83], v[158:161], v[202:205], v[80:83]
	v_mfma_f32_16x16x32_bf16 v[76:79], v[166:169], v[194:197], v[76:79]
	v_mfma_f32_16x16x32_bf16 v[72:75], v[166:169], v[202:205], v[72:75]
	v_mfma_f32_16x16x32_bf16 v[68:71], v[186:189], v[194:197], v[68:71]
	v_mfma_f32_16x16x32_bf16 v[64:67], v[186:189], v[202:205], v[64:67]
	v_mfma_f32_16x16x32_bf16 v[92:95], v[154:157], v[198:201], v[92:95]
	v_mfma_f32_16x16x32_bf16 v[88:91], v[154:157], v[206:209], v[88:91]
	v_mfma_f32_16x16x32_bf16 v[84:87], v[162:165], v[198:201], v[84:87]
	v_mfma_f32_16x16x32_bf16 v[80:83], v[162:165], v[206:209], v[80:83]
	v_mfma_f32_16x16x32_bf16 v[76:79], v[182:185], v[198:201], v[76:79]
	v_mfma_f32_16x16x32_bf16 v[72:75], v[182:185], v[206:209], v[72:75]
	v_mfma_f32_16x16x32_bf16 v[68:71], v[190:193], v[198:201], v[68:71]
	v_mfma_f32_16x16x32_bf16 v[64:67], v[190:193], v[206:209], v[64:67]
	s_setprio 0
	s_barrier
	ds_read_b128 v[150:153], v179 offset:16384
	ds_read_b128 v[154:157], v179 offset:17408
	ds_read_b128 v[158:161], v179 offset:18432
	ds_read_b128 v[162:165], v179 offset:19456
	ds_read_b128 v[166:169], v179 offset:20480
	ds_read_b128 v[182:185], v179 offset:21504
	ds_read_b128 v[186:189], v179 offset:22528
	ds_read_b128 v[190:193], v179 offset:23552
	s_mov_b32 m0, s97
	v_lshl_add_u64 v[214:215], v[170:171], 0, s[14:15]
	global_load_lds_dwordx4 v[214:215], off
	s_mov_b32 m0, s51
	v_lshl_add_u64 v[210:211], v[170:171], 0, s[16:17]
	global_load_lds_dwordx4 v[210:211], off
	s_mov_b32 m0, s56
	v_lshl_add_u64 v[212:213], v[132:133], 0, s[14:15]
	global_load_lds_dwordx4 v[212:213], off
	s_mov_b32 m0, s57
	v_lshl_add_u64 v[214:215], v[132:133], 0, s[16:17]
	global_load_lds_dwordx4 v[214:215], off
	s_waitcnt vmcnt(6)
	s_waitcnt lgkmcnt(0)
	s_barrier
	s_setprio 1
	v_mfma_f32_16x16x32_bf16 v[60:63], v[150:153], v[128:131], v[60:63]
	v_mfma_f32_16x16x32_bf16 v[56:59], v[150:153], v[142:145], v[56:59]
	v_mfma_f32_16x16x32_bf16 v[52:55], v[158:161], v[128:131], v[52:55]
	v_mfma_f32_16x16x32_bf16 v[48:51], v[158:161], v[142:145], v[48:51]
	v_mfma_f32_16x16x32_bf16 v[44:47], v[166:169], v[128:131], v[44:47]
	v_mfma_f32_16x16x32_bf16 v[40:43], v[166:169], v[142:145], v[40:43]
	v_mfma_f32_16x16x32_bf16 v[36:39], v[186:189], v[128:131], v[36:39]
	v_mfma_f32_16x16x32_bf16 v[32:35], v[186:189], v[142:145], v[32:35]
	v_mfma_f32_16x16x32_bf16 v[60:63], v[154:157], v[136:139], v[60:63]
	v_mfma_f32_16x16x32_bf16 v[56:59], v[154:157], v[146:149], v[56:59]
	v_mfma_f32_16x16x32_bf16 v[52:55], v[162:165], v[136:139], v[52:55]
	v_mfma_f32_16x16x32_bf16 v[48:51], v[162:165], v[146:149], v[48:51]
	v_mfma_f32_16x16x32_bf16 v[44:47], v[182:185], v[136:139], v[44:47]
	v_mfma_f32_16x16x32_bf16 v[40:43], v[182:185], v[146:149], v[40:43]
	v_mfma_f32_16x16x32_bf16 v[36:39], v[190:193], v[136:139], v[36:39]
	v_mfma_f32_16x16x32_bf16 v[32:35], v[190:193], v[146:149], v[32:35]
	v_mfma_f32_16x16x32_bf16 v[28:31], v[150:153], v[194:197], v[28:31]
	v_mfma_f32_16x16x32_bf16 v[24:27], v[150:153], v[202:205], v[24:27]
	v_mfma_f32_16x16x32_bf16 v[20:23], v[158:161], v[194:197], v[20:23]
	v_mfma_f32_16x16x32_bf16 v[16:19], v[158:161], v[202:205], v[16:19]
	v_mfma_f32_16x16x32_bf16 v[12:15], v[166:169], v[194:197], v[12:15]
	v_mfma_f32_16x16x32_bf16 v[8:11], v[166:169], v[202:205], v[8:11]
	v_mfma_f32_16x16x32_bf16 v[4:7], v[186:189], v[194:197], v[4:7]
	v_mfma_f32_16x16x32_bf16 v[0:3], v[186:189], v[202:205], v[0:3]
	v_mfma_f32_16x16x32_bf16 v[28:31], v[154:157], v[198:201], v[28:31]
	v_mfma_f32_16x16x32_bf16 v[24:27], v[154:157], v[206:209], v[24:27]
	v_mfma_f32_16x16x32_bf16 v[20:23], v[162:165], v[198:201], v[20:23]
	v_mfma_f32_16x16x32_bf16 v[16:19], v[162:165], v[206:209], v[16:19]
	v_mfma_f32_16x16x32_bf16 v[12:15], v[182:185], v[198:201], v[12:15]
	v_mfma_f32_16x16x32_bf16 v[8:11], v[182:185], v[206:209], v[8:11]
	v_mfma_f32_16x16x32_bf16 v[4:7], v[190:193], v[198:201], v[4:7]
	v_mfma_f32_16x16x32_bf16 v[0:3], v[190:193], v[206:209], v[0:3]
	s_setprio 0
	s_barrier
; #define STAGE(P, BASE, br, kt) do { const char* _g = (const char*)((BASE) + (size_t)(br) * K + (size_t)(kt) * G_BK); \
;     _Pragma("unroll") for (int _i = 0; _i < 2; ++_i) { \
;       __builtin_amdgcn_global_load_lds((const unsigned*)(_g + (size_t)_i * 128 * K + sg_off), (unsigned*)((char*)(P) + wid * 1024 + _i * 8192), 16, 0, 0); } } while (0)
; #define LDA(dst, b, h) _Pragma("unroll") for (int m = 0; m < 4; ++m) _Pragma("unroll") for (int k = 0; k < 2; ++k) \
;     dst[m][k] = *reinterpret_cast<const bf16x8*>((const char*)shm + aoff + (((b) * 2 + (h)) * 16384 + m * 2048 + k * 1024))
; #define LDB(dst, b, h) _Pragma("unroll") for (int n = 0; n < 2; ++n) _Pragma("unroll") for (int k = 0; k < 2; ++k) \
;     dst[n][k] = *reinterpret_cast<const bf16x8*>((const char*)shm + boff + (((b) * 2 + (h)) * 16384 + n * 2048 + k * 1024))
; #define MMA(ai, bj, At, Bt_) do { __builtin_amdgcn_s_setprio(1); \
;     _Pragma("unroll") for (int m = 0; m < 4; ++m) _Pragma("unroll") for (int n = 0; n < 2; ++n) _Pragma("unroll") for (int k = 0; k < 2; ++k) \
;       acc[ai][bj][m][n] = mfma16(At[m][k], Bt_[n][k], acc[ai][bj][m][n]); \
;     __builtin_amdgcn_s_setprio(0); } while (0)
; #define WAIT_L(n) asm volatile("s_waitcnt lgkmcnt(" #n ")" ::: "memory")
; #define BAR __builtin_amdgcn_s_barrier()
; #define SCHED __builtin_amdgcn_sched_barrier(0)
; template <class Epi>
; __device__ __forceinline__ void gemm_phase(const bfr* __restrict__ A, int lda, const bfr* __restrict__ Bt, int K,
;                                            int nM, int nN, const Epi& epi, bfr* shm, int wv, int nMfull, int ksplit) {
;     ...
;       LDB(B0, 1, 0); SCHED; LDA(At, 1, 0); STAGE(SA(0, 1), Ak, brow + G_HALF, t + 2);
;       WAIT_L(8); BAR; WAIT_L(0); MMA(0, 0, At, B0); BAR; SCHED;
;       LDB(B1, 1, 1); STAGE(SB(1, 0), Bk, bcol, t + 3);
;       BAR; WAIT_L(0); MMA(0, 1, At, B1); BAR;
	ds_read_b128 v[128:131], v181 offset:32768
	ds_read_b128 v[136:139], v181 offset:33792
	ds_read_b128 v[142:145], v181 offset:34816
	ds_read_b128 v[146:149], v181 offset:35840
	ds_read_b128 v[150:153], v179 offset:32768
	ds_read_b128 v[154:157], v179 offset:33792
	ds_read_b128 v[158:161], v179 offset:34816
	ds_read_b128 v[162:165], v179 offset:35840
	ds_read_b128 v[166:169], v179 offset:36864
	ds_read_b128 v[182:185], v179 offset:37888
	ds_read_b128 v[186:189], v179 offset:38912
	ds_read_b128 v[190:193], v179 offset:39936
	ds_read_b128 v[194:197], v181 offset:49152
	ds_read_b128 v[198:201], v181 offset:50176
	ds_read_b128 v[202:205], v181 offset:51200
	ds_read_b128 v[206:209], v181 offset:52224
	s_mov_b32 m0, s33
	v_lshl_add_u64 v[210:211], v[170:171], 0, s[18:19]
	global_load_lds_dwordx4 v[210:211], off
	s_mov_b32 m0, s22
	v_lshl_add_u64 v[212:213], v[170:171], 0, s[20:21]
	global_load_lds_dwordx4 v[212:213], off
	s_mov_b32 m0, s23
	v_lshl_add_u64 v[214:215], v[132:133], 0, s[18:19]
	global_load_lds_dwordx4 v[214:215], off
	s_mov_b32 m0, s24
	v_lshl_add_u64 v[210:211], v[132:133], 0, s[20:21]
	global_load_lds_dwordx4 v[210:211], off
	s_waitcnt vmcnt(8)
	s_waitcnt lgkmcnt(0)
	s_barrier
	s_setprio 1
	v_mfma_f32_16x16x32_bf16 v[124:127], v[150:153], v[128:131], v[124:127]
	v_mfma_f32_16x16x32_bf16 v[120:123], v[150:153], v[142:145], v[120:123]
	v_mfma_f32_16x16x32_bf16 v[116:119], v[158:161], v[128:131], v[116:119]
	v_mfma_f32_16x16x32_bf16 v[112:115], v[158:161], v[142:145], v[112:115]
	v_mfma_f32_16x16x32_bf16 v[108:111], v[166:169], v[128:131], v[108:111]
	v_mfma_f32_16x16x32_bf16 v[104:107], v[166:169], v[142:145], v[104:107]
	v_mfma_f32_16x16x32_bf16 v[100:103], v[186:189], v[128:131], v[100:103]
	v_mfma_f32_16x16x32_bf16 v[96:99], v[186:189], v[142:145], v[96:99]
	v_mfma_f32_16x16x32_bf16 v[124:127], v[154:157], v[136:139], v[124:127]
	v_mfma_f32_16x16x32_bf16 v[120:123], v[154:157], v[146:149], v[120:123]
	v_mfma_f32_16x16x32_bf16 v[116:119], v[162:165], v[136:139], v[116:119]
	v_mfma_f32_16x16x32_bf16 v[112:115], v[162:165], v[146:149], v[112:115]
	v_mfma_f32_16x16x32_bf16 v[108:111], v[182:185], v[136:139], v[108:111]
	v_mfma_f32_16x16x32_bf16 v[104:107], v[182:185], v[146:149], v[104:107]
	v_mfma_f32_16x16x32_bf16 v[100:103], v[190:193], v[136:139], v[100:103]
	v_mfma_f32_16x16x32_bf16 v[96:99], v[190:193], v[146:149], v[96:99]
	v_mfma_f32_16x16x32_bf16 v[92:95], v[150:153], v[194:197], v[92:95]
	v_mfma_f32_16x16x32_bf16 v[88:91], v[150:153], v[202:205], v[88:91]
	v_mfma_f32_16x16x32_bf16 v[84:87], v[158:161], v[194:197], v[84:87]
	v_mfma_f32_16x16x32_bf16 v[80:83], v[158:161], v[202:205], v[80:83]
	v_mfma_f32_16x16x32_bf16 v[76:79], v[166:169], v[194:197], v[76:79]
	v_mfma_f32_16x16x32_bf16 v[72:75], v[166:169], v[202:205], v[72:75]
	v_mfma_f32_16x16x32_bf16 v[68:71], v[186:189], v[194:197], v[68:71]
	v_mfma_f32_16x16x32_bf16 v[64:67], v[186:189], v[202:205], v[64:67]
	v_mfma_f32_16x16x32_bf16 v[92:95], v[154:157], v[198:201], v[92:95]
	v_mfma_f32_16x16x32_bf16 v[88:91], v[154:157], v[206:209], v[88:91]
	v_mfma_f32_16x16x32_bf16 v[84:87], v[162:165], v[198:201], v[84:87]
	v_mfma_f32_16x16x32_bf16 v[80:83], v[162:165], v[206:209], v[80:83]
	v_mfma_f32_16x16x32_bf16 v[76:79], v[182:185], v[198:201], v[76:79]
	v_mfma_f32_16x16x32_bf16 v[72:75], v[182:185], v[206:209], v[72:75]
	v_mfma_f32_16x16x32_bf16 v[68:71], v[190:193], v[198:201], v[68:71]
	v_mfma_f32_16x16x32_bf16 v[64:67], v[190:193], v[206:209], v[64:67]
	s_setprio 0
	s_barrier
; #define STAGE(P, BASE, br, kt) do { const char* _g = (const char*)((BASE) + (size_t)(br) * K + (size_t)(kt) * G_BK); \
;     _Pragma("unroll") for (int _i = 0; _i < 2; ++_i) { \
;       __builtin_amdgcn_global_load_lds((const unsigned*)(_g + (size_t)_i * 128 * K + sg_off), (unsigned*)((char*)(P) + wid * 1024 + _i * 8192), 16, 0, 0); } } while (0)
; #define LDA(dst, b, h) _Pragma("unroll") for (int m = 0; m < 4; ++m) _Pragma("unroll") for (int k = 0; k < 2; ++k) \
;     dst[m][k] = *reinterpret_cast<const bf16x8*>((const char*)shm + aoff + (((b) * 2 + (h)) * 16384 + m * 2048 + k * 1024))
; #define MMA(ai, bj, At, Bt_) do { __builtin_amdgcn_s_setprio(1); \
;     _Pragma("unroll") for (int m = 0; m < 4; ++m) _Pragma("unroll") for (int n = 0; n < 2; ++n) _Pragma("unroll") for (int k = 0; k < 2; ++k) \
;       acc[ai][bj][m][n] = mfma16(At[m][k], Bt_[n][k], acc[ai][bj][m][n]); \
;     __builtin_amdgcn_s_setprio(0); } while (0)
; #define WAIT_V(n) asm volatile("s_waitcnt vmcnt(" #n ")" ::: "memory")
; #define WAIT_L(n) asm volatile("s_waitcnt lgkmcnt(" #n ")" ::: "memory")
; #define BAR __builtin_amdgcn_s_barrier()
; #define SCHED __builtin_amdgcn_sched_barrier(0)
; template <class Epi>
; __device__ __forceinline__ void gemm_phase(const bfr* __restrict__ A, int lda, const bfr* __restrict__ Bt, int K,
;                                            int nM, int nN, const Epi& epi, bfr* shm, int wv, int nMfull, int ksplit) {
;     ...
;       LDA(At, 1, 1); STAGE(SA(1, 0), Ak, brow, t + 3);
;       BAR; WAIT_L(0); MMA(1, 0, At, B0); BAR; SCHED;
;       STAGE(SB(1, 1), Bk, bcol + G_HALF, t + 3);
;       WAIT_V(6); BAR; MMA(1, 1, At, B1); BAR;
;     }
	ds_read_b128 v[150:153], v179 offset:49152
	ds_read_b128 v[154:157], v179 offset:50176
	ds_read_b128 v[158:161], v179 offset:51200
	ds_read_b128 v[162:165], v179 offset:52224
	ds_read_b128 v[166:169], v179 offset:53248
	ds_read_b128 v[182:185], v179 offset:54272
	ds_read_b128 v[186:189], v179 offset:55296
	ds_read_b128 v[190:193], v179 offset:56320
	s_mov_b32 m0, s25
	v_lshl_add_u64 v[212:213], v[170:171], 0, s[30:31]
	global_load_lds_dwordx4 v[212:213], off
	s_mov_b32 m0, s26
	v_lshl_add_u64 v[214:215], v[170:171], 0, s[40:41]
	global_load_lds_dwordx4 v[214:215], off
	s_mov_b32 m0, s27
	v_lshl_add_u64 v[210:211], v[132:133], 0, s[30:31]
	global_load_lds_dwordx4 v[210:211], off
	s_mov_b32 m0, s28
	v_lshl_add_u64 v[212:213], v[132:133], 0, s[40:41]
	global_load_lds_dwordx4 v[212:213], off
	s_mov_b32 m0, s29
	s_mov_b64 s[12:13], 0x40180
	v_lshl_add_u64 v[214:215], v[170:171], 0, s[12:13]
	global_load_lds_dwordx4 v[214:215], off
	s_mov_b32 m0, s9
	s_mov_b64 s[12:13], 0x60180
	v_lshl_add_u64 v[210:211], v[170:171], 0, s[12:13]
	global_load_lds_dwordx4 v[210:211], off
	s_waitcnt vmcnt(6)
	s_waitcnt lgkmcnt(0)
	s_barrier
	s_setprio 1
	v_mfma_f32_16x16x32_bf16 v[60:63], v[150:153], v[128:131], v[60:63]
	v_mfma_f32_16x16x32_bf16 v[56:59], v[150:153], v[142:145], v[56:59]
	v_mfma_f32_16x16x32_bf16 v[52:55], v[158:161], v[128:131], v[52:55]
	v_mfma_f32_16x16x32_bf16 v[48:51], v[158:161], v[142:145], v[48:51]
	v_mfma_f32_16x16x32_bf16 v[44:47], v[166:169], v[128:131], v[44:47]
	v_mfma_f32_16x16x32_bf16 v[40:43], v[166:169], v[142:145], v[40:43]
	v_mfma_f32_16x16x32_bf16 v[36:39], v[186:189], v[128:131], v[36:39]
	v_mfma_f32_16x16x32_bf16 v[32:35], v[186:189], v[142:145], v[32:35]
	v_mfma_f32_16x16x32_bf16 v[60:63], v[154:157], v[136:139], v[60:63]
	v_mfma_f32_16x16x32_bf16 v[56:59], v[154:157], v[146:149], v[56:59]
	v_mfma_f32_16x16x32_bf16 v[52:55], v[162:165], v[136:139], v[52:55]
	v_mfma_f32_16x16x32_bf16 v[48:51], v[162:165], v[146:149], v[48:51]
	v_mfma_f32_16x16x32_bf16 v[44:47], v[182:185], v[136:139], v[44:47]
	v_mfma_f32_16x16x32_bf16 v[40:43], v[182:185], v[146:149], v[40:43]
	v_mfma_f32_16x16x32_bf16 v[36:39], v[190:193], v[136:139], v[36:39]
	v_mfma_f32_16x16x32_bf16 v[32:35], v[190:193], v[146:149], v[32:35]
	v_mfma_f32_16x16x32_bf16 v[28:31], v[150:153], v[194:197], v[28:31]
	v_mfma_f32_16x16x32_bf16 v[24:27], v[150:153], v[202:205], v[24:27]
	v_mfma_f32_16x16x32_bf16 v[20:23], v[158:161], v[194:197], v[20:23]
	v_mfma_f32_16x16x32_bf16 v[16:19], v[158:161], v[202:205], v[16:19]
	v_mfma_f32_16x16x32_bf16 v[12:15], v[166:169], v[194:197], v[12:15]
	v_mfma_f32_16x16x32_bf16 v[8:11], v[166:169], v[202:205], v[8:11]
	v_mfma_f32_16x16x32_bf16 v[4:7], v[186:189], v[194:197], v[4:7]
	v_mfma_f32_16x16x32_bf16 v[0:3], v[186:189], v[202:205], v[0:3]
	v_mfma_f32_16x16x32_bf16 v[28:31], v[154:157], v[198:201], v[28:31]
	v_mfma_f32_16x16x32_bf16 v[24:27], v[154:157], v[206:209], v[24:27]
	v_mfma_f32_16x16x32_bf16 v[20:23], v[162:165], v[198:201], v[20:23]
	v_mfma_f32_16x16x32_bf16 v[16:19], v[162:165], v[206:209], v[16:19]
	v_mfma_f32_16x16x32_bf16 v[12:15], v[182:185], v[198:201], v[12:15]
	v_mfma_f32_16x16x32_bf16 v[8:11], v[182:185], v[206:209], v[8:11]
	v_mfma_f32_16x16x32_bf16 v[4:7], v[190:193], v[198:201], v[4:7]
	v_mfma_f32_16x16x32_bf16 v[0:3], v[190:193], v[206:209], v[0:3]
	s_setprio 0
	s_add_i32 s6, s6, 2
	s_add_u32 s2, s2, 0x100
	s_addc_u32 s3, s3, 0
	s_add_u32 s4, s4, 0x100
	s_addc_u32 s5, s5, 0
	s_cmp_ge_i32 s6, s1
	s_barrier
	s_cbranch_scc0 .LBB0_396
	v_readlane_b32 s60, v255, 41

; #define WAIT_V(n) asm volatile("s_waitcnt vmcnt(" #n ")" ::: "memory")
; #define BAR __builtin_amdgcn_s_barrier()
; template <class Epi>
; __device__ __forceinline__ void gemm_phase(const bfr* __restrict__ A, int lda, const bfr* __restrict__ Bt, int K,
;                                            int nM, int nN, const Epi& epi, bfr* shm, int wv, int nMfull, int ksplit) {
;     ...
;     f32x4 acc[2][2][4][2];
; #pragma unroll
;     for (int a = 0; a < 2; a++)
; #pragma unroll
;       for (int b = 0; b < 2; b++)
; #pragma unroll
;         for (int m = 0; m < 4; m++)
; #pragma unroll
;           for (int n = 0; n < 2; n++) acc[a][b][m][n] = f32x4{0.f, 0.f, 0.f, 0.f};
;     bf16x8 At[4][2], B0[2][2], B1[2][2];
;     if (wr == 1) BAR;
;     WAIT_V(10); BAR;
;     WAIT_V(6); BAR;
;     for (int t = 0; t < nt - 2; t += 2) {
.LBB0_521:
	v_readlane_b32 s52, v255, 10
	s_lshl_b64 s[42:43], s[8:9], 1
	v_readlane_b32 s60, v255, 18
	v_readlane_b32 s61, v255, 19
	s_add_u32 s8, s60, s42
	s_waitcnt vmcnt(8)
	s_barrier
	s_waitcnt vmcnt(6)
	s_addc_u32 s39, s61, s43
	v_mov_b32_e32 v127, 0
	s_cmp_lt_u32 s38, 3
	v_mov_b32_e32 v126, v127
	v_mov_b32_e32 v125, v127
	v_mov_b32_e32 v124, v127
	v_mov_b32_e32 v123, v127
	v_mov_b32_e32 v122, v127
	v_mov_b32_e32 v121, v127
	v_mov_b32_e32 v120, v127
	v_mov_b32_e32 v119, v127
	v_mov_b32_e32 v118, v127
	v_mov_b32_e32 v117, v127
	v_mov_b32_e32 v116, v127
	v_mov_b32_e32 v115, v127
	v_mov_b32_e32 v114, v127
	v_mov_b32_e32 v113, v127
	v_mov_b32_e32 v112, v127
	v_mov_b32_e32 v111, v127
	v_mov_b32_e32 v110, v127
	v_mov_b32_e32 v109, v127
	v_mov_b32_e32 v108, v127
	v_mov_b32_e32 v107, v127
	v_mov_b32_e32 v106, v127
	v_mov_b32_e32 v105, v127
	v_mov_b32_e32 v104, v127
	v_mov_b32_e32 v103, v127
	v_mov_b32_e32 v102, v127
	v_mov_b32_e32 v101, v127
	v_mov_b32_e32 v100, v127
	v_mov_b32_e32 v99, v127
	v_mov_b32_e32 v98, v127
	v_mov_b32_e32 v97, v127
	v_mov_b32_e32 v96, v127
	s_waitcnt vmcnt(0)
	v_mov_b32_e32 v95, v127
	v_mov_b32_e32 v94, v127
	v_mov_b32_e32 v93, v127
	v_mov_b32_e32 v92, v127
	v_mov_b32_e32 v91, v127
	v_mov_b32_e32 v90, v127
	v_mov_b32_e32 v89, v127
	v_mov_b32_e32 v88, v127
	v_mov_b32_e32 v87, v127
	v_mov_b32_e32 v86, v127
	v_mov_b32_e32 v85, v127
	v_mov_b32_e32 v84, v127
	v_mov_b32_e32 v83, v127
	v_mov_b32_e32 v82, v127
	v_mov_b32_e32 v81, v127
	v_mov_b32_e32 v80, v127
	v_mov_b32_e32 v79, v127
	v_mov_b32_e32 v78, v127
	v_mov_b32_e32 v77, v127
	v_mov_b32_e32 v76, v127
	v_mov_b32_e32 v75, v127
	v_mov_b32_e32 v74, v127
	v_mov_b32_e32 v73, v127
	v_mov_b32_e32 v72, v127
	v_mov_b32_e32 v71, v127
	v_mov_b32_e32 v70, v127
	v_mov_b32_e32 v69, v127
	v_mov_b32_e32 v68, v127
	v_mov_b32_e32 v67, v127
	v_mov_b32_e32 v66, v127
	v_mov_b32_e32 v65, v127
	v_mov_b32_e32 v64, v127
	v_mov_b32_e32 v63, v127
	v_mov_b32_e32 v62, v127
	v_mov_b32_e32 v61, v127
	v_mov_b32_e32 v60, v127
	v_mov_b32_e32 v59, v127
	v_mov_b32_e32 v58, v127
	v_mov_b32_e32 v57, v127
	v_mov_b32_e32 v56, v127
	v_mov_b32_e32 v55, v127
	v_mov_b32_e32 v54, v127
	v_mov_b32_e32 v53, v127
	v_mov_b32_e32 v52, v127
	v_mov_b32_e32 v51, v127
	v_mov_b32_e32 v50, v127
	v_mov_b32_e32 v49, v127
	v_mov_b32_e32 v48, v127
	v_mov_b32_e32 v47, v127
	v_mov_b32_e32 v46, v127
	v_mov_b32_e32 v45, v127
	v_mov_b32_e32 v44, v127
	v_mov_b32_e32 v43, v127
	v_mov_b32_e32 v42, v127
	v_mov_b32_e32 v41, v127
	v_mov_b32_e32 v40, v127
	v_mov_b32_e32 v39, v127
	v_mov_b32_e32 v38, v127
	v_mov_b32_e32 v37, v127
	v_mov_b32_e32 v36, v127
	v_mov_b32_e32 v35, v127
	v_mov_b32_e32 v34, v127
	v_mov_b32_e32 v33, v127
	v_mov_b32_e32 v32, v127
	v_mov_b32_e32 v31, v127
	v_mov_b32_e32 v30, v127
	v_mov_b32_e32 v29, v127
	v_mov_b32_e32 v28, v127
	v_mov_b32_e32 v27, v127
	v_mov_b32_e32 v26, v127
	v_mov_b32_e32 v25, v127
	v_mov_b32_e32 v24, v127
	v_mov_b32_e32 v23, v127
	v_mov_b32_e32 v22, v127
	v_mov_b32_e32 v21, v127
	v_mov_b32_e32 v20, v127
	v_mov_b32_e32 v19, v127
	v_mov_b32_e32 v18, v127
	v_mov_b32_e32 v17, v127
	v_mov_b32_e32 v16, v127
	v_mov_b32_e32 v15, v127
	v_mov_b32_e32 v14, v127
	v_mov_b32_e32 v13, v127
	v_mov_b32_e32 v12, v127
	v_mov_b32_e32 v11, v127
	v_mov_b32_e32 v10, v127
	v_mov_b32_e32 v9, v127
	v_mov_b32_e32 v8, v127
	v_mov_b32_e32 v7, v127
	v_mov_b32_e32 v6, v127
	v_mov_b32_e32 v5, v127
	v_mov_b32_e32 v4, v127
	v_mov_b32_e32 v3, v127
	v_mov_b32_e32 v2, v127
	v_mov_b32_e32 v1, v127
	v_mov_b32_e32 v0, v127
	v_readlane_b32 s53, v255, 11
	v_readlane_b32 s54, v255, 12
	v_readlane_b32 s55, v255, 13
	v_readlane_b32 s56, v255, 14
	v_readlane_b32 s57, v255, 15
	v_readlane_b32 s58, v255, 16
	v_readlane_b32 s59, v255, 17
	v_readlane_b32 s62, v255, 20
	v_readlane_b32 s63, v255, 21
	v_readlane_b32 s64, v255, 22
	v_readlane_b32 s65, v255, 23
	v_readlane_b32 s66, v255, 24
	v_readlane_b32 s67, v255, 25
	s_barrier
	s_cbranch_scc1 .LBB0_524
	v_readlane_b32 s52, v254, 54
	s_add_i32 s46, s38, -2
	v_readlane_b32 s60, v254, 62
	v_readlane_b32 s61, v254, 63
	s_add_u32 s41, s60, s42
	s_addc_u32 s44, s61, s43
	s_ashr_i32 s49, s48, 31
	s_lshl_b64 s[42:43], s[48:49], 11
	s_add_u32 s42, s41, s42
	s_addc_u32 s43, s44, s43
	s_ashr_i32 s41, s40, 31
	s_lshl_b64 s[44:45], s[40:41], 11
	s_add_u32 s44, s8, s44
	v_mov_b32_e32 v0, 0
	s_addc_u32 s45, s39, s45
	s_mov_b32 s41, 0
	v_readlane_b32 s53, v254, 55
	v_readlane_b32 s54, v254, 56
	v_readlane_b32 s55, v254, 57
	v_readlane_b32 s56, v254, 58
	v_readlane_b32 s57, v254, 59
	v_readlane_b32 s58, v254, 60
	v_readlane_b32 s59, v254, 61
	v_readlane_b32 s62, v255, 0
	v_readlane_b32 s63, v255, 1
	v_readlane_b32 s64, v255, 2
	v_readlane_b32 s65, v255, 3
	v_readlane_b32 s66, v255, 4
	v_readlane_b32 s67, v255, 5
; #define STAGE(P, BASE, br, kt) do { const char* _g = (const char*)((BASE) + (size_t)(br) * K + (size_t)(kt) * G_BK); \
;     _Pragma("unroll") for (int _i = 0; _i < 2; ++_i) { \
;       __builtin_amdgcn_global_load_lds((const unsigned*)(_g + (size_t)_i * 128 * K + sg_off), (unsigned*)((char*)(P) + wid * 1024 + _i * 8192), 16, 0, 0); } } while (0)
; #define LDA(dst, b, h) _Pragma("unroll") for (int m = 0; m < 4; ++m) _Pragma("unroll") for (int k = 0; k < 2; ++k) \
;     dst[m][k] = *reinterpret_cast<const bf16x8*>((const char*)shm + aoff + (((b) * 2 + (h)) * 16384 + m * 2048 + k * 1024))
; #define LDB(dst, b, h) _Pragma("unroll") for (int n = 0; n < 2; ++n) _Pragma("unroll") for (int k = 0; k < 2; ++k) \
;     dst[n][k] = *reinterpret_cast<const bf16x8*>((const char*)shm + boff + (((b) * 2 + (h)) * 16384 + n * 2048 + k * 1024))
; #define MMA(ai, bj, At, Bt_) do { __builtin_amdgcn_s_setprio(1); \
;     _Pragma("unroll") for (int m = 0; m < 4; ++m) _Pragma("unroll") for (int n = 0; n < 2; ++n) _Pragma("unroll") for (int k = 0; k < 2; ++k) \
;       acc[ai][bj][m][n] = mfma16(At[m][k], Bt_[n][k], acc[ai][bj][m][n]); \
;     __builtin_amdgcn_s_setprio(0); } while (0)
; #define WAIT_V(n) asm volatile("s_waitcnt vmcnt(" #n ")" ::: "memory")
; #define WAIT_L(n) asm volatile("s_waitcnt lgkmcnt(" #n ")" ::: "memory")
; #define BAR __builtin_amdgcn_s_barrier()
; #define SCHED __builtin_amdgcn_sched_barrier(0)
; template <class Epi>
; __device__ __forceinline__ void gemm_phase(const bfr* __restrict__ A, int lda, const bfr* __restrict__ Bt, int K,
;                                            int nM, int nN, const Epi& epi, bfr* shm, int wv, int nMfull, int ksplit) {
;     ...
;       LDB(B0, 0, 0); SCHED; LDA(At, 0, 0); STAGE(SA(1, 1), Ak, brow + G_HALF, t + 1);
;       WAIT_L(8); BAR; WAIT_L(0); MMA(0, 0, At, B0); BAR; SCHED;
;       LDB(B1, 0, 1); STAGE(SB(0, 0), Bk, bcol, t + 2);
;       BAR; WAIT_L(0); MMA(0, 1, At, B1); BAR;
;       LDA(At, 0, 1); STAGE(SA(0, 0), Ak, brow, t + 2);
;       BAR; WAIT_L(0); MMA(1, 0, At, B0); BAR; SCHED;
;       STAGE(SB(0, 1), Bk, bcol + G_HALF, t + 2);
;       WAIT_V(6); BAR; MMA(1, 1, At, B1); BAR;
.LBB0_523:
	ds_read_b128 v[138:141], v179
	ds_read_b128 v[142:145], v179 offset:1024
	ds_read_b128 v[146:149], v179 offset:2048
	ds_read_b128 v[150:153], v179 offset:3072
	ds_read_b128 v[154:157], v178
	ds_read_b128 v[158:161], v178 offset:1024
	ds_read_b128 v[162:165], v178 offset:2048
	ds_read_b128 v[166:169], v178 offset:3072
	ds_read_b128 v[170:173], v178 offset:4096
	ds_read_b128 v[174:177], v178 offset:5120
	ds_read_b128 v[184:187], v178 offset:6144
	ds_read_b128 v[188:191], v178 offset:7168
	ds_read_b128 v[192:195], v179 offset:16384
	ds_read_b128 v[196:199], v179 offset:17408
	ds_read_b128 v[200:203], v179 offset:18432
	ds_read_b128 v[204:207], v179 offset:19456
	v_lshl_add_u64 v[208:209], s[44:45], 0, v[136:137]
	v_lshl_add_u64 v[210:211], s[42:43], 0, v[136:137]
	s_mov_b32 m0, s92
	s_mov_b64 s[52:53], 0x40080
	v_lshl_add_u64 v[214:215], v[208:209], 0, s[52:53]
	global_load_lds_dwordx4 v[214:215], off
	s_mov_b32 m0, s93
	s_mov_b64 s[52:53], 0x60080
	v_lshl_add_u64 v[216:217], v[208:209], 0, s[52:53]
	global_load_lds_dwordx4 v[216:217], off
	s_waitcnt lgkmcnt(0)
	s_barrier
	s_setprio 1
	v_mfma_f32_16x16x32_bf16 v[124:127], v[154:157], v[138:141], v[124:127]
	v_mfma_f32_16x16x32_bf16 v[120:123], v[154:157], v[146:149], v[120:123]
	v_mfma_f32_16x16x32_bf16 v[116:119], v[162:165], v[138:141], v[116:119]
	v_mfma_f32_16x16x32_bf16 v[112:115], v[162:165], v[146:149], v[112:115]
	v_mfma_f32_16x16x32_bf16 v[108:111], v[170:173], v[138:141], v[108:111]
	v_mfma_f32_16x16x32_bf16 v[104:107], v[170:173], v[146:149], v[104:107]
	v_mfma_f32_16x16x32_bf16 v[100:103], v[184:187], v[138:141], v[100:103]
	v_mfma_f32_16x16x32_bf16 v[96:99], v[184:187], v[146:149], v[96:99]
	v_mfma_f32_16x16x32_bf16 v[124:127], v[158:161], v[142:145], v[124:127]
	v_mfma_f32_16x16x32_bf16 v[120:123], v[158:161], v[150:153], v[120:123]
	v_mfma_f32_16x16x32_bf16 v[116:119], v[166:169], v[142:145], v[116:119]
	v_mfma_f32_16x16x32_bf16 v[112:115], v[166:169], v[150:153], v[112:115]
	v_mfma_f32_16x16x32_bf16 v[108:111], v[174:177], v[142:145], v[108:111]
	v_mfma_f32_16x16x32_bf16 v[104:107], v[174:177], v[150:153], v[104:107]
	v_mfma_f32_16x16x32_bf16 v[100:103], v[188:191], v[142:145], v[100:103]
	v_mfma_f32_16x16x32_bf16 v[96:99], v[188:191], v[150:153], v[96:99]
	v_mfma_f32_16x16x32_bf16 v[92:95], v[154:157], v[192:195], v[92:95]
	v_mfma_f32_16x16x32_bf16 v[88:91], v[154:157], v[200:203], v[88:91]
	v_mfma_f32_16x16x32_bf16 v[84:87], v[162:165], v[192:195], v[84:87]
	v_mfma_f32_16x16x32_bf16 v[80:83], v[162:165], v[200:203], v[80:83]
	v_mfma_f32_16x16x32_bf16 v[76:79], v[170:173], v[192:195], v[76:79]
	v_mfma_f32_16x16x32_bf16 v[72:75], v[170:173], v[200:203], v[72:75]
	v_mfma_f32_16x16x32_bf16 v[68:71], v[184:187], v[192:195], v[68:71]
	v_mfma_f32_16x16x32_bf16 v[64:67], v[184:187], v[200:203], v[64:67]
	v_mfma_f32_16x16x32_bf16 v[92:95], v[158:161], v[196:199], v[92:95]
	v_mfma_f32_16x16x32_bf16 v[88:91], v[158:161], v[204:207], v[88:91]
	v_mfma_f32_16x16x32_bf16 v[84:87], v[166:169], v[196:199], v[84:87]
	v_mfma_f32_16x16x32_bf16 v[80:83], v[166:169], v[204:207], v[80:83]
	v_mfma_f32_16x16x32_bf16 v[76:79], v[174:177], v[196:199], v[76:79]
	v_mfma_f32_16x16x32_bf16 v[72:75], v[174:177], v[204:207], v[72:75]
	v_mfma_f32_16x16x32_bf16 v[68:71], v[188:191], v[196:199], v[68:71]
	v_mfma_f32_16x16x32_bf16 v[64:67], v[188:191], v[204:207], v[64:67]
	s_setprio 0
	s_barrier
	ds_read_b128 v[154:157], v178 offset:16384
	ds_read_b128 v[158:161], v178 offset:17408
	ds_read_b128 v[162:165], v178 offset:18432
	ds_read_b128 v[166:169], v178 offset:19456
	ds_read_b128 v[170:173], v178 offset:20480
	ds_read_b128 v[174:177], v178 offset:21504
	ds_read_b128 v[184:187], v178 offset:22528
	ds_read_b128 v[188:191], v178 offset:23552
	s_mov_b32 m0, s94
	v_lshl_add_u64 v[218:219], v[210:211], 0, s[16:17]
	global_load_lds_dwordx4 v[218:219], off
	s_mov_b32 m0, s95
	v_lshl_add_u64 v[214:215], v[210:211], 0, s[18:19]
	global_load_lds_dwordx4 v[214:215], off
	s_mov_b32 m0, s91
	v_lshl_add_u64 v[216:217], v[208:209], 0, s[16:17]
	global_load_lds_dwordx4 v[216:217], off
	s_mov_b32 m0, s96
	v_lshl_add_u64 v[218:219], v[208:209], 0, s[18:19]
	global_load_lds_dwordx4 v[218:219], off
	s_waitcnt vmcnt(6)
	s_waitcnt lgkmcnt(0)
	s_barrier
	s_setprio 1
	v_mfma_f32_16x16x32_bf16 v[60:63], v[154:157], v[138:141], v[60:63]
	v_mfma_f32_16x16x32_bf16 v[56:59], v[154:157], v[146:149], v[56:59]
	v_mfma_f32_16x16x32_bf16 v[52:55], v[162:165], v[138:141], v[52:55]
	v_mfma_f32_16x16x32_bf16 v[48:51], v[162:165], v[146:149], v[48:51]
	v_mfma_f32_16x16x32_bf16 v[44:47], v[170:173], v[138:141], v[44:47]
	v_mfma_f32_16x16x32_bf16 v[40:43], v[170:173], v[146:149], v[40:43]
	v_mfma_f32_16x16x32_bf16 v[36:39], v[184:187], v[138:141], v[36:39]
	v_mfma_f32_16x16x32_bf16 v[32:35], v[184:187], v[146:149], v[32:35]
	v_mfma_f32_16x16x32_bf16 v[60:63], v[158:161], v[142:145], v[60:63]
	v_mfma_f32_16x16x32_bf16 v[56:59], v[158:161], v[150:153], v[56:59]
	v_mfma_f32_16x16x32_bf16 v[52:55], v[166:169], v[142:145], v[52:55]
	v_mfma_f32_16x16x32_bf16 v[48:51], v[166:169], v[150:153], v[48:51]
	v_mfma_f32_16x16x32_bf16 v[44:47], v[174:177], v[142:145], v[44:47]
	v_mfma_f32_16x16x32_bf16 v[40:43], v[174:177], v[150:153], v[40:43]
	v_mfma_f32_16x16x32_bf16 v[36:39], v[188:191], v[142:145], v[36:39]
	v_mfma_f32_16x16x32_bf16 v[32:35], v[188:191], v[150:153], v[32:35]
	v_mfma_f32_16x16x32_bf16 v[28:31], v[154:157], v[192:195], v[28:31]
	v_mfma_f32_16x16x32_bf16 v[24:27], v[154:157], v[200:203], v[24:27]
	v_mfma_f32_16x16x32_bf16 v[20:23], v[162:165], v[192:195], v[20:23]
	v_mfma_f32_16x16x32_bf16 v[16:19], v[162:165], v[200:203], v[16:19]
	v_mfma_f32_16x16x32_bf16 v[12:15], v[170:173], v[192:195], v[12:15]
	v_mfma_f32_16x16x32_bf16 v[8:11], v[170:173], v[200:203], v[8:11]
	v_mfma_f32_16x16x32_bf16 v[4:7], v[184:187], v[192:195], v[4:7]
	v_mfma_f32_16x16x32_bf16 v[0:3], v[184:187], v[200:203], v[0:3]
	v_mfma_f32_16x16x32_bf16 v[28:31], v[158:161], v[196:199], v[28:31]
	v_mfma_f32_16x16x32_bf16 v[24:27], v[158:161], v[204:207], v[24:27]
	v_mfma_f32_16x16x32_bf16 v[20:23], v[166:169], v[196:199], v[20:23]
	v_mfma_f32_16x16x32_bf16 v[16:19], v[166:169], v[204:207], v[16:19]
	v_mfma_f32_16x16x32_bf16 v[12:15], v[174:177], v[196:199], v[12:15]
	v_mfma_f32_16x16x32_bf16 v[8:11], v[174:177], v[204:207], v[8:11]
	v_mfma_f32_16x16x32_bf16 v[4:7], v[188:191], v[196:199], v[4:7]
	v_mfma_f32_16x16x32_bf16 v[0:3], v[188:191], v[204:207], v[0:3]
	s_setprio 0
	s_barrier
; #define STAGE(P, BASE, br, kt) do { const char* _g = (const char*)((BASE) + (size_t)(br) * K + (size_t)(kt) * G_BK); \
;     _Pragma("unroll") for (int _i = 0; _i < 2; ++_i) { \
;       __builtin_amdgcn_global_load_lds((const unsigned*)(_g + (size_t)_i * 128 * K + sg_off), (unsigned*)((char*)(P) + wid * 1024 + _i * 8192), 16, 0, 0); } } while (0)
; #define LDA(dst, b, h) _Pragma("unroll") for (int m = 0; m < 4; ++m) _Pragma("unroll") for (int k = 0; k < 2; ++k) \
;     dst[m][k] = *reinterpret_cast<const bf16x8*>((const char*)shm + aoff + (((b) * 2 + (h)) * 16384 + m * 2048 + k * 1024))
; #define LDB(dst, b, h) _Pragma("unroll") for (int n = 0; n < 2; ++n) _Pragma("unroll") for (int k = 0; k < 2; ++k) \
;     dst[n][k] = *reinterpret_cast<const bf16x8*>((const char*)shm + boff + (((b) * 2 + (h)) * 16384 + n * 2048 + k * 1024))
; #define MMA(ai, bj, At, Bt_) do { __builtin_amdgcn_s_setprio(1); \
;     _Pragma("unroll") for (int m = 0; m < 4; ++m) _Pragma("unroll") for (int n = 0; n < 2; ++n) _Pragma("unroll") for (int k = 0; k < 2; ++k) \
;       acc[ai][bj][m][n] = mfma16(At[m][k], Bt_[n][k], acc[ai][bj][m][n]); \
;     __builtin_amdgcn_s_setprio(0); } while (0)
; #define WAIT_V(n) asm volatile("s_waitcnt vmcnt(" #n ")" ::: "memory")
; #define WAIT_L(n) asm volatile("s_waitcnt lgkmcnt(" #n ")" ::: "memory")
; #define BAR __builtin_amdgcn_s_barrier()
; #define SCHED __builtin_amdgcn_sched_barrier(0)
; template <class Epi>
; __device__ __forceinline__ void gemm_phase(const bfr* __restrict__ A, int lda, const bfr* __restrict__ Bt, int K,
;                                            int nM, int nN, const Epi& epi, bfr* shm, int wv, int nMfull, int ksplit) {
;     ...
;       LDB(B0, 1, 0); SCHED; LDA(At, 1, 0); STAGE(SA(0, 1), Ak, brow + G_HALF, t + 2);
;       WAIT_L(8); BAR; WAIT_L(0); MMA(0, 0, At, B0); BAR; SCHED;
;       LDB(B1, 1, 1); STAGE(SB(1, 0), Bk, bcol, t + 3);
;       BAR; WAIT_L(0); MMA(0, 1, At, B1); BAR;
;       LDA(At, 1, 1); STAGE(SA(1, 0), Ak, brow, t + 3);
;       BAR; WAIT_L(0); MMA(1, 0, At, B0); BAR; SCHED;
;       STAGE(SB(1, 1), Bk, bcol + G_HALF, t + 3);
;       WAIT_V(6); BAR; MMA(1, 1, At, B1); BAR;
;     }
	ds_read_b128 v[138:141], v179 offset:32768
	ds_read_b128 v[142:145], v179 offset:33792
	ds_read_b128 v[146:149], v179 offset:34816
	ds_read_b128 v[150:153], v179 offset:35840
	ds_read_b128 v[154:157], v178 offset:32768
	ds_read_b128 v[158:161], v178 offset:33792
	ds_read_b128 v[162:165], v178 offset:34816
	ds_read_b128 v[166:169], v178 offset:35840
	ds_read_b128 v[170:173], v178 offset:36864
	ds_read_b128 v[174:177], v178 offset:37888
	ds_read_b128 v[184:187], v178 offset:38912
	ds_read_b128 v[188:191], v178 offset:39936
	ds_read_b128 v[192:195], v179 offset:49152
	ds_read_b128 v[196:199], v179 offset:50176
	ds_read_b128 v[200:203], v179 offset:51200
	ds_read_b128 v[204:207], v179 offset:52224
	s_mov_b32 m0, s97
	v_lshl_add_u64 v[214:215], v[210:211], 0, s[20:21]
	global_load_lds_dwordx4 v[214:215], off
	s_mov_b32 m0, s34
	v_lshl_add_u64 v[216:217], v[210:211], 0, s[22:23]
	global_load_lds_dwordx4 v[216:217], off
	s_mov_b32 m0, s35
	v_lshl_add_u64 v[218:219], v[208:209], 0, s[20:21]
	global_load_lds_dwordx4 v[218:219], off
	s_mov_b32 m0, s36
	v_lshl_add_u64 v[214:215], v[208:209], 0, s[22:23]
	global_load_lds_dwordx4 v[214:215], off
	s_waitcnt vmcnt(8)
	s_waitcnt lgkmcnt(0)
	s_barrier
	s_setprio 1
	v_mfma_f32_16x16x32_bf16 v[124:127], v[154:157], v[138:141], v[124:127]
	v_mfma_f32_16x16x32_bf16 v[120:123], v[154:157], v[146:149], v[120:123]
	v_mfma_f32_16x16x32_bf16 v[116:119], v[162:165], v[138:141], v[116:119]
	v_mfma_f32_16x16x32_bf16 v[112:115], v[162:165], v[146:149], v[112:115]
	v_mfma_f32_16x16x32_bf16 v[108:111], v[170:173], v[138:141], v[108:111]
	v_mfma_f32_16x16x32_bf16 v[104:107], v[170:173], v[146:149], v[104:107]
	v_mfma_f32_16x16x32_bf16 v[100:103], v[184:187], v[138:141], v[100:103]
	v_mfma_f32_16x16x32_bf16 v[96:99], v[184:187], v[146:149], v[96:99]
	v_mfma_f32_16x16x32_bf16 v[124:127], v[158:161], v[142:145], v[124:127]
	v_mfma_f32_16x16x32_bf16 v[120:123], v[158:161], v[150:153], v[120:123]
	v_mfma_f32_16x16x32_bf16 v[116:119], v[166:169], v[142:145], v[116:119]
	v_mfma_f32_16x16x32_bf16 v[112:115], v[166:169], v[150:153], v[112:115]
	v_mfma_f32_16x16x32_bf16 v[108:111], v[174:177], v[142:145], v[108:111]
	v_mfma_f32_16x16x32_bf16 v[104:107], v[174:177], v[150:153], v[104:107]
	v_mfma_f32_16x16x32_bf16 v[100:103], v[188:191], v[142:145], v[100:103]
	v_mfma_f32_16x16x32_bf16 v[96:99], v[188:191], v[150:153], v[96:99]
	v_mfma_f32_16x16x32_bf16 v[92:95], v[154:157], v[192:195], v[92:95]
	v_mfma_f32_16x16x32_bf16 v[88:91], v[154:157], v[200:203], v[88:91]
	v_mfma_f32_16x16x32_bf16 v[84:87], v[162:165], v[192:195], v[84:87]
	v_mfma_f32_16x16x32_bf16 v[80:83], v[162:165], v[200:203], v[80:83]
	v_mfma_f32_16x16x32_bf16 v[76:79], v[170:173], v[192:195], v[76:79]
	v_mfma_f32_16x16x32_bf16 v[72:75], v[170:173], v[200:203], v[72:75]
	v_mfma_f32_16x16x32_bf16 v[68:71], v[184:187], v[192:195], v[68:71]
	v_mfma_f32_16x16x32_bf16 v[64:67], v[184:187], v[200:203], v[64:67]
	v_mfma_f32_16x16x32_bf16 v[92:95], v[158:161], v[196:199], v[92:95]
	v_mfma_f32_16x16x32_bf16 v[88:91], v[158:161], v[204:207], v[88:91]
	v_mfma_f32_16x16x32_bf16 v[84:87], v[166:169], v[196:199], v[84:87]
	v_mfma_f32_16x16x32_bf16 v[80:83], v[166:169], v[204:207], v[80:83]
	v_mfma_f32_16x16x32_bf16 v[76:79], v[174:177], v[196:199], v[76:79]
	v_mfma_f32_16x16x32_bf16 v[72:75], v[174:177], v[204:207], v[72:75]
	v_mfma_f32_16x16x32_bf16 v[68:71], v[188:191], v[196:199], v[68:71]
	v_mfma_f32_16x16x32_bf16 v[64:67], v[188:191], v[204:207], v[64:67]
	s_setprio 0
	s_barrier
	ds_read_b128 v[154:157], v178 offset:49152
	ds_read_b128 v[158:161], v178 offset:50176
	ds_read_b128 v[162:165], v178 offset:51200
	ds_read_b128 v[166:169], v178 offset:52224
	ds_read_b128 v[170:173], v178 offset:53248
	ds_read_b128 v[174:177], v178 offset:54272
	ds_read_b128 v[184:187], v178 offset:55296
	ds_read_b128 v[188:191], v178 offset:56320
	s_mov_b32 m0, s37
	v_lshl_add_u64 v[216:217], v[210:211], 0, s[24:25]
	global_load_lds_dwordx4 v[216:217], off
	s_mov_b32 m0, s12
	v_lshl_add_u64 v[218:219], v[210:211], 0, s[26:27]
	global_load_lds_dwordx4 v[218:219], off
	s_mov_b32 m0, s13
	v_lshl_add_u64 v[214:215], v[208:209], 0, s[24:25]
	global_load_lds_dwordx4 v[214:215], off
	s_mov_b32 m0, s28
	v_lshl_add_u64 v[216:217], v[208:209], 0, s[26:27]
	global_load_lds_dwordx4 v[216:217], off
	s_mov_b32 m0, s29
	s_mov_b64 s[52:53], 0x40180
	v_lshl_add_u64 v[218:219], v[210:211], 0, s[52:53]
	global_load_lds_dwordx4 v[218:219], off
	s_mov_b32 m0, s30
	s_mov_b64 s[52:53], 0x60180
	v_lshl_add_u64 v[214:215], v[210:211], 0, s[52:53]
	global_load_lds_dwordx4 v[214:215], off
	s_waitcnt vmcnt(6)
	s_waitcnt lgkmcnt(0)
	s_barrier
	s_setprio 1
	v_mfma_f32_16x16x32_bf16 v[60:63], v[154:157], v[138:141], v[60:63]
	v_mfma_f32_16x16x32_bf16 v[56:59], v[154:157], v[146:149], v[56:59]
	v_mfma_f32_16x16x32_bf16 v[52:55], v[162:165], v[138:141], v[52:55]
	v_mfma_f32_16x16x32_bf16 v[48:51], v[162:165], v[146:149], v[48:51]
	v_mfma_f32_16x16x32_bf16 v[44:47], v[170:173], v[138:141], v[44:47]
	v_mfma_f32_16x16x32_bf16 v[40:43], v[170:173], v[146:149], v[40:43]
	v_mfma_f32_16x16x32_bf16 v[36:39], v[184:187], v[138:141], v[36:39]
	v_mfma_f32_16x16x32_bf16 v[32:35], v[184:187], v[146:149], v[32:35]
	v_mfma_f32_16x16x32_bf16 v[60:63], v[158:161], v[142:145], v[60:63]
	v_mfma_f32_16x16x32_bf16 v[56:59], v[158:161], v[150:153], v[56:59]
	v_mfma_f32_16x16x32_bf16 v[52:55], v[166:169], v[142:145], v[52:55]
	v_mfma_f32_16x16x32_bf16 v[48:51], v[166:169], v[150:153], v[48:51]
	v_mfma_f32_16x16x32_bf16 v[44:47], v[174:177], v[142:145], v[44:47]
	v_mfma_f32_16x16x32_bf16 v[40:43], v[174:177], v[150:153], v[40:43]
	v_mfma_f32_16x16x32_bf16 v[36:39], v[188:191], v[142:145], v[36:39]
	v_mfma_f32_16x16x32_bf16 v[32:35], v[188:191], v[150:153], v[32:35]
	v_mfma_f32_16x16x32_bf16 v[28:31], v[154:157], v[192:195], v[28:31]
	v_mfma_f32_16x16x32_bf16 v[24:27], v[154:157], v[200:203], v[24:27]
	v_mfma_f32_16x16x32_bf16 v[20:23], v[162:165], v[192:195], v[20:23]
	v_mfma_f32_16x16x32_bf16 v[16:19], v[162:165], v[200:203], v[16:19]
	v_mfma_f32_16x16x32_bf16 v[12:15], v[170:173], v[192:195], v[12:15]
	v_mfma_f32_16x16x32_bf16 v[8:11], v[170:173], v[200:203], v[8:11]
	v_mfma_f32_16x16x32_bf16 v[4:7], v[184:187], v[192:195], v[4:7]
	v_mfma_f32_16x16x32_bf16 v[0:3], v[184:187], v[200:203], v[0:3]
	v_mfma_f32_16x16x32_bf16 v[28:31], v[158:161], v[196:199], v[28:31]
	v_mfma_f32_16x16x32_bf16 v[24:27], v[158:161], v[204:207], v[24:27]
	v_mfma_f32_16x16x32_bf16 v[20:23], v[166:169], v[196:199], v[20:23]
	v_mfma_f32_16x16x32_bf16 v[16:19], v[166:169], v[204:207], v[16:19]
	v_mfma_f32_16x16x32_bf16 v[12:15], v[174:177], v[196:199], v[12:15]
	v_mfma_f32_16x16x32_bf16 v[8:11], v[174:177], v[204:207], v[8:11]
	v_mfma_f32_16x16x32_bf16 v[4:7], v[188:191], v[196:199], v[4:7]
	v_mfma_f32_16x16x32_bf16 v[0:3], v[188:191], v[204:207], v[0:3]
	s_setprio 0
	s_add_i32 s41, s41, 2
	s_add_u32 s42, s42, 0x100
	s_addc_u32 s43, s43, 0
	s_add_u32 s44, s44, 0x100
	s_addc_u32 s45, s45, 0
	s_cmp_ge_i32 s41, s46
	s_barrier
	s_cbranch_scc0 .LBB0_523

; #define STAGE(P, BASE, br, kt) do { const char* _g = (const char*)((BASE) + (size_t)(br) * K + (size_t)(kt) * G_BK); \
;     _Pragma("unroll") for (int _i = 0; _i < 2; ++_i) { \
;       __builtin_amdgcn_global_load_lds((const unsigned*)(_g + (size_t)_i * 128 * K + sg_off), (unsigned*)((char*)(P) + wid * 1024 + _i * 8192), 16, 0, 0); } } while (0)
; #define LDA(dst, b, h) _Pragma("unroll") for (int m = 0; m < 4; ++m) _Pragma("unroll") for (int k = 0; k < 2; ++k) \
;     dst[m][k] = *reinterpret_cast<const bf16x8*>((const char*)shm + aoff + (((b) * 2 + (h)) * 16384 + m * 2048 + k * 1024))
; #define LDB(dst, b, h) _Pragma("unroll") for (int n = 0; n < 2; ++n) _Pragma("unroll") for (int k = 0; k < 2; ++k) \
;     dst[n][k] = *reinterpret_cast<const bf16x8*>((const char*)shm + boff + (((b) * 2 + (h)) * 16384 + n * 2048 + k * 1024))
; #define MMA(ai, bj, At, Bt_) do { __builtin_amdgcn_s_setprio(1); \
;     _Pragma("unroll") for (int m = 0; m < 4; ++m) _Pragma("unroll") for (int n = 0; n < 2; ++n) _Pragma("unroll") for (int k = 0; k < 2; ++k) \
;       acc[ai][bj][m][n] = mfma16(At[m][k], Bt_[n][k], acc[ai][bj][m][n]); \
;     __builtin_amdgcn_s_setprio(0); } while (0)
; #define WAIT_V(n) asm volatile("s_waitcnt vmcnt(" #n ")" ::: "memory")
; #define WAIT_L(n) asm volatile("s_waitcnt lgkmcnt(" #n ")" ::: "memory")
; #define BAR __builtin_amdgcn_s_barrier()
; #define SCHED __builtin_amdgcn_sched_barrier(0)
; template <class Epi>
; __device__ __forceinline__ void gemm_phase(const bfr* __restrict__ A, int lda, const bfr* __restrict__ Bt, int K,
;                                            int nM, int nN, const Epi& epi, bfr* shm, int wv, int nMfull, int ksplit) {
;     ...
;     f32x4 acc[2][2][4][2];
; #pragma unroll
;     for (int a = 0; a < 2; a++)
; #pragma unroll
;       for (int b = 0; b < 2; b++)
; #pragma unroll
;         for (int m = 0; m < 4; m++)
; #pragma unroll
;           for (int n = 0; n < 2; n++) acc[a][b][m][n] = f32x4{0.f, 0.f, 0.f, 0.f};
;     bf16x8 At[4][2], B0[2][2], B1[2][2];
;     if (wr == 1) BAR;
;     WAIT_V(10); BAR;
;     WAIT_V(6); BAR;
;     for (int t = 0; t < nt - 2; t += 2) {
;       LDB(B0, 0, 0); SCHED; LDA(At, 0, 0); STAGE(SA(1, 1), Ak, brow + G_HALF, t + 1);
;       WAIT_L(8); BAR; WAIT_L(0); MMA(0, 0, At, B0); BAR; SCHED;
.LBB0_671:
	s_waitcnt vmcnt(8)
	s_barrier
	s_waitcnt vmcnt(6)
	v_mov_b32_e32 v127, 0
	s_cmp_lt_u32 s22, 3
	v_mov_b32_e32 v126, v127
	v_mov_b32_e32 v125, v127
	v_mov_b32_e32 v124, v127
	v_mov_b32_e32 v123, v127
	v_mov_b32_e32 v122, v127
	v_mov_b32_e32 v121, v127
	v_mov_b32_e32 v120, v127
	v_mov_b32_e32 v119, v127
	v_mov_b32_e32 v118, v127
	v_mov_b32_e32 v117, v127
	v_mov_b32_e32 v116, v127
	v_mov_b32_e32 v115, v127
	v_mov_b32_e32 v114, v127
	v_mov_b32_e32 v113, v127
	v_mov_b32_e32 v112, v127
	v_mov_b32_e32 v111, v127
	v_mov_b32_e32 v110, v127
	v_mov_b32_e32 v109, v127
	v_mov_b32_e32 v108, v127
	v_mov_b32_e32 v107, v127
	v_mov_b32_e32 v106, v127
	v_mov_b32_e32 v105, v127
	v_mov_b32_e32 v104, v127
	v_mov_b32_e32 v103, v127
	v_mov_b32_e32 v102, v127
	v_mov_b32_e32 v101, v127
	v_mov_b32_e32 v100, v127
	v_mov_b32_e32 v99, v127
	v_mov_b32_e32 v98, v127
	v_mov_b32_e32 v97, v127
	v_mov_b32_e32 v96, v127
	v_mov_b32_e32 v95, v127
	v_mov_b32_e32 v94, v127
	v_mov_b32_e32 v93, v127
	v_mov_b32_e32 v92, v127
	v_mov_b32_e32 v91, v127
	v_mov_b32_e32 v90, v127
	v_mov_b32_e32 v89, v127
	v_mov_b32_e32 v88, v127
	v_mov_b32_e32 v87, v127
	v_mov_b32_e32 v86, v127
	v_mov_b32_e32 v85, v127
	v_mov_b32_e32 v84, v127
	v_mov_b32_e32 v83, v127
	v_mov_b32_e32 v82, v127
	v_mov_b32_e32 v81, v127
	v_mov_b32_e32 v80, v127
	v_mov_b32_e32 v79, v127
	v_mov_b32_e32 v78, v127
	v_mov_b32_e32 v77, v127
	v_mov_b32_e32 v76, v127
	v_mov_b32_e32 v75, v127
	v_mov_b32_e32 v74, v127
	v_mov_b32_e32 v73, v127
	v_mov_b32_e32 v72, v127
	v_mov_b32_e32 v71, v127
	v_mov_b32_e32 v70, v127
	v_mov_b32_e32 v69, v127
	v_mov_b32_e32 v68, v127
	v_mov_b32_e32 v67, v127
	v_mov_b32_e32 v66, v127
	v_mov_b32_e32 v65, v127
	v_mov_b32_e32 v64, v127
	v_mov_b32_e32 v63, v127
	v_mov_b32_e32 v62, v127
	v_mov_b32_e32 v61, v127
	v_mov_b32_e32 v60, v127
	v_mov_b32_e32 v59, v127
	v_mov_b32_e32 v58, v127
	v_mov_b32_e32 v57, v127
	v_mov_b32_e32 v56, v127
	v_mov_b32_e32 v55, v127
	v_mov_b32_e32 v54, v127
	v_mov_b32_e32 v53, v127
	v_mov_b32_e32 v52, v127
	v_mov_b32_e32 v51, v127
	v_mov_b32_e32 v50, v127
	v_mov_b32_e32 v49, v127
	v_mov_b32_e32 v48, v127
	v_mov_b32_e32 v47, v127
	v_mov_b32_e32 v46, v127
	v_mov_b32_e32 v45, v127
	v_mov_b32_e32 v44, v127
	v_mov_b32_e32 v43, v127
	v_mov_b32_e32 v42, v127
	v_mov_b32_e32 v41, v127
	v_mov_b32_e32 v40, v127
	v_mov_b32_e32 v39, v127
	v_mov_b32_e32 v38, v127
	v_mov_b32_e32 v37, v127
	v_mov_b32_e32 v36, v127
	v_mov_b32_e32 v35, v127
	v_mov_b32_e32 v34, v127
	v_mov_b32_e32 v33, v127
	v_mov_b32_e32 v32, v127
	v_mov_b32_e32 v31, v127
	v_mov_b32_e32 v30, v127
	v_mov_b32_e32 v29, v127
	v_mov_b32_e32 v28, v127
	v_mov_b32_e32 v27, v127
	v_mov_b32_e32 v26, v127
	v_mov_b32_e32 v25, v127
	v_mov_b32_e32 v24, v127
	v_mov_b32_e32 v23, v127
	v_mov_b32_e32 v22, v127
	v_mov_b32_e32 v21, v127
	v_mov_b32_e32 v20, v127
	v_mov_b32_e32 v19, v127
	v_mov_b32_e32 v18, v127
	v_mov_b32_e32 v17, v127
	v_mov_b32_e32 v16, v127
	v_mov_b32_e32 v15, v127
	v_mov_b32_e32 v14, v127
	v_mov_b32_e32 v13, v127
	v_mov_b32_e32 v12, v127
	v_mov_b32_e32 v11, v127
	v_mov_b32_e32 v10, v127
	v_mov_b32_e32 v9, v127
	v_mov_b32_e32 v8, v127
	v_mov_b32_e32 v7, v127
	v_mov_b32_e32 v6, v127
	v_mov_b32_e32 v5, v127
	v_mov_b32_e32 v4, v127
	v_mov_b32_e32 v3, v127
	v_mov_b32_e32 v2, v127
	v_mov_b32_e32 v1, v127
	v_mov_b32_e32 v0, v127
	s_barrier
	s_cbranch_scc1 .LBB0_674
	s_ashr_i32 s31, s30, 31
	s_ashr_i32 s35, s34, 31
	v_readlane_b32 s60, v254, 54
	s_add_i32 s2, s22, -2
	s_lshl_b64 s[6:7], s[30:31], 11
	s_lshl_b64 s[24:25], s[34:35], 11
	v_readlane_b32 s62, v254, 56
	v_readlane_b32 s63, v254, 57
	s_add_u32 s6, s62, s6
	s_addc_u32 s7, s63, s7
	s_add_u32 s24, s80, s24
	v_mov_b32_e32 v0, 0
	s_addc_u32 s25, s81, s25
	s_mov_b32 s3, 0
	v_readlane_b32 s61, v254, 55
	v_readlane_b32 s64, v254, 58
	v_readlane_b32 s65, v254, 59
	v_readlane_b32 s66, v254, 60
	v_readlane_b32 s67, v254, 61
	v_readlane_b32 s68, v254, 62
	v_readlane_b32 s69, v254, 63
	v_readlane_b32 s70, v255, 0
	v_readlane_b32 s71, v255, 1
	v_readlane_b32 s72, v255, 2
	v_readlane_b32 s73, v255, 3
	v_readlane_b32 s74, v255, 4
	v_readlane_b32 s75, v255, 5
.LBB0_673:
	ds_read_b128 v[138:141], v169
	ds_read_b128 v[142:145], v169 offset:1024
	ds_read_b128 v[146:149], v169 offset:2048
	ds_read_b128 v[150:153], v169 offset:3072
	ds_read_b128 v[154:157], v129
	ds_read_b128 v[158:161], v129 offset:1024
	ds_read_b128 v[162:165], v129 offset:2048
	ds_read_b128 v[172:175], v129 offset:3072
	ds_read_b128 v[180:183], v129 offset:4096
	ds_read_b128 v[184:187], v129 offset:5120
	ds_read_b128 v[188:191], v129 offset:6144
	ds_read_b128 v[192:195], v129 offset:7168
	ds_read_b128 v[196:199], v169 offset:16384
	ds_read_b128 v[200:203], v169 offset:17408
	ds_read_b128 v[204:207], v169 offset:18432
	ds_read_b128 v[208:211], v169 offset:19456
	v_lshl_add_u64 v[166:167], s[24:25], 0, v[136:137]
	v_lshl_add_u64 v[176:177], s[6:7], 0, v[136:137]
	s_mov_b32 m0, s52
	s_mov_b64 s[26:27], 0x40080
	v_lshl_add_u64 v[214:215], v[166:167], 0, s[26:27]
	global_load_lds_dwordx4 v[214:215], off
	s_mov_b32 m0, s53
	s_mov_b64 s[26:27], 0x60080
	v_lshl_add_u64 v[216:217], v[166:167], 0, s[26:27]
	global_load_lds_dwordx4 v[216:217], off
	s_waitcnt lgkmcnt(0)
	s_barrier
; #define STAGE(P, BASE, br, kt) do { const char* _g = (const char*)((BASE) + (size_t)(br) * K + (size_t)(kt) * G_BK); \
;     _Pragma("unroll") for (int _i = 0; _i < 2; ++_i) { \
;       __builtin_amdgcn_global_load_lds((const unsigned*)(_g + (size_t)_i * 128 * K + sg_off), (unsigned*)((char*)(P) + wid * 1024 + _i * 8192), 16, 0, 0); } } while (0)
; #define LDA(dst, b, h) _Pragma("unroll") for (int m = 0; m < 4; ++m) _Pragma("unroll") for (int k = 0; k < 2; ++k) \
;     dst[m][k] = *reinterpret_cast<const bf16x8*>((const char*)shm + aoff + (((b) * 2 + (h)) * 16384 + m * 2048 + k * 1024))
; #define LDB(dst, b, h) _Pragma("unroll") for (int n = 0; n < 2; ++n) _Pragma("unroll") for (int k = 0; k < 2; ++k) \
;     dst[n][k] = *reinterpret_cast<const bf16x8*>((const char*)shm + boff + (((b) * 2 + (h)) * 16384 + n * 2048 + k * 1024))
; #define MMA(ai, bj, At, Bt_) do { __builtin_amdgcn_s_setprio(1); \
;     _Pragma("unroll") for (int m = 0; m < 4; ++m) _Pragma("unroll") for (int n = 0; n < 2; ++n) _Pragma("unroll") for (int k = 0; k < 2; ++k) \
;       acc[ai][bj][m][n] = mfma16(At[m][k], Bt_[n][k], acc[ai][bj][m][n]); \
;     __builtin_amdgcn_s_setprio(0); } while (0)
; #define WAIT_V(n) asm volatile("s_waitcnt vmcnt(" #n ")" ::: "memory")
; #define WAIT_L(n) asm volatile("s_waitcnt lgkmcnt(" #n ")" ::: "memory")
; #define BAR __builtin_amdgcn_s_barrier()
; #define SCHED __builtin_amdgcn_sched_barrier(0)
; template <class Epi>
; __device__ __forceinline__ void gemm_phase(const bfr* __restrict__ A, int lda, const bfr* __restrict__ Bt, int K,
;                                            int nM, int nN, const Epi& epi, bfr* shm, int wv, int nMfull, int ksplit) {
;     ...
;       WAIT_L(8); BAR; WAIT_L(0); MMA(0, 0, At, B0); BAR; SCHED;
;       LDB(B1, 0, 1); STAGE(SB(0, 0), Bk, bcol, t + 2);
;       BAR; WAIT_L(0); MMA(0, 1, At, B1); BAR;
;       LDA(At, 0, 1); STAGE(SA(0, 0), Ak, brow, t + 2);
;       BAR; WAIT_L(0); MMA(1, 0, At, B0); BAR; SCHED;
;       STAGE(SB(0, 1), Bk, bcol + G_HALF, t + 2);
;       WAIT_V(6); BAR; MMA(1, 1, At, B1); BAR;
	s_setprio 1
	v_mfma_f32_16x16x32_bf16 v[124:127], v[154:157], v[138:141], v[124:127]
	v_mfma_f32_16x16x32_bf16 v[120:123], v[154:157], v[146:149], v[120:123]
	v_mfma_f32_16x16x32_bf16 v[116:119], v[162:165], v[138:141], v[116:119]
	v_mfma_f32_16x16x32_bf16 v[112:115], v[162:165], v[146:149], v[112:115]
	v_mfma_f32_16x16x32_bf16 v[108:111], v[180:183], v[138:141], v[108:111]
	v_mfma_f32_16x16x32_bf16 v[104:107], v[180:183], v[146:149], v[104:107]
	v_mfma_f32_16x16x32_bf16 v[100:103], v[188:191], v[138:141], v[100:103]
	v_mfma_f32_16x16x32_bf16 v[96:99], v[188:191], v[146:149], v[96:99]
	v_mfma_f32_16x16x32_bf16 v[124:127], v[158:161], v[142:145], v[124:127]
	v_mfma_f32_16x16x32_bf16 v[120:123], v[158:161], v[150:153], v[120:123]
	v_mfma_f32_16x16x32_bf16 v[116:119], v[172:175], v[142:145], v[116:119]
	v_mfma_f32_16x16x32_bf16 v[112:115], v[172:175], v[150:153], v[112:115]
	v_mfma_f32_16x16x32_bf16 v[108:111], v[184:187], v[142:145], v[108:111]
	v_mfma_f32_16x16x32_bf16 v[104:107], v[184:187], v[150:153], v[104:107]
	v_mfma_f32_16x16x32_bf16 v[100:103], v[192:195], v[142:145], v[100:103]
	v_mfma_f32_16x16x32_bf16 v[96:99], v[192:195], v[150:153], v[96:99]
	v_mfma_f32_16x16x32_bf16 v[92:95], v[154:157], v[196:199], v[92:95]
	v_mfma_f32_16x16x32_bf16 v[88:91], v[154:157], v[204:207], v[88:91]
	v_mfma_f32_16x16x32_bf16 v[84:87], v[162:165], v[196:199], v[84:87]
	v_mfma_f32_16x16x32_bf16 v[80:83], v[162:165], v[204:207], v[80:83]
	v_mfma_f32_16x16x32_bf16 v[76:79], v[180:183], v[196:199], v[76:79]
	v_mfma_f32_16x16x32_bf16 v[72:75], v[180:183], v[204:207], v[72:75]
	v_mfma_f32_16x16x32_bf16 v[68:71], v[188:191], v[196:199], v[68:71]
	v_mfma_f32_16x16x32_bf16 v[64:67], v[188:191], v[204:207], v[64:67]
	v_mfma_f32_16x16x32_bf16 v[92:95], v[158:161], v[200:203], v[92:95]
	v_mfma_f32_16x16x32_bf16 v[88:91], v[158:161], v[208:211], v[88:91]
	v_mfma_f32_16x16x32_bf16 v[84:87], v[172:175], v[200:203], v[84:87]
	v_mfma_f32_16x16x32_bf16 v[80:83], v[172:175], v[208:211], v[80:83]
	v_mfma_f32_16x16x32_bf16 v[76:79], v[184:187], v[200:203], v[76:79]
	v_mfma_f32_16x16x32_bf16 v[72:75], v[184:187], v[208:211], v[72:75]
	v_mfma_f32_16x16x32_bf16 v[68:71], v[192:195], v[200:203], v[68:71]
	v_mfma_f32_16x16x32_bf16 v[64:67], v[192:195], v[208:211], v[64:67]
	s_setprio 0
	s_barrier
	ds_read_b128 v[154:157], v129 offset:16384
	ds_read_b128 v[158:161], v129 offset:17408
	ds_read_b128 v[162:165], v129 offset:18432
	ds_read_b128 v[172:175], v129 offset:19456
	ds_read_b128 v[180:183], v129 offset:20480
	ds_read_b128 v[184:187], v129 offset:21504
	ds_read_b128 v[188:191], v129 offset:22528
	ds_read_b128 v[192:195], v129 offset:23552
	s_mov_b32 m0, s39
	s_mov_b64 s[26:27], 0xb00100
	v_lshl_add_u64 v[218:219], v[176:177], 0, s[26:27]
	global_load_lds_dwordx4 v[218:219], off
	s_mov_b32 m0, s40
	s_mov_b64 s[26:27], 0xb20100
	v_lshl_add_u64 v[214:215], v[176:177], 0, s[26:27]
	global_load_lds_dwordx4 v[214:215], off
	s_mov_b32 m0, s38
	s_mov_b64 s[26:27], 0x100
	v_lshl_add_u64 v[216:217], v[166:167], 0, s[26:27]
	global_load_lds_dwordx4 v[216:217], off
	s_mov_b32 m0, s41
	s_mov_b64 s[26:27], 0x20100
	v_lshl_add_u64 v[218:219], v[166:167], 0, s[26:27]
	global_load_lds_dwordx4 v[218:219], off
	s_waitcnt vmcnt(6)
	s_waitcnt lgkmcnt(0)
	s_barrier
	s_setprio 1
	v_mfma_f32_16x16x32_bf16 v[60:63], v[154:157], v[138:141], v[60:63]
	v_mfma_f32_16x16x32_bf16 v[56:59], v[154:157], v[146:149], v[56:59]
	v_mfma_f32_16x16x32_bf16 v[52:55], v[162:165], v[138:141], v[52:55]
	v_mfma_f32_16x16x32_bf16 v[48:51], v[162:165], v[146:149], v[48:51]
	v_mfma_f32_16x16x32_bf16 v[44:47], v[180:183], v[138:141], v[44:47]
	v_mfma_f32_16x16x32_bf16 v[40:43], v[180:183], v[146:149], v[40:43]
	v_mfma_f32_16x16x32_bf16 v[36:39], v[188:191], v[138:141], v[36:39]
	v_mfma_f32_16x16x32_bf16 v[32:35], v[188:191], v[146:149], v[32:35]
	v_mfma_f32_16x16x32_bf16 v[60:63], v[158:161], v[142:145], v[60:63]
	v_mfma_f32_16x16x32_bf16 v[56:59], v[158:161], v[150:153], v[56:59]
	v_mfma_f32_16x16x32_bf16 v[52:55], v[172:175], v[142:145], v[52:55]
	v_mfma_f32_16x16x32_bf16 v[48:51], v[172:175], v[150:153], v[48:51]
	v_mfma_f32_16x16x32_bf16 v[44:47], v[184:187], v[142:145], v[44:47]
	v_mfma_f32_16x16x32_bf16 v[40:43], v[184:187], v[150:153], v[40:43]
	v_mfma_f32_16x16x32_bf16 v[36:39], v[192:195], v[142:145], v[36:39]
	v_mfma_f32_16x16x32_bf16 v[32:35], v[192:195], v[150:153], v[32:35]
	v_mfma_f32_16x16x32_bf16 v[28:31], v[154:157], v[196:199], v[28:31]
	v_mfma_f32_16x16x32_bf16 v[24:27], v[154:157], v[204:207], v[24:27]
	v_mfma_f32_16x16x32_bf16 v[20:23], v[162:165], v[196:199], v[20:23]
	v_mfma_f32_16x16x32_bf16 v[16:19], v[162:165], v[204:207], v[16:19]
	v_mfma_f32_16x16x32_bf16 v[12:15], v[180:183], v[196:199], v[12:15]
	v_mfma_f32_16x16x32_bf16 v[8:11], v[180:183], v[204:207], v[8:11]
	v_mfma_f32_16x16x32_bf16 v[4:7], v[188:191], v[196:199], v[4:7]
	v_mfma_f32_16x16x32_bf16 v[0:3], v[188:191], v[204:207], v[0:3]
	v_mfma_f32_16x16x32_bf16 v[28:31], v[158:161], v[200:203], v[28:31]
	v_mfma_f32_16x16x32_bf16 v[24:27], v[158:161], v[208:211], v[24:27]
	v_mfma_f32_16x16x32_bf16 v[20:23], v[172:175], v[200:203], v[20:23]
	v_mfma_f32_16x16x32_bf16 v[16:19], v[172:175], v[208:211], v[16:19]
	v_mfma_f32_16x16x32_bf16 v[12:15], v[184:187], v[200:203], v[12:15]
	v_mfma_f32_16x16x32_bf16 v[8:11], v[184:187], v[208:211], v[8:11]
	v_mfma_f32_16x16x32_bf16 v[4:7], v[192:195], v[200:203], v[4:7]
	v_mfma_f32_16x16x32_bf16 v[0:3], v[192:195], v[208:211], v[0:3]
	s_setprio 0
	s_barrier
; #define STAGE(P, BASE, br, kt) do { const char* _g = (const char*)((BASE) + (size_t)(br) * K + (size_t)(kt) * G_BK); \
;     _Pragma("unroll") for (int _i = 0; _i < 2; ++_i) { \
;       __builtin_amdgcn_global_load_lds((const unsigned*)(_g + (size_t)_i * 128 * K + sg_off), (unsigned*)((char*)(P) + wid * 1024 + _i * 8192), 16, 0, 0); } } while (0)
; #define LDA(dst, b, h) _Pragma("unroll") for (int m = 0; m < 4; ++m) _Pragma("unroll") for (int k = 0; k < 2; ++k) \
;     dst[m][k] = *reinterpret_cast<const bf16x8*>((const char*)shm + aoff + (((b) * 2 + (h)) * 16384 + m * 2048 + k * 1024))
; #define LDB(dst, b, h) _Pragma("unroll") for (int n = 0; n < 2; ++n) _Pragma("unroll") for (int k = 0; k < 2; ++k) \
;     dst[n][k] = *reinterpret_cast<const bf16x8*>((const char*)shm + boff + (((b) * 2 + (h)) * 16384 + n * 2048 + k * 1024))
; #define MMA(ai, bj, At, Bt_) do { __builtin_amdgcn_s_setprio(1); \
;     _Pragma("unroll") for (int m = 0; m < 4; ++m) _Pragma("unroll") for (int n = 0; n < 2; ++n) _Pragma("unroll") for (int k = 0; k < 2; ++k) \
;       acc[ai][bj][m][n] = mfma16(At[m][k], Bt_[n][k], acc[ai][bj][m][n]); \
;     __builtin_amdgcn_s_setprio(0); } while (0)
; #define WAIT_L(n) asm volatile("s_waitcnt lgkmcnt(" #n ")" ::: "memory")
; #define BAR __builtin_amdgcn_s_barrier()
; #define SCHED __builtin_amdgcn_sched_barrier(0)
; template <class Epi>
; __device__ __forceinline__ void gemm_phase(const bfr* __restrict__ A, int lda, const bfr* __restrict__ Bt, int K,
;                                            int nM, int nN, const Epi& epi, bfr* shm, int wv, int nMfull, int ksplit) {
;     ...
;       LDB(B0, 1, 0); SCHED; LDA(At, 1, 0); STAGE(SA(0, 1), Ak, brow + G_HALF, t + 2);
;       WAIT_L(8); BAR; WAIT_L(0); MMA(0, 0, At, B0); BAR; SCHED;
;       LDB(B1, 1, 1); STAGE(SB(1, 0), Bk, bcol, t + 3);
;       BAR; WAIT_L(0); MMA(0, 1, At, B1); BAR;
	ds_read_b128 v[138:141], v169 offset:32768
	ds_read_b128 v[142:145], v169 offset:33792
	ds_read_b128 v[146:149], v169 offset:34816
	ds_read_b128 v[150:153], v169 offset:35840
	ds_read_b128 v[154:157], v129 offset:32768
	ds_read_b128 v[158:161], v129 offset:33792
	ds_read_b128 v[162:165], v129 offset:34816
	ds_read_b128 v[172:175], v129 offset:35840
	ds_read_b128 v[180:183], v129 offset:36864
	ds_read_b128 v[184:187], v129 offset:37888
	ds_read_b128 v[188:191], v129 offset:38912
	ds_read_b128 v[192:195], v129 offset:39936
	ds_read_b128 v[196:199], v169 offset:49152
	ds_read_b128 v[200:203], v169 offset:50176
	ds_read_b128 v[204:207], v169 offset:51200
	ds_read_b128 v[208:211], v169 offset:52224
	s_mov_b32 m0, s42
	s_mov_b64 s[26:27], 0xb40100
	v_lshl_add_u64 v[214:215], v[176:177], 0, s[26:27]
	global_load_lds_dwordx4 v[214:215], off
	s_mov_b32 m0, s43
	s_mov_b64 s[26:27], 0xb60100
	v_lshl_add_u64 v[216:217], v[176:177], 0, s[26:27]
	global_load_lds_dwordx4 v[216:217], off
	s_mov_b32 m0, s44
	s_mov_b64 s[26:27], 0x40100
	v_lshl_add_u64 v[218:219], v[166:167], 0, s[26:27]
	global_load_lds_dwordx4 v[218:219], off
	s_mov_b32 m0, s45
	s_mov_b64 s[26:27], 0x60100
	v_lshl_add_u64 v[214:215], v[166:167], 0, s[26:27]
	global_load_lds_dwordx4 v[214:215], off
	s_waitcnt vmcnt(8)
	s_waitcnt lgkmcnt(0)
	s_barrier
	s_setprio 1
	v_mfma_f32_16x16x32_bf16 v[124:127], v[154:157], v[138:141], v[124:127]
	v_mfma_f32_16x16x32_bf16 v[120:123], v[154:157], v[146:149], v[120:123]
	v_mfma_f32_16x16x32_bf16 v[116:119], v[162:165], v[138:141], v[116:119]
	v_mfma_f32_16x16x32_bf16 v[112:115], v[162:165], v[146:149], v[112:115]
	v_mfma_f32_16x16x32_bf16 v[108:111], v[180:183], v[138:141], v[108:111]
	v_mfma_f32_16x16x32_bf16 v[104:107], v[180:183], v[146:149], v[104:107]
	v_mfma_f32_16x16x32_bf16 v[100:103], v[188:191], v[138:141], v[100:103]
	v_mfma_f32_16x16x32_bf16 v[96:99], v[188:191], v[146:149], v[96:99]
	v_mfma_f32_16x16x32_bf16 v[124:127], v[158:161], v[142:145], v[124:127]
	v_mfma_f32_16x16x32_bf16 v[120:123], v[158:161], v[150:153], v[120:123]
	v_mfma_f32_16x16x32_bf16 v[116:119], v[172:175], v[142:145], v[116:119]
	v_mfma_f32_16x16x32_bf16 v[112:115], v[172:175], v[150:153], v[112:115]
	v_mfma_f32_16x16x32_bf16 v[108:111], v[184:187], v[142:145], v[108:111]
	v_mfma_f32_16x16x32_bf16 v[104:107], v[184:187], v[150:153], v[104:107]
	v_mfma_f32_16x16x32_bf16 v[100:103], v[192:195], v[142:145], v[100:103]
	v_mfma_f32_16x16x32_bf16 v[96:99], v[192:195], v[150:153], v[96:99]
	v_mfma_f32_16x16x32_bf16 v[92:95], v[154:157], v[196:199], v[92:95]
	v_mfma_f32_16x16x32_bf16 v[88:91], v[154:157], v[204:207], v[88:91]
	v_mfma_f32_16x16x32_bf16 v[84:87], v[162:165], v[196:199], v[84:87]
	v_mfma_f32_16x16x32_bf16 v[80:83], v[162:165], v[204:207], v[80:83]
	v_mfma_f32_16x16x32_bf16 v[76:79], v[180:183], v[196:199], v[76:79]
	v_mfma_f32_16x16x32_bf16 v[72:75], v[180:183], v[204:207], v[72:75]
	v_mfma_f32_16x16x32_bf16 v[68:71], v[188:191], v[196:199], v[68:71]
	v_mfma_f32_16x16x32_bf16 v[64:67], v[188:191], v[204:207], v[64:67]
	v_mfma_f32_16x16x32_bf16 v[92:95], v[158:161], v[200:203], v[92:95]
	v_mfma_f32_16x16x32_bf16 v[88:91], v[158:161], v[208:211], v[88:91]
	v_mfma_f32_16x16x32_bf16 v[84:87], v[172:175], v[200:203], v[84:87]
	v_mfma_f32_16x16x32_bf16 v[80:83], v[172:175], v[208:211], v[80:83]
	v_mfma_f32_16x16x32_bf16 v[76:79], v[184:187], v[200:203], v[76:79]
	v_mfma_f32_16x16x32_bf16 v[72:75], v[184:187], v[208:211], v[72:75]
	v_mfma_f32_16x16x32_bf16 v[68:71], v[192:195], v[200:203], v[68:71]
	v_mfma_f32_16x16x32_bf16 v[64:67], v[192:195], v[208:211], v[64:67]
	s_setprio 0
	s_barrier
; #define STAGE(P, BASE, br, kt) do { const char* _g = (const char*)((BASE) + (size_t)(br) * K + (size_t)(kt) * G_BK); \
;     _Pragma("unroll") for (int _i = 0; _i < 2; ++_i) { \
;       __builtin_amdgcn_global_load_lds((const unsigned*)(_g + (size_t)_i * 128 * K + sg_off), (unsigned*)((char*)(P) + wid * 1024 + _i * 8192), 16, 0, 0); } } while (0)
; #define LDA(dst, b, h) _Pragma("unroll") for (int m = 0; m < 4; ++m) _Pragma("unroll") for (int k = 0; k < 2; ++k) \
;     dst[m][k] = *reinterpret_cast<const bf16x8*>((const char*)shm + aoff + (((b) * 2 + (h)) * 16384 + m * 2048 + k * 1024))
; #define MMA(ai, bj, At, Bt_) do { __builtin_amdgcn_s_setprio(1); \
;     _Pragma("unroll") for (int m = 0; m < 4; ++m) _Pragma("unroll") for (int n = 0; n < 2; ++n) _Pragma("unroll") for (int k = 0; k < 2; ++k) \
;       acc[ai][bj][m][n] = mfma16(At[m][k], Bt_[n][k], acc[ai][bj][m][n]); \
;     __builtin_amdgcn_s_setprio(0); } while (0)
; #define WAIT_V(n) asm volatile("s_waitcnt vmcnt(" #n ")" ::: "memory")
; #define WAIT_L(n) asm volatile("s_waitcnt lgkmcnt(" #n ")" ::: "memory")
; #define BAR __builtin_amdgcn_s_barrier()
; #define SCHED __builtin_amdgcn_sched_barrier(0)
; template <class Epi>
; __device__ __forceinline__ void gemm_phase(const bfr* __restrict__ A, int lda, const bfr* __restrict__ Bt, int K,
;                                            int nM, int nN, const Epi& epi, bfr* shm, int wv, int nMfull, int ksplit) {
;     ...
;       LDA(At, 1, 1); STAGE(SA(1, 0), Ak, brow, t + 3);
;       BAR; WAIT_L(0); MMA(1, 0, At, B0); BAR; SCHED;
;       STAGE(SB(1, 1), Bk, bcol + G_HALF, t + 3);
;       WAIT_V(6); BAR; MMA(1, 1, At, B1); BAR;
;     }
	ds_read_b128 v[154:157], v129 offset:49152
	ds_read_b128 v[158:161], v129 offset:50176
	ds_read_b128 v[162:165], v129 offset:51200
	ds_read_b128 v[172:175], v129 offset:52224
	ds_read_b128 v[180:183], v129 offset:53248
	ds_read_b128 v[184:187], v129 offset:54272
	ds_read_b128 v[188:191], v129 offset:55296
	ds_read_b128 v[192:195], v129 offset:56320
	s_mov_b32 m0, s46
	s_mov_b64 s[26:27], 0xb00180
	v_lshl_add_u64 v[216:217], v[176:177], 0, s[26:27]
	global_load_lds_dwordx4 v[216:217], off
	s_mov_b32 m0, s47
	s_mov_b64 s[26:27], 0xb20180
	v_lshl_add_u64 v[218:219], v[176:177], 0, s[26:27]
	global_load_lds_dwordx4 v[218:219], off
	s_mov_b32 m0, s48
	s_mov_b64 s[26:27], 0x180
	v_lshl_add_u64 v[214:215], v[166:167], 0, s[26:27]
	global_load_lds_dwordx4 v[214:215], off
	s_mov_b32 m0, s49
	s_mov_b64 s[26:27], 0x20180
	v_lshl_add_u64 v[216:217], v[166:167], 0, s[26:27]
	global_load_lds_dwordx4 v[216:217], off
	s_mov_b32 m0, s50
	s_mov_b64 s[26:27], 0xb40180
	v_lshl_add_u64 v[218:219], v[176:177], 0, s[26:27]
	global_load_lds_dwordx4 v[218:219], off
	s_mov_b32 m0, s51
	s_mov_b64 s[26:27], 0xb60180
	v_lshl_add_u64 v[214:215], v[176:177], 0, s[26:27]
	global_load_lds_dwordx4 v[214:215], off
	s_waitcnt vmcnt(6)
	s_waitcnt lgkmcnt(0)
	s_barrier
	s_setprio 1
	v_mfma_f32_16x16x32_bf16 v[60:63], v[154:157], v[138:141], v[60:63]
	v_mfma_f32_16x16x32_bf16 v[56:59], v[154:157], v[146:149], v[56:59]
	v_mfma_f32_16x16x32_bf16 v[52:55], v[162:165], v[138:141], v[52:55]
	v_mfma_f32_16x16x32_bf16 v[48:51], v[162:165], v[146:149], v[48:51]
	v_mfma_f32_16x16x32_bf16 v[44:47], v[180:183], v[138:141], v[44:47]
	v_mfma_f32_16x16x32_bf16 v[40:43], v[180:183], v[146:149], v[40:43]
	v_mfma_f32_16x16x32_bf16 v[36:39], v[188:191], v[138:141], v[36:39]
	v_mfma_f32_16x16x32_bf16 v[32:35], v[188:191], v[146:149], v[32:35]
	v_mfma_f32_16x16x32_bf16 v[60:63], v[158:161], v[142:145], v[60:63]
	v_mfma_f32_16x16x32_bf16 v[56:59], v[158:161], v[150:153], v[56:59]
	v_mfma_f32_16x16x32_bf16 v[52:55], v[172:175], v[142:145], v[52:55]
	v_mfma_f32_16x16x32_bf16 v[48:51], v[172:175], v[150:153], v[48:51]
	v_mfma_f32_16x16x32_bf16 v[44:47], v[184:187], v[142:145], v[44:47]
	v_mfma_f32_16x16x32_bf16 v[40:43], v[184:187], v[150:153], v[40:43]
	v_mfma_f32_16x16x32_bf16 v[36:39], v[192:195], v[142:145], v[36:39]
	v_mfma_f32_16x16x32_bf16 v[32:35], v[192:195], v[150:153], v[32:35]
	v_mfma_f32_16x16x32_bf16 v[28:31], v[154:157], v[196:199], v[28:31]
	v_mfma_f32_16x16x32_bf16 v[24:27], v[154:157], v[204:207], v[24:27]
	v_mfma_f32_16x16x32_bf16 v[20:23], v[162:165], v[196:199], v[20:23]
	v_mfma_f32_16x16x32_bf16 v[16:19], v[162:165], v[204:207], v[16:19]
	v_mfma_f32_16x16x32_bf16 v[12:15], v[180:183], v[196:199], v[12:15]
	v_mfma_f32_16x16x32_bf16 v[8:11], v[180:183], v[204:207], v[8:11]
	v_mfma_f32_16x16x32_bf16 v[4:7], v[188:191], v[196:199], v[4:7]
	v_mfma_f32_16x16x32_bf16 v[0:3], v[188:191], v[204:207], v[0:3]
	v_mfma_f32_16x16x32_bf16 v[28:31], v[158:161], v[200:203], v[28:31]
	v_mfma_f32_16x16x32_bf16 v[24:27], v[158:161], v[208:211], v[24:27]
	v_mfma_f32_16x16x32_bf16 v[20:23], v[172:175], v[200:203], v[20:23]
	v_mfma_f32_16x16x32_bf16 v[16:19], v[172:175], v[208:211], v[16:19]
	v_mfma_f32_16x16x32_bf16 v[12:15], v[184:187], v[200:203], v[12:15]
	v_mfma_f32_16x16x32_bf16 v[8:11], v[184:187], v[208:211], v[8:11]
	v_mfma_f32_16x16x32_bf16 v[4:7], v[192:195], v[200:203], v[4:7]
	v_mfma_f32_16x16x32_bf16 v[0:3], v[192:195], v[208:211], v[0:3]
	s_setprio 0
	s_add_i32 s3, s3, 2
	s_add_u32 s6, s6, 0x100
	s_addc_u32 s7, s7, 0
	s_add_u32 s24, s24, 0x100
	s_addc_u32 s25, s25, 0
	s_cmp_ge_i32 s3, s2
	s_barrier
	s_cbranch_scc0 .LBB0_673

; #define WAIT_V(n) asm volatile("s_waitcnt vmcnt(" #n ")" ::: "memory")
; #define BAR __builtin_amdgcn_s_barrier()
; template <class Epi>
; __device__ __forceinline__ void gemm_phase(const bfr* __restrict__ A, int lda, const bfr* __restrict__ Bt, int K,
;                                            int nM, int nN, const Epi& epi, bfr* shm, int wv, int nMfull, int ksplit) {
;     ...
;     f32x4 acc[2][2][4][2];
; #pragma unroll
;     for (int a = 0; a < 2; a++)
; #pragma unroll
;       for (int b = 0; b < 2; b++)
; #pragma unroll
;         for (int m = 0; m < 4; m++)
; #pragma unroll
;           for (int n = 0; n < 2; n++) acc[a][b][m][n] = f32x4{0.f, 0.f, 0.f, 0.f};
;     bf16x8 At[4][2], B0[2][2], B1[2][2];
;     if (wr == 1) BAR;
;     WAIT_V(10); BAR;
;     WAIT_V(6); BAR;
;     for (int t = 0; t < nt - 2; t += 2) {
.LBB0_727:
	v_readlane_b32 s60, v255, 10
	s_lshl_b64 s[38:39], s[10:11], 1
	v_readlane_b32 s66, v255, 16
	v_readlane_b32 s67, v255, 17
	s_add_u32 s10, s66, s38
	s_waitcnt vmcnt(8)
	s_barrier
	s_waitcnt vmcnt(6)
	s_addc_u32 s31, s67, s39
	v_mov_b32_e32 v127, 0
	s_cmp_lt_u32 s30, 3
	v_mov_b32_e32 v126, v127
	v_mov_b32_e32 v125, v127
	v_mov_b32_e32 v124, v127
	v_mov_b32_e32 v123, v127
	v_mov_b32_e32 v122, v127
	v_mov_b32_e32 v121, v127
	v_mov_b32_e32 v120, v127
	v_mov_b32_e32 v119, v127
	v_mov_b32_e32 v118, v127
	v_mov_b32_e32 v117, v127
	v_mov_b32_e32 v116, v127
	v_mov_b32_e32 v115, v127
	v_mov_b32_e32 v114, v127
	v_mov_b32_e32 v113, v127
	v_mov_b32_e32 v112, v127
	v_mov_b32_e32 v111, v127
	v_mov_b32_e32 v110, v127
	v_mov_b32_e32 v109, v127
	v_mov_b32_e32 v108, v127
	v_mov_b32_e32 v107, v127
	v_mov_b32_e32 v106, v127
	v_mov_b32_e32 v105, v127
	v_mov_b32_e32 v104, v127
	v_mov_b32_e32 v103, v127
	v_mov_b32_e32 v102, v127
	v_mov_b32_e32 v101, v127
	v_mov_b32_e32 v100, v127
	v_mov_b32_e32 v99, v127
	v_mov_b32_e32 v98, v127
	v_mov_b32_e32 v97, v127
	v_mov_b32_e32 v96, v127
	v_mov_b32_e32 v95, v127
	v_mov_b32_e32 v94, v127
	v_mov_b32_e32 v93, v127
	v_mov_b32_e32 v92, v127
	v_mov_b32_e32 v91, v127
	v_mov_b32_e32 v90, v127
	v_mov_b32_e32 v89, v127
	v_mov_b32_e32 v88, v127
	v_mov_b32_e32 v87, v127
	v_mov_b32_e32 v86, v127
	v_mov_b32_e32 v85, v127
	v_mov_b32_e32 v84, v127
	v_mov_b32_e32 v83, v127
	v_mov_b32_e32 v82, v127
	v_mov_b32_e32 v81, v127
	v_mov_b32_e32 v80, v127
	v_mov_b32_e32 v79, v127
	v_mov_b32_e32 v78, v127
	v_mov_b32_e32 v77, v127
	v_mov_b32_e32 v76, v127
	v_mov_b32_e32 v75, v127
	v_mov_b32_e32 v74, v127
	v_mov_b32_e32 v73, v127
	v_mov_b32_e32 v72, v127
	v_mov_b32_e32 v71, v127
	v_mov_b32_e32 v70, v127
	v_mov_b32_e32 v69, v127
	v_mov_b32_e32 v68, v127
	v_mov_b32_e32 v67, v127
	v_mov_b32_e32 v66, v127
	v_mov_b32_e32 v65, v127
	v_mov_b32_e32 v64, v127
	v_mov_b32_e32 v63, v127
	v_mov_b32_e32 v62, v127
	v_mov_b32_e32 v61, v127
	v_mov_b32_e32 v60, v127
	v_mov_b32_e32 v59, v127
	v_mov_b32_e32 v58, v127
	v_mov_b32_e32 v57, v127
	v_mov_b32_e32 v56, v127
	v_mov_b32_e32 v55, v127
	v_mov_b32_e32 v54, v127
	v_mov_b32_e32 v53, v127
	v_mov_b32_e32 v52, v127
	v_mov_b32_e32 v51, v127
	v_mov_b32_e32 v50, v127
	v_mov_b32_e32 v49, v127
	v_mov_b32_e32 v48, v127
	v_mov_b32_e32 v47, v127
	v_mov_b32_e32 v46, v127
	v_mov_b32_e32 v45, v127
	v_mov_b32_e32 v44, v127
	v_mov_b32_e32 v43, v127
	v_mov_b32_e32 v42, v127
	v_mov_b32_e32 v41, v127
	v_mov_b32_e32 v40, v127
	v_mov_b32_e32 v39, v127
	v_mov_b32_e32 v38, v127
	v_mov_b32_e32 v37, v127
	v_mov_b32_e32 v36, v127
	v_mov_b32_e32 v35, v127
	v_mov_b32_e32 v34, v127
	v_mov_b32_e32 v33, v127
	v_mov_b32_e32 v32, v127
	v_mov_b32_e32 v31, v127
	v_mov_b32_e32 v30, v127
	v_mov_b32_e32 v29, v127
	v_mov_b32_e32 v28, v127
	v_mov_b32_e32 v27, v127
	v_mov_b32_e32 v26, v127
	v_mov_b32_e32 v25, v127
	v_mov_b32_e32 v24, v127
	v_mov_b32_e32 v23, v127
	v_mov_b32_e32 v22, v127
	v_mov_b32_e32 v21, v127
	v_mov_b32_e32 v20, v127
	v_mov_b32_e32 v19, v127
	v_mov_b32_e32 v18, v127
	v_mov_b32_e32 v17, v127
	v_mov_b32_e32 v16, v127
	v_mov_b32_e32 v15, v127
	v_mov_b32_e32 v14, v127
	v_mov_b32_e32 v13, v127
	v_mov_b32_e32 v12, v127
	v_mov_b32_e32 v11, v127
	v_mov_b32_e32 v10, v127
	v_mov_b32_e32 v9, v127
	v_mov_b32_e32 v8, v127
	v_mov_b32_e32 v7, v127
	v_mov_b32_e32 v6, v127
	v_mov_b32_e32 v5, v127
	v_mov_b32_e32 v4, v127
	v_mov_b32_e32 v3, v127
	v_mov_b32_e32 v2, v127
	v_mov_b32_e32 v1, v127
	v_mov_b32_e32 v0, v127
	v_readlane_b32 s61, v255, 11
	v_readlane_b32 s62, v255, 12
	v_readlane_b32 s63, v255, 13
	v_readlane_b32 s64, v255, 14
	v_readlane_b32 s65, v255, 15
	v_readlane_b32 s68, v255, 18
	v_readlane_b32 s69, v255, 19
	v_readlane_b32 s70, v255, 20
	v_readlane_b32 s71, v255, 21
	v_readlane_b32 s72, v255, 22
	v_readlane_b32 s73, v255, 23
	v_readlane_b32 s74, v255, 24
	v_readlane_b32 s75, v255, 25
	s_barrier
	s_cbranch_scc1 .LBB0_730
	s_mul_i32 s40, s36, 0xb00
	s_add_i32 s2, s30, -2
	s_ashr_i32 s41, s40, 31
	s_mul_i32 s34, s95, 0x1600
	s_mul_hi_i32 s35, s95, 0x1600
	s_add_u32 s34, s10, s34
	s_addc_u32 s35, s31, s35
	s_lshl_b64 s[40:41], s[40:41], 1
	s_add_u32 s37, s40, s38
	v_readlane_b32 s60, v254, 54
	s_addc_u32 s39, s41, s39
	v_readlane_b32 s64, v254, 58
	v_readlane_b32 s65, v254, 59
	s_add_u32 s38, s64, s37
	v_mov_b32_e32 v0, 0
	s_addc_u32 s39, s65, s39
	s_mov_b32 s37, 0
	v_readlane_b32 s61, v254, 55
	v_readlane_b32 s62, v254, 56
	v_readlane_b32 s63, v254, 57
	v_readlane_b32 s66, v254, 60
	v_readlane_b32 s67, v254, 61
	v_readlane_b32 s68, v254, 62
	v_readlane_b32 s69, v254, 63
	v_readlane_b32 s70, v255, 0
	v_readlane_b32 s71, v255, 1
	v_readlane_b32 s72, v255, 2
	v_readlane_b32 s73, v255, 3
	v_readlane_b32 s74, v255, 4
	v_readlane_b32 s75, v255, 5
; #define STAGE(P, BASE, br, kt) do { const char* _g = (const char*)((BASE) + (size_t)(br) * K + (size_t)(kt) * G_BK); \
;     _Pragma("unroll") for (int _i = 0; _i < 2; ++_i) { \
;       __builtin_amdgcn_global_load_lds((const unsigned*)(_g + (size_t)_i * 128 * K + sg_off), (unsigned*)((char*)(P) + wid * 1024 + _i * 8192), 16, 0, 0); } } while (0)
; #define LDA(dst, b, h) _Pragma("unroll") for (int m = 0; m < 4; ++m) _Pragma("unroll") for (int k = 0; k < 2; ++k) \
;     dst[m][k] = *reinterpret_cast<const bf16x8*>((const char*)shm + aoff + (((b) * 2 + (h)) * 16384 + m * 2048 + k * 1024))
; #define LDB(dst, b, h) _Pragma("unroll") for (int n = 0; n < 2; ++n) _Pragma("unroll") for (int k = 0; k < 2; ++k) \
;     dst[n][k] = *reinterpret_cast<const bf16x8*>((const char*)shm + boff + (((b) * 2 + (h)) * 16384 + n * 2048 + k * 1024))
; #define MMA(ai, bj, At, Bt_) do { __builtin_amdgcn_s_setprio(1); \
;     _Pragma("unroll") for (int m = 0; m < 4; ++m) _Pragma("unroll") for (int n = 0; n < 2; ++n) _Pragma("unroll") for (int k = 0; k < 2; ++k) \
;       acc[ai][bj][m][n] = mfma16(At[m][k], Bt_[n][k], acc[ai][bj][m][n]); \
;     __builtin_amdgcn_s_setprio(0); } while (0)
; #define WAIT_V(n) asm volatile("s_waitcnt vmcnt(" #n ")" ::: "memory")
; #define WAIT_L(n) asm volatile("s_waitcnt lgkmcnt(" #n ")" ::: "memory")
; #define BAR __builtin_amdgcn_s_barrier()
; #define SCHED __builtin_amdgcn_sched_barrier(0)
; template <class Epi>
; __device__ __forceinline__ void gemm_phase(const bfr* __restrict__ A, int lda, const bfr* __restrict__ Bt, int K,
;                                            int nM, int nN, const Epi& epi, bfr* shm, int wv, int nMfull, int ksplit) {
;     ...
;       LDB(B0, 0, 0); SCHED; LDA(At, 0, 0); STAGE(SA(1, 1), Ak, brow + G_HALF, t + 1);
;       WAIT_L(8); BAR; WAIT_L(0); MMA(0, 0, At, B0); BAR; SCHED;
;       LDB(B1, 0, 1); STAGE(SB(0, 0), Bk, bcol, t + 2);
;       BAR; WAIT_L(0); MMA(0, 1, At, B1); BAR;
;       LDA(At, 0, 1); STAGE(SA(0, 0), Ak, brow, t + 2);
;       BAR; WAIT_L(0); MMA(1, 0, At, B0); BAR; SCHED;
;       STAGE(SB(0, 1), Bk, bcol + G_HALF, t + 2);
;       WAIT_V(6); BAR; MMA(1, 1, At, B1); BAR;
.LBB0_729:
	ds_read_b128 v[138:141], v179
	ds_read_b128 v[142:145], v179 offset:1024
	ds_read_b128 v[146:149], v179 offset:2048
	ds_read_b128 v[150:153], v179 offset:3072
	ds_read_b128 v[154:157], v178
	ds_read_b128 v[158:161], v178 offset:1024
	ds_read_b128 v[162:165], v178 offset:2048
	ds_read_b128 v[166:169], v178 offset:3072
	ds_read_b128 v[170:173], v178 offset:4096
	ds_read_b128 v[174:177], v178 offset:5120
	ds_read_b128 v[184:187], v178 offset:6144
	ds_read_b128 v[188:191], v178 offset:7168
	ds_read_b128 v[192:195], v179 offset:16384
	ds_read_b128 v[196:199], v179 offset:17408
	ds_read_b128 v[200:203], v179 offset:18432
	ds_read_b128 v[204:207], v179 offset:19456
	v_lshl_add_u64 v[208:209], s[34:35], 0, v[136:137]
	v_lshl_add_u64 v[210:211], s[38:39], 0, v[136:137]
	s_mov_b32 m0, s52
	v_lshl_add_u64 v[214:215], v[208:209], 0, s[16:17]
	global_load_lds_dwordx4 v[214:215], off
	s_mov_b32 m0, s53
	v_lshl_add_u64 v[216:217], v[208:209], 0, s[18:19]
	global_load_lds_dwordx4 v[216:217], off
	s_waitcnt lgkmcnt(0)
	s_barrier
	s_setprio 1
	v_mfma_f32_16x16x32_bf16 v[124:127], v[154:157], v[138:141], v[124:127]
	v_mfma_f32_16x16x32_bf16 v[120:123], v[154:157], v[146:149], v[120:123]
	v_mfma_f32_16x16x32_bf16 v[116:119], v[162:165], v[138:141], v[116:119]
	v_mfma_f32_16x16x32_bf16 v[112:115], v[162:165], v[146:149], v[112:115]
	v_mfma_f32_16x16x32_bf16 v[108:111], v[170:173], v[138:141], v[108:111]
	v_mfma_f32_16x16x32_bf16 v[104:107], v[170:173], v[146:149], v[104:107]
	v_mfma_f32_16x16x32_bf16 v[100:103], v[184:187], v[138:141], v[100:103]
	v_mfma_f32_16x16x32_bf16 v[96:99], v[184:187], v[146:149], v[96:99]
	v_mfma_f32_16x16x32_bf16 v[124:127], v[158:161], v[142:145], v[124:127]
	v_mfma_f32_16x16x32_bf16 v[120:123], v[158:161], v[150:153], v[120:123]
	v_mfma_f32_16x16x32_bf16 v[116:119], v[166:169], v[142:145], v[116:119]
	v_mfma_f32_16x16x32_bf16 v[112:115], v[166:169], v[150:153], v[112:115]
	v_mfma_f32_16x16x32_bf16 v[108:111], v[174:177], v[142:145], v[108:111]
	v_mfma_f32_16x16x32_bf16 v[104:107], v[174:177], v[150:153], v[104:107]
	v_mfma_f32_16x16x32_bf16 v[100:103], v[188:191], v[142:145], v[100:103]
	v_mfma_f32_16x16x32_bf16 v[96:99], v[188:191], v[150:153], v[96:99]
	v_mfma_f32_16x16x32_bf16 v[92:95], v[154:157], v[192:195], v[92:95]
	v_mfma_f32_16x16x32_bf16 v[88:91], v[154:157], v[200:203], v[88:91]
	v_mfma_f32_16x16x32_bf16 v[84:87], v[162:165], v[192:195], v[84:87]
	v_mfma_f32_16x16x32_bf16 v[80:83], v[162:165], v[200:203], v[80:83]
	v_mfma_f32_16x16x32_bf16 v[76:79], v[170:173], v[192:195], v[76:79]
	v_mfma_f32_16x16x32_bf16 v[72:75], v[170:173], v[200:203], v[72:75]
	v_mfma_f32_16x16x32_bf16 v[68:71], v[184:187], v[192:195], v[68:71]
	v_mfma_f32_16x16x32_bf16 v[64:67], v[184:187], v[200:203], v[64:67]
	v_mfma_f32_16x16x32_bf16 v[92:95], v[158:161], v[196:199], v[92:95]
	v_mfma_f32_16x16x32_bf16 v[88:91], v[158:161], v[204:207], v[88:91]
	v_mfma_f32_16x16x32_bf16 v[84:87], v[166:169], v[196:199], v[84:87]
	v_mfma_f32_16x16x32_bf16 v[80:83], v[166:169], v[204:207], v[80:83]
	v_mfma_f32_16x16x32_bf16 v[76:79], v[174:177], v[196:199], v[76:79]
	v_mfma_f32_16x16x32_bf16 v[72:75], v[174:177], v[204:207], v[72:75]
	v_mfma_f32_16x16x32_bf16 v[68:71], v[188:191], v[196:199], v[68:71]
	v_mfma_f32_16x16x32_bf16 v[64:67], v[188:191], v[204:207], v[64:67]
	s_setprio 0
	s_barrier
	ds_read_b128 v[154:157], v178 offset:16384
	ds_read_b128 v[158:161], v178 offset:17408
	ds_read_b128 v[162:165], v178 offset:18432
	ds_read_b128 v[166:169], v178 offset:19456
	ds_read_b128 v[170:173], v178 offset:20480
	ds_read_b128 v[174:177], v178 offset:21504
	ds_read_b128 v[184:187], v178 offset:22528
	ds_read_b128 v[188:191], v178 offset:23552
	s_mov_b32 m0, s54
	s_mov_b64 s[40:41], 0x580100
	v_lshl_add_u64 v[218:219], v[210:211], 0, s[40:41]
	global_load_lds_dwordx4 v[218:219], off
	s_mov_b32 m0, s55
	s_mov_b64 s[40:41], 0x5d8100
	v_lshl_add_u64 v[214:215], v[210:211], 0, s[40:41]
	global_load_lds_dwordx4 v[214:215], off
	s_mov_b32 m0, s51
	s_mov_b64 s[40:41], 0x100
	v_lshl_add_u64 v[216:217], v[208:209], 0, s[40:41]
	global_load_lds_dwordx4 v[216:217], off
	s_mov_b32 m0, s56
	s_mov_b64 s[40:41], 0x58100
	v_lshl_add_u64 v[218:219], v[208:209], 0, s[40:41]
	global_load_lds_dwordx4 v[218:219], off
	s_waitcnt vmcnt(6)
	s_waitcnt lgkmcnt(0)
	s_barrier
	s_setprio 1
	v_mfma_f32_16x16x32_bf16 v[60:63], v[154:157], v[138:141], v[60:63]
	v_mfma_f32_16x16x32_bf16 v[56:59], v[154:157], v[146:149], v[56:59]
	v_mfma_f32_16x16x32_bf16 v[52:55], v[162:165], v[138:141], v[52:55]
	v_mfma_f32_16x16x32_bf16 v[48:51], v[162:165], v[146:149], v[48:51]
	v_mfma_f32_16x16x32_bf16 v[44:47], v[170:173], v[138:141], v[44:47]
	v_mfma_f32_16x16x32_bf16 v[40:43], v[170:173], v[146:149], v[40:43]
	v_mfma_f32_16x16x32_bf16 v[36:39], v[184:187], v[138:141], v[36:39]
	v_mfma_f32_16x16x32_bf16 v[32:35], v[184:187], v[146:149], v[32:35]
	v_mfma_f32_16x16x32_bf16 v[60:63], v[158:161], v[142:145], v[60:63]
	v_mfma_f32_16x16x32_bf16 v[56:59], v[158:161], v[150:153], v[56:59]
	v_mfma_f32_16x16x32_bf16 v[52:55], v[166:169], v[142:145], v[52:55]
	v_mfma_f32_16x16x32_bf16 v[48:51], v[166:169], v[150:153], v[48:51]
	v_mfma_f32_16x16x32_bf16 v[44:47], v[174:177], v[142:145], v[44:47]
	v_mfma_f32_16x16x32_bf16 v[40:43], v[174:177], v[150:153], v[40:43]
	v_mfma_f32_16x16x32_bf16 v[36:39], v[188:191], v[142:145], v[36:39]
	v_mfma_f32_16x16x32_bf16 v[32:35], v[188:191], v[150:153], v[32:35]
	v_mfma_f32_16x16x32_bf16 v[28:31], v[154:157], v[192:195], v[28:31]
	v_mfma_f32_16x16x32_bf16 v[24:27], v[154:157], v[200:203], v[24:27]
	v_mfma_f32_16x16x32_bf16 v[20:23], v[162:165], v[192:195], v[20:23]
	v_mfma_f32_16x16x32_bf16 v[16:19], v[162:165], v[200:203], v[16:19]
	v_mfma_f32_16x16x32_bf16 v[12:15], v[170:173], v[192:195], v[12:15]
	v_mfma_f32_16x16x32_bf16 v[8:11], v[170:173], v[200:203], v[8:11]
	v_mfma_f32_16x16x32_bf16 v[4:7], v[184:187], v[192:195], v[4:7]
	v_mfma_f32_16x16x32_bf16 v[0:3], v[184:187], v[200:203], v[0:3]
	v_mfma_f32_16x16x32_bf16 v[28:31], v[158:161], v[196:199], v[28:31]
	v_mfma_f32_16x16x32_bf16 v[24:27], v[158:161], v[204:207], v[24:27]
	v_mfma_f32_16x16x32_bf16 v[20:23], v[166:169], v[196:199], v[20:23]
	v_mfma_f32_16x16x32_bf16 v[16:19], v[166:169], v[204:207], v[16:19]
	v_mfma_f32_16x16x32_bf16 v[12:15], v[174:177], v[196:199], v[12:15]
	v_mfma_f32_16x16x32_bf16 v[8:11], v[174:177], v[204:207], v[8:11]
	v_mfma_f32_16x16x32_bf16 v[4:7], v[188:191], v[196:199], v[4:7]
	v_mfma_f32_16x16x32_bf16 v[0:3], v[188:191], v[204:207], v[0:3]
	s_setprio 0
	s_barrier
; #define STAGE(P, BASE, br, kt) do { const char* _g = (const char*)((BASE) + (size_t)(br) * K + (size_t)(kt) * G_BK); \
;     _Pragma("unroll") for (int _i = 0; _i < 2; ++_i) { \
;       __builtin_amdgcn_global_load_lds((const unsigned*)(_g + (size_t)_i * 128 * K + sg_off), (unsigned*)((char*)(P) + wid * 1024 + _i * 8192), 16, 0, 0); } } while (0)
; #define LDA(dst, b, h) _Pragma("unroll") for (int m = 0; m < 4; ++m) _Pragma("unroll") for (int k = 0; k < 2; ++k) \
;     dst[m][k] = *reinterpret_cast<const bf16x8*>((const char*)shm + aoff + (((b) * 2 + (h)) * 16384 + m * 2048 + k * 1024))
; #define LDB(dst, b, h) _Pragma("unroll") for (int n = 0; n < 2; ++n) _Pragma("unroll") for (int k = 0; k < 2; ++k) \
;     dst[n][k] = *reinterpret_cast<const bf16x8*>((const char*)shm + boff + (((b) * 2 + (h)) * 16384 + n * 2048 + k * 1024))
; #define MMA(ai, bj, At, Bt_) do { __builtin_amdgcn_s_setprio(1); \
;     _Pragma("unroll") for (int m = 0; m < 4; ++m) _Pragma("unroll") for (int n = 0; n < 2; ++n) _Pragma("unroll") for (int k = 0; k < 2; ++k) \
;       acc[ai][bj][m][n] = mfma16(At[m][k], Bt_[n][k], acc[ai][bj][m][n]); \
;     __builtin_amdgcn_s_setprio(0); } while (0)
; #define WAIT_L(n) asm volatile("s_waitcnt lgkmcnt(" #n ")" ::: "memory")
; #define BAR __builtin_amdgcn_s_barrier()
; #define SCHED __builtin_amdgcn_sched_barrier(0)
; template <class Epi>
; __device__ __forceinline__ void gemm_phase(const bfr* __restrict__ A, int lda, const bfr* __restrict__ Bt, int K,
;                                            int nM, int nN, const Epi& epi, bfr* shm, int wv, int nMfull, int ksplit) {
;     ...
;       LDB(B0, 1, 0); SCHED; LDA(At, 1, 0); STAGE(SA(0, 1), Ak, brow + G_HALF, t + 2);
;       WAIT_L(8); BAR; WAIT_L(0); MMA(0, 0, At, B0); BAR; SCHED;
;       LDB(B1, 1, 1); STAGE(SB(1, 0), Bk, bcol, t + 3);
;       BAR; WAIT_L(0); MMA(0, 1, At, B1); BAR;
	ds_read_b128 v[138:141], v179 offset:32768
	ds_read_b128 v[142:145], v179 offset:33792
	ds_read_b128 v[146:149], v179 offset:34816
	ds_read_b128 v[150:153], v179 offset:35840
	ds_read_b128 v[154:157], v178 offset:32768
	ds_read_b128 v[158:161], v178 offset:33792
	ds_read_b128 v[162:165], v178 offset:34816
	ds_read_b128 v[166:169], v178 offset:35840
	ds_read_b128 v[170:173], v178 offset:36864
	ds_read_b128 v[174:177], v178 offset:37888
	ds_read_b128 v[184:187], v178 offset:38912
	ds_read_b128 v[188:191], v178 offset:39936
	ds_read_b128 v[192:195], v179 offset:49152
	ds_read_b128 v[196:199], v179 offset:50176
	ds_read_b128 v[200:203], v179 offset:51200
	ds_read_b128 v[204:207], v179 offset:52224
	s_mov_b32 m0, s57
	s_mov_b64 s[40:41], 0x630100
	v_lshl_add_u64 v[214:215], v[210:211], 0, s[40:41]
	global_load_lds_dwordx4 v[214:215], off
	s_mov_b32 m0, s58
	s_mov_b64 s[40:41], 0x688100
	v_lshl_add_u64 v[216:217], v[210:211], 0, s[40:41]
	global_load_lds_dwordx4 v[216:217], off
	s_mov_b32 m0, s59
	s_mov_b64 s[40:41], 0xb0100
	v_lshl_add_u64 v[218:219], v[208:209], 0, s[40:41]
	global_load_lds_dwordx4 v[218:219], off
	s_mov_b32 m0, s82
	s_mov_b64 s[40:41], 0x108100
	v_lshl_add_u64 v[214:215], v[208:209], 0, s[40:41]
	global_load_lds_dwordx4 v[214:215], off
	s_waitcnt vmcnt(8)
	s_waitcnt lgkmcnt(0)
	s_barrier
	s_setprio 1
	v_mfma_f32_16x16x32_bf16 v[124:127], v[154:157], v[138:141], v[124:127]
	v_mfma_f32_16x16x32_bf16 v[120:123], v[154:157], v[146:149], v[120:123]
	v_mfma_f32_16x16x32_bf16 v[116:119], v[162:165], v[138:141], v[116:119]
	v_mfma_f32_16x16x32_bf16 v[112:115], v[162:165], v[146:149], v[112:115]
	v_mfma_f32_16x16x32_bf16 v[108:111], v[170:173], v[138:141], v[108:111]
	v_mfma_f32_16x16x32_bf16 v[104:107], v[170:173], v[146:149], v[104:107]
	v_mfma_f32_16x16x32_bf16 v[100:103], v[184:187], v[138:141], v[100:103]
	v_mfma_f32_16x16x32_bf16 v[96:99], v[184:187], v[146:149], v[96:99]
	v_mfma_f32_16x16x32_bf16 v[124:127], v[158:161], v[142:145], v[124:127]
	v_mfma_f32_16x16x32_bf16 v[120:123], v[158:161], v[150:153], v[120:123]
	v_mfma_f32_16x16x32_bf16 v[116:119], v[166:169], v[142:145], v[116:119]
	v_mfma_f32_16x16x32_bf16 v[112:115], v[166:169], v[150:153], v[112:115]
	v_mfma_f32_16x16x32_bf16 v[108:111], v[174:177], v[142:145], v[108:111]
	v_mfma_f32_16x16x32_bf16 v[104:107], v[174:177], v[150:153], v[104:107]
	v_mfma_f32_16x16x32_bf16 v[100:103], v[188:191], v[142:145], v[100:103]
	v_mfma_f32_16x16x32_bf16 v[96:99], v[188:191], v[150:153], v[96:99]
	v_mfma_f32_16x16x32_bf16 v[92:95], v[154:157], v[192:195], v[92:95]
	v_mfma_f32_16x16x32_bf16 v[88:91], v[154:157], v[200:203], v[88:91]
	v_mfma_f32_16x16x32_bf16 v[84:87], v[162:165], v[192:195], v[84:87]
	v_mfma_f32_16x16x32_bf16 v[80:83], v[162:165], v[200:203], v[80:83]
	v_mfma_f32_16x16x32_bf16 v[76:79], v[170:173], v[192:195], v[76:79]
	v_mfma_f32_16x16x32_bf16 v[72:75], v[170:173], v[200:203], v[72:75]
	v_mfma_f32_16x16x32_bf16 v[68:71], v[184:187], v[192:195], v[68:71]
	v_mfma_f32_16x16x32_bf16 v[64:67], v[184:187], v[200:203], v[64:67]
	v_mfma_f32_16x16x32_bf16 v[92:95], v[158:161], v[196:199], v[92:95]
	v_mfma_f32_16x16x32_bf16 v[88:91], v[158:161], v[204:207], v[88:91]
	v_mfma_f32_16x16x32_bf16 v[84:87], v[166:169], v[196:199], v[84:87]
	v_mfma_f32_16x16x32_bf16 v[80:83], v[166:169], v[204:207], v[80:83]
	v_mfma_f32_16x16x32_bf16 v[76:79], v[174:177], v[196:199], v[76:79]
	v_mfma_f32_16x16x32_bf16 v[72:75], v[174:177], v[204:207], v[72:75]
	v_mfma_f32_16x16x32_bf16 v[68:71], v[188:191], v[196:199], v[68:71]
	v_mfma_f32_16x16x32_bf16 v[64:67], v[188:191], v[204:207], v[64:67]
	s_setprio 0
	s_barrier
; #define STAGE(P, BASE, br, kt) do { const char* _g = (const char*)((BASE) + (size_t)(br) * K + (size_t)(kt) * G_BK); \
;     _Pragma("unroll") for (int _i = 0; _i < 2; ++_i) { \
;       __builtin_amdgcn_global_load_lds((const unsigned*)(_g + (size_t)_i * 128 * K + sg_off), (unsigned*)((char*)(P) + wid * 1024 + _i * 8192), 16, 0, 0); } } while (0)
; #define LDA(dst, b, h) _Pragma("unroll") for (int m = 0; m < 4; ++m) _Pragma("unroll") for (int k = 0; k < 2; ++k) \
;     dst[m][k] = *reinterpret_cast<const bf16x8*>((const char*)shm + aoff + (((b) * 2 + (h)) * 16384 + m * 2048 + k * 1024))
; #define MMA(ai, bj, At, Bt_) do { __builtin_amdgcn_s_setprio(1); \
;     _Pragma("unroll") for (int m = 0; m < 4; ++m) _Pragma("unroll") for (int n = 0; n < 2; ++n) _Pragma("unroll") for (int k = 0; k < 2; ++k) \
;       acc[ai][bj][m][n] = mfma16(At[m][k], Bt_[n][k], acc[ai][bj][m][n]); \
;     __builtin_amdgcn_s_setprio(0); } while (0)
; #define WAIT_V(n) asm volatile("s_waitcnt vmcnt(" #n ")" ::: "memory")
; #define WAIT_L(n) asm volatile("s_waitcnt lgkmcnt(" #n ")" ::: "memory")
; #define BAR __builtin_amdgcn_s_barrier()
; #define SCHED __builtin_amdgcn_sched_barrier(0)
; template <class Epi>
; __device__ __forceinline__ void gemm_phase(const bfr* __restrict__ A, int lda, const bfr* __restrict__ Bt, int K,
;                                            int nM, int nN, const Epi& epi, bfr* shm, int wv, int nMfull, int ksplit) {
;     ...
;       LDA(At, 1, 1); STAGE(SA(1, 0), Ak, brow, t + 3);
;       BAR; WAIT_L(0); MMA(1, 0, At, B0); BAR; SCHED;
;       STAGE(SB(1, 1), Bk, bcol + G_HALF, t + 3);
;       WAIT_V(6); BAR; MMA(1, 1, At, B1); BAR;
;     }
	ds_read_b128 v[154:157], v178 offset:49152
	ds_read_b128 v[158:161], v178 offset:50176
	ds_read_b128 v[162:165], v178 offset:51200
	ds_read_b128 v[166:169], v178 offset:52224
	ds_read_b128 v[170:173], v178 offset:53248
	ds_read_b128 v[174:177], v178 offset:54272
	ds_read_b128 v[184:187], v178 offset:55296
	ds_read_b128 v[188:191], v178 offset:56320
	s_mov_b32 m0, s83
	s_mov_b64 s[40:41], 0x580180
	v_lshl_add_u64 v[216:217], v[210:211], 0, s[40:41]
	global_load_lds_dwordx4 v[216:217], off
	s_mov_b32 m0, s84
	s_mov_b64 s[40:41], 0x5d8180
	v_lshl_add_u64 v[218:219], v[210:211], 0, s[40:41]
	global_load_lds_dwordx4 v[218:219], off
	s_mov_b32 m0, s85
	s_mov_b64 s[40:41], 0x180
	v_lshl_add_u64 v[214:215], v[208:209], 0, s[40:41]
	global_load_lds_dwordx4 v[214:215], off
	s_mov_b32 m0, s90
	s_mov_b64 s[40:41], 0x58180
	v_lshl_add_u64 v[216:217], v[208:209], 0, s[40:41]
	global_load_lds_dwordx4 v[216:217], off
	s_mov_b32 m0, s91
	s_mov_b64 s[40:41], 0x630180
	v_lshl_add_u64 v[218:219], v[210:211], 0, s[40:41]
	global_load_lds_dwordx4 v[218:219], off
	s_mov_b32 m0, s92
	s_mov_b64 s[40:41], 0x688180
	v_lshl_add_u64 v[214:215], v[210:211], 0, s[40:41]
	global_load_lds_dwordx4 v[214:215], off
	s_waitcnt vmcnt(6)
	s_waitcnt lgkmcnt(0)
	s_barrier
	s_setprio 1
	v_mfma_f32_16x16x32_bf16 v[60:63], v[154:157], v[138:141], v[60:63]
	v_mfma_f32_16x16x32_bf16 v[56:59], v[154:157], v[146:149], v[56:59]
	v_mfma_f32_16x16x32_bf16 v[52:55], v[162:165], v[138:141], v[52:55]
	v_mfma_f32_16x16x32_bf16 v[48:51], v[162:165], v[146:149], v[48:51]
	v_mfma_f32_16x16x32_bf16 v[44:47], v[170:173], v[138:141], v[44:47]
	v_mfma_f32_16x16x32_bf16 v[40:43], v[170:173], v[146:149], v[40:43]
	v_mfma_f32_16x16x32_bf16 v[36:39], v[184:187], v[138:141], v[36:39]
	v_mfma_f32_16x16x32_bf16 v[32:35], v[184:187], v[146:149], v[32:35]
	v_mfma_f32_16x16x32_bf16 v[60:63], v[158:161], v[142:145], v[60:63]
	v_mfma_f32_16x16x32_bf16 v[56:59], v[158:161], v[150:153], v[56:59]
	v_mfma_f32_16x16x32_bf16 v[52:55], v[166:169], v[142:145], v[52:55]
	v_mfma_f32_16x16x32_bf16 v[48:51], v[166:169], v[150:153], v[48:51]
	v_mfma_f32_16x16x32_bf16 v[44:47], v[174:177], v[142:145], v[44:47]
	v_mfma_f32_16x16x32_bf16 v[40:43], v[174:177], v[150:153], v[40:43]
	v_mfma_f32_16x16x32_bf16 v[36:39], v[188:191], v[142:145], v[36:39]
	v_mfma_f32_16x16x32_bf16 v[32:35], v[188:191], v[150:153], v[32:35]
	v_mfma_f32_16x16x32_bf16 v[28:31], v[154:157], v[192:195], v[28:31]
	v_mfma_f32_16x16x32_bf16 v[24:27], v[154:157], v[200:203], v[24:27]
	v_mfma_f32_16x16x32_bf16 v[20:23], v[162:165], v[192:195], v[20:23]
	v_mfma_f32_16x16x32_bf16 v[16:19], v[162:165], v[200:203], v[16:19]
	v_mfma_f32_16x16x32_bf16 v[12:15], v[170:173], v[192:195], v[12:15]
	v_mfma_f32_16x16x32_bf16 v[8:11], v[170:173], v[200:203], v[8:11]
	v_mfma_f32_16x16x32_bf16 v[4:7], v[184:187], v[192:195], v[4:7]
	v_mfma_f32_16x16x32_bf16 v[0:3], v[184:187], v[200:203], v[0:3]
	v_mfma_f32_16x16x32_bf16 v[28:31], v[158:161], v[196:199], v[28:31]
	v_mfma_f32_16x16x32_bf16 v[24:27], v[158:161], v[204:207], v[24:27]
	v_mfma_f32_16x16x32_bf16 v[20:23], v[166:169], v[196:199], v[20:23]
	v_mfma_f32_16x16x32_bf16 v[16:19], v[166:169], v[204:207], v[16:19]
	v_mfma_f32_16x16x32_bf16 v[12:15], v[174:177], v[196:199], v[12:15]
	v_mfma_f32_16x16x32_bf16 v[8:11], v[174:177], v[204:207], v[8:11]
	v_mfma_f32_16x16x32_bf16 v[4:7], v[188:191], v[196:199], v[4:7]
	v_mfma_f32_16x16x32_bf16 v[0:3], v[188:191], v[204:207], v[0:3]
	s_setprio 0
	s_add_i32 s37, s37, 2
	s_add_u32 s38, s38, 0x100
	s_addc_u32 s39, s39, 0
	s_add_u32 s34, s34, 0x100
	s_addc_u32 s35, s35, 0
	s_cmp_ge_i32 s37, s2
	s_barrier
	s_cbranch_scc0 .LBB0_729

; #define STAGE(P, BASE, br, kt) do { const char* _g = (const char*)((BASE) + (size_t)(br) * K + (size_t)(kt) * G_BK); \
;     _Pragma("unroll") for (int _i = 0; _i < 2; ++_i) { \
;       __builtin_amdgcn_global_load_lds((const unsigned*)(_g + (size_t)_i * 128 * K + sg_off), (unsigned*)((char*)(P) + wid * 1024 + _i * 8192), 16, 0, 0); } } while (0)
; #define LDA(dst, b, h) _Pragma("unroll") for (int m = 0; m < 4; ++m) _Pragma("unroll") for (int k = 0; k < 2; ++k) \
;     dst[m][k] = *reinterpret_cast<const bf16x8*>((const char*)shm + aoff + (((b) * 2 + (h)) * 16384 + m * 2048 + k * 1024))
; #define LDB(dst, b, h) _Pragma("unroll") for (int n = 0; n < 2; ++n) _Pragma("unroll") for (int k = 0; k < 2; ++k) \
;     dst[n][k] = *reinterpret_cast<const bf16x8*>((const char*)shm + boff + (((b) * 2 + (h)) * 16384 + n * 2048 + k * 1024))
; #define MMA(ai, bj, At, Bt_) do { __builtin_amdgcn_s_setprio(1); \
;     _Pragma("unroll") for (int m = 0; m < 4; ++m) _Pragma("unroll") for (int n = 0; n < 2; ++n) _Pragma("unroll") for (int k = 0; k < 2; ++k) \
;       acc[ai][bj][m][n] = mfma16(At[m][k], Bt_[n][k], acc[ai][bj][m][n]); \
;     __builtin_amdgcn_s_setprio(0); } while (0)
; #define WAIT_V(n) asm volatile("s_waitcnt vmcnt(" #n ")" ::: "memory")
; #define WAIT_L(n) asm volatile("s_waitcnt lgkmcnt(" #n ")" ::: "memory")
; #define BAR __builtin_amdgcn_s_barrier()
; #define SCHED __builtin_amdgcn_sched_barrier(0)
; template <class Epi>
; __device__ __forceinline__ void gemm_phase(const bfr* __restrict__ A, int lda, const bfr* __restrict__ Bt, int K,
;                                            int nM, int nN, const Epi& epi, bfr* shm, int wv, int nMfull, int ksplit) {
;     ...
;     f32x4 acc[2][2][4][2];
; #pragma unroll
;     for (int a = 0; a < 2; a++)
; #pragma unroll
;       for (int b = 0; b < 2; b++)
; #pragma unroll
;         for (int m = 0; m < 4; m++)
; #pragma unroll
;           for (int n = 0; n < 2; n++) acc[a][b][m][n] = f32x4{0.f, 0.f, 0.f, 0.f};
;     bf16x8 At[4][2], B0[2][2], B1[2][2];
;     if (wr == 1) BAR;
;     WAIT_V(10); BAR;
;     WAIT_V(6); BAR;
;     for (int t = 0; t < nt - 2; t += 2) {
;       LDB(B0, 0, 0); SCHED; LDA(At, 0, 0); STAGE(SA(1, 1), Ak, brow + G_HALF, t + 1);
;       WAIT_L(8); BAR; WAIT_L(0); MMA(0, 0, At, B0); BAR; SCHED;
;       LDB(B1, 0, 1); STAGE(SB(0, 0), Bk, bcol, t + 2);
.LBB0_877:
	s_waitcnt vmcnt(8)
	s_barrier
	s_waitcnt vmcnt(6)
	v_mov_b32_e32 v127, 0
	s_cmp_lt_u32 s20, 3
	v_mov_b32_e32 v126, v127
	v_mov_b32_e32 v125, v127
	v_mov_b32_e32 v124, v127
	v_mov_b32_e32 v123, v127
	v_mov_b32_e32 v122, v127
	v_mov_b32_e32 v121, v127
	v_mov_b32_e32 v120, v127
	v_mov_b32_e32 v119, v127
	v_mov_b32_e32 v118, v127
	v_mov_b32_e32 v117, v127
	v_mov_b32_e32 v116, v127
	v_mov_b32_e32 v115, v127
	v_mov_b32_e32 v114, v127
	v_mov_b32_e32 v113, v127
	v_mov_b32_e32 v112, v127
	v_mov_b32_e32 v111, v127
	v_mov_b32_e32 v110, v127
	v_mov_b32_e32 v109, v127
	v_mov_b32_e32 v108, v127
	v_mov_b32_e32 v107, v127
	v_mov_b32_e32 v106, v127
	v_mov_b32_e32 v105, v127
	v_mov_b32_e32 v104, v127
	v_mov_b32_e32 v103, v127
	v_mov_b32_e32 v102, v127
	v_mov_b32_e32 v101, v127
	v_mov_b32_e32 v100, v127
	v_mov_b32_e32 v99, v127
	v_mov_b32_e32 v98, v127
	v_mov_b32_e32 v97, v127
	v_mov_b32_e32 v96, v127
	v_mov_b32_e32 v95, v127
	v_mov_b32_e32 v94, v127
	v_mov_b32_e32 v93, v127
	v_mov_b32_e32 v92, v127
	v_mov_b32_e32 v91, v127
	v_mov_b32_e32 v90, v127
	v_mov_b32_e32 v89, v127
	v_mov_b32_e32 v88, v127
	v_mov_b32_e32 v87, v127
	v_mov_b32_e32 v86, v127
	v_mov_b32_e32 v85, v127
	v_mov_b32_e32 v84, v127
	v_mov_b32_e32 v83, v127
	v_mov_b32_e32 v82, v127
	v_mov_b32_e32 v81, v127
	v_mov_b32_e32 v80, v127
	v_mov_b32_e32 v79, v127
	v_mov_b32_e32 v78, v127
	v_mov_b32_e32 v77, v127
	v_mov_b32_e32 v76, v127
	v_mov_b32_e32 v75, v127
	v_mov_b32_e32 v74, v127
	v_mov_b32_e32 v73, v127
	v_mov_b32_e32 v72, v127
	v_mov_b32_e32 v71, v127
	v_mov_b32_e32 v70, v127
	v_mov_b32_e32 v69, v127
	v_mov_b32_e32 v68, v127
	v_mov_b32_e32 v67, v127
	v_mov_b32_e32 v66, v127
	v_mov_b32_e32 v65, v127
	v_mov_b32_e32 v64, v127
	v_mov_b32_e32 v63, v127
	v_mov_b32_e32 v62, v127
	v_mov_b32_e32 v61, v127
	v_mov_b32_e32 v60, v127
	v_mov_b32_e32 v59, v127
	v_mov_b32_e32 v58, v127
	v_mov_b32_e32 v57, v127
	v_mov_b32_e32 v56, v127
	v_mov_b32_e32 v55, v127
	v_mov_b32_e32 v54, v127
	v_mov_b32_e32 v53, v127
	v_mov_b32_e32 v52, v127
	v_mov_b32_e32 v51, v127
	v_mov_b32_e32 v50, v127
	v_mov_b32_e32 v49, v127
	v_mov_b32_e32 v48, v127
	v_mov_b32_e32 v47, v127
	v_mov_b32_e32 v46, v127
	v_mov_b32_e32 v45, v127
	v_mov_b32_e32 v44, v127
	v_mov_b32_e32 v43, v127
	v_mov_b32_e32 v42, v127
	v_mov_b32_e32 v41, v127
	v_mov_b32_e32 v40, v127
	v_mov_b32_e32 v39, v127
	v_mov_b32_e32 v38, v127
	v_mov_b32_e32 v37, v127
	v_mov_b32_e32 v36, v127
	v_mov_b32_e32 v35, v127
	v_mov_b32_e32 v34, v127
	v_mov_b32_e32 v33, v127
	v_mov_b32_e32 v32, v127
	v_mov_b32_e32 v31, v127
	v_mov_b32_e32 v30, v127
	v_mov_b32_e32 v29, v127
	v_mov_b32_e32 v28, v127
	v_mov_b32_e32 v27, v127
	v_mov_b32_e32 v26, v127
	v_mov_b32_e32 v25, v127
	v_mov_b32_e32 v24, v127
	v_mov_b32_e32 v23, v127
	v_mov_b32_e32 v22, v127
	v_mov_b32_e32 v21, v127
	v_mov_b32_e32 v20, v127
	v_mov_b32_e32 v19, v127
	v_mov_b32_e32 v18, v127
	v_mov_b32_e32 v17, v127
	v_mov_b32_e32 v16, v127
	v_mov_b32_e32 v15, v127
	v_mov_b32_e32 v14, v127
	v_mov_b32_e32 v13, v127
	v_mov_b32_e32 v12, v127
	v_mov_b32_e32 v11, v127
	v_mov_b32_e32 v10, v127
	v_mov_b32_e32 v9, v127
	v_mov_b32_e32 v8, v127
	v_mov_b32_e32 v7, v127
	v_mov_b32_e32 v6, v127
	v_mov_b32_e32 v5, v127
	v_mov_b32_e32 v4, v127
	v_mov_b32_e32 v3, v127
	v_mov_b32_e32 v2, v127
	v_mov_b32_e32 v1, v127
	v_mov_b32_e32 v0, v127
	s_barrier
	s_cbranch_scc1 .LBB0_880
	s_ashr_i32 s29, s28, 31
	s_ashr_i32 s31, s30, 31
	v_readlane_b32 s56, v254, 54
	s_add_i32 s21, s20, -2
	s_lshl_b64 s[4:5], s[28:29], 11
	s_lshl_b64 s[22:23], s[30:31], 11
	v_readlane_b32 s58, v254, 56
	v_readlane_b32 s59, v254, 57
	s_add_u32 s4, s58, s4
	s_addc_u32 s5, s59, s5
	s_add_u32 s22, s80, s22
	v_mov_b32_e32 v0, 0
	s_addc_u32 s23, s81, s23
	s_mov_b32 s24, 0
	v_readlane_b32 s57, v254, 55
	v_readlane_b32 s60, v254, 58
	v_readlane_b32 s61, v254, 59
	v_readlane_b32 s62, v254, 60
	v_readlane_b32 s63, v254, 61
	v_readlane_b32 s64, v254, 62
	v_readlane_b32 s65, v254, 63
	v_readlane_b32 s66, v255, 0
	v_readlane_b32 s67, v255, 1
	v_readlane_b32 s68, v255, 2
	v_readlane_b32 s69, v255, 3
	v_readlane_b32 s70, v255, 4
	v_readlane_b32 s71, v255, 5
.LBB0_879:
	ds_read_b128 v[138:141], v169
	ds_read_b128 v[142:145], v169 offset:1024
	ds_read_b128 v[146:149], v169 offset:2048
	ds_read_b128 v[150:153], v169 offset:3072
	ds_read_b128 v[154:157], v129
	ds_read_b128 v[158:161], v129 offset:1024
	ds_read_b128 v[162:165], v129 offset:2048
	ds_read_b128 v[172:175], v129 offset:3072
	ds_read_b128 v[180:183], v129 offset:4096
	ds_read_b128 v[184:187], v129 offset:5120
	ds_read_b128 v[188:191], v129 offset:6144
	ds_read_b128 v[192:195], v129 offset:7168
	ds_read_b128 v[196:199], v169 offset:16384
	ds_read_b128 v[200:203], v169 offset:17408
	ds_read_b128 v[204:207], v169 offset:18432
	ds_read_b128 v[208:211], v169 offset:19456
	v_lshl_add_u64 v[166:167], s[22:23], 0, v[136:137]
	v_lshl_add_u64 v[176:177], s[4:5], 0, v[136:137]
	s_mov_b32 m0, s50
	s_mov_b64 s[26:27], 0x40080
	v_lshl_add_u64 v[214:215], v[166:167], 0, s[26:27]
	global_load_lds_dwordx4 v[214:215], off
	s_mov_b32 m0, s51
	s_mov_b64 s[26:27], 0x60080
	v_lshl_add_u64 v[216:217], v[166:167], 0, s[26:27]
	global_load_lds_dwordx4 v[216:217], off
	s_waitcnt lgkmcnt(0)
	s_barrier
; #define STAGE(P, BASE, br, kt) do { const char* _g = (const char*)((BASE) + (size_t)(br) * K + (size_t)(kt) * G_BK); \
;     _Pragma("unroll") for (int _i = 0; _i < 2; ++_i) { \
;       __builtin_amdgcn_global_load_lds((const unsigned*)(_g + (size_t)_i * 128 * K + sg_off), (unsigned*)((char*)(P) + wid * 1024 + _i * 8192), 16, 0, 0); } } while (0)
; #define LDA(dst, b, h) _Pragma("unroll") for (int m = 0; m < 4; ++m) _Pragma("unroll") for (int k = 0; k < 2; ++k) \
;     dst[m][k] = *reinterpret_cast<const bf16x8*>((const char*)shm + aoff + (((b) * 2 + (h)) * 16384 + m * 2048 + k * 1024))
; #define LDB(dst, b, h) _Pragma("unroll") for (int n = 0; n < 2; ++n) _Pragma("unroll") for (int k = 0; k < 2; ++k) \
;     dst[n][k] = *reinterpret_cast<const bf16x8*>((const char*)shm + boff + (((b) * 2 + (h)) * 16384 + n * 2048 + k * 1024))
; #define MMA(ai, bj, At, Bt_) do { __builtin_amdgcn_s_setprio(1); \
;     _Pragma("unroll") for (int m = 0; m < 4; ++m) _Pragma("unroll") for (int n = 0; n < 2; ++n) _Pragma("unroll") for (int k = 0; k < 2; ++k) \
;       acc[ai][bj][m][n] = mfma16(At[m][k], Bt_[n][k], acc[ai][bj][m][n]); \
;     __builtin_amdgcn_s_setprio(0); } while (0)
; #define WAIT_V(n) asm volatile("s_waitcnt vmcnt(" #n ")" ::: "memory")
; #define WAIT_L(n) asm volatile("s_waitcnt lgkmcnt(" #n ")" ::: "memory")
; #define BAR __builtin_amdgcn_s_barrier()
; #define SCHED __builtin_amdgcn_sched_barrier(0)
; template <class Epi>
; __device__ __forceinline__ void gemm_phase(const bfr* __restrict__ A, int lda, const bfr* __restrict__ Bt, int K,
;                                            int nM, int nN, const Epi& epi, bfr* shm, int wv, int nMfull, int ksplit) {
;     ...
;       LDB(B0, 0, 0); SCHED; LDA(At, 0, 0); STAGE(SA(1, 1), Ak, brow + G_HALF, t + 1);
;       WAIT_L(8); BAR; WAIT_L(0); MMA(0, 0, At, B0); BAR; SCHED;
;       LDB(B1, 0, 1); STAGE(SB(0, 0), Bk, bcol, t + 2);
;       BAR; WAIT_L(0); MMA(0, 1, At, B1); BAR;
;       LDA(At, 0, 1); STAGE(SA(0, 0), Ak, brow, t + 2);
;       BAR; WAIT_L(0); MMA(1, 0, At, B0); BAR; SCHED;
;       STAGE(SB(0, 1), Bk, bcol + G_HALF, t + 2);
;       WAIT_V(6); BAR; MMA(1, 1, At, B1); BAR;
	s_setprio 1
	v_mfma_f32_16x16x32_bf16 v[124:127], v[154:157], v[138:141], v[124:127]
	v_mfma_f32_16x16x32_bf16 v[120:123], v[154:157], v[146:149], v[120:123]
	v_mfma_f32_16x16x32_bf16 v[116:119], v[162:165], v[138:141], v[116:119]
	v_mfma_f32_16x16x32_bf16 v[112:115], v[162:165], v[146:149], v[112:115]
	v_mfma_f32_16x16x32_bf16 v[108:111], v[180:183], v[138:141], v[108:111]
	v_mfma_f32_16x16x32_bf16 v[104:107], v[180:183], v[146:149], v[104:107]
	v_mfma_f32_16x16x32_bf16 v[100:103], v[188:191], v[138:141], v[100:103]
	v_mfma_f32_16x16x32_bf16 v[96:99], v[188:191], v[146:149], v[96:99]
	v_mfma_f32_16x16x32_bf16 v[124:127], v[158:161], v[142:145], v[124:127]
	v_mfma_f32_16x16x32_bf16 v[120:123], v[158:161], v[150:153], v[120:123]
	v_mfma_f32_16x16x32_bf16 v[116:119], v[172:175], v[142:145], v[116:119]
	v_mfma_f32_16x16x32_bf16 v[112:115], v[172:175], v[150:153], v[112:115]
	v_mfma_f32_16x16x32_bf16 v[108:111], v[184:187], v[142:145], v[108:111]
	v_mfma_f32_16x16x32_bf16 v[104:107], v[184:187], v[150:153], v[104:107]
	v_mfma_f32_16x16x32_bf16 v[100:103], v[192:195], v[142:145], v[100:103]
	v_mfma_f32_16x16x32_bf16 v[96:99], v[192:195], v[150:153], v[96:99]
	v_mfma_f32_16x16x32_bf16 v[92:95], v[154:157], v[196:199], v[92:95]
	v_mfma_f32_16x16x32_bf16 v[88:91], v[154:157], v[204:207], v[88:91]
	v_mfma_f32_16x16x32_bf16 v[84:87], v[162:165], v[196:199], v[84:87]
	v_mfma_f32_16x16x32_bf16 v[80:83], v[162:165], v[204:207], v[80:83]
	v_mfma_f32_16x16x32_bf16 v[76:79], v[180:183], v[196:199], v[76:79]
	v_mfma_f32_16x16x32_bf16 v[72:75], v[180:183], v[204:207], v[72:75]
	v_mfma_f32_16x16x32_bf16 v[68:71], v[188:191], v[196:199], v[68:71]
	v_mfma_f32_16x16x32_bf16 v[64:67], v[188:191], v[204:207], v[64:67]
	v_mfma_f32_16x16x32_bf16 v[92:95], v[158:161], v[200:203], v[92:95]
	v_mfma_f32_16x16x32_bf16 v[88:91], v[158:161], v[208:211], v[88:91]
	v_mfma_f32_16x16x32_bf16 v[84:87], v[172:175], v[200:203], v[84:87]
	v_mfma_f32_16x16x32_bf16 v[80:83], v[172:175], v[208:211], v[80:83]
	v_mfma_f32_16x16x32_bf16 v[76:79], v[184:187], v[200:203], v[76:79]
	v_mfma_f32_16x16x32_bf16 v[72:75], v[184:187], v[208:211], v[72:75]
	v_mfma_f32_16x16x32_bf16 v[68:71], v[192:195], v[200:203], v[68:71]
	v_mfma_f32_16x16x32_bf16 v[64:67], v[192:195], v[208:211], v[64:67]
	s_setprio 0
	s_barrier
	ds_read_b128 v[154:157], v129 offset:16384
	ds_read_b128 v[158:161], v129 offset:17408
	ds_read_b128 v[162:165], v129 offset:18432
	ds_read_b128 v[172:175], v129 offset:19456
	ds_read_b128 v[180:183], v129 offset:20480
	ds_read_b128 v[184:187], v129 offset:21504
	ds_read_b128 v[188:191], v129 offset:22528
	ds_read_b128 v[192:195], v129 offset:23552
	s_mov_b32 m0, s37
	s_mov_b64 s[26:27], 0x1600100
	v_lshl_add_u64 v[218:219], v[176:177], 0, s[26:27]
	global_load_lds_dwordx4 v[218:219], off
	s_mov_b32 m0, s38
	s_mov_b64 s[26:27], 0x1620100
	v_lshl_add_u64 v[214:215], v[176:177], 0, s[26:27]
	global_load_lds_dwordx4 v[214:215], off
	s_mov_b32 m0, s36
	s_mov_b64 s[26:27], 0x100
	v_lshl_add_u64 v[216:217], v[166:167], 0, s[26:27]
	global_load_lds_dwordx4 v[216:217], off
	s_mov_b32 m0, s39
	s_mov_b64 s[26:27], 0x20100
	v_lshl_add_u64 v[218:219], v[166:167], 0, s[26:27]
	global_load_lds_dwordx4 v[218:219], off
	s_waitcnt vmcnt(6)
	s_waitcnt lgkmcnt(0)
	s_barrier
	s_setprio 1
	v_mfma_f32_16x16x32_bf16 v[60:63], v[154:157], v[138:141], v[60:63]
	v_mfma_f32_16x16x32_bf16 v[56:59], v[154:157], v[146:149], v[56:59]
	v_mfma_f32_16x16x32_bf16 v[52:55], v[162:165], v[138:141], v[52:55]
	v_mfma_f32_16x16x32_bf16 v[48:51], v[162:165], v[146:149], v[48:51]
	v_mfma_f32_16x16x32_bf16 v[44:47], v[180:183], v[138:141], v[44:47]
	v_mfma_f32_16x16x32_bf16 v[40:43], v[180:183], v[146:149], v[40:43]
	v_mfma_f32_16x16x32_bf16 v[36:39], v[188:191], v[138:141], v[36:39]
	v_mfma_f32_16x16x32_bf16 v[32:35], v[188:191], v[146:149], v[32:35]
	v_mfma_f32_16x16x32_bf16 v[60:63], v[158:161], v[142:145], v[60:63]
	v_mfma_f32_16x16x32_bf16 v[56:59], v[158:161], v[150:153], v[56:59]
	v_mfma_f32_16x16x32_bf16 v[52:55], v[172:175], v[142:145], v[52:55]
	v_mfma_f32_16x16x32_bf16 v[48:51], v[172:175], v[150:153], v[48:51]
	v_mfma_f32_16x16x32_bf16 v[44:47], v[184:187], v[142:145], v[44:47]
	v_mfma_f32_16x16x32_bf16 v[40:43], v[184:187], v[150:153], v[40:43]
	v_mfma_f32_16x16x32_bf16 v[36:39], v[192:195], v[142:145], v[36:39]
	v_mfma_f32_16x16x32_bf16 v[32:35], v[192:195], v[150:153], v[32:35]
	v_mfma_f32_16x16x32_bf16 v[28:31], v[154:157], v[196:199], v[28:31]
	v_mfma_f32_16x16x32_bf16 v[24:27], v[154:157], v[204:207], v[24:27]
	v_mfma_f32_16x16x32_bf16 v[20:23], v[162:165], v[196:199], v[20:23]
	v_mfma_f32_16x16x32_bf16 v[16:19], v[162:165], v[204:207], v[16:19]
	v_mfma_f32_16x16x32_bf16 v[12:15], v[180:183], v[196:199], v[12:15]
	v_mfma_f32_16x16x32_bf16 v[8:11], v[180:183], v[204:207], v[8:11]
	v_mfma_f32_16x16x32_bf16 v[4:7], v[188:191], v[196:199], v[4:7]
	v_mfma_f32_16x16x32_bf16 v[0:3], v[188:191], v[204:207], v[0:3]
	v_mfma_f32_16x16x32_bf16 v[28:31], v[158:161], v[200:203], v[28:31]
	v_mfma_f32_16x16x32_bf16 v[24:27], v[158:161], v[208:211], v[24:27]
	v_mfma_f32_16x16x32_bf16 v[20:23], v[172:175], v[200:203], v[20:23]
	v_mfma_f32_16x16x32_bf16 v[16:19], v[172:175], v[208:211], v[16:19]
	v_mfma_f32_16x16x32_bf16 v[12:15], v[184:187], v[200:203], v[12:15]
	v_mfma_f32_16x16x32_bf16 v[8:11], v[184:187], v[208:211], v[8:11]
	v_mfma_f32_16x16x32_bf16 v[4:7], v[192:195], v[200:203], v[4:7]
	v_mfma_f32_16x16x32_bf16 v[0:3], v[192:195], v[208:211], v[0:3]
	s_setprio 0
	s_barrier
; #define STAGE(P, BASE, br, kt) do { const char* _g = (const char*)((BASE) + (size_t)(br) * K + (size_t)(kt) * G_BK); \
;     _Pragma("unroll") for (int _i = 0; _i < 2; ++_i) { \
;       __builtin_amdgcn_global_load_lds((const unsigned*)(_g + (size_t)_i * 128 * K + sg_off), (unsigned*)((char*)(P) + wid * 1024 + _i * 8192), 16, 0, 0); } } while (0)
; #define LDA(dst, b, h) _Pragma("unroll") for (int m = 0; m < 4; ++m) _Pragma("unroll") for (int k = 0; k < 2; ++k) \
;     dst[m][k] = *reinterpret_cast<const bf16x8*>((const char*)shm + aoff + (((b) * 2 + (h)) * 16384 + m * 2048 + k * 1024))
; #define LDB(dst, b, h) _Pragma("unroll") for (int n = 0; n < 2; ++n) _Pragma("unroll") for (int k = 0; k < 2; ++k) \
;     dst[n][k] = *reinterpret_cast<const bf16x8*>((const char*)shm + boff + (((b) * 2 + (h)) * 16384 + n * 2048 + k * 1024))
; #define MMA(ai, bj, At, Bt_) do { __builtin_amdgcn_s_setprio(1); \
;     _Pragma("unroll") for (int m = 0; m < 4; ++m) _Pragma("unroll") for (int n = 0; n < 2; ++n) _Pragma("unroll") for (int k = 0; k < 2; ++k) \
;       acc[ai][bj][m][n] = mfma16(At[m][k], Bt_[n][k], acc[ai][bj][m][n]); \
;     __builtin_amdgcn_s_setprio(0); } while (0)
; #define WAIT_L(n) asm volatile("s_waitcnt lgkmcnt(" #n ")" ::: "memory")
; #define BAR __builtin_amdgcn_s_barrier()
; #define SCHED __builtin_amdgcn_sched_barrier(0)
; template <class Epi>
; __device__ __forceinline__ void gemm_phase(const bfr* __restrict__ A, int lda, const bfr* __restrict__ Bt, int K,
;                                            int nM, int nN, const Epi& epi, bfr* shm, int wv, int nMfull, int ksplit) {
;     ...
;       LDB(B0, 1, 0); SCHED; LDA(At, 1, 0); STAGE(SA(0, 1), Ak, brow + G_HALF, t + 2);
;       WAIT_L(8); BAR; WAIT_L(0); MMA(0, 0, At, B0); BAR; SCHED;
;       LDB(B1, 1, 1); STAGE(SB(1, 0), Bk, bcol, t + 3);
;       BAR; WAIT_L(0); MMA(0, 1, At, B1); BAR;
	ds_read_b128 v[138:141], v169 offset:32768
	ds_read_b128 v[142:145], v169 offset:33792
	ds_read_b128 v[146:149], v169 offset:34816
	ds_read_b128 v[150:153], v169 offset:35840
	ds_read_b128 v[154:157], v129 offset:32768
	ds_read_b128 v[158:161], v129 offset:33792
	ds_read_b128 v[162:165], v129 offset:34816
	ds_read_b128 v[172:175], v129 offset:35840
	ds_read_b128 v[180:183], v129 offset:36864
	ds_read_b128 v[184:187], v129 offset:37888
	ds_read_b128 v[188:191], v129 offset:38912
	ds_read_b128 v[192:195], v129 offset:39936
	ds_read_b128 v[196:199], v169 offset:49152
	ds_read_b128 v[200:203], v169 offset:50176
	ds_read_b128 v[204:207], v169 offset:51200
	ds_read_b128 v[208:211], v169 offset:52224
	s_mov_b32 m0, s40
	s_mov_b64 s[26:27], 0x1640100
	v_lshl_add_u64 v[214:215], v[176:177], 0, s[26:27]
	global_load_lds_dwordx4 v[214:215], off
	s_mov_b32 m0, s41
	s_mov_b64 s[26:27], 0x1660100
	v_lshl_add_u64 v[216:217], v[176:177], 0, s[26:27]
	global_load_lds_dwordx4 v[216:217], off
	s_mov_b32 m0, s42
	s_mov_b64 s[26:27], 0x40100
	v_lshl_add_u64 v[218:219], v[166:167], 0, s[26:27]
	global_load_lds_dwordx4 v[218:219], off
	s_mov_b32 m0, s43
	s_mov_b64 s[26:27], 0x60100
	v_lshl_add_u64 v[214:215], v[166:167], 0, s[26:27]
	global_load_lds_dwordx4 v[214:215], off
	s_waitcnt vmcnt(8)
	s_waitcnt lgkmcnt(0)
	s_barrier
	s_setprio 1
	v_mfma_f32_16x16x32_bf16 v[124:127], v[154:157], v[138:141], v[124:127]
	v_mfma_f32_16x16x32_bf16 v[120:123], v[154:157], v[146:149], v[120:123]
	v_mfma_f32_16x16x32_bf16 v[116:119], v[162:165], v[138:141], v[116:119]
	v_mfma_f32_16x16x32_bf16 v[112:115], v[162:165], v[146:149], v[112:115]
	v_mfma_f32_16x16x32_bf16 v[108:111], v[180:183], v[138:141], v[108:111]
	v_mfma_f32_16x16x32_bf16 v[104:107], v[180:183], v[146:149], v[104:107]
	v_mfma_f32_16x16x32_bf16 v[100:103], v[188:191], v[138:141], v[100:103]
	v_mfma_f32_16x16x32_bf16 v[96:99], v[188:191], v[146:149], v[96:99]
	v_mfma_f32_16x16x32_bf16 v[124:127], v[158:161], v[142:145], v[124:127]
	v_mfma_f32_16x16x32_bf16 v[120:123], v[158:161], v[150:153], v[120:123]
	v_mfma_f32_16x16x32_bf16 v[116:119], v[172:175], v[142:145], v[116:119]
	v_mfma_f32_16x16x32_bf16 v[112:115], v[172:175], v[150:153], v[112:115]
	v_mfma_f32_16x16x32_bf16 v[108:111], v[184:187], v[142:145], v[108:111]
	v_mfma_f32_16x16x32_bf16 v[104:107], v[184:187], v[150:153], v[104:107]
	v_mfma_f32_16x16x32_bf16 v[100:103], v[192:195], v[142:145], v[100:103]
	v_mfma_f32_16x16x32_bf16 v[96:99], v[192:195], v[150:153], v[96:99]
	v_mfma_f32_16x16x32_bf16 v[92:95], v[154:157], v[196:199], v[92:95]
	v_mfma_f32_16x16x32_bf16 v[88:91], v[154:157], v[204:207], v[88:91]
	v_mfma_f32_16x16x32_bf16 v[84:87], v[162:165], v[196:199], v[84:87]
	v_mfma_f32_16x16x32_bf16 v[80:83], v[162:165], v[204:207], v[80:83]
	v_mfma_f32_16x16x32_bf16 v[76:79], v[180:183], v[196:199], v[76:79]
	v_mfma_f32_16x16x32_bf16 v[72:75], v[180:183], v[204:207], v[72:75]
	v_mfma_f32_16x16x32_bf16 v[68:71], v[188:191], v[196:199], v[68:71]
	v_mfma_f32_16x16x32_bf16 v[64:67], v[188:191], v[204:207], v[64:67]
	v_mfma_f32_16x16x32_bf16 v[92:95], v[158:161], v[200:203], v[92:95]
	v_mfma_f32_16x16x32_bf16 v[88:91], v[158:161], v[208:211], v[88:91]
	v_mfma_f32_16x16x32_bf16 v[84:87], v[172:175], v[200:203], v[84:87]
	v_mfma_f32_16x16x32_bf16 v[80:83], v[172:175], v[208:211], v[80:83]
	v_mfma_f32_16x16x32_bf16 v[76:79], v[184:187], v[200:203], v[76:79]
	v_mfma_f32_16x16x32_bf16 v[72:75], v[184:187], v[208:211], v[72:75]
	v_mfma_f32_16x16x32_bf16 v[68:71], v[192:195], v[200:203], v[68:71]
	v_mfma_f32_16x16x32_bf16 v[64:67], v[192:195], v[208:211], v[64:67]
	s_setprio 0
	s_barrier
; #define STAGE(P, BASE, br, kt) do { const char* _g = (const char*)((BASE) + (size_t)(br) * K + (size_t)(kt) * G_BK); \
;     _Pragma("unroll") for (int _i = 0; _i < 2; ++_i) { \
;       __builtin_amdgcn_global_load_lds((const unsigned*)(_g + (size_t)_i * 128 * K + sg_off), (unsigned*)((char*)(P) + wid * 1024 + _i * 8192), 16, 0, 0); } } while (0)
; #define LDA(dst, b, h) _Pragma("unroll") for (int m = 0; m < 4; ++m) _Pragma("unroll") for (int k = 0; k < 2; ++k) \
;     dst[m][k] = *reinterpret_cast<const bf16x8*>((const char*)shm + aoff + (((b) * 2 + (h)) * 16384 + m * 2048 + k * 1024))
; #define MMA(ai, bj, At, Bt_) do { __builtin_amdgcn_s_setprio(1); \
;     _Pragma("unroll") for (int m = 0; m < 4; ++m) _Pragma("unroll") for (int n = 0; n < 2; ++n) _Pragma("unroll") for (int k = 0; k < 2; ++k) \
;       acc[ai][bj][m][n] = mfma16(At[m][k], Bt_[n][k], acc[ai][bj][m][n]); \
;     __builtin_amdgcn_s_setprio(0); } while (0)
; #define WAIT_V(n) asm volatile("s_waitcnt vmcnt(" #n ")" ::: "memory")
; #define WAIT_L(n) asm volatile("s_waitcnt lgkmcnt(" #n ")" ::: "memory")
; #define BAR __builtin_amdgcn_s_barrier()
; #define SCHED __builtin_amdgcn_sched_barrier(0)
; template <class Epi>
; __device__ __forceinline__ void gemm_phase(const bfr* __restrict__ A, int lda, const bfr* __restrict__ Bt, int K,
;                                            int nM, int nN, const Epi& epi, bfr* shm, int wv, int nMfull, int ksplit) {
;     ...
;       LDA(At, 1, 1); STAGE(SA(1, 0), Ak, brow, t + 3);
;       BAR; WAIT_L(0); MMA(1, 0, At, B0); BAR; SCHED;
;       STAGE(SB(1, 1), Bk, bcol + G_HALF, t + 3);
;       WAIT_V(6); BAR; MMA(1, 1, At, B1); BAR;
;     }
	ds_read_b128 v[154:157], v129 offset:49152
	ds_read_b128 v[158:161], v129 offset:50176
	ds_read_b128 v[162:165], v129 offset:51200
	ds_read_b128 v[172:175], v129 offset:52224
	ds_read_b128 v[180:183], v129 offset:53248
	ds_read_b128 v[184:187], v129 offset:54272
	ds_read_b128 v[188:191], v129 offset:55296
	ds_read_b128 v[192:195], v129 offset:56320
	s_mov_b32 m0, s44
	s_mov_b64 s[26:27], 0x1600180
	v_lshl_add_u64 v[216:217], v[176:177], 0, s[26:27]
	global_load_lds_dwordx4 v[216:217], off
	s_mov_b32 m0, s45
	s_mov_b64 s[26:27], 0x1620180
	v_lshl_add_u64 v[218:219], v[176:177], 0, s[26:27]
	global_load_lds_dwordx4 v[218:219], off
	s_mov_b32 m0, s46
	s_mov_b64 s[26:27], 0x180
	v_lshl_add_u64 v[214:215], v[166:167], 0, s[26:27]
	global_load_lds_dwordx4 v[214:215], off
	s_mov_b32 m0, s47
	s_mov_b64 s[26:27], 0x20180
	v_lshl_add_u64 v[216:217], v[166:167], 0, s[26:27]
	global_load_lds_dwordx4 v[216:217], off
	s_mov_b32 m0, s48
	s_mov_b64 s[26:27], 0x1640180
	v_lshl_add_u64 v[218:219], v[176:177], 0, s[26:27]
	global_load_lds_dwordx4 v[218:219], off
	s_mov_b32 m0, s49
	s_mov_b64 s[26:27], 0x1660180
	v_lshl_add_u64 v[214:215], v[176:177], 0, s[26:27]
	global_load_lds_dwordx4 v[214:215], off
	s_waitcnt vmcnt(6)
	s_waitcnt lgkmcnt(0)
	s_barrier
	s_setprio 1
	v_mfma_f32_16x16x32_bf16 v[60:63], v[154:157], v[138:141], v[60:63]
	v_mfma_f32_16x16x32_bf16 v[56:59], v[154:157], v[146:149], v[56:59]
	v_mfma_f32_16x16x32_bf16 v[52:55], v[162:165], v[138:141], v[52:55]
	v_mfma_f32_16x16x32_bf16 v[48:51], v[162:165], v[146:149], v[48:51]
	v_mfma_f32_16x16x32_bf16 v[44:47], v[180:183], v[138:141], v[44:47]
	v_mfma_f32_16x16x32_bf16 v[40:43], v[180:183], v[146:149], v[40:43]
	v_mfma_f32_16x16x32_bf16 v[36:39], v[188:191], v[138:141], v[36:39]
	v_mfma_f32_16x16x32_bf16 v[32:35], v[188:191], v[146:149], v[32:35]
	v_mfma_f32_16x16x32_bf16 v[60:63], v[158:161], v[142:145], v[60:63]
	v_mfma_f32_16x16x32_bf16 v[56:59], v[158:161], v[150:153], v[56:59]
	v_mfma_f32_16x16x32_bf16 v[52:55], v[172:175], v[142:145], v[52:55]
	v_mfma_f32_16x16x32_bf16 v[48:51], v[172:175], v[150:153], v[48:51]
	v_mfma_f32_16x16x32_bf16 v[44:47], v[184:187], v[142:145], v[44:47]
	v_mfma_f32_16x16x32_bf16 v[40:43], v[184:187], v[150:153], v[40:43]
	v_mfma_f32_16x16x32_bf16 v[36:39], v[192:195], v[142:145], v[36:39]
	v_mfma_f32_16x16x32_bf16 v[32:35], v[192:195], v[150:153], v[32:35]
	v_mfma_f32_16x16x32_bf16 v[28:31], v[154:157], v[196:199], v[28:31]
	v_mfma_f32_16x16x32_bf16 v[24:27], v[154:157], v[204:207], v[24:27]
	v_mfma_f32_16x16x32_bf16 v[20:23], v[162:165], v[196:199], v[20:23]
	v_mfma_f32_16x16x32_bf16 v[16:19], v[162:165], v[204:207], v[16:19]
	v_mfma_f32_16x16x32_bf16 v[12:15], v[180:183], v[196:199], v[12:15]
	v_mfma_f32_16x16x32_bf16 v[8:11], v[180:183], v[204:207], v[8:11]
	v_mfma_f32_16x16x32_bf16 v[4:7], v[188:191], v[196:199], v[4:7]
	v_mfma_f32_16x16x32_bf16 v[0:3], v[188:191], v[204:207], v[0:3]
	v_mfma_f32_16x16x32_bf16 v[28:31], v[158:161], v[200:203], v[28:31]
	v_mfma_f32_16x16x32_bf16 v[24:27], v[158:161], v[208:211], v[24:27]
	v_mfma_f32_16x16x32_bf16 v[20:23], v[172:175], v[200:203], v[20:23]
	v_mfma_f32_16x16x32_bf16 v[16:19], v[172:175], v[208:211], v[16:19]
	v_mfma_f32_16x16x32_bf16 v[12:15], v[184:187], v[200:203], v[12:15]
	v_mfma_f32_16x16x32_bf16 v[8:11], v[184:187], v[208:211], v[8:11]
	v_mfma_f32_16x16x32_bf16 v[4:7], v[192:195], v[200:203], v[4:7]
	v_mfma_f32_16x16x32_bf16 v[0:3], v[192:195], v[208:211], v[0:3]
	s_setprio 0
	s_add_i32 s24, s24, 2
	s_add_u32 s4, s4, 0x100
	s_addc_u32 s5, s5, 0
	s_add_u32 s22, s22, 0x100
	s_addc_u32 s23, s23, 0
	s_cmp_ge_i32 s24, s21
	s_barrier
	s_cbranch_scc0 .LBB0_879

; #define WAIT_V(n) asm volatile("s_waitcnt vmcnt(" #n ")" ::: "memory")
; #define BAR __builtin_amdgcn_s_barrier()
; template <class Epi>
; __device__ __forceinline__ void gemm_phase(const bfr* __restrict__ A, int lda, const bfr* __restrict__ Bt, int K,
;                                            int nM, int nN, const Epi& epi, bfr* shm, int wv, int nMfull, int ksplit) {
;     ...
;     f32x4 acc[2][2][4][2];
; #pragma unroll
;     for (int a = 0; a < 2; a++)
; #pragma unroll
;       for (int b = 0; b < 2; b++)
; #pragma unroll
;         for (int m = 0; m < 4; m++)
; #pragma unroll
;           for (int n = 0; n < 2; n++) acc[a][b][m][n] = f32x4{0.f, 0.f, 0.f, 0.f};
;     bf16x8 At[4][2], B0[2][2], B1[2][2];
;     if (wr == 1) BAR;
;     WAIT_V(10); BAR;
;     WAIT_V(6); BAR;
;     for (int t = 0; t < nt - 2; t += 2) {
.LBB0_933:
	v_readlane_b32 s60, v255, 10
	s_lshl_b64 s[36:37], s[8:9], 1
	v_readlane_b32 s66, v255, 16
	v_readlane_b32 s67, v255, 17
	s_add_u32 s8, s66, s36
	s_waitcnt vmcnt(8)
	s_barrier
	s_waitcnt vmcnt(6)
	s_addc_u32 s29, s67, s37
	v_mov_b32_e32 v127, 0
	s_cmp_lt_u32 s28, 3
	v_mov_b32_e32 v126, v127
	v_mov_b32_e32 v125, v127
	v_mov_b32_e32 v124, v127
	v_mov_b32_e32 v123, v127
	v_mov_b32_e32 v122, v127
	v_mov_b32_e32 v121, v127
	v_mov_b32_e32 v120, v127
	v_mov_b32_e32 v119, v127
	v_mov_b32_e32 v118, v127
	v_mov_b32_e32 v117, v127
	v_mov_b32_e32 v116, v127
	v_mov_b32_e32 v115, v127
	v_mov_b32_e32 v114, v127
	v_mov_b32_e32 v113, v127
	v_mov_b32_e32 v112, v127
	v_mov_b32_e32 v111, v127
	v_mov_b32_e32 v110, v127
	v_mov_b32_e32 v109, v127
	v_mov_b32_e32 v108, v127
	v_mov_b32_e32 v107, v127
	v_mov_b32_e32 v106, v127
	v_mov_b32_e32 v105, v127
	v_mov_b32_e32 v104, v127
	v_mov_b32_e32 v103, v127
	v_mov_b32_e32 v102, v127
	v_mov_b32_e32 v101, v127
	v_mov_b32_e32 v100, v127
	v_mov_b32_e32 v99, v127
	v_mov_b32_e32 v98, v127
	v_mov_b32_e32 v97, v127
	v_mov_b32_e32 v96, v127
	v_mov_b32_e32 v95, v127
	v_mov_b32_e32 v94, v127
	v_mov_b32_e32 v93, v127
	v_mov_b32_e32 v92, v127
	v_mov_b32_e32 v91, v127
	v_mov_b32_e32 v90, v127
	v_mov_b32_e32 v89, v127
	v_mov_b32_e32 v88, v127
	v_mov_b32_e32 v87, v127
	v_mov_b32_e32 v86, v127
	v_mov_b32_e32 v85, v127
	v_mov_b32_e32 v84, v127
	v_mov_b32_e32 v83, v127
	v_mov_b32_e32 v82, v127
	v_mov_b32_e32 v81, v127
	v_mov_b32_e32 v80, v127
	v_mov_b32_e32 v79, v127
	v_mov_b32_e32 v78, v127
	v_mov_b32_e32 v77, v127
	v_mov_b32_e32 v76, v127
	v_mov_b32_e32 v75, v127
	v_mov_b32_e32 v74, v127
	v_mov_b32_e32 v73, v127
	v_mov_b32_e32 v72, v127
	v_mov_b32_e32 v71, v127
	v_mov_b32_e32 v70, v127
	v_mov_b32_e32 v69, v127
	v_mov_b32_e32 v68, v127
	v_mov_b32_e32 v67, v127
	v_mov_b32_e32 v66, v127
	v_mov_b32_e32 v65, v127
	v_mov_b32_e32 v64, v127
	v_mov_b32_e32 v63, v127
	v_mov_b32_e32 v62, v127
	v_mov_b32_e32 v61, v127
	v_mov_b32_e32 v60, v127
	v_mov_b32_e32 v59, v127
	v_mov_b32_e32 v58, v127
	v_mov_b32_e32 v57, v127
	v_mov_b32_e32 v56, v127
	v_mov_b32_e32 v55, v127
	v_mov_b32_e32 v54, v127
	v_mov_b32_e32 v53, v127
	v_mov_b32_e32 v52, v127
	v_mov_b32_e32 v51, v127
	v_mov_b32_e32 v50, v127
	v_mov_b32_e32 v49, v127
	v_mov_b32_e32 v48, v127
	v_mov_b32_e32 v47, v127
	v_mov_b32_e32 v46, v127
	v_mov_b32_e32 v45, v127
	v_mov_b32_e32 v44, v127
	v_mov_b32_e32 v43, v127
	v_mov_b32_e32 v42, v127
	v_mov_b32_e32 v41, v127
	v_mov_b32_e32 v40, v127
	v_mov_b32_e32 v39, v127
	v_mov_b32_e32 v38, v127
	v_mov_b32_e32 v37, v127
	v_mov_b32_e32 v36, v127
	v_mov_b32_e32 v35, v127
	v_mov_b32_e32 v34, v127
	v_mov_b32_e32 v33, v127
	v_mov_b32_e32 v32, v127
	v_mov_b32_e32 v31, v127
	v_mov_b32_e32 v30, v127
	v_mov_b32_e32 v29, v127
	v_mov_b32_e32 v28, v127
	v_mov_b32_e32 v27, v127
	v_mov_b32_e32 v26, v127
	v_mov_b32_e32 v25, v127
	v_mov_b32_e32 v24, v127
	v_mov_b32_e32 v23, v127
	v_mov_b32_e32 v22, v127
	v_mov_b32_e32 v21, v127
	v_mov_b32_e32 v20, v127
	v_mov_b32_e32 v19, v127
	v_mov_b32_e32 v18, v127
	v_mov_b32_e32 v17, v127
	v_mov_b32_e32 v16, v127
	v_mov_b32_e32 v15, v127
	v_mov_b32_e32 v14, v127
	v_mov_b32_e32 v13, v127
	v_mov_b32_e32 v12, v127
	v_mov_b32_e32 v11, v127
	v_mov_b32_e32 v10, v127
	v_mov_b32_e32 v9, v127
	v_mov_b32_e32 v8, v127
	v_mov_b32_e32 v7, v127
	v_mov_b32_e32 v6, v127
	v_mov_b32_e32 v5, v127
	v_mov_b32_e32 v4, v127
	v_mov_b32_e32 v3, v127
	v_mov_b32_e32 v2, v127
	v_mov_b32_e32 v1, v127
	v_mov_b32_e32 v0, v127
	v_readlane_b32 s61, v255, 11
	v_readlane_b32 s62, v255, 12
	v_readlane_b32 s63, v255, 13
	v_readlane_b32 s64, v255, 14
	v_readlane_b32 s65, v255, 15
	v_readlane_b32 s68, v255, 18
	v_readlane_b32 s69, v255, 19
	v_readlane_b32 s70, v255, 20
	v_readlane_b32 s71, v255, 21
	v_readlane_b32 s72, v255, 22
	v_readlane_b32 s73, v255, 23
	v_readlane_b32 s74, v255, 24
	v_readlane_b32 s75, v255, 25
	s_barrier
	s_cbranch_scc1 .LBB0_936
	s_mul_i32 s40, s34, 0xb00
	s_add_i32 s35, s28, -2
	s_ashr_i32 s41, s40, 31
	s_mul_i32 s30, s93, 0x1600
	s_mul_hi_i32 s31, s93, 0x1600
	s_add_u32 s30, s8, s30
	s_addc_u32 s31, s29, s31
	s_lshl_b64 s[40:41], s[40:41], 1
	s_add_u32 s36, s40, s36
	v_readlane_b32 s60, v254, 54
	s_addc_u32 s37, s41, s37
	v_readlane_b32 s64, v254, 58
	v_readlane_b32 s65, v254, 59
	s_add_u32 s36, s64, s36
	v_mov_b32_e32 v0, 0
	s_addc_u32 s37, s65, s37
	s_mov_b32 s39, 0
	v_readlane_b32 s61, v254, 55
	v_readlane_b32 s62, v254, 56
	v_readlane_b32 s63, v254, 57
	v_readlane_b32 s66, v254, 60
	v_readlane_b32 s67, v254, 61
	v_readlane_b32 s68, v254, 62
	v_readlane_b32 s69, v254, 63
	v_readlane_b32 s70, v255, 0
	v_readlane_b32 s71, v255, 1
	v_readlane_b32 s72, v255, 2
	v_readlane_b32 s73, v255, 3
	v_readlane_b32 s74, v255, 4
	v_readlane_b32 s75, v255, 5
; #define STAGE(P, BASE, br, kt) do { const char* _g = (const char*)((BASE) + (size_t)(br) * K + (size_t)(kt) * G_BK); \
;     _Pragma("unroll") for (int _i = 0; _i < 2; ++_i) { \
;       __builtin_amdgcn_global_load_lds((const unsigned*)(_g + (size_t)_i * 128 * K + sg_off), (unsigned*)((char*)(P) + wid * 1024 + _i * 8192), 16, 0, 0); } } while (0)
; #define LDA(dst, b, h) _Pragma("unroll") for (int m = 0; m < 4; ++m) _Pragma("unroll") for (int k = 0; k < 2; ++k) \
;     dst[m][k] = *reinterpret_cast<const bf16x8*>((const char*)shm + aoff + (((b) * 2 + (h)) * 16384 + m * 2048 + k * 1024))
; #define LDB(dst, b, h) _Pragma("unroll") for (int n = 0; n < 2; ++n) _Pragma("unroll") for (int k = 0; k < 2; ++k) \
;     dst[n][k] = *reinterpret_cast<const bf16x8*>((const char*)shm + boff + (((b) * 2 + (h)) * 16384 + n * 2048 + k * 1024))
; #define MMA(ai, bj, At, Bt_) do { __builtin_amdgcn_s_setprio(1); \
;     _Pragma("unroll") for (int m = 0; m < 4; ++m) _Pragma("unroll") for (int n = 0; n < 2; ++n) _Pragma("unroll") for (int k = 0; k < 2; ++k) \
;       acc[ai][bj][m][n] = mfma16(At[m][k], Bt_[n][k], acc[ai][bj][m][n]); \
;     __builtin_amdgcn_s_setprio(0); } while (0)
; #define WAIT_V(n) asm volatile("s_waitcnt vmcnt(" #n ")" ::: "memory")
; #define WAIT_L(n) asm volatile("s_waitcnt lgkmcnt(" #n ")" ::: "memory")
; #define BAR __builtin_amdgcn_s_barrier()
; #define SCHED __builtin_amdgcn_sched_barrier(0)
; template <class Epi>
; __device__ __forceinline__ void gemm_phase(const bfr* __restrict__ A, int lda, const bfr* __restrict__ Bt, int K,
;                                            int nM, int nN, const Epi& epi, bfr* shm, int wv, int nMfull, int ksplit) {
;     ...
;       LDB(B0, 0, 0); SCHED; LDA(At, 0, 0); STAGE(SA(1, 1), Ak, brow + G_HALF, t + 1);
;       WAIT_L(8); BAR; WAIT_L(0); MMA(0, 0, At, B0); BAR; SCHED;
;       LDB(B1, 0, 1); STAGE(SB(0, 0), Bk, bcol, t + 2);
;       BAR; WAIT_L(0); MMA(0, 1, At, B1); BAR;
;       LDA(At, 0, 1); STAGE(SA(0, 0), Ak, brow, t + 2);
;       BAR; WAIT_L(0); MMA(1, 0, At, B0); BAR; SCHED;
;       STAGE(SB(0, 1), Bk, bcol + G_HALF, t + 2);
;       WAIT_V(6); BAR; MMA(1, 1, At, B1); BAR;
.LBB0_935:
	ds_read_b128 v[138:141], v179
	ds_read_b128 v[142:145], v179 offset:1024
	ds_read_b128 v[146:149], v179 offset:2048
	ds_read_b128 v[150:153], v179 offset:3072
	ds_read_b128 v[154:157], v178
	ds_read_b128 v[158:161], v178 offset:1024
	ds_read_b128 v[162:165], v178 offset:2048
	ds_read_b128 v[166:169], v178 offset:3072
	ds_read_b128 v[170:173], v178 offset:4096
	ds_read_b128 v[174:177], v178 offset:5120
	ds_read_b128 v[184:187], v178 offset:6144
	ds_read_b128 v[188:191], v178 offset:7168
	ds_read_b128 v[192:195], v179 offset:16384
	ds_read_b128 v[196:199], v179 offset:17408
	ds_read_b128 v[200:203], v179 offset:18432
	ds_read_b128 v[204:207], v179 offset:19456
	v_lshl_add_u64 v[208:209], s[30:31], 0, v[136:137]
	v_lshl_add_u64 v[210:211], s[36:37], 0, v[136:137]
	s_mov_b32 m0, s50
	v_lshl_add_u64 v[214:215], v[208:209], 0, s[12:13]
	global_load_lds_dwordx4 v[214:215], off
	s_mov_b32 m0, s51
	v_lshl_add_u64 v[216:217], v[208:209], 0, s[14:15]
	global_load_lds_dwordx4 v[216:217], off
	s_waitcnt lgkmcnt(0)
	s_barrier
	s_setprio 1
	v_mfma_f32_16x16x32_bf16 v[124:127], v[154:157], v[138:141], v[124:127]
	v_mfma_f32_16x16x32_bf16 v[120:123], v[154:157], v[146:149], v[120:123]
	v_mfma_f32_16x16x32_bf16 v[116:119], v[162:165], v[138:141], v[116:119]
	v_mfma_f32_16x16x32_bf16 v[112:115], v[162:165], v[146:149], v[112:115]
	v_mfma_f32_16x16x32_bf16 v[108:111], v[170:173], v[138:141], v[108:111]
	v_mfma_f32_16x16x32_bf16 v[104:107], v[170:173], v[146:149], v[104:107]
	v_mfma_f32_16x16x32_bf16 v[100:103], v[184:187], v[138:141], v[100:103]
	v_mfma_f32_16x16x32_bf16 v[96:99], v[184:187], v[146:149], v[96:99]
	v_mfma_f32_16x16x32_bf16 v[124:127], v[158:161], v[142:145], v[124:127]
	v_mfma_f32_16x16x32_bf16 v[120:123], v[158:161], v[150:153], v[120:123]
	v_mfma_f32_16x16x32_bf16 v[116:119], v[166:169], v[142:145], v[116:119]
	v_mfma_f32_16x16x32_bf16 v[112:115], v[166:169], v[150:153], v[112:115]
	v_mfma_f32_16x16x32_bf16 v[108:111], v[174:177], v[142:145], v[108:111]
	v_mfma_f32_16x16x32_bf16 v[104:107], v[174:177], v[150:153], v[104:107]
	v_mfma_f32_16x16x32_bf16 v[100:103], v[188:191], v[142:145], v[100:103]
	v_mfma_f32_16x16x32_bf16 v[96:99], v[188:191], v[150:153], v[96:99]
	v_mfma_f32_16x16x32_bf16 v[92:95], v[154:157], v[192:195], v[92:95]
	v_mfma_f32_16x16x32_bf16 v[88:91], v[154:157], v[200:203], v[88:91]
	v_mfma_f32_16x16x32_bf16 v[84:87], v[162:165], v[192:195], v[84:87]
	v_mfma_f32_16x16x32_bf16 v[80:83], v[162:165], v[200:203], v[80:83]
	v_mfma_f32_16x16x32_bf16 v[76:79], v[170:173], v[192:195], v[76:79]
	v_mfma_f32_16x16x32_bf16 v[72:75], v[170:173], v[200:203], v[72:75]
	v_mfma_f32_16x16x32_bf16 v[68:71], v[184:187], v[192:195], v[68:71]
	v_mfma_f32_16x16x32_bf16 v[64:67], v[184:187], v[200:203], v[64:67]
	v_mfma_f32_16x16x32_bf16 v[92:95], v[158:161], v[196:199], v[92:95]
	v_mfma_f32_16x16x32_bf16 v[88:91], v[158:161], v[204:207], v[88:91]
	v_mfma_f32_16x16x32_bf16 v[84:87], v[166:169], v[196:199], v[84:87]
	v_mfma_f32_16x16x32_bf16 v[80:83], v[166:169], v[204:207], v[80:83]
	v_mfma_f32_16x16x32_bf16 v[76:79], v[174:177], v[196:199], v[76:79]
	v_mfma_f32_16x16x32_bf16 v[72:75], v[174:177], v[204:207], v[72:75]
	v_mfma_f32_16x16x32_bf16 v[68:71], v[188:191], v[196:199], v[68:71]
	v_mfma_f32_16x16x32_bf16 v[64:67], v[188:191], v[204:207], v[64:67]
	s_setprio 0
	s_barrier
	ds_read_b128 v[154:157], v178 offset:16384
	ds_read_b128 v[158:161], v178 offset:17408
	ds_read_b128 v[162:165], v178 offset:18432
	ds_read_b128 v[166:169], v178 offset:19456
	ds_read_b128 v[170:173], v178 offset:20480
	ds_read_b128 v[174:177], v178 offset:21504
	ds_read_b128 v[184:187], v178 offset:22528
	ds_read_b128 v[188:191], v178 offset:23552
	s_mov_b32 m0, s52
	s_mov_b64 s[40:41], 0xb00100
	v_lshl_add_u64 v[218:219], v[210:211], 0, s[40:41]
	global_load_lds_dwordx4 v[218:219], off
	s_mov_b32 m0, s53
	s_mov_b64 s[40:41], 0xb58100
	v_lshl_add_u64 v[214:215], v[210:211], 0, s[40:41]
	global_load_lds_dwordx4 v[214:215], off
	s_mov_b32 m0, s49
	s_mov_b64 s[40:41], 0x100
	v_lshl_add_u64 v[216:217], v[208:209], 0, s[40:41]
	global_load_lds_dwordx4 v[216:217], off
	s_mov_b32 m0, s54
	s_mov_b64 s[40:41], 0x58100
	v_lshl_add_u64 v[218:219], v[208:209], 0, s[40:41]
	global_load_lds_dwordx4 v[218:219], off
	s_waitcnt vmcnt(6)
	s_waitcnt lgkmcnt(0)
	s_barrier
	s_setprio 1
	v_mfma_f32_16x16x32_bf16 v[60:63], v[154:157], v[138:141], v[60:63]
	v_mfma_f32_16x16x32_bf16 v[56:59], v[154:157], v[146:149], v[56:59]
	v_mfma_f32_16x16x32_bf16 v[52:55], v[162:165], v[138:141], v[52:55]
	v_mfma_f32_16x16x32_bf16 v[48:51], v[162:165], v[146:149], v[48:51]
	v_mfma_f32_16x16x32_bf16 v[44:47], v[170:173], v[138:141], v[44:47]
	v_mfma_f32_16x16x32_bf16 v[40:43], v[170:173], v[146:149], v[40:43]
	v_mfma_f32_16x16x32_bf16 v[36:39], v[184:187], v[138:141], v[36:39]
	v_mfma_f32_16x16x32_bf16 v[32:35], v[184:187], v[146:149], v[32:35]
	v_mfma_f32_16x16x32_bf16 v[60:63], v[158:161], v[142:145], v[60:63]
	v_mfma_f32_16x16x32_bf16 v[56:59], v[158:161], v[150:153], v[56:59]
	v_mfma_f32_16x16x32_bf16 v[52:55], v[166:169], v[142:145], v[52:55]
	v_mfma_f32_16x16x32_bf16 v[48:51], v[166:169], v[150:153], v[48:51]
	v_mfma_f32_16x16x32_bf16 v[44:47], v[174:177], v[142:145], v[44:47]
	v_mfma_f32_16x16x32_bf16 v[40:43], v[174:177], v[150:153], v[40:43]
	v_mfma_f32_16x16x32_bf16 v[36:39], v[188:191], v[142:145], v[36:39]
	v_mfma_f32_16x16x32_bf16 v[32:35], v[188:191], v[150:153], v[32:35]
	v_mfma_f32_16x16x32_bf16 v[28:31], v[154:157], v[192:195], v[28:31]
	v_mfma_f32_16x16x32_bf16 v[24:27], v[154:157], v[200:203], v[24:27]
	v_mfma_f32_16x16x32_bf16 v[20:23], v[162:165], v[192:195], v[20:23]
	v_mfma_f32_16x16x32_bf16 v[16:19], v[162:165], v[200:203], v[16:19]
	v_mfma_f32_16x16x32_bf16 v[12:15], v[170:173], v[192:195], v[12:15]
	v_mfma_f32_16x16x32_bf16 v[8:11], v[170:173], v[200:203], v[8:11]
	v_mfma_f32_16x16x32_bf16 v[4:7], v[184:187], v[192:195], v[4:7]
	v_mfma_f32_16x16x32_bf16 v[0:3], v[184:187], v[200:203], v[0:3]
	v_mfma_f32_16x16x32_bf16 v[28:31], v[158:161], v[196:199], v[28:31]
	v_mfma_f32_16x16x32_bf16 v[24:27], v[158:161], v[204:207], v[24:27]
	v_mfma_f32_16x16x32_bf16 v[20:23], v[166:169], v[196:199], v[20:23]
	v_mfma_f32_16x16x32_bf16 v[16:19], v[166:169], v[204:207], v[16:19]
	v_mfma_f32_16x16x32_bf16 v[12:15], v[174:177], v[196:199], v[12:15]
	v_mfma_f32_16x16x32_bf16 v[8:11], v[174:177], v[204:207], v[8:11]
	v_mfma_f32_16x16x32_bf16 v[4:7], v[188:191], v[196:199], v[4:7]
	v_mfma_f32_16x16x32_bf16 v[0:3], v[188:191], v[204:207], v[0:3]
	s_setprio 0
	s_barrier
; #define STAGE(P, BASE, br, kt) do { const char* _g = (const char*)((BASE) + (size_t)(br) * K + (size_t)(kt) * G_BK); \
;     _Pragma("unroll") for (int _i = 0; _i < 2; ++_i) { \
;       __builtin_amdgcn_global_load_lds((const unsigned*)(_g + (size_t)_i * 128 * K + sg_off), (unsigned*)((char*)(P) + wid * 1024 + _i * 8192), 16, 0, 0); } } while (0)
; #define LDA(dst, b, h) _Pragma("unroll") for (int m = 0; m < 4; ++m) _Pragma("unroll") for (int k = 0; k < 2; ++k) \
;     dst[m][k] = *reinterpret_cast<const bf16x8*>((const char*)shm + aoff + (((b) * 2 + (h)) * 16384 + m * 2048 + k * 1024))
; #define LDB(dst, b, h) _Pragma("unroll") for (int n = 0; n < 2; ++n) _Pragma("unroll") for (int k = 0; k < 2; ++k) \
;     dst[n][k] = *reinterpret_cast<const bf16x8*>((const char*)shm + boff + (((b) * 2 + (h)) * 16384 + n * 2048 + k * 1024))
; #define MMA(ai, bj, At, Bt_) do { __builtin_amdgcn_s_setprio(1); \
;     _Pragma("unroll") for (int m = 0; m < 4; ++m) _Pragma("unroll") for (int n = 0; n < 2; ++n) _Pragma("unroll") for (int k = 0; k < 2; ++k) \
;       acc[ai][bj][m][n] = mfma16(At[m][k], Bt_[n][k], acc[ai][bj][m][n]); \
;     __builtin_amdgcn_s_setprio(0); } while (0)
; #define WAIT_L(n) asm volatile("s_waitcnt lgkmcnt(" #n ")" ::: "memory")
; #define BAR __builtin_amdgcn_s_barrier()
; #define SCHED __builtin_amdgcn_sched_barrier(0)
; template <class Epi>
; __device__ __forceinline__ void gemm_phase(const bfr* __restrict__ A, int lda, const bfr* __restrict__ Bt, int K,
;                                            int nM, int nN, const Epi& epi, bfr* shm, int wv, int nMfull, int ksplit) {
;     ...
;       LDB(B0, 1, 0); SCHED; LDA(At, 1, 0); STAGE(SA(0, 1), Ak, brow + G_HALF, t + 2);
;       WAIT_L(8); BAR; WAIT_L(0); MMA(0, 0, At, B0); BAR; SCHED;
;       LDB(B1, 1, 1); STAGE(SB(1, 0), Bk, bcol, t + 3);
;       BAR; WAIT_L(0); MMA(0, 1, At, B1); BAR;
	ds_read_b128 v[138:141], v179 offset:32768
	ds_read_b128 v[142:145], v179 offset:33792
	ds_read_b128 v[146:149], v179 offset:34816
	ds_read_b128 v[150:153], v179 offset:35840
	ds_read_b128 v[154:157], v178 offset:32768
	ds_read_b128 v[158:161], v178 offset:33792
	ds_read_b128 v[162:165], v178 offset:34816
	ds_read_b128 v[166:169], v178 offset:35840
	ds_read_b128 v[170:173], v178 offset:36864
	ds_read_b128 v[174:177], v178 offset:37888
	ds_read_b128 v[184:187], v178 offset:38912
	ds_read_b128 v[188:191], v178 offset:39936
	ds_read_b128 v[192:195], v179 offset:49152
	ds_read_b128 v[196:199], v179 offset:50176
	ds_read_b128 v[200:203], v179 offset:51200
	ds_read_b128 v[204:207], v179 offset:52224
	s_mov_b32 m0, s55
	s_mov_b64 s[40:41], 0xbb0100
	v_lshl_add_u64 v[214:215], v[210:211], 0, s[40:41]
	global_load_lds_dwordx4 v[214:215], off
	s_mov_b32 m0, s56
	s_mov_b64 s[40:41], 0xc08100
	v_lshl_add_u64 v[216:217], v[210:211], 0, s[40:41]
	global_load_lds_dwordx4 v[216:217], off
	s_mov_b32 m0, s57
	s_mov_b64 s[40:41], 0xb0100
	v_lshl_add_u64 v[218:219], v[208:209], 0, s[40:41]
	global_load_lds_dwordx4 v[218:219], off
	s_mov_b32 m0, s58
	s_mov_b64 s[40:41], 0x108100
	v_lshl_add_u64 v[214:215], v[208:209], 0, s[40:41]
	global_load_lds_dwordx4 v[214:215], off
	s_waitcnt vmcnt(8)
	s_waitcnt lgkmcnt(0)
	s_barrier
	s_setprio 1
	v_mfma_f32_16x16x32_bf16 v[124:127], v[154:157], v[138:141], v[124:127]
	v_mfma_f32_16x16x32_bf16 v[120:123], v[154:157], v[146:149], v[120:123]
	v_mfma_f32_16x16x32_bf16 v[116:119], v[162:165], v[138:141], v[116:119]
	v_mfma_f32_16x16x32_bf16 v[112:115], v[162:165], v[146:149], v[112:115]
	v_mfma_f32_16x16x32_bf16 v[108:111], v[170:173], v[138:141], v[108:111]
	v_mfma_f32_16x16x32_bf16 v[104:107], v[170:173], v[146:149], v[104:107]
	v_mfma_f32_16x16x32_bf16 v[100:103], v[184:187], v[138:141], v[100:103]
	v_mfma_f32_16x16x32_bf16 v[96:99], v[184:187], v[146:149], v[96:99]
	v_mfma_f32_16x16x32_bf16 v[124:127], v[158:161], v[142:145], v[124:127]
	v_mfma_f32_16x16x32_bf16 v[120:123], v[158:161], v[150:153], v[120:123]
	v_mfma_f32_16x16x32_bf16 v[116:119], v[166:169], v[142:145], v[116:119]
	v_mfma_f32_16x16x32_bf16 v[112:115], v[166:169], v[150:153], v[112:115]
	v_mfma_f32_16x16x32_bf16 v[108:111], v[174:177], v[142:145], v[108:111]
	v_mfma_f32_16x16x32_bf16 v[104:107], v[174:177], v[150:153], v[104:107]
	v_mfma_f32_16x16x32_bf16 v[100:103], v[188:191], v[142:145], v[100:103]
	v_mfma_f32_16x16x32_bf16 v[96:99], v[188:191], v[150:153], v[96:99]
	v_mfma_f32_16x16x32_bf16 v[92:95], v[154:157], v[192:195], v[92:95]
	v_mfma_f32_16x16x32_bf16 v[88:91], v[154:157], v[200:203], v[88:91]
	v_mfma_f32_16x16x32_bf16 v[84:87], v[162:165], v[192:195], v[84:87]
	v_mfma_f32_16x16x32_bf16 v[80:83], v[162:165], v[200:203], v[80:83]
	v_mfma_f32_16x16x32_bf16 v[76:79], v[170:173], v[192:195], v[76:79]
	v_mfma_f32_16x16x32_bf16 v[72:75], v[170:173], v[200:203], v[72:75]
	v_mfma_f32_16x16x32_bf16 v[68:71], v[184:187], v[192:195], v[68:71]
	v_mfma_f32_16x16x32_bf16 v[64:67], v[184:187], v[200:203], v[64:67]
	v_mfma_f32_16x16x32_bf16 v[92:95], v[158:161], v[196:199], v[92:95]
	v_mfma_f32_16x16x32_bf16 v[88:91], v[158:161], v[204:207], v[88:91]
	v_mfma_f32_16x16x32_bf16 v[84:87], v[166:169], v[196:199], v[84:87]
	v_mfma_f32_16x16x32_bf16 v[80:83], v[166:169], v[204:207], v[80:83]
	v_mfma_f32_16x16x32_bf16 v[76:79], v[174:177], v[196:199], v[76:79]
	v_mfma_f32_16x16x32_bf16 v[72:75], v[174:177], v[204:207], v[72:75]
	v_mfma_f32_16x16x32_bf16 v[68:71], v[188:191], v[196:199], v[68:71]
	v_mfma_f32_16x16x32_bf16 v[64:67], v[188:191], v[204:207], v[64:67]
	s_setprio 0
	s_barrier
; #define STAGE(P, BASE, br, kt) do { const char* _g = (const char*)((BASE) + (size_t)(br) * K + (size_t)(kt) * G_BK); \
;     _Pragma("unroll") for (int _i = 0; _i < 2; ++_i) { \
;       __builtin_amdgcn_global_load_lds((const unsigned*)(_g + (size_t)_i * 128 * K + sg_off), (unsigned*)((char*)(P) + wid * 1024 + _i * 8192), 16, 0, 0); } } while (0)
; #define LDA(dst, b, h) _Pragma("unroll") for (int m = 0; m < 4; ++m) _Pragma("unroll") for (int k = 0; k < 2; ++k) \
;     dst[m][k] = *reinterpret_cast<const bf16x8*>((const char*)shm + aoff + (((b) * 2 + (h)) * 16384 + m * 2048 + k * 1024))
; #define MMA(ai, bj, At, Bt_) do { __builtin_amdgcn_s_setprio(1); \
;     _Pragma("unroll") for (int m = 0; m < 4; ++m) _Pragma("unroll") for (int n = 0; n < 2; ++n) _Pragma("unroll") for (int k = 0; k < 2; ++k) \
;       acc[ai][bj][m][n] = mfma16(At[m][k], Bt_[n][k], acc[ai][bj][m][n]); \
;     __builtin_amdgcn_s_setprio(0); } while (0)
; #define WAIT_V(n) asm volatile("s_waitcnt vmcnt(" #n ")" ::: "memory")
; #define WAIT_L(n) asm volatile("s_waitcnt lgkmcnt(" #n ")" ::: "memory")
; #define BAR __builtin_amdgcn_s_barrier()
; #define SCHED __builtin_amdgcn_sched_barrier(0)
; template <class Epi>
; __device__ __forceinline__ void gemm_phase(const bfr* __restrict__ A, int lda, const bfr* __restrict__ Bt, int K,
;                                            int nM, int nN, const Epi& epi, bfr* shm, int wv, int nMfull, int ksplit) {
;     ...
;       LDA(At, 1, 1); STAGE(SA(1, 0), Ak, brow, t + 3);
;       BAR; WAIT_L(0); MMA(1, 0, At, B0); BAR; SCHED;
;       STAGE(SB(1, 1), Bk, bcol + G_HALF, t + 3);
;       WAIT_V(6); BAR; MMA(1, 1, At, B1); BAR;
;     }
	ds_read_b128 v[154:157], v178 offset:49152
	ds_read_b128 v[158:161], v178 offset:50176
	ds_read_b128 v[162:165], v178 offset:51200
	ds_read_b128 v[166:169], v178 offset:52224
	ds_read_b128 v[170:173], v178 offset:53248
	ds_read_b128 v[174:177], v178 offset:54272
	ds_read_b128 v[184:187], v178 offset:55296
	ds_read_b128 v[188:191], v178 offset:56320
	s_mov_b32 m0, s59
	s_mov_b64 s[40:41], 0xb00180
	v_lshl_add_u64 v[216:217], v[210:211], 0, s[40:41]
	global_load_lds_dwordx4 v[216:217], off
	s_mov_b32 m0, s82
	s_mov_b64 s[40:41], 0xb58180
	v_lshl_add_u64 v[218:219], v[210:211], 0, s[40:41]
	global_load_lds_dwordx4 v[218:219], off
	s_mov_b32 m0, s83
	s_mov_b64 s[40:41], 0x180
	v_lshl_add_u64 v[214:215], v[208:209], 0, s[40:41]
	global_load_lds_dwordx4 v[214:215], off
	s_mov_b32 m0, s84
	s_mov_b64 s[40:41], 0x58180
	v_lshl_add_u64 v[216:217], v[208:209], 0, s[40:41]
	global_load_lds_dwordx4 v[216:217], off
	s_mov_b32 m0, s85
	s_mov_b64 s[40:41], 0xbb0180
	v_lshl_add_u64 v[218:219], v[210:211], 0, s[40:41]
	global_load_lds_dwordx4 v[218:219], off
	s_mov_b32 m0, s90
	s_mov_b64 s[40:41], 0xc08180
	v_lshl_add_u64 v[214:215], v[210:211], 0, s[40:41]
	global_load_lds_dwordx4 v[214:215], off
	s_waitcnt vmcnt(6)
	s_waitcnt lgkmcnt(0)
	s_barrier
	s_setprio 1
	v_mfma_f32_16x16x32_bf16 v[60:63], v[154:157], v[138:141], v[60:63]
	v_mfma_f32_16x16x32_bf16 v[56:59], v[154:157], v[146:149], v[56:59]
	v_mfma_f32_16x16x32_bf16 v[52:55], v[162:165], v[138:141], v[52:55]
	v_mfma_f32_16x16x32_bf16 v[48:51], v[162:165], v[146:149], v[48:51]
	v_mfma_f32_16x16x32_bf16 v[44:47], v[170:173], v[138:141], v[44:47]
	v_mfma_f32_16x16x32_bf16 v[40:43], v[170:173], v[146:149], v[40:43]
	v_mfma_f32_16x16x32_bf16 v[36:39], v[184:187], v[138:141], v[36:39]
	v_mfma_f32_16x16x32_bf16 v[32:35], v[184:187], v[146:149], v[32:35]
	v_mfma_f32_16x16x32_bf16 v[60:63], v[158:161], v[142:145], v[60:63]
	v_mfma_f32_16x16x32_bf16 v[56:59], v[158:161], v[150:153], v[56:59]
	v_mfma_f32_16x16x32_bf16 v[52:55], v[166:169], v[142:145], v[52:55]
	v_mfma_f32_16x16x32_bf16 v[48:51], v[166:169], v[150:153], v[48:51]
	v_mfma_f32_16x16x32_bf16 v[44:47], v[174:177], v[142:145], v[44:47]
	v_mfma_f32_16x16x32_bf16 v[40:43], v[174:177], v[150:153], v[40:43]
	v_mfma_f32_16x16x32_bf16 v[36:39], v[188:191], v[142:145], v[36:39]
	v_mfma_f32_16x16x32_bf16 v[32:35], v[188:191], v[150:153], v[32:35]
	v_mfma_f32_16x16x32_bf16 v[28:31], v[154:157], v[192:195], v[28:31]
	v_mfma_f32_16x16x32_bf16 v[24:27], v[154:157], v[200:203], v[24:27]
	v_mfma_f32_16x16x32_bf16 v[20:23], v[162:165], v[192:195], v[20:23]
	v_mfma_f32_16x16x32_bf16 v[16:19], v[162:165], v[200:203], v[16:19]
	v_mfma_f32_16x16x32_bf16 v[12:15], v[170:173], v[192:195], v[12:15]
	v_mfma_f32_16x16x32_bf16 v[8:11], v[170:173], v[200:203], v[8:11]
	v_mfma_f32_16x16x32_bf16 v[4:7], v[184:187], v[192:195], v[4:7]
	v_mfma_f32_16x16x32_bf16 v[0:3], v[184:187], v[200:203], v[0:3]
	v_mfma_f32_16x16x32_bf16 v[28:31], v[158:161], v[196:199], v[28:31]
	v_mfma_f32_16x16x32_bf16 v[24:27], v[158:161], v[204:207], v[24:27]
	v_mfma_f32_16x16x32_bf16 v[20:23], v[166:169], v[196:199], v[20:23]
	v_mfma_f32_16x16x32_bf16 v[16:19], v[166:169], v[204:207], v[16:19]
	v_mfma_f32_16x16x32_bf16 v[12:15], v[174:177], v[196:199], v[12:15]
	v_mfma_f32_16x16x32_bf16 v[8:11], v[174:177], v[204:207], v[8:11]
	v_mfma_f32_16x16x32_bf16 v[4:7], v[188:191], v[196:199], v[4:7]
	v_mfma_f32_16x16x32_bf16 v[0:3], v[188:191], v[204:207], v[0:3]
	s_setprio 0
	s_add_i32 s39, s39, 2
	s_add_u32 s36, s36, 0x100
	s_addc_u32 s37, s37, 0
	s_add_u32 s30, s30, 0x100
	s_addc_u32 s31, s31, 0
	s_cmp_ge_i32 s39, s35
	s_barrier
	s_cbranch_scc0 .LBB0_935

; #define WAIT_V(n) asm volatile("s_waitcnt vmcnt(" #n ")" ::: "memory")
; #define BAR __builtin_amdgcn_s_barrier()
; template <class Epi>
; __device__ __forceinline__ void gemm_phase(const bfr* __restrict__ A, int lda, const bfr* __restrict__ Bt, int K,
;                                            int nM, int nN, const Epi& epi, bfr* shm, int wv, int nMfull, int ksplit) {
;     ...
;     f32x4 acc[2][2][4][2];
; #pragma unroll
;     for (int a = 0; a < 2; a++)
; #pragma unroll
;       for (int b = 0; b < 2; b++)
; #pragma unroll
;         for (int m = 0; m < 4; m++)
; #pragma unroll
;           for (int n = 0; n < 2; n++) acc[a][b][m][n] = f32x4{0.f, 0.f, 0.f, 0.f};
;     bf16x8 At[4][2], B0[2][2], B1[2][2];
;     if (wr == 1) BAR;
;     WAIT_V(10); BAR;
;     WAIT_V(6); BAR;
;     for (int t = 0; t < nt - 2; t += 2) {
.LBB0_1084:
	s_waitcnt vmcnt(8)
	s_barrier
	s_waitcnt vmcnt(6)
	v_mov_b32_e32 v127, 0
	s_cmp_lt_u32 s38, 3
	v_mov_b32_e32 v126, v127
	v_mov_b32_e32 v125, v127
	v_mov_b32_e32 v124, v127
	v_mov_b32_e32 v123, v127
	v_mov_b32_e32 v122, v127
	v_mov_b32_e32 v121, v127
	v_mov_b32_e32 v120, v127
	v_mov_b32_e32 v119, v127
	v_mov_b32_e32 v118, v127
	v_mov_b32_e32 v117, v127
	v_mov_b32_e32 v116, v127
	v_mov_b32_e32 v115, v127
	v_mov_b32_e32 v114, v127
	v_mov_b32_e32 v113, v127
	v_mov_b32_e32 v112, v127
	v_mov_b32_e32 v111, v127
	v_mov_b32_e32 v110, v127
	v_mov_b32_e32 v109, v127
	v_mov_b32_e32 v108, v127
	v_mov_b32_e32 v107, v127
	v_mov_b32_e32 v106, v127
	v_mov_b32_e32 v105, v127
	v_mov_b32_e32 v104, v127
	v_mov_b32_e32 v103, v127
	v_mov_b32_e32 v102, v127
	v_mov_b32_e32 v101, v127
	v_mov_b32_e32 v100, v127
	v_mov_b32_e32 v99, v127
	v_mov_b32_e32 v98, v127
	v_mov_b32_e32 v97, v127
	v_mov_b32_e32 v96, v127
	v_mov_b32_e32 v95, v127
	v_mov_b32_e32 v94, v127
	v_mov_b32_e32 v93, v127
	v_mov_b32_e32 v92, v127
	v_mov_b32_e32 v91, v127
	v_mov_b32_e32 v90, v127
	v_mov_b32_e32 v89, v127
	v_mov_b32_e32 v88, v127
	v_mov_b32_e32 v87, v127
	v_mov_b32_e32 v86, v127
	v_mov_b32_e32 v85, v127
	v_mov_b32_e32 v84, v127
	v_mov_b32_e32 v83, v127
	v_mov_b32_e32 v82, v127
	v_mov_b32_e32 v81, v127
	v_mov_b32_e32 v80, v127
	v_mov_b32_e32 v79, v127
	v_mov_b32_e32 v78, v127
	v_mov_b32_e32 v77, v127
	v_mov_b32_e32 v76, v127
	v_mov_b32_e32 v75, v127
	v_mov_b32_e32 v74, v127
	v_mov_b32_e32 v73, v127
	v_mov_b32_e32 v72, v127
	v_mov_b32_e32 v71, v127
	v_mov_b32_e32 v70, v127
	v_mov_b32_e32 v69, v127
	v_mov_b32_e32 v68, v127
	v_mov_b32_e32 v67, v127
	v_mov_b32_e32 v66, v127
	v_mov_b32_e32 v65, v127
	v_mov_b32_e32 v64, v127
	v_mov_b32_e32 v63, v127
	v_mov_b32_e32 v62, v127
	v_mov_b32_e32 v61, v127
	v_mov_b32_e32 v60, v127
	v_mov_b32_e32 v59, v127
	v_mov_b32_e32 v58, v127
	v_mov_b32_e32 v57, v127
	v_mov_b32_e32 v56, v127
	v_mov_b32_e32 v55, v127
	v_mov_b32_e32 v54, v127
	v_mov_b32_e32 v53, v127
	v_mov_b32_e32 v52, v127
	v_mov_b32_e32 v51, v127
	v_mov_b32_e32 v50, v127
	v_mov_b32_e32 v49, v127
	v_mov_b32_e32 v48, v127
	v_mov_b32_e32 v47, v127
	v_mov_b32_e32 v46, v127
	v_mov_b32_e32 v45, v127
	v_mov_b32_e32 v44, v127
	v_mov_b32_e32 v43, v127
	v_mov_b32_e32 v42, v127
	v_mov_b32_e32 v41, v127
	v_mov_b32_e32 v40, v127
	v_mov_b32_e32 v39, v127
	v_mov_b32_e32 v38, v127
	v_mov_b32_e32 v37, v127
	v_mov_b32_e32 v36, v127
	v_mov_b32_e32 v35, v127
	v_mov_b32_e32 v34, v127
	v_mov_b32_e32 v33, v127
	v_mov_b32_e32 v32, v127
	v_mov_b32_e32 v31, v127
	v_mov_b32_e32 v30, v127
	v_mov_b32_e32 v29, v127
	v_mov_b32_e32 v28, v127
	v_mov_b32_e32 v27, v127
	v_mov_b32_e32 v26, v127
	v_mov_b32_e32 v25, v127
	v_mov_b32_e32 v24, v127
	v_mov_b32_e32 v23, v127
	v_mov_b32_e32 v22, v127
	v_mov_b32_e32 v21, v127
	v_mov_b32_e32 v20, v127
	v_mov_b32_e32 v19, v127
	v_mov_b32_e32 v18, v127
	v_mov_b32_e32 v17, v127
	v_mov_b32_e32 v16, v127
	v_mov_b32_e32 v15, v127
	v_mov_b32_e32 v14, v127
	v_mov_b32_e32 v13, v127
	v_mov_b32_e32 v12, v127
	v_mov_b32_e32 v11, v127
	v_mov_b32_e32 v10, v127
	v_mov_b32_e32 v9, v127
	v_mov_b32_e32 v8, v127
	v_mov_b32_e32 v7, v127
	v_mov_b32_e32 v6, v127
	v_mov_b32_e32 v5, v127
	v_mov_b32_e32 v4, v127
	v_mov_b32_e32 v3, v127
	v_mov_b32_e32 v2, v127
	v_mov_b32_e32 v1, v127
	v_mov_b32_e32 v0, v127
	s_barrier
	s_cbranch_scc1 .LBB0_1087
	v_readlane_b32 s52, v254, 54
	s_ashr_i32 s49, s48, 31
	s_ashr_i32 s47, s46, 31
	v_readlane_b32 s62, v255, 0
	v_readlane_b32 s63, v255, 1
	s_add_i32 s39, s38, -2
	s_lshl_b64 s[2:3], s[48:49], 11
	s_lshl_b64 s[36:37], s[46:47], 11
	v_readlane_b32 s53, v254, 55
	v_readlane_b32 s54, v254, 56
	v_readlane_b32 s55, v254, 57
	v_readlane_b32 s56, v254, 58
	v_readlane_b32 s57, v254, 59
	v_readlane_b32 s58, v254, 60
	v_readlane_b32 s59, v254, 61
	v_readlane_b32 s60, v254, 62
	v_readlane_b32 s61, v254, 63
	v_readlane_b32 s64, v255, 2
	v_readlane_b32 s65, v255, 3
	v_readlane_b32 s66, v255, 4
	v_readlane_b32 s67, v255, 5
	s_mov_b64 s[50:51], s[62:63]
	s_add_u32 s2, s50, s2
	v_readlane_b32 s52, v255, 10
	s_addc_u32 s3, s51, s3
	v_readlane_b32 s56, v255, 14
	v_readlane_b32 s57, v255, 15
	s_add_u32 s36, s56, s36
	v_mov_b32_e32 v0, 0
	s_addc_u32 s37, s57, s37
	s_mov_b32 s40, 0
	v_readlane_b32 s53, v255, 11
	v_readlane_b32 s54, v255, 12
	v_readlane_b32 s55, v255, 13
	v_readlane_b32 s58, v255, 16
	v_readlane_b32 s59, v255, 17
	v_readlane_b32 s60, v255, 18
	v_readlane_b32 s61, v255, 19
	v_readlane_b32 s62, v255, 20
	v_readlane_b32 s63, v255, 21
	v_readlane_b32 s64, v255, 22
	v_readlane_b32 s65, v255, 23
	v_readlane_b32 s66, v255, 24
	v_readlane_b32 s67, v255, 25
; #define STAGE(P, BASE, br, kt) do { const char* _g = (const char*)((BASE) + (size_t)(br) * K + (size_t)(kt) * G_BK); \
;     _Pragma("unroll") for (int _i = 0; _i < 2; ++_i) { \
;       __builtin_amdgcn_global_load_lds((const unsigned*)(_g + (size_t)_i * 128 * K + sg_off), (unsigned*)((char*)(P) + wid * 1024 + _i * 8192), 16, 0, 0); } } while (0)
; #define LDA(dst, b, h) _Pragma("unroll") for (int m = 0; m < 4; ++m) _Pragma("unroll") for (int k = 0; k < 2; ++k) \
;     dst[m][k] = *reinterpret_cast<const bf16x8*>((const char*)shm + aoff + (((b) * 2 + (h)) * 16384 + m * 2048 + k * 1024))
; #define LDB(dst, b, h) _Pragma("unroll") for (int n = 0; n < 2; ++n) _Pragma("unroll") for (int k = 0; k < 2; ++k) \
;     dst[n][k] = *reinterpret_cast<const bf16x8*>((const char*)shm + boff + (((b) * 2 + (h)) * 16384 + n * 2048 + k * 1024))
; #define MMA(ai, bj, At, Bt_) do { __builtin_amdgcn_s_setprio(1); \
;     _Pragma("unroll") for (int m = 0; m < 4; ++m) _Pragma("unroll") for (int n = 0; n < 2; ++n) _Pragma("unroll") for (int k = 0; k < 2; ++k) \
;       acc[ai][bj][m][n] = mfma16(At[m][k], Bt_[n][k], acc[ai][bj][m][n]); \
;     __builtin_amdgcn_s_setprio(0); } while (0)
; #define WAIT_V(n) asm volatile("s_waitcnt vmcnt(" #n ")" ::: "memory")
; #define WAIT_L(n) asm volatile("s_waitcnt lgkmcnt(" #n ")" ::: "memory")
; #define BAR __builtin_amdgcn_s_barrier()
; #define SCHED __builtin_amdgcn_sched_barrier(0)
; template <class Epi>
; __device__ __forceinline__ void gemm_phase(const bfr* __restrict__ A, int lda, const bfr* __restrict__ Bt, int K,
;                                            int nM, int nN, const Epi& epi, bfr* shm, int wv, int nMfull, int ksplit) {
;     ...
;       LDB(B0, 0, 0); SCHED; LDA(At, 0, 0); STAGE(SA(1, 1), Ak, brow + G_HALF, t + 1);
;       WAIT_L(8); BAR; WAIT_L(0); MMA(0, 0, At, B0); BAR; SCHED;
;       LDB(B1, 0, 1); STAGE(SB(0, 0), Bk, bcol, t + 2);
;       BAR; WAIT_L(0); MMA(0, 1, At, B1); BAR;
;       LDA(At, 0, 1); STAGE(SA(0, 0), Ak, brow, t + 2);
;       BAR; WAIT_L(0); MMA(1, 0, At, B0); BAR; SCHED;
;       STAGE(SB(0, 1), Bk, bcol + G_HALF, t + 2);
;       WAIT_V(6); BAR; MMA(1, 1, At, B1); BAR;
.LBB0_1086:
	ds_read_b128 v[148:151], v137
	ds_read_b128 v[152:155], v137 offset:1024
	ds_read_b128 v[162:165], v137 offset:2048
	ds_read_b128 v[166:169], v137 offset:3072
	ds_read_b128 v[170:173], v129
	ds_read_b128 v[174:177], v129 offset:1024
	ds_read_b128 v[178:181], v129 offset:2048
	ds_read_b128 v[182:185], v129 offset:3072
	ds_read_b128 v[186:189], v129 offset:4096
	ds_read_b128 v[190:193], v129 offset:5120
	ds_read_b128 v[194:197], v129 offset:6144
	ds_read_b128 v[198:201], v129 offset:7168
	ds_read_b128 v[202:205], v137 offset:16384
	ds_read_b128 v[206:209], v137 offset:17408
	ds_read_b128 v[210:213], v137 offset:18432
	ds_read_b128 v[214:217], v137 offset:19456
	v_lshl_add_u64 v[142:143], s[36:37], 0, v[140:141]
	v_lshl_add_u64 v[218:219], s[2:3], 0, v[140:141]
	s_mov_b32 m0, s95
	s_mov_b64 s[42:43], 0x40080
	v_lshl_add_u64 v[222:223], v[142:143], 0, s[42:43]
	global_load_lds_dwordx4 v[222:223], off
	s_mov_b32 m0, s96
	s_mov_b64 s[42:43], 0x60080
	v_lshl_add_u64 v[224:225], v[142:143], 0, s[42:43]
	global_load_lds_dwordx4 v[224:225], off
	s_waitcnt lgkmcnt(0)
	s_barrier
	s_setprio 1
	v_mfma_f32_16x16x32_bf16 v[124:127], v[170:173], v[148:151], v[124:127]
	v_mfma_f32_16x16x32_bf16 v[120:123], v[170:173], v[162:165], v[120:123]
	v_mfma_f32_16x16x32_bf16 v[116:119], v[178:181], v[148:151], v[116:119]
	v_mfma_f32_16x16x32_bf16 v[112:115], v[178:181], v[162:165], v[112:115]
	v_mfma_f32_16x16x32_bf16 v[108:111], v[186:189], v[148:151], v[108:111]
	v_mfma_f32_16x16x32_bf16 v[104:107], v[186:189], v[162:165], v[104:107]
	v_mfma_f32_16x16x32_bf16 v[100:103], v[194:197], v[148:151], v[100:103]
	v_mfma_f32_16x16x32_bf16 v[96:99], v[194:197], v[162:165], v[96:99]
	v_mfma_f32_16x16x32_bf16 v[124:127], v[174:177], v[152:155], v[124:127]
	v_mfma_f32_16x16x32_bf16 v[120:123], v[174:177], v[166:169], v[120:123]
	v_mfma_f32_16x16x32_bf16 v[116:119], v[182:185], v[152:155], v[116:119]
	v_mfma_f32_16x16x32_bf16 v[112:115], v[182:185], v[166:169], v[112:115]
	v_mfma_f32_16x16x32_bf16 v[108:111], v[190:193], v[152:155], v[108:111]
	v_mfma_f32_16x16x32_bf16 v[104:107], v[190:193], v[166:169], v[104:107]
	v_mfma_f32_16x16x32_bf16 v[100:103], v[198:201], v[152:155], v[100:103]
	v_mfma_f32_16x16x32_bf16 v[96:99], v[198:201], v[166:169], v[96:99]
	v_mfma_f32_16x16x32_bf16 v[92:95], v[170:173], v[202:205], v[92:95]
	v_mfma_f32_16x16x32_bf16 v[88:91], v[170:173], v[210:213], v[88:91]
	v_mfma_f32_16x16x32_bf16 v[84:87], v[178:181], v[202:205], v[84:87]
	v_mfma_f32_16x16x32_bf16 v[80:83], v[178:181], v[210:213], v[80:83]
	v_mfma_f32_16x16x32_bf16 v[76:79], v[186:189], v[202:205], v[76:79]
	v_mfma_f32_16x16x32_bf16 v[72:75], v[186:189], v[210:213], v[72:75]
	v_mfma_f32_16x16x32_bf16 v[68:71], v[194:197], v[202:205], v[68:71]
	v_mfma_f32_16x16x32_bf16 v[64:67], v[194:197], v[210:213], v[64:67]
	v_mfma_f32_16x16x32_bf16 v[92:95], v[174:177], v[206:209], v[92:95]
	v_mfma_f32_16x16x32_bf16 v[88:91], v[174:177], v[214:217], v[88:91]
	v_mfma_f32_16x16x32_bf16 v[84:87], v[182:185], v[206:209], v[84:87]
	v_mfma_f32_16x16x32_bf16 v[80:83], v[182:185], v[214:217], v[80:83]
	v_mfma_f32_16x16x32_bf16 v[76:79], v[190:193], v[206:209], v[76:79]
	v_mfma_f32_16x16x32_bf16 v[72:75], v[190:193], v[214:217], v[72:75]
	v_mfma_f32_16x16x32_bf16 v[68:71], v[198:201], v[206:209], v[68:71]
	v_mfma_f32_16x16x32_bf16 v[64:67], v[198:201], v[214:217], v[64:67]
	s_setprio 0
	s_barrier
	ds_read_b128 v[170:173], v129 offset:16384
	ds_read_b128 v[174:177], v129 offset:17408
	ds_read_b128 v[178:181], v129 offset:18432
	ds_read_b128 v[182:185], v129 offset:19456
	ds_read_b128 v[186:189], v129 offset:20480
	ds_read_b128 v[190:193], v129 offset:21504
	ds_read_b128 v[194:197], v129 offset:22528
	ds_read_b128 v[198:201], v129 offset:23552
	s_mov_b32 m0, s97
	v_lshl_add_u64 v[226:227], v[218:219], 0, s[8:9]
	global_load_lds_dwordx4 v[226:227], off
	s_mov_b32 m0, s92
	v_lshl_add_u64 v[222:223], v[218:219], 0, s[10:11]
	global_load_lds_dwordx4 v[222:223], off
	s_mov_b32 m0, s31
	v_lshl_add_u64 v[224:225], v[142:143], 0, s[8:9]
	global_load_lds_dwordx4 v[224:225], off
	s_mov_b32 m0, s94
	v_lshl_add_u64 v[226:227], v[142:143], 0, s[10:11]
	global_load_lds_dwordx4 v[226:227], off
	s_waitcnt vmcnt(6)
	s_waitcnt lgkmcnt(0)
	s_barrier
	s_setprio 1
	v_mfma_f32_16x16x32_bf16 v[60:63], v[170:173], v[148:151], v[60:63]
	v_mfma_f32_16x16x32_bf16 v[56:59], v[170:173], v[162:165], v[56:59]
	v_mfma_f32_16x16x32_bf16 v[52:55], v[178:181], v[148:151], v[52:55]
	v_mfma_f32_16x16x32_bf16 v[48:51], v[178:181], v[162:165], v[48:51]
	v_mfma_f32_16x16x32_bf16 v[44:47], v[186:189], v[148:151], v[44:47]
	v_mfma_f32_16x16x32_bf16 v[40:43], v[186:189], v[162:165], v[40:43]
	v_mfma_f32_16x16x32_bf16 v[36:39], v[194:197], v[148:151], v[36:39]
	v_mfma_f32_16x16x32_bf16 v[32:35], v[194:197], v[162:165], v[32:35]
	v_mfma_f32_16x16x32_bf16 v[60:63], v[174:177], v[152:155], v[60:63]
	v_mfma_f32_16x16x32_bf16 v[56:59], v[174:177], v[166:169], v[56:59]
	v_mfma_f32_16x16x32_bf16 v[52:55], v[182:185], v[152:155], v[52:55]
	v_mfma_f32_16x16x32_bf16 v[48:51], v[182:185], v[166:169], v[48:51]
	v_mfma_f32_16x16x32_bf16 v[44:47], v[190:193], v[152:155], v[44:47]
	v_mfma_f32_16x16x32_bf16 v[40:43], v[190:193], v[166:169], v[40:43]
	v_mfma_f32_16x16x32_bf16 v[36:39], v[198:201], v[152:155], v[36:39]
	v_mfma_f32_16x16x32_bf16 v[32:35], v[198:201], v[166:169], v[32:35]
	v_mfma_f32_16x16x32_bf16 v[28:31], v[170:173], v[202:205], v[28:31]
	v_mfma_f32_16x16x32_bf16 v[24:27], v[170:173], v[210:213], v[24:27]
	v_mfma_f32_16x16x32_bf16 v[20:23], v[178:181], v[202:205], v[20:23]
	v_mfma_f32_16x16x32_bf16 v[16:19], v[178:181], v[210:213], v[16:19]
	v_mfma_f32_16x16x32_bf16 v[12:15], v[186:189], v[202:205], v[12:15]
	v_mfma_f32_16x16x32_bf16 v[8:11], v[186:189], v[210:213], v[8:11]
	v_mfma_f32_16x16x32_bf16 v[4:7], v[194:197], v[202:205], v[4:7]
	v_mfma_f32_16x16x32_bf16 v[0:3], v[194:197], v[210:213], v[0:3]
	v_mfma_f32_16x16x32_bf16 v[28:31], v[174:177], v[206:209], v[28:31]
	v_mfma_f32_16x16x32_bf16 v[24:27], v[174:177], v[214:217], v[24:27]
	v_mfma_f32_16x16x32_bf16 v[20:23], v[182:185], v[206:209], v[20:23]
	v_mfma_f32_16x16x32_bf16 v[16:19], v[182:185], v[214:217], v[16:19]
	v_mfma_f32_16x16x32_bf16 v[12:15], v[190:193], v[206:209], v[12:15]
	v_mfma_f32_16x16x32_bf16 v[8:11], v[190:193], v[214:217], v[8:11]
	v_mfma_f32_16x16x32_bf16 v[4:7], v[198:201], v[206:209], v[4:7]
	v_mfma_f32_16x16x32_bf16 v[0:3], v[198:201], v[214:217], v[0:3]
	s_setprio 0
	s_barrier
; #define STAGE(P, BASE, br, kt) do { const char* _g = (const char*)((BASE) + (size_t)(br) * K + (size_t)(kt) * G_BK); \
;     _Pragma("unroll") for (int _i = 0; _i < 2; ++_i) { \
;       __builtin_amdgcn_global_load_lds((const unsigned*)(_g + (size_t)_i * 128 * K + sg_off), (unsigned*)((char*)(P) + wid * 1024 + _i * 8192), 16, 0, 0); } } while (0)
; #define LDA(dst, b, h) _Pragma("unroll") for (int m = 0; m < 4; ++m) _Pragma("unroll") for (int k = 0; k < 2; ++k) \
;     dst[m][k] = *reinterpret_cast<const bf16x8*>((const char*)shm + aoff + (((b) * 2 + (h)) * 16384 + m * 2048 + k * 1024))
; #define LDB(dst, b, h) _Pragma("unroll") for (int n = 0; n < 2; ++n) _Pragma("unroll") for (int k = 0; k < 2; ++k) \
;     dst[n][k] = *reinterpret_cast<const bf16x8*>((const char*)shm + boff + (((b) * 2 + (h)) * 16384 + n * 2048 + k * 1024))
; #define MMA(ai, bj, At, Bt_) do { __builtin_amdgcn_s_setprio(1); \
;     _Pragma("unroll") for (int m = 0; m < 4; ++m) _Pragma("unroll") for (int n = 0; n < 2; ++n) _Pragma("unroll") for (int k = 0; k < 2; ++k) \
;       acc[ai][bj][m][n] = mfma16(At[m][k], Bt_[n][k], acc[ai][bj][m][n]); \
;     __builtin_amdgcn_s_setprio(0); } while (0)
; #define WAIT_V(n) asm volatile("s_waitcnt vmcnt(" #n ")" ::: "memory")
; #define WAIT_L(n) asm volatile("s_waitcnt lgkmcnt(" #n ")" ::: "memory")
; #define BAR __builtin_amdgcn_s_barrier()
; #define SCHED __builtin_amdgcn_sched_barrier(0)
; template <class Epi>
; __device__ __forceinline__ void gemm_phase(const bfr* __restrict__ A, int lda, const bfr* __restrict__ Bt, int K,
;                                            int nM, int nN, const Epi& epi, bfr* shm, int wv, int nMfull, int ksplit) {
;     ...
;       LDB(B0, 1, 0); SCHED; LDA(At, 1, 0); STAGE(SA(0, 1), Ak, brow + G_HALF, t + 2);
;       WAIT_L(8); BAR; WAIT_L(0); MMA(0, 0, At, B0); BAR; SCHED;
;       LDB(B1, 1, 1); STAGE(SB(1, 0), Bk, bcol, t + 3);
;       BAR; WAIT_L(0); MMA(0, 1, At, B1); BAR;
;       LDA(At, 1, 1); STAGE(SA(1, 0), Ak, brow, t + 3);
;       BAR; WAIT_L(0); MMA(1, 0, At, B0); BAR; SCHED;
;       STAGE(SB(1, 1), Bk, bcol + G_HALF, t + 3);
;       WAIT_V(6); BAR; MMA(1, 1, At, B1); BAR;
;     }
	ds_read_b128 v[148:151], v137 offset:32768
	ds_read_b128 v[152:155], v137 offset:33792
	ds_read_b128 v[162:165], v137 offset:34816
	ds_read_b128 v[166:169], v137 offset:35840
	ds_read_b128 v[170:173], v129 offset:32768
	ds_read_b128 v[174:177], v129 offset:33792
	ds_read_b128 v[178:181], v129 offset:34816
	ds_read_b128 v[182:185], v129 offset:35840
	ds_read_b128 v[186:189], v129 offset:36864
	ds_read_b128 v[190:193], v129 offset:37888
	ds_read_b128 v[194:197], v129 offset:38912
	ds_read_b128 v[198:201], v129 offset:39936
	ds_read_b128 v[202:205], v137 offset:49152
	ds_read_b128 v[206:209], v137 offset:50176
	ds_read_b128 v[210:213], v137 offset:51200
	ds_read_b128 v[214:217], v137 offset:52224
	s_mov_b32 m0, s91
	v_lshl_add_u64 v[222:223], v[218:219], 0, s[12:13]
	global_load_lds_dwordx4 v[222:223], off
	s_mov_b32 m0, s93
	v_lshl_add_u64 v[224:225], v[218:219], 0, s[14:15]
	global_load_lds_dwordx4 v[224:225], off
	s_mov_b32 m0, s22
	v_lshl_add_u64 v[226:227], v[142:143], 0, s[12:13]
	global_load_lds_dwordx4 v[226:227], off
	s_mov_b32 m0, s23
	v_lshl_add_u64 v[222:223], v[142:143], 0, s[14:15]
	global_load_lds_dwordx4 v[222:223], off
	s_waitcnt vmcnt(8)
	s_waitcnt lgkmcnt(0)
	s_barrier
	s_setprio 1
	v_mfma_f32_16x16x32_bf16 v[124:127], v[170:173], v[148:151], v[124:127]
	v_mfma_f32_16x16x32_bf16 v[120:123], v[170:173], v[162:165], v[120:123]
	v_mfma_f32_16x16x32_bf16 v[116:119], v[178:181], v[148:151], v[116:119]
	v_mfma_f32_16x16x32_bf16 v[112:115], v[178:181], v[162:165], v[112:115]
	v_mfma_f32_16x16x32_bf16 v[108:111], v[186:189], v[148:151], v[108:111]
	v_mfma_f32_16x16x32_bf16 v[104:107], v[186:189], v[162:165], v[104:107]
	v_mfma_f32_16x16x32_bf16 v[100:103], v[194:197], v[148:151], v[100:103]
	v_mfma_f32_16x16x32_bf16 v[96:99], v[194:197], v[162:165], v[96:99]
	v_mfma_f32_16x16x32_bf16 v[124:127], v[174:177], v[152:155], v[124:127]
	v_mfma_f32_16x16x32_bf16 v[120:123], v[174:177], v[166:169], v[120:123]
	v_mfma_f32_16x16x32_bf16 v[116:119], v[182:185], v[152:155], v[116:119]
	v_mfma_f32_16x16x32_bf16 v[112:115], v[182:185], v[166:169], v[112:115]
	v_mfma_f32_16x16x32_bf16 v[108:111], v[190:193], v[152:155], v[108:111]
	v_mfma_f32_16x16x32_bf16 v[104:107], v[190:193], v[166:169], v[104:107]
	v_mfma_f32_16x16x32_bf16 v[100:103], v[198:201], v[152:155], v[100:103]
	v_mfma_f32_16x16x32_bf16 v[96:99], v[198:201], v[166:169], v[96:99]
	v_mfma_f32_16x16x32_bf16 v[92:95], v[170:173], v[202:205], v[92:95]
	v_mfma_f32_16x16x32_bf16 v[88:91], v[170:173], v[210:213], v[88:91]
	v_mfma_f32_16x16x32_bf16 v[84:87], v[178:181], v[202:205], v[84:87]
	v_mfma_f32_16x16x32_bf16 v[80:83], v[178:181], v[210:213], v[80:83]
	v_mfma_f32_16x16x32_bf16 v[76:79], v[186:189], v[202:205], v[76:79]
	v_mfma_f32_16x16x32_bf16 v[72:75], v[186:189], v[210:213], v[72:75]
	v_mfma_f32_16x16x32_bf16 v[68:71], v[194:197], v[202:205], v[68:71]
	v_mfma_f32_16x16x32_bf16 v[64:67], v[194:197], v[210:213], v[64:67]
	v_mfma_f32_16x16x32_bf16 v[92:95], v[174:177], v[206:209], v[92:95]
	v_mfma_f32_16x16x32_bf16 v[88:91], v[174:177], v[214:217], v[88:91]
	v_mfma_f32_16x16x32_bf16 v[84:87], v[182:185], v[206:209], v[84:87]
	v_mfma_f32_16x16x32_bf16 v[80:83], v[182:185], v[214:217], v[80:83]
	v_mfma_f32_16x16x32_bf16 v[76:79], v[190:193], v[206:209], v[76:79]
	v_mfma_f32_16x16x32_bf16 v[72:75], v[190:193], v[214:217], v[72:75]
	v_mfma_f32_16x16x32_bf16 v[68:71], v[198:201], v[206:209], v[68:71]
	v_mfma_f32_16x16x32_bf16 v[64:67], v[198:201], v[214:217], v[64:67]
	s_setprio 0
	s_barrier
	ds_read_b128 v[170:173], v129 offset:49152
	ds_read_b128 v[174:177], v129 offset:50176
	ds_read_b128 v[178:181], v129 offset:51200
	ds_read_b128 v[182:185], v129 offset:52224
	ds_read_b128 v[186:189], v129 offset:53248
	ds_read_b128 v[190:193], v129 offset:54272
	ds_read_b128 v[194:197], v129 offset:55296
	ds_read_b128 v[198:201], v129 offset:56320
	s_mov_b32 m0, s24
	v_lshl_add_u64 v[224:225], v[218:219], 0, s[16:17]
	global_load_lds_dwordx4 v[224:225], off
	s_mov_b32 m0, s25
	v_lshl_add_u64 v[226:227], v[218:219], 0, s[18:19]
	global_load_lds_dwordx4 v[226:227], off
	s_mov_b32 m0, s28
	v_lshl_add_u64 v[222:223], v[142:143], 0, s[16:17]
	global_load_lds_dwordx4 v[222:223], off
	s_mov_b32 m0, s20
	v_lshl_add_u64 v[224:225], v[142:143], 0, s[18:19]
	global_load_lds_dwordx4 v[224:225], off
	s_mov_b32 m0, s21
	s_mov_b64 s[42:43], 0x40180
	v_lshl_add_u64 v[226:227], v[218:219], 0, s[42:43]
	global_load_lds_dwordx4 v[226:227], off
	s_mov_b32 m0, s29
	s_mov_b64 s[42:43], 0x60180
	v_lshl_add_u64 v[222:223], v[218:219], 0, s[42:43]
	global_load_lds_dwordx4 v[222:223], off
	s_waitcnt vmcnt(6)
	s_waitcnt lgkmcnt(0)
	s_barrier
	s_setprio 1
	v_mfma_f32_16x16x32_bf16 v[60:63], v[170:173], v[148:151], v[60:63]
	v_mfma_f32_16x16x32_bf16 v[56:59], v[170:173], v[162:165], v[56:59]
	v_mfma_f32_16x16x32_bf16 v[52:55], v[178:181], v[148:151], v[52:55]
	v_mfma_f32_16x16x32_bf16 v[48:51], v[178:181], v[162:165], v[48:51]
	v_mfma_f32_16x16x32_bf16 v[44:47], v[186:189], v[148:151], v[44:47]
	v_mfma_f32_16x16x32_bf16 v[40:43], v[186:189], v[162:165], v[40:43]
	v_mfma_f32_16x16x32_bf16 v[36:39], v[194:197], v[148:151], v[36:39]
	v_mfma_f32_16x16x32_bf16 v[32:35], v[194:197], v[162:165], v[32:35]
	v_mfma_f32_16x16x32_bf16 v[60:63], v[174:177], v[152:155], v[60:63]
	v_mfma_f32_16x16x32_bf16 v[56:59], v[174:177], v[166:169], v[56:59]
	v_mfma_f32_16x16x32_bf16 v[52:55], v[182:185], v[152:155], v[52:55]
	v_mfma_f32_16x16x32_bf16 v[48:51], v[182:185], v[166:169], v[48:51]
	v_mfma_f32_16x16x32_bf16 v[44:47], v[190:193], v[152:155], v[44:47]
	v_mfma_f32_16x16x32_bf16 v[40:43], v[190:193], v[166:169], v[40:43]
	v_mfma_f32_16x16x32_bf16 v[36:39], v[198:201], v[152:155], v[36:39]
	v_mfma_f32_16x16x32_bf16 v[32:35], v[198:201], v[166:169], v[32:35]
	v_mfma_f32_16x16x32_bf16 v[28:31], v[170:173], v[202:205], v[28:31]
	v_mfma_f32_16x16x32_bf16 v[24:27], v[170:173], v[210:213], v[24:27]
	v_mfma_f32_16x16x32_bf16 v[20:23], v[178:181], v[202:205], v[20:23]
	v_mfma_f32_16x16x32_bf16 v[16:19], v[178:181], v[210:213], v[16:19]
	v_mfma_f32_16x16x32_bf16 v[12:15], v[186:189], v[202:205], v[12:15]
	v_mfma_f32_16x16x32_bf16 v[8:11], v[186:189], v[210:213], v[8:11]
	v_mfma_f32_16x16x32_bf16 v[4:7], v[194:197], v[202:205], v[4:7]
	v_mfma_f32_16x16x32_bf16 v[0:3], v[194:197], v[210:213], v[0:3]
	v_mfma_f32_16x16x32_bf16 v[28:31], v[174:177], v[206:209], v[28:31]
	v_mfma_f32_16x16x32_bf16 v[24:27], v[174:177], v[214:217], v[24:27]
	v_mfma_f32_16x16x32_bf16 v[20:23], v[182:185], v[206:209], v[20:23]
	v_mfma_f32_16x16x32_bf16 v[16:19], v[182:185], v[214:217], v[16:19]
	v_mfma_f32_16x16x32_bf16 v[12:15], v[190:193], v[206:209], v[12:15]
	v_mfma_f32_16x16x32_bf16 v[8:11], v[190:193], v[214:217], v[8:11]
	v_mfma_f32_16x16x32_bf16 v[4:7], v[198:201], v[206:209], v[4:7]
	v_mfma_f32_16x16x32_bf16 v[0:3], v[198:201], v[214:217], v[0:3]
	s_setprio 0
	s_add_i32 s40, s40, 2
	s_add_u32 s2, s2, 0x100
	s_addc_u32 s3, s3, 0
	s_add_u32 s36, s36, 0x100
	s_addc_u32 s37, s37, 0
	s_cmp_ge_i32 s40, s39
	s_barrier
	s_cbranch_scc0 .LBB0_1086

; #define WAIT_V(n) asm volatile("s_waitcnt vmcnt(" #n ")" ::: "memory")
; #define BAR __builtin_amdgcn_s_barrier()
; template <class Epi>
; __device__ __forceinline__ void gemm_phase(const bfr* __restrict__ A, int lda, const bfr* __restrict__ Bt, int K,
;                                            int nM, int nN, const Epi& epi, bfr* shm, int wv, int nMfull, int ksplit) {
;     ...
;     f32x4 acc[2][2][4][2];
; #pragma unroll
;     for (int a = 0; a < 2; a++)
; #pragma unroll
;       for (int b = 0; b < 2; b++)
; #pragma unroll
;         for (int m = 0; m < 4; m++)
; #pragma unroll
;           for (int n = 0; n < 2; n++) acc[a][b][m][n] = f32x4{0.f, 0.f, 0.f, 0.f};
;     bf16x8 At[4][2], B0[2][2], B1[2][2];
;     if (wr == 1) BAR;
;     WAIT_V(10); BAR;
;     WAIT_V(6); BAR;
;     for (int t = 0; t < nt - 2; t += 2) {
.LBB0_1214:
	s_waitcnt vmcnt(8)
	s_barrier
	s_waitcnt vmcnt(6)
	v_mov_b32_e32 v127, 0
	s_cmp_lt_u32 s38, 3
	v_mov_b32_e32 v126, v127
	v_mov_b32_e32 v125, v127
	v_mov_b32_e32 v124, v127
	v_mov_b32_e32 v123, v127
	v_mov_b32_e32 v122, v127
	v_mov_b32_e32 v121, v127
	v_mov_b32_e32 v120, v127
	v_mov_b32_e32 v119, v127
	v_mov_b32_e32 v118, v127
	v_mov_b32_e32 v117, v127
	v_mov_b32_e32 v116, v127
	v_mov_b32_e32 v115, v127
	v_mov_b32_e32 v114, v127
	v_mov_b32_e32 v113, v127
	v_mov_b32_e32 v112, v127
	v_mov_b32_e32 v111, v127
	v_mov_b32_e32 v110, v127
	v_mov_b32_e32 v109, v127
	v_mov_b32_e32 v108, v127
	v_mov_b32_e32 v107, v127
	v_mov_b32_e32 v106, v127
	v_mov_b32_e32 v105, v127
	v_mov_b32_e32 v104, v127
	v_mov_b32_e32 v103, v127
	v_mov_b32_e32 v102, v127
	v_mov_b32_e32 v101, v127
	v_mov_b32_e32 v100, v127
	v_mov_b32_e32 v99, v127
	v_mov_b32_e32 v98, v127
	v_mov_b32_e32 v97, v127
	v_mov_b32_e32 v96, v127
	v_mov_b32_e32 v95, v127
	v_mov_b32_e32 v94, v127
	v_mov_b32_e32 v93, v127
	v_mov_b32_e32 v92, v127
	v_mov_b32_e32 v91, v127
	v_mov_b32_e32 v90, v127
	v_mov_b32_e32 v89, v127
	v_mov_b32_e32 v88, v127
	v_mov_b32_e32 v87, v127
	v_mov_b32_e32 v86, v127
	v_mov_b32_e32 v85, v127
	v_mov_b32_e32 v84, v127
	v_mov_b32_e32 v83, v127
	v_mov_b32_e32 v82, v127
	v_mov_b32_e32 v81, v127
	v_mov_b32_e32 v80, v127
	v_mov_b32_e32 v79, v127
	v_mov_b32_e32 v78, v127
	v_mov_b32_e32 v77, v127
	v_mov_b32_e32 v76, v127
	v_mov_b32_e32 v75, v127
	v_mov_b32_e32 v74, v127
	v_mov_b32_e32 v73, v127
	v_mov_b32_e32 v72, v127
	v_mov_b32_e32 v71, v127
	v_mov_b32_e32 v70, v127
	v_mov_b32_e32 v69, v127
	v_mov_b32_e32 v68, v127
	v_mov_b32_e32 v67, v127
	v_mov_b32_e32 v66, v127
	v_mov_b32_e32 v65, v127
	v_mov_b32_e32 v64, v127
	v_mov_b32_e32 v63, v127
	v_mov_b32_e32 v62, v127
	v_mov_b32_e32 v61, v127
	v_mov_b32_e32 v60, v127
	v_mov_b32_e32 v59, v127
	v_mov_b32_e32 v58, v127
	v_mov_b32_e32 v57, v127
	v_mov_b32_e32 v56, v127
	v_mov_b32_e32 v55, v127
	v_mov_b32_e32 v54, v127
	v_mov_b32_e32 v53, v127
	v_mov_b32_e32 v52, v127
	v_mov_b32_e32 v51, v127
	v_mov_b32_e32 v50, v127
	v_mov_b32_e32 v49, v127
	v_mov_b32_e32 v48, v127
	v_mov_b32_e32 v47, v127
	v_mov_b32_e32 v46, v127
	v_mov_b32_e32 v45, v127
	v_mov_b32_e32 v44, v127
	v_mov_b32_e32 v43, v127
	v_mov_b32_e32 v42, v127
	v_mov_b32_e32 v41, v127
	v_mov_b32_e32 v40, v127
	v_mov_b32_e32 v39, v127
	v_mov_b32_e32 v38, v127
	v_mov_b32_e32 v37, v127
	v_mov_b32_e32 v36, v127
	v_mov_b32_e32 v35, v127
	v_mov_b32_e32 v34, v127
	v_mov_b32_e32 v33, v127
	v_mov_b32_e32 v32, v127
	v_mov_b32_e32 v31, v127
	v_mov_b32_e32 v30, v127
	v_mov_b32_e32 v29, v127
	v_mov_b32_e32 v28, v127
	v_mov_b32_e32 v27, v127
	v_mov_b32_e32 v26, v127
	v_mov_b32_e32 v25, v127
	v_mov_b32_e32 v24, v127
	v_mov_b32_e32 v23, v127
	v_mov_b32_e32 v22, v127
	v_mov_b32_e32 v21, v127
	v_mov_b32_e32 v20, v127
	v_mov_b32_e32 v19, v127
	v_mov_b32_e32 v18, v127
	v_mov_b32_e32 v17, v127
	v_mov_b32_e32 v16, v127
	v_mov_b32_e32 v15, v127
	v_mov_b32_e32 v14, v127
	v_mov_b32_e32 v13, v127
	v_mov_b32_e32 v12, v127
	v_mov_b32_e32 v11, v127
	v_mov_b32_e32 v10, v127
	v_mov_b32_e32 v9, v127
	v_mov_b32_e32 v8, v127
	v_mov_b32_e32 v7, v127
	v_mov_b32_e32 v6, v127
	v_mov_b32_e32 v5, v127
	v_mov_b32_e32 v4, v127
	v_mov_b32_e32 v3, v127
	v_mov_b32_e32 v2, v127
	v_mov_b32_e32 v1, v127
	v_mov_b32_e32 v0, v127
	s_barrier
	s_cbranch_scc1 .LBB0_1217
	s_ashr_i32 s49, s48, 31
	s_ashr_i32 s41, s40, 31
	v_readlane_b32 s4, v254, 54
	s_add_i32 s31, s38, -2
	s_lshl_b64 s[42:43], s[48:49], 11
	s_lshl_b64 s[44:45], s[40:41], 11
	v_readlane_b32 s16, v255, 2
	v_readlane_b32 s5, v254, 55
	v_readlane_b32 s6, v254, 56
	v_readlane_b32 s7, v254, 57
	v_readlane_b32 s8, v254, 58
	v_readlane_b32 s9, v254, 59
	v_readlane_b32 s10, v254, 60
	v_readlane_b32 s11, v254, 61
	v_readlane_b32 s12, v254, 62
	v_readlane_b32 s13, v254, 63
	v_readlane_b32 s14, v255, 0
	v_readlane_b32 s15, v255, 1
	v_readlane_b32 s17, v255, 3
	v_readlane_b32 s18, v255, 4
	v_readlane_b32 s19, v255, 5
	s_add_u32 s42, s16, s42
	s_addc_u32 s43, s17, s43
	v_readlane_b32 s4, v255, 10
	v_readlane_b32 s12, v255, 18
	v_readlane_b32 s13, v255, 19
	s_add_u32 s44, s12, s44
	v_mov_b32_e32 v0, 0
	s_addc_u32 s45, s13, s45
	s_mov_b32 s39, 0
	v_readlane_b32 s5, v255, 11
	v_readlane_b32 s6, v255, 12
	v_readlane_b32 s7, v255, 13
	v_readlane_b32 s8, v255, 14
	v_readlane_b32 s9, v255, 15
	v_readlane_b32 s10, v255, 16
	v_readlane_b32 s11, v255, 17
	v_readlane_b32 s14, v255, 20
	v_readlane_b32 s15, v255, 21
	v_readlane_b32 s16, v255, 22
	v_readlane_b32 s17, v255, 23
	v_readlane_b32 s18, v255, 24
	v_readlane_b32 s19, v255, 25
; #define STAGE(P, BASE, br, kt) do { const char* _g = (const char*)((BASE) + (size_t)(br) * K + (size_t)(kt) * G_BK); \
;     _Pragma("unroll") for (int _i = 0; _i < 2; ++_i) { \
;       __builtin_amdgcn_global_load_lds((const unsigned*)(_g + (size_t)_i * 128 * K + sg_off), (unsigned*)((char*)(P) + wid * 1024 + _i * 8192), 16, 0, 0); } } while (0)
; #define LDA(dst, b, h) _Pragma("unroll") for (int m = 0; m < 4; ++m) _Pragma("unroll") for (int k = 0; k < 2; ++k) \
;     dst[m][k] = *reinterpret_cast<const bf16x8*>((const char*)shm + aoff + (((b) * 2 + (h)) * 16384 + m * 2048 + k * 1024))
; #define LDB(dst, b, h) _Pragma("unroll") for (int n = 0; n < 2; ++n) _Pragma("unroll") for (int k = 0; k < 2; ++k) \
;     dst[n][k] = *reinterpret_cast<const bf16x8*>((const char*)shm + boff + (((b) * 2 + (h)) * 16384 + n * 2048 + k * 1024))
; #define MMA(ai, bj, At, Bt_) do { __builtin_amdgcn_s_setprio(1); \
;     _Pragma("unroll") for (int m = 0; m < 4; ++m) _Pragma("unroll") for (int n = 0; n < 2; ++n) _Pragma("unroll") for (int k = 0; k < 2; ++k) \
;       acc[ai][bj][m][n] = mfma16(At[m][k], Bt_[n][k], acc[ai][bj][m][n]); \
;     __builtin_amdgcn_s_setprio(0); } while (0)
; #define WAIT_V(n) asm volatile("s_waitcnt vmcnt(" #n ")" ::: "memory")
; #define WAIT_L(n) asm volatile("s_waitcnt lgkmcnt(" #n ")" ::: "memory")
; #define BAR __builtin_amdgcn_s_barrier()
; #define SCHED __builtin_amdgcn_sched_barrier(0)
; template <class Epi>
; __device__ __forceinline__ void gemm_phase(const bfr* __restrict__ A, int lda, const bfr* __restrict__ Bt, int K,
;                                            int nM, int nN, const Epi& epi, bfr* shm, int wv, int nMfull, int ksplit) {
;     ...
;       LDB(B0, 0, 0); SCHED; LDA(At, 0, 0); STAGE(SA(1, 1), Ak, brow + G_HALF, t + 1);
;       WAIT_L(8); BAR; WAIT_L(0); MMA(0, 0, At, B0); BAR; SCHED;
;       LDB(B1, 0, 1); STAGE(SB(0, 0), Bk, bcol, t + 2);
;       BAR; WAIT_L(0); MMA(0, 1, At, B1); BAR;
;       LDA(At, 0, 1); STAGE(SA(0, 0), Ak, brow, t + 2);
;       BAR; WAIT_L(0); MMA(1, 0, At, B0); BAR; SCHED;
;       STAGE(SB(0, 1), Bk, bcol + G_HALF, t + 2);
;       WAIT_V(6); BAR; MMA(1, 1, At, B1); BAR;
.LBB0_1216:
	ds_read_b128 v[142:145], v169
	ds_read_b128 v[146:149], v169 offset:1024
	ds_read_b128 v[150:153], v169 offset:2048
	ds_read_b128 v[154:157], v169 offset:3072
	ds_read_b128 v[158:161], v168
	ds_read_b128 v[162:165], v168 offset:1024
	ds_read_b128 v[174:177], v168 offset:2048
	ds_read_b128 v[178:181], v168 offset:3072
	ds_read_b128 v[182:185], v168 offset:4096
	ds_read_b128 v[186:189], v168 offset:5120
	ds_read_b128 v[190:193], v168 offset:6144
	ds_read_b128 v[194:197], v168 offset:7168
	ds_read_b128 v[198:201], v169 offset:16384
	ds_read_b128 v[202:205], v169 offset:17408
	ds_read_b128 v[206:209], v169 offset:18432
	ds_read_b128 v[210:213], v169 offset:19456
	v_lshl_add_u64 v[166:167], s[44:45], 0, v[140:141]
	v_lshl_add_u64 v[214:215], s[42:43], 0, v[140:141]
	s_mov_b32 m0, s82
	s_mov_b64 s[46:47], 0x40080
	v_lshl_add_u64 v[218:219], v[166:167], 0, s[46:47]
	global_load_lds_dwordx4 v[218:219], off
	s_mov_b32 m0, s83
	s_mov_b64 s[46:47], 0x60080
	v_lshl_add_u64 v[220:221], v[166:167], 0, s[46:47]
	global_load_lds_dwordx4 v[220:221], off
	s_waitcnt lgkmcnt(0)
	s_barrier
	s_setprio 1
	v_mfma_f32_16x16x32_bf16 v[124:127], v[158:161], v[142:145], v[124:127]
	v_mfma_f32_16x16x32_bf16 v[120:123], v[158:161], v[150:153], v[120:123]
	v_mfma_f32_16x16x32_bf16 v[116:119], v[174:177], v[142:145], v[116:119]
	v_mfma_f32_16x16x32_bf16 v[112:115], v[174:177], v[150:153], v[112:115]
	v_mfma_f32_16x16x32_bf16 v[108:111], v[182:185], v[142:145], v[108:111]
	v_mfma_f32_16x16x32_bf16 v[104:107], v[182:185], v[150:153], v[104:107]
	v_mfma_f32_16x16x32_bf16 v[100:103], v[190:193], v[142:145], v[100:103]
	v_mfma_f32_16x16x32_bf16 v[96:99], v[190:193], v[150:153], v[96:99]
	v_mfma_f32_16x16x32_bf16 v[124:127], v[162:165], v[146:149], v[124:127]
	v_mfma_f32_16x16x32_bf16 v[120:123], v[162:165], v[154:157], v[120:123]
	v_mfma_f32_16x16x32_bf16 v[116:119], v[178:181], v[146:149], v[116:119]
	v_mfma_f32_16x16x32_bf16 v[112:115], v[178:181], v[154:157], v[112:115]
	v_mfma_f32_16x16x32_bf16 v[108:111], v[186:189], v[146:149], v[108:111]
	v_mfma_f32_16x16x32_bf16 v[104:107], v[186:189], v[154:157], v[104:107]
	v_mfma_f32_16x16x32_bf16 v[100:103], v[194:197], v[146:149], v[100:103]
	v_mfma_f32_16x16x32_bf16 v[96:99], v[194:197], v[154:157], v[96:99]
	v_mfma_f32_16x16x32_bf16 v[92:95], v[158:161], v[198:201], v[92:95]
	v_mfma_f32_16x16x32_bf16 v[88:91], v[158:161], v[206:209], v[88:91]
	v_mfma_f32_16x16x32_bf16 v[84:87], v[174:177], v[198:201], v[84:87]
	v_mfma_f32_16x16x32_bf16 v[80:83], v[174:177], v[206:209], v[80:83]
	v_mfma_f32_16x16x32_bf16 v[76:79], v[182:185], v[198:201], v[76:79]
	v_mfma_f32_16x16x32_bf16 v[72:75], v[182:185], v[206:209], v[72:75]
	v_mfma_f32_16x16x32_bf16 v[68:71], v[190:193], v[198:201], v[68:71]
	v_mfma_f32_16x16x32_bf16 v[64:67], v[190:193], v[206:209], v[64:67]
	v_mfma_f32_16x16x32_bf16 v[92:95], v[162:165], v[202:205], v[92:95]
	v_mfma_f32_16x16x32_bf16 v[88:91], v[162:165], v[210:213], v[88:91]
	v_mfma_f32_16x16x32_bf16 v[84:87], v[178:181], v[202:205], v[84:87]
	v_mfma_f32_16x16x32_bf16 v[80:83], v[178:181], v[210:213], v[80:83]
	v_mfma_f32_16x16x32_bf16 v[76:79], v[186:189], v[202:205], v[76:79]
	v_mfma_f32_16x16x32_bf16 v[72:75], v[186:189], v[210:213], v[72:75]
	v_mfma_f32_16x16x32_bf16 v[68:71], v[194:197], v[202:205], v[68:71]
	v_mfma_f32_16x16x32_bf16 v[64:67], v[194:197], v[210:213], v[64:67]
	s_setprio 0
	s_barrier
	ds_read_b128 v[158:161], v168 offset:16384
	ds_read_b128 v[162:165], v168 offset:17408
	ds_read_b128 v[174:177], v168 offset:18432
	ds_read_b128 v[178:181], v168 offset:19456
	ds_read_b128 v[182:185], v168 offset:20480
	ds_read_b128 v[186:189], v168 offset:21504
	ds_read_b128 v[190:193], v168 offset:22528
	ds_read_b128 v[194:197], v168 offset:23552
	s_mov_b32 m0, s84
	v_lshl_add_u64 v[222:223], v[214:215], 0, s[78:79]
	global_load_lds_dwordx4 v[222:223], off
	s_mov_b32 m0, s85
	v_lshl_add_u64 v[218:219], v[214:215], 0, s[80:81]
	global_load_lds_dwordx4 v[218:219], off
	s_mov_b32 m0, s71
	v_lshl_add_u64 v[220:221], v[166:167], 0, s[78:79]
	global_load_lds_dwordx4 v[220:221], off
	s_mov_b32 m0, s87
	v_lshl_add_u64 v[222:223], v[166:167], 0, s[80:81]
	global_load_lds_dwordx4 v[222:223], off
	s_waitcnt vmcnt(6)
	s_waitcnt lgkmcnt(0)
	s_barrier
	s_setprio 1
	v_mfma_f32_16x16x32_bf16 v[60:63], v[158:161], v[142:145], v[60:63]
	v_mfma_f32_16x16x32_bf16 v[56:59], v[158:161], v[150:153], v[56:59]
	v_mfma_f32_16x16x32_bf16 v[52:55], v[174:177], v[142:145], v[52:55]
	v_mfma_f32_16x16x32_bf16 v[48:51], v[174:177], v[150:153], v[48:51]
	v_mfma_f32_16x16x32_bf16 v[44:47], v[182:185], v[142:145], v[44:47]
	v_mfma_f32_16x16x32_bf16 v[40:43], v[182:185], v[150:153], v[40:43]
	v_mfma_f32_16x16x32_bf16 v[36:39], v[190:193], v[142:145], v[36:39]
	v_mfma_f32_16x16x32_bf16 v[32:35], v[190:193], v[150:153], v[32:35]
	v_mfma_f32_16x16x32_bf16 v[60:63], v[162:165], v[146:149], v[60:63]
	v_mfma_f32_16x16x32_bf16 v[56:59], v[162:165], v[154:157], v[56:59]
	v_mfma_f32_16x16x32_bf16 v[52:55], v[178:181], v[146:149], v[52:55]
	v_mfma_f32_16x16x32_bf16 v[48:51], v[178:181], v[154:157], v[48:51]
	v_mfma_f32_16x16x32_bf16 v[44:47], v[186:189], v[146:149], v[44:47]
	v_mfma_f32_16x16x32_bf16 v[40:43], v[186:189], v[154:157], v[40:43]
	v_mfma_f32_16x16x32_bf16 v[36:39], v[194:197], v[146:149], v[36:39]
	v_mfma_f32_16x16x32_bf16 v[32:35], v[194:197], v[154:157], v[32:35]
	v_mfma_f32_16x16x32_bf16 v[28:31], v[158:161], v[198:201], v[28:31]
	v_mfma_f32_16x16x32_bf16 v[24:27], v[158:161], v[206:209], v[24:27]
	v_mfma_f32_16x16x32_bf16 v[20:23], v[174:177], v[198:201], v[20:23]
	v_mfma_f32_16x16x32_bf16 v[16:19], v[174:177], v[206:209], v[16:19]
	v_mfma_f32_16x16x32_bf16 v[12:15], v[182:185], v[198:201], v[12:15]
	v_mfma_f32_16x16x32_bf16 v[8:11], v[182:185], v[206:209], v[8:11]
	v_mfma_f32_16x16x32_bf16 v[4:7], v[190:193], v[198:201], v[4:7]
	v_mfma_f32_16x16x32_bf16 v[0:3], v[190:193], v[206:209], v[0:3]
	v_mfma_f32_16x16x32_bf16 v[28:31], v[162:165], v[202:205], v[28:31]
	v_mfma_f32_16x16x32_bf16 v[24:27], v[162:165], v[210:213], v[24:27]
	v_mfma_f32_16x16x32_bf16 v[20:23], v[178:181], v[202:205], v[20:23]
	v_mfma_f32_16x16x32_bf16 v[16:19], v[178:181], v[210:213], v[16:19]
	v_mfma_f32_16x16x32_bf16 v[12:15], v[186:189], v[202:205], v[12:15]
	v_mfma_f32_16x16x32_bf16 v[8:11], v[186:189], v[210:213], v[8:11]
	v_mfma_f32_16x16x32_bf16 v[4:7], v[194:197], v[202:205], v[4:7]
	v_mfma_f32_16x16x32_bf16 v[0:3], v[194:197], v[210:213], v[0:3]
	s_setprio 0
	s_barrier
; #define STAGE(P, BASE, br, kt) do { const char* _g = (const char*)((BASE) + (size_t)(br) * K + (size_t)(kt) * G_BK); \
;     _Pragma("unroll") for (int _i = 0; _i < 2; ++_i) { \
;       __builtin_amdgcn_global_load_lds((const unsigned*)(_g + (size_t)_i * 128 * K + sg_off), (unsigned*)((char*)(P) + wid * 1024 + _i * 8192), 16, 0, 0); } } while (0)
; #define LDA(dst, b, h) _Pragma("unroll") for (int m = 0; m < 4; ++m) _Pragma("unroll") for (int k = 0; k < 2; ++k) \
;     dst[m][k] = *reinterpret_cast<const bf16x8*>((const char*)shm + aoff + (((b) * 2 + (h)) * 16384 + m * 2048 + k * 1024))
; #define LDB(dst, b, h) _Pragma("unroll") for (int n = 0; n < 2; ++n) _Pragma("unroll") for (int k = 0; k < 2; ++k) \
;     dst[n][k] = *reinterpret_cast<const bf16x8*>((const char*)shm + boff + (((b) * 2 + (h)) * 16384 + n * 2048 + k * 1024))
; #define MMA(ai, bj, At, Bt_) do { __builtin_amdgcn_s_setprio(1); \
;     _Pragma("unroll") for (int m = 0; m < 4; ++m) _Pragma("unroll") for (int n = 0; n < 2; ++n) _Pragma("unroll") for (int k = 0; k < 2; ++k) \
;       acc[ai][bj][m][n] = mfma16(At[m][k], Bt_[n][k], acc[ai][bj][m][n]); \
;     __builtin_amdgcn_s_setprio(0); } while (0)
; #define WAIT_V(n) asm volatile("s_waitcnt vmcnt(" #n ")" ::: "memory")
; #define WAIT_L(n) asm volatile("s_waitcnt lgkmcnt(" #n ")" ::: "memory")
; #define BAR __builtin_amdgcn_s_barrier()
; #define SCHED __builtin_amdgcn_sched_barrier(0)
; template <class Epi>
; __device__ __forceinline__ void gemm_phase(const bfr* __restrict__ A, int lda, const bfr* __restrict__ Bt, int K,
;                                            int nM, int nN, const Epi& epi, bfr* shm, int wv, int nMfull, int ksplit) {
;     ...
;       LDB(B0, 1, 0); SCHED; LDA(At, 1, 0); STAGE(SA(0, 1), Ak, brow + G_HALF, t + 2);
;       WAIT_L(8); BAR; WAIT_L(0); MMA(0, 0, At, B0); BAR; SCHED;
;       LDB(B1, 1, 1); STAGE(SB(1, 0), Bk, bcol, t + 3);
;       BAR; WAIT_L(0); MMA(0, 1, At, B1); BAR;
;       LDA(At, 1, 1); STAGE(SA(1, 0), Ak, brow, t + 3);
;       BAR; WAIT_L(0); MMA(1, 0, At, B0); BAR; SCHED;
;       STAGE(SB(1, 1), Bk, bcol + G_HALF, t + 3);
;       WAIT_V(6); BAR; MMA(1, 1, At, B1); BAR;
;     }
	ds_read_b128 v[142:145], v169 offset:32768
	ds_read_b128 v[146:149], v169 offset:33792
	ds_read_b128 v[150:153], v169 offset:34816
	ds_read_b128 v[154:157], v169 offset:35840
	ds_read_b128 v[158:161], v168 offset:32768
	ds_read_b128 v[162:165], v168 offset:33792
	ds_read_b128 v[174:177], v168 offset:34816
	ds_read_b128 v[178:181], v168 offset:35840
	ds_read_b128 v[182:185], v168 offset:36864
	ds_read_b128 v[186:189], v168 offset:37888
	ds_read_b128 v[190:193], v168 offset:38912
	ds_read_b128 v[194:197], v168 offset:39936
	ds_read_b128 v[198:201], v169 offset:49152
	ds_read_b128 v[202:205], v169 offset:50176
	ds_read_b128 v[206:209], v169 offset:51200
	ds_read_b128 v[210:213], v169 offset:52224
	s_mov_b32 m0, s90
	v_lshl_add_u64 v[218:219], v[214:215], 0, s[88:89]
	global_load_lds_dwordx4 v[218:219], off
	s_mov_b32 m0, s91
	v_lshl_add_u64 v[220:221], v[214:215], 0, s[34:35]
	global_load_lds_dwordx4 v[220:221], off
	s_mov_b32 m0, s92
	v_lshl_add_u64 v[222:223], v[166:167], 0, s[88:89]
	global_load_lds_dwordx4 v[222:223], off
	s_mov_b32 m0, s93
	v_lshl_add_u64 v[218:219], v[166:167], 0, s[34:35]
	global_load_lds_dwordx4 v[218:219], off
	s_waitcnt vmcnt(8)
	s_waitcnt lgkmcnt(0)
	s_barrier
	s_setprio 1
	v_mfma_f32_16x16x32_bf16 v[124:127], v[158:161], v[142:145], v[124:127]
	v_mfma_f32_16x16x32_bf16 v[120:123], v[158:161], v[150:153], v[120:123]
	v_mfma_f32_16x16x32_bf16 v[116:119], v[174:177], v[142:145], v[116:119]
	v_mfma_f32_16x16x32_bf16 v[112:115], v[174:177], v[150:153], v[112:115]
	v_mfma_f32_16x16x32_bf16 v[108:111], v[182:185], v[142:145], v[108:111]
	v_mfma_f32_16x16x32_bf16 v[104:107], v[182:185], v[150:153], v[104:107]
	v_mfma_f32_16x16x32_bf16 v[100:103], v[190:193], v[142:145], v[100:103]
	v_mfma_f32_16x16x32_bf16 v[96:99], v[190:193], v[150:153], v[96:99]
	v_mfma_f32_16x16x32_bf16 v[124:127], v[162:165], v[146:149], v[124:127]
	v_mfma_f32_16x16x32_bf16 v[120:123], v[162:165], v[154:157], v[120:123]
	v_mfma_f32_16x16x32_bf16 v[116:119], v[178:181], v[146:149], v[116:119]
	v_mfma_f32_16x16x32_bf16 v[112:115], v[178:181], v[154:157], v[112:115]
	v_mfma_f32_16x16x32_bf16 v[108:111], v[186:189], v[146:149], v[108:111]
	v_mfma_f32_16x16x32_bf16 v[104:107], v[186:189], v[154:157], v[104:107]
	v_mfma_f32_16x16x32_bf16 v[100:103], v[194:197], v[146:149], v[100:103]
	v_mfma_f32_16x16x32_bf16 v[96:99], v[194:197], v[154:157], v[96:99]
	v_mfma_f32_16x16x32_bf16 v[92:95], v[158:161], v[198:201], v[92:95]
	v_mfma_f32_16x16x32_bf16 v[88:91], v[158:161], v[206:209], v[88:91]
	v_mfma_f32_16x16x32_bf16 v[84:87], v[174:177], v[198:201], v[84:87]
	v_mfma_f32_16x16x32_bf16 v[80:83], v[174:177], v[206:209], v[80:83]
	v_mfma_f32_16x16x32_bf16 v[76:79], v[182:185], v[198:201], v[76:79]
	v_mfma_f32_16x16x32_bf16 v[72:75], v[182:185], v[206:209], v[72:75]
	v_mfma_f32_16x16x32_bf16 v[68:71], v[190:193], v[198:201], v[68:71]
	v_mfma_f32_16x16x32_bf16 v[64:67], v[190:193], v[206:209], v[64:67]
	v_mfma_f32_16x16x32_bf16 v[92:95], v[162:165], v[202:205], v[92:95]
	v_mfma_f32_16x16x32_bf16 v[88:91], v[162:165], v[210:213], v[88:91]
	v_mfma_f32_16x16x32_bf16 v[84:87], v[178:181], v[202:205], v[84:87]
	v_mfma_f32_16x16x32_bf16 v[80:83], v[178:181], v[210:213], v[80:83]
	v_mfma_f32_16x16x32_bf16 v[76:79], v[186:189], v[202:205], v[76:79]
	v_mfma_f32_16x16x32_bf16 v[72:75], v[186:189], v[210:213], v[72:75]
	v_mfma_f32_16x16x32_bf16 v[68:71], v[194:197], v[202:205], v[68:71]
	v_mfma_f32_16x16x32_bf16 v[64:67], v[194:197], v[210:213], v[64:67]
	s_setprio 0
	s_barrier
	ds_read_b128 v[158:161], v168 offset:49152
	ds_read_b128 v[162:165], v168 offset:50176
	ds_read_b128 v[174:177], v168 offset:51200
	ds_read_b128 v[178:181], v168 offset:52224
	ds_read_b128 v[182:185], v168 offset:53248
	ds_read_b128 v[186:189], v168 offset:54272
	ds_read_b128 v[190:193], v168 offset:55296
	ds_read_b128 v[194:197], v168 offset:56320
	s_mov_b32 m0, s94
	v_lshl_add_u64 v[220:221], v[214:215], 0, s[20:21]
	global_load_lds_dwordx4 v[220:221], off
	s_mov_b32 m0, s95
	v_lshl_add_u64 v[222:223], v[214:215], 0, s[22:23]
	global_load_lds_dwordx4 v[222:223], off
	s_mov_b32 m0, s96
	v_lshl_add_u64 v[218:219], v[166:167], 0, s[20:21]
	global_load_lds_dwordx4 v[218:219], off
	s_mov_b32 m0, s97
	v_lshl_add_u64 v[220:221], v[166:167], 0, s[22:23]
	global_load_lds_dwordx4 v[220:221], off
	s_mov_b32 m0, s0
	s_mov_b64 s[46:47], 0x40180
	v_lshl_add_u64 v[222:223], v[214:215], 0, s[46:47]
	global_load_lds_dwordx4 v[222:223], off
	s_mov_b32 m0, s1
	s_mov_b64 s[46:47], 0x60180
	v_lshl_add_u64 v[218:219], v[214:215], 0, s[46:47]
	global_load_lds_dwordx4 v[218:219], off
	s_waitcnt vmcnt(6)
	s_waitcnt lgkmcnt(0)
	s_barrier
	s_setprio 1
	v_mfma_f32_16x16x32_bf16 v[60:63], v[158:161], v[142:145], v[60:63]
	v_mfma_f32_16x16x32_bf16 v[56:59], v[158:161], v[150:153], v[56:59]
	v_mfma_f32_16x16x32_bf16 v[52:55], v[174:177], v[142:145], v[52:55]
	v_mfma_f32_16x16x32_bf16 v[48:51], v[174:177], v[150:153], v[48:51]
	v_mfma_f32_16x16x32_bf16 v[44:47], v[182:185], v[142:145], v[44:47]
	v_mfma_f32_16x16x32_bf16 v[40:43], v[182:185], v[150:153], v[40:43]
	v_mfma_f32_16x16x32_bf16 v[36:39], v[190:193], v[142:145], v[36:39]
	v_mfma_f32_16x16x32_bf16 v[32:35], v[190:193], v[150:153], v[32:35]
	v_mfma_f32_16x16x32_bf16 v[60:63], v[162:165], v[146:149], v[60:63]
	v_mfma_f32_16x16x32_bf16 v[56:59], v[162:165], v[154:157], v[56:59]
	v_mfma_f32_16x16x32_bf16 v[52:55], v[178:181], v[146:149], v[52:55]
	v_mfma_f32_16x16x32_bf16 v[48:51], v[178:181], v[154:157], v[48:51]
	v_mfma_f32_16x16x32_bf16 v[44:47], v[186:189], v[146:149], v[44:47]
	v_mfma_f32_16x16x32_bf16 v[40:43], v[186:189], v[154:157], v[40:43]
	v_mfma_f32_16x16x32_bf16 v[36:39], v[194:197], v[146:149], v[36:39]
	v_mfma_f32_16x16x32_bf16 v[32:35], v[194:197], v[154:157], v[32:35]
	v_mfma_f32_16x16x32_bf16 v[28:31], v[158:161], v[198:201], v[28:31]
	v_mfma_f32_16x16x32_bf16 v[24:27], v[158:161], v[206:209], v[24:27]
	v_mfma_f32_16x16x32_bf16 v[20:23], v[174:177], v[198:201], v[20:23]
	v_mfma_f32_16x16x32_bf16 v[16:19], v[174:177], v[206:209], v[16:19]
	v_mfma_f32_16x16x32_bf16 v[12:15], v[182:185], v[198:201], v[12:15]
	v_mfma_f32_16x16x32_bf16 v[8:11], v[182:185], v[206:209], v[8:11]
	v_mfma_f32_16x16x32_bf16 v[4:7], v[190:193], v[198:201], v[4:7]
	v_mfma_f32_16x16x32_bf16 v[0:3], v[190:193], v[206:209], v[0:3]
	v_mfma_f32_16x16x32_bf16 v[28:31], v[162:165], v[202:205], v[28:31]
	v_mfma_f32_16x16x32_bf16 v[24:27], v[162:165], v[210:213], v[24:27]
	v_mfma_f32_16x16x32_bf16 v[20:23], v[178:181], v[202:205], v[20:23]
	v_mfma_f32_16x16x32_bf16 v[16:19], v[178:181], v[210:213], v[16:19]
	v_mfma_f32_16x16x32_bf16 v[12:15], v[186:189], v[202:205], v[12:15]
	v_mfma_f32_16x16x32_bf16 v[8:11], v[186:189], v[210:213], v[8:11]
	v_mfma_f32_16x16x32_bf16 v[4:7], v[194:197], v[202:205], v[4:7]
	v_mfma_f32_16x16x32_bf16 v[0:3], v[194:197], v[210:213], v[0:3]
	s_setprio 0
	s_add_i32 s39, s39, 2
	s_add_u32 s42, s42, 0x100
	s_addc_u32 s43, s43, 0
	s_add_u32 s44, s44, 0x100
	s_addc_u32 s45, s45, 0
	s_cmp_ge_i32 s39, s31
	s_barrier
	s_cbranch_scc0 .LBB0_1216

; #define WAIT_V(n) asm volatile("s_waitcnt vmcnt(" #n ")" ::: "memory")
; #define BAR __builtin_amdgcn_s_barrier()
; template <class Epi>
; __device__ __forceinline__ void gemm_phase(const bfr* __restrict__ A, int lda, const bfr* __restrict__ Bt, int K,
;                                            int nM, int nN, const Epi& epi, bfr* shm, int wv, int nMfull, int ksplit) {
;     ...
;     f32x4 acc[2][2][4][2];
; #pragma unroll
;     for (int a = 0; a < 2; a++)
; #pragma unroll
;       for (int b = 0; b < 2; b++)
; #pragma unroll
;         for (int m = 0; m < 4; m++)
; #pragma unroll
;           for (int n = 0; n < 2; n++) acc[a][b][m][n] = f32x4{0.f, 0.f, 0.f, 0.f};
;     bf16x8 At[4][2], B0[2][2], B1[2][2];
;     if (wr == 1) BAR;
;     WAIT_V(10); BAR;
;     WAIT_V(6); BAR;
;     for (int t = 0; t < nt - 2; t += 2) {
.LBB0_1325:
	s_waitcnt vmcnt(8)
	s_barrier
	s_waitcnt vmcnt(6)
	v_mov_b32_e32 v127, 0
	s_cmp_lt_u32 s48, 3
	v_mov_b32_e32 v126, v127
	v_mov_b32_e32 v125, v127
	v_mov_b32_e32 v124, v127
	v_mov_b32_e32 v123, v127
	v_mov_b32_e32 v122, v127
	v_mov_b32_e32 v121, v127
	v_mov_b32_e32 v120, v127
	v_mov_b32_e32 v119, v127
	v_mov_b32_e32 v118, v127
	v_mov_b32_e32 v117, v127
	v_mov_b32_e32 v116, v127
	v_mov_b32_e32 v115, v127
	v_mov_b32_e32 v114, v127
	v_mov_b32_e32 v113, v127
	v_mov_b32_e32 v112, v127
	v_mov_b32_e32 v111, v127
	v_mov_b32_e32 v110, v127
	v_mov_b32_e32 v109, v127
	v_mov_b32_e32 v108, v127
	v_mov_b32_e32 v107, v127
	v_mov_b32_e32 v106, v127
	v_mov_b32_e32 v105, v127
	v_mov_b32_e32 v104, v127
	v_mov_b32_e32 v103, v127
	v_mov_b32_e32 v102, v127
	v_mov_b32_e32 v101, v127
	v_mov_b32_e32 v100, v127
	v_mov_b32_e32 v99, v127
	v_mov_b32_e32 v98, v127
	v_mov_b32_e32 v97, v127
	v_mov_b32_e32 v96, v127
	v_mov_b32_e32 v95, v127
	v_mov_b32_e32 v94, v127
	v_mov_b32_e32 v93, v127
	v_mov_b32_e32 v92, v127
	v_mov_b32_e32 v91, v127
	v_mov_b32_e32 v90, v127
	v_mov_b32_e32 v89, v127
	v_mov_b32_e32 v88, v127
	v_mov_b32_e32 v87, v127
	v_mov_b32_e32 v86, v127
	v_mov_b32_e32 v85, v127
	v_mov_b32_e32 v84, v127
	v_mov_b32_e32 v83, v127
	v_mov_b32_e32 v82, v127
	v_mov_b32_e32 v81, v127
	v_mov_b32_e32 v80, v127
	v_mov_b32_e32 v79, v127
	v_mov_b32_e32 v78, v127
	v_mov_b32_e32 v77, v127
	v_mov_b32_e32 v76, v127
	v_mov_b32_e32 v75, v127
	v_mov_b32_e32 v74, v127
	v_mov_b32_e32 v73, v127
	v_mov_b32_e32 v72, v127
	v_mov_b32_e32 v71, v127
	v_mov_b32_e32 v70, v127
	v_mov_b32_e32 v69, v127
	v_mov_b32_e32 v68, v127
	v_mov_b32_e32 v67, v127
	v_mov_b32_e32 v66, v127
	v_mov_b32_e32 v65, v127
	v_mov_b32_e32 v64, v127
	v_mov_b32_e32 v63, v127
	v_mov_b32_e32 v62, v127
	v_mov_b32_e32 v61, v127
	v_mov_b32_e32 v60, v127
	v_mov_b32_e32 v59, v127
	v_mov_b32_e32 v58, v127
	v_mov_b32_e32 v57, v127
	v_mov_b32_e32 v56, v127
	v_mov_b32_e32 v55, v127
	v_mov_b32_e32 v54, v127
	v_mov_b32_e32 v53, v127
	v_mov_b32_e32 v52, v127
	v_mov_b32_e32 v51, v127
	v_mov_b32_e32 v50, v127
	v_mov_b32_e32 v49, v127
	v_mov_b32_e32 v48, v127
	v_mov_b32_e32 v47, v127
	v_mov_b32_e32 v46, v127
	v_mov_b32_e32 v45, v127
	v_mov_b32_e32 v44, v127
	v_mov_b32_e32 v43, v127
	v_mov_b32_e32 v42, v127
	v_mov_b32_e32 v41, v127
	v_mov_b32_e32 v40, v127
	v_mov_b32_e32 v39, v127
	v_mov_b32_e32 v38, v127
	v_mov_b32_e32 v37, v127
	v_mov_b32_e32 v36, v127
	v_mov_b32_e32 v35, v127
	v_mov_b32_e32 v34, v127
	v_mov_b32_e32 v33, v127
	v_mov_b32_e32 v32, v127
	v_mov_b32_e32 v31, v127
	v_mov_b32_e32 v30, v127
	v_mov_b32_e32 v29, v127
	v_mov_b32_e32 v28, v127
	v_mov_b32_e32 v27, v127
	v_mov_b32_e32 v26, v127
	v_mov_b32_e32 v25, v127
	v_mov_b32_e32 v24, v127
	v_mov_b32_e32 v23, v127
	v_mov_b32_e32 v22, v127
	v_mov_b32_e32 v21, v127
	v_mov_b32_e32 v20, v127
	v_mov_b32_e32 v19, v127
	v_mov_b32_e32 v18, v127
	v_mov_b32_e32 v17, v127
	v_mov_b32_e32 v16, v127
	v_mov_b32_e32 v15, v127
	v_mov_b32_e32 v14, v127
	v_mov_b32_e32 v13, v127
	v_mov_b32_e32 v12, v127
	v_mov_b32_e32 v11, v127
	v_mov_b32_e32 v10, v127
	v_mov_b32_e32 v9, v127
	v_mov_b32_e32 v8, v127
	v_mov_b32_e32 v7, v127
	v_mov_b32_e32 v6, v127
	v_mov_b32_e32 v5, v127
	v_mov_b32_e32 v4, v127
	v_mov_b32_e32 v3, v127
	v_mov_b32_e32 v2, v127
	v_mov_b32_e32 v1, v127
	v_mov_b32_e32 v0, v127
	s_barrier
	s_cbranch_scc1 .LBB0_1328
	s_ashr_i32 s59, s58, 31
	s_ashr_i32 s5, s4, 31
	v_readlane_b32 s60, v254, 54
	s_add_i32 s0, s48, -2
	s_lshl_b64 s[50:51], s[58:59], 11
	s_lshl_b64 s[52:53], s[4:5], 11
	v_readlane_b32 s62, v254, 56
	v_readlane_b32 s61, v254, 55
	v_readlane_b32 s63, v254, 57
	v_readlane_b32 s64, v254, 58
	v_readlane_b32 s65, v254, 59
	v_readlane_b32 s66, v254, 60
	v_readlane_b32 s67, v254, 61
	v_readlane_b32 s68, v254, 62
	v_readlane_b32 s69, v254, 63
	v_readlane_b32 s70, v255, 0
	v_readlane_b32 s71, v255, 1
	v_readlane_b32 s72, v255, 2
	v_readlane_b32 s73, v255, 3
	v_readlane_b32 s74, v255, 4
	v_readlane_b32 s75, v255, 5
	s_add_u32 s50, s62, s50
	s_addc_u32 s51, s63, s51
	v_readlane_b32 s60, v255, 10
	v_readlane_b32 s64, v255, 14
	v_readlane_b32 s65, v255, 15
	s_add_u32 s52, s64, s52
	v_mov_b32_e32 v0, 0
	s_addc_u32 s53, s65, s53
	s_mov_b32 s1, 0
	v_readlane_b32 s61, v255, 11
	v_readlane_b32 s62, v255, 12
	v_readlane_b32 s63, v255, 13
	v_readlane_b32 s66, v255, 16
	v_readlane_b32 s67, v255, 17
	v_readlane_b32 s68, v255, 18
	v_readlane_b32 s69, v255, 19
	v_readlane_b32 s70, v255, 20
	v_readlane_b32 s71, v255, 21
	v_readlane_b32 s72, v255, 22
	v_readlane_b32 s73, v255, 23
	v_readlane_b32 s74, v255, 24
	v_readlane_b32 s75, v255, 25
; #define STAGE(P, BASE, br, kt) do { const char* _g = (const char*)((BASE) + (size_t)(br) * K + (size_t)(kt) * G_BK); \
;     _Pragma("unroll") for (int _i = 0; _i < 2; ++_i) { \
;       __builtin_amdgcn_global_load_lds((const unsigned*)(_g + (size_t)_i * 128 * K + sg_off), (unsigned*)((char*)(P) + wid * 1024 + _i * 8192), 16, 0, 0); } } while (0)
; #define LDA(dst, b, h) _Pragma("unroll") for (int m = 0; m < 4; ++m) _Pragma("unroll") for (int k = 0; k < 2; ++k) \
;     dst[m][k] = *reinterpret_cast<const bf16x8*>((const char*)shm + aoff + (((b) * 2 + (h)) * 16384 + m * 2048 + k * 1024))
; #define LDB(dst, b, h) _Pragma("unroll") for (int n = 0; n < 2; ++n) _Pragma("unroll") for (int k = 0; k < 2; ++k) \
;     dst[n][k] = *reinterpret_cast<const bf16x8*>((const char*)shm + boff + (((b) * 2 + (h)) * 16384 + n * 2048 + k * 1024))
; #define MMA(ai, bj, At, Bt_) do { __builtin_amdgcn_s_setprio(1); \
;     _Pragma("unroll") for (int m = 0; m < 4; ++m) _Pragma("unroll") for (int n = 0; n < 2; ++n) _Pragma("unroll") for (int k = 0; k < 2; ++k) \
;       acc[ai][bj][m][n] = mfma16(At[m][k], Bt_[n][k], acc[ai][bj][m][n]); \
;     __builtin_amdgcn_s_setprio(0); } while (0)
; #define WAIT_V(n) asm volatile("s_waitcnt vmcnt(" #n ")" ::: "memory")
; #define WAIT_L(n) asm volatile("s_waitcnt lgkmcnt(" #n ")" ::: "memory")
; #define BAR __builtin_amdgcn_s_barrier()
; #define SCHED __builtin_amdgcn_sched_barrier(0)
; template <class Epi>
; __device__ __forceinline__ void gemm_phase(const bfr* __restrict__ A, int lda, const bfr* __restrict__ Bt, int K,
;                                            int nM, int nN, const Epi& epi, bfr* shm, int wv, int nMfull, int ksplit) {
;     ...
;       LDB(B0, 0, 0); SCHED; LDA(At, 0, 0); STAGE(SA(1, 1), Ak, brow + G_HALF, t + 1);
;       WAIT_L(8); BAR; WAIT_L(0); MMA(0, 0, At, B0); BAR; SCHED;
;       LDB(B1, 0, 1); STAGE(SB(0, 0), Bk, bcol, t + 2);
;       BAR; WAIT_L(0); MMA(0, 1, At, B1); BAR;
;       LDA(At, 0, 1); STAGE(SA(0, 0), Ak, brow, t + 2);
;       BAR; WAIT_L(0); MMA(1, 0, At, B0); BAR; SCHED;
;       STAGE(SB(0, 1), Bk, bcol + G_HALF, t + 2);
;       WAIT_V(6); BAR; MMA(1, 1, At, B1); BAR;
.LBB0_1327:
	ds_read_b128 v[136:139], v143
	ds_read_b128 v[148:151], v143 offset:1024
	ds_read_b128 v[152:155], v143 offset:2048
	ds_read_b128 v[156:159], v143 offset:3072
	ds_read_b128 v[160:163], v142
	ds_read_b128 v[164:167], v142 offset:1024
	ds_read_b128 v[168:171], v142 offset:2048
	ds_read_b128 v[172:175], v142 offset:3072
	ds_read_b128 v[176:179], v142 offset:4096
	ds_read_b128 v[180:183], v142 offset:5120
	ds_read_b128 v[184:187], v142 offset:6144
	ds_read_b128 v[188:191], v142 offset:7168
	ds_read_b128 v[192:195], v143 offset:16384
	ds_read_b128 v[196:199], v143 offset:17408
	ds_read_b128 v[200:203], v143 offset:18432
	ds_read_b128 v[204:207], v143 offset:19456
	v_lshl_add_u64 v[140:141], s[52:53], 0, v[134:135]
	v_lshl_add_u64 v[208:209], s[50:51], 0, v[134:135]
	s_mov_b32 m0, s90
	s_mov_b64 s[54:55], 0x40080
	v_lshl_add_u64 v[212:213], v[140:141], 0, s[54:55]
	global_load_lds_dwordx4 v[212:213], off
	s_mov_b32 m0, s91
	s_mov_b64 s[54:55], 0x60080
	v_lshl_add_u64 v[214:215], v[140:141], 0, s[54:55]
	global_load_lds_dwordx4 v[214:215], off
	s_waitcnt lgkmcnt(0)
	s_barrier
	s_setprio 1
	v_mfma_f32_16x16x32_bf16 v[124:127], v[160:163], v[136:139], v[124:127]
	v_mfma_f32_16x16x32_bf16 v[120:123], v[160:163], v[152:155], v[120:123]
	v_mfma_f32_16x16x32_bf16 v[116:119], v[168:171], v[136:139], v[116:119]
	v_mfma_f32_16x16x32_bf16 v[112:115], v[168:171], v[152:155], v[112:115]
	v_mfma_f32_16x16x32_bf16 v[108:111], v[176:179], v[136:139], v[108:111]
	v_mfma_f32_16x16x32_bf16 v[104:107], v[176:179], v[152:155], v[104:107]
	v_mfma_f32_16x16x32_bf16 v[100:103], v[184:187], v[136:139], v[100:103]
	v_mfma_f32_16x16x32_bf16 v[96:99], v[184:187], v[152:155], v[96:99]
	v_mfma_f32_16x16x32_bf16 v[124:127], v[164:167], v[148:151], v[124:127]
	v_mfma_f32_16x16x32_bf16 v[120:123], v[164:167], v[156:159], v[120:123]
	v_mfma_f32_16x16x32_bf16 v[116:119], v[172:175], v[148:151], v[116:119]
	v_mfma_f32_16x16x32_bf16 v[112:115], v[172:175], v[156:159], v[112:115]
	v_mfma_f32_16x16x32_bf16 v[108:111], v[180:183], v[148:151], v[108:111]
	v_mfma_f32_16x16x32_bf16 v[104:107], v[180:183], v[156:159], v[104:107]
	v_mfma_f32_16x16x32_bf16 v[100:103], v[188:191], v[148:151], v[100:103]
	v_mfma_f32_16x16x32_bf16 v[96:99], v[188:191], v[156:159], v[96:99]
	v_mfma_f32_16x16x32_bf16 v[92:95], v[160:163], v[192:195], v[92:95]
	v_mfma_f32_16x16x32_bf16 v[88:91], v[160:163], v[200:203], v[88:91]
	v_mfma_f32_16x16x32_bf16 v[84:87], v[168:171], v[192:195], v[84:87]
	v_mfma_f32_16x16x32_bf16 v[80:83], v[168:171], v[200:203], v[80:83]
	v_mfma_f32_16x16x32_bf16 v[76:79], v[176:179], v[192:195], v[76:79]
	v_mfma_f32_16x16x32_bf16 v[72:75], v[176:179], v[200:203], v[72:75]
	v_mfma_f32_16x16x32_bf16 v[68:71], v[184:187], v[192:195], v[68:71]
	v_mfma_f32_16x16x32_bf16 v[64:67], v[184:187], v[200:203], v[64:67]
	v_mfma_f32_16x16x32_bf16 v[92:95], v[164:167], v[196:199], v[92:95]
	v_mfma_f32_16x16x32_bf16 v[88:91], v[164:167], v[204:207], v[88:91]
	v_mfma_f32_16x16x32_bf16 v[84:87], v[172:175], v[196:199], v[84:87]
	v_mfma_f32_16x16x32_bf16 v[80:83], v[172:175], v[204:207], v[80:83]
	v_mfma_f32_16x16x32_bf16 v[76:79], v[180:183], v[196:199], v[76:79]
	v_mfma_f32_16x16x32_bf16 v[72:75], v[180:183], v[204:207], v[72:75]
	v_mfma_f32_16x16x32_bf16 v[68:71], v[188:191], v[196:199], v[68:71]
	v_mfma_f32_16x16x32_bf16 v[64:67], v[188:191], v[204:207], v[64:67]
	s_setprio 0
	s_barrier
	ds_read_b128 v[160:163], v142 offset:16384
	ds_read_b128 v[164:167], v142 offset:17408
	ds_read_b128 v[168:171], v142 offset:18432
	ds_read_b128 v[172:175], v142 offset:19456
	ds_read_b128 v[176:179], v142 offset:20480
	ds_read_b128 v[180:183], v142 offset:21504
	ds_read_b128 v[184:187], v142 offset:22528
	ds_read_b128 v[188:191], v142 offset:23552
	s_mov_b32 m0, s7
	s_mov_b64 s[54:55], 0x2100100
	v_lshl_add_u64 v[216:217], v[208:209], 0, s[54:55]
	global_load_lds_dwordx4 v[216:217], off
	s_mov_b32 m0, s78
	s_mov_b64 s[54:55], 0x2120100
	v_lshl_add_u64 v[212:213], v[208:209], 0, s[54:55]
	global_load_lds_dwordx4 v[212:213], off
	s_mov_b32 m0, s6
	s_mov_b64 s[54:55], 0x100
	v_lshl_add_u64 v[214:215], v[140:141], 0, s[54:55]
	global_load_lds_dwordx4 v[214:215], off
	s_mov_b32 m0, s79
	v_lshl_add_u64 v[216:217], v[140:141], 0, s[16:17]
	global_load_lds_dwordx4 v[216:217], off
	s_waitcnt vmcnt(6)
	s_waitcnt lgkmcnt(0)
	s_barrier
	s_setprio 1
	v_mfma_f32_16x16x32_bf16 v[60:63], v[160:163], v[136:139], v[60:63]
	v_mfma_f32_16x16x32_bf16 v[56:59], v[160:163], v[152:155], v[56:59]
	v_mfma_f32_16x16x32_bf16 v[52:55], v[168:171], v[136:139], v[52:55]
	v_mfma_f32_16x16x32_bf16 v[48:51], v[168:171], v[152:155], v[48:51]
	v_mfma_f32_16x16x32_bf16 v[44:47], v[176:179], v[136:139], v[44:47]
	v_mfma_f32_16x16x32_bf16 v[40:43], v[176:179], v[152:155], v[40:43]
	v_mfma_f32_16x16x32_bf16 v[36:39], v[184:187], v[136:139], v[36:39]
	v_mfma_f32_16x16x32_bf16 v[32:35], v[184:187], v[152:155], v[32:35]
	v_mfma_f32_16x16x32_bf16 v[60:63], v[164:167], v[148:151], v[60:63]
	v_mfma_f32_16x16x32_bf16 v[56:59], v[164:167], v[156:159], v[56:59]
	v_mfma_f32_16x16x32_bf16 v[52:55], v[172:175], v[148:151], v[52:55]
	v_mfma_f32_16x16x32_bf16 v[48:51], v[172:175], v[156:159], v[48:51]
	v_mfma_f32_16x16x32_bf16 v[44:47], v[180:183], v[148:151], v[44:47]
	v_mfma_f32_16x16x32_bf16 v[40:43], v[180:183], v[156:159], v[40:43]
	v_mfma_f32_16x16x32_bf16 v[36:39], v[188:191], v[148:151], v[36:39]
	v_mfma_f32_16x16x32_bf16 v[32:35], v[188:191], v[156:159], v[32:35]
	v_mfma_f32_16x16x32_bf16 v[28:31], v[160:163], v[192:195], v[28:31]
	v_mfma_f32_16x16x32_bf16 v[24:27], v[160:163], v[200:203], v[24:27]
	v_mfma_f32_16x16x32_bf16 v[20:23], v[168:171], v[192:195], v[20:23]
	v_mfma_f32_16x16x32_bf16 v[16:19], v[168:171], v[200:203], v[16:19]
	v_mfma_f32_16x16x32_bf16 v[12:15], v[176:179], v[192:195], v[12:15]
	v_mfma_f32_16x16x32_bf16 v[8:11], v[176:179], v[200:203], v[8:11]
	v_mfma_f32_16x16x32_bf16 v[4:7], v[184:187], v[192:195], v[4:7]
	v_mfma_f32_16x16x32_bf16 v[0:3], v[184:187], v[200:203], v[0:3]
	v_mfma_f32_16x16x32_bf16 v[28:31], v[164:167], v[196:199], v[28:31]
	v_mfma_f32_16x16x32_bf16 v[24:27], v[164:167], v[204:207], v[24:27]
	v_mfma_f32_16x16x32_bf16 v[20:23], v[172:175], v[196:199], v[20:23]
	v_mfma_f32_16x16x32_bf16 v[16:19], v[172:175], v[204:207], v[16:19]
	v_mfma_f32_16x16x32_bf16 v[12:15], v[180:183], v[196:199], v[12:15]
	v_mfma_f32_16x16x32_bf16 v[8:11], v[180:183], v[204:207], v[8:11]
	v_mfma_f32_16x16x32_bf16 v[4:7], v[188:191], v[196:199], v[4:7]
	v_mfma_f32_16x16x32_bf16 v[0:3], v[188:191], v[204:207], v[0:3]
	s_setprio 0
	s_barrier
; #define STAGE(P, BASE, br, kt) do { const char* _g = (const char*)((BASE) + (size_t)(br) * K + (size_t)(kt) * G_BK); \
;     _Pragma("unroll") for (int _i = 0; _i < 2; ++_i) { \
;       __builtin_amdgcn_global_load_lds((const unsigned*)(_g + (size_t)_i * 128 * K + sg_off), (unsigned*)((char*)(P) + wid * 1024 + _i * 8192), 16, 0, 0); } } while (0)
; #define LDA(dst, b, h) _Pragma("unroll") for (int m = 0; m < 4; ++m) _Pragma("unroll") for (int k = 0; k < 2; ++k) \
;     dst[m][k] = *reinterpret_cast<const bf16x8*>((const char*)shm + aoff + (((b) * 2 + (h)) * 16384 + m * 2048 + k * 1024))
; #define LDB(dst, b, h) _Pragma("unroll") for (int n = 0; n < 2; ++n) _Pragma("unroll") for (int k = 0; k < 2; ++k) \
;     dst[n][k] = *reinterpret_cast<const bf16x8*>((const char*)shm + boff + (((b) * 2 + (h)) * 16384 + n * 2048 + k * 1024))
; #define MMA(ai, bj, At, Bt_) do { __builtin_amdgcn_s_setprio(1); \
;     _Pragma("unroll") for (int m = 0; m < 4; ++m) _Pragma("unroll") for (int n = 0; n < 2; ++n) _Pragma("unroll") for (int k = 0; k < 2; ++k) \
;       acc[ai][bj][m][n] = mfma16(At[m][k], Bt_[n][k], acc[ai][bj][m][n]); \
;     __builtin_amdgcn_s_setprio(0); } while (0)
; #define WAIT_V(n) asm volatile("s_waitcnt vmcnt(" #n ")" ::: "memory")
; #define WAIT_L(n) asm volatile("s_waitcnt lgkmcnt(" #n ")" ::: "memory")
; #define BAR __builtin_amdgcn_s_barrier()
; #define SCHED __builtin_amdgcn_sched_barrier(0)
; template <class Epi>
; __device__ __forceinline__ void gemm_phase(const bfr* __restrict__ A, int lda, const bfr* __restrict__ Bt, int K,
;                                            int nM, int nN, const Epi& epi, bfr* shm, int wv, int nMfull, int ksplit) {
;     ...
;       LDB(B0, 1, 0); SCHED; LDA(At, 1, 0); STAGE(SA(0, 1), Ak, brow + G_HALF, t + 2);
;       WAIT_L(8); BAR; WAIT_L(0); MMA(0, 0, At, B0); BAR; SCHED;
;       LDB(B1, 1, 1); STAGE(SB(1, 0), Bk, bcol, t + 3);
;       BAR; WAIT_L(0); MMA(0, 1, At, B1); BAR;
;       LDA(At, 1, 1); STAGE(SA(1, 0), Ak, brow, t + 3);
;       BAR; WAIT_L(0); MMA(1, 0, At, B0); BAR; SCHED;
;       STAGE(SB(1, 1), Bk, bcol + G_HALF, t + 3);
;       WAIT_V(6); BAR; MMA(1, 1, At, B1); BAR;
;     }
	ds_read_b128 v[136:139], v143 offset:32768
	ds_read_b128 v[148:151], v143 offset:33792
	ds_read_b128 v[152:155], v143 offset:34816
	ds_read_b128 v[156:159], v143 offset:35840
	ds_read_b128 v[160:163], v142 offset:32768
	ds_read_b128 v[164:167], v142 offset:33792
	ds_read_b128 v[168:171], v142 offset:34816
	ds_read_b128 v[172:175], v142 offset:35840
	ds_read_b128 v[176:179], v142 offset:36864
	ds_read_b128 v[180:183], v142 offset:37888
	ds_read_b128 v[184:187], v142 offset:38912
	ds_read_b128 v[188:191], v142 offset:39936
	ds_read_b128 v[192:195], v143 offset:49152
	ds_read_b128 v[196:199], v143 offset:50176
	ds_read_b128 v[200:203], v143 offset:51200
	ds_read_b128 v[204:207], v143 offset:52224
	s_mov_b32 m0, s80
	v_lshl_add_u64 v[212:213], v[208:209], 0, s[18:19]
	global_load_lds_dwordx4 v[212:213], off
	s_mov_b32 m0, s81
	v_lshl_add_u64 v[214:215], v[208:209], 0, s[20:21]
	global_load_lds_dwordx4 v[214:215], off
	s_mov_b32 m0, s82
	v_lshl_add_u64 v[216:217], v[140:141], 0, s[22:23]
	global_load_lds_dwordx4 v[216:217], off
	s_mov_b32 m0, s83
	v_lshl_add_u64 v[212:213], v[140:141], 0, s[24:25]
	global_load_lds_dwordx4 v[212:213], off
	s_waitcnt vmcnt(8)
	s_waitcnt lgkmcnt(0)
	s_barrier
	s_setprio 1
	v_mfma_f32_16x16x32_bf16 v[124:127], v[160:163], v[136:139], v[124:127]
	v_mfma_f32_16x16x32_bf16 v[120:123], v[160:163], v[152:155], v[120:123]
	v_mfma_f32_16x16x32_bf16 v[116:119], v[168:171], v[136:139], v[116:119]
	v_mfma_f32_16x16x32_bf16 v[112:115], v[168:171], v[152:155], v[112:115]
	v_mfma_f32_16x16x32_bf16 v[108:111], v[176:179], v[136:139], v[108:111]
	v_mfma_f32_16x16x32_bf16 v[104:107], v[176:179], v[152:155], v[104:107]
	v_mfma_f32_16x16x32_bf16 v[100:103], v[184:187], v[136:139], v[100:103]
	v_mfma_f32_16x16x32_bf16 v[96:99], v[184:187], v[152:155], v[96:99]
	v_mfma_f32_16x16x32_bf16 v[124:127], v[164:167], v[148:151], v[124:127]
	v_mfma_f32_16x16x32_bf16 v[120:123], v[164:167], v[156:159], v[120:123]
	v_mfma_f32_16x16x32_bf16 v[116:119], v[172:175], v[148:151], v[116:119]
	v_mfma_f32_16x16x32_bf16 v[112:115], v[172:175], v[156:159], v[112:115]
	v_mfma_f32_16x16x32_bf16 v[108:111], v[180:183], v[148:151], v[108:111]
	v_mfma_f32_16x16x32_bf16 v[104:107], v[180:183], v[156:159], v[104:107]
	v_mfma_f32_16x16x32_bf16 v[100:103], v[188:191], v[148:151], v[100:103]
	v_mfma_f32_16x16x32_bf16 v[96:99], v[188:191], v[156:159], v[96:99]
	v_mfma_f32_16x16x32_bf16 v[92:95], v[160:163], v[192:195], v[92:95]
	v_mfma_f32_16x16x32_bf16 v[88:91], v[160:163], v[200:203], v[88:91]
	v_mfma_f32_16x16x32_bf16 v[84:87], v[168:171], v[192:195], v[84:87]
	v_mfma_f32_16x16x32_bf16 v[80:83], v[168:171], v[200:203], v[80:83]
	v_mfma_f32_16x16x32_bf16 v[76:79], v[176:179], v[192:195], v[76:79]
	v_mfma_f32_16x16x32_bf16 v[72:75], v[176:179], v[200:203], v[72:75]
	v_mfma_f32_16x16x32_bf16 v[68:71], v[184:187], v[192:195], v[68:71]
	v_mfma_f32_16x16x32_bf16 v[64:67], v[184:187], v[200:203], v[64:67]
	v_mfma_f32_16x16x32_bf16 v[92:95], v[164:167], v[196:199], v[92:95]
	v_mfma_f32_16x16x32_bf16 v[88:91], v[164:167], v[204:207], v[88:91]
	v_mfma_f32_16x16x32_bf16 v[84:87], v[172:175], v[196:199], v[84:87]
	v_mfma_f32_16x16x32_bf16 v[80:83], v[172:175], v[204:207], v[80:83]
	v_mfma_f32_16x16x32_bf16 v[76:79], v[180:183], v[196:199], v[76:79]
	v_mfma_f32_16x16x32_bf16 v[72:75], v[180:183], v[204:207], v[72:75]
	v_mfma_f32_16x16x32_bf16 v[68:71], v[188:191], v[196:199], v[68:71]
	v_mfma_f32_16x16x32_bf16 v[64:67], v[188:191], v[204:207], v[64:67]
	s_setprio 0
	s_barrier
	ds_read_b128 v[160:163], v142 offset:49152
	ds_read_b128 v[164:167], v142 offset:50176
	ds_read_b128 v[168:171], v142 offset:51200
	ds_read_b128 v[172:175], v142 offset:52224
	ds_read_b128 v[176:179], v142 offset:53248
	ds_read_b128 v[180:183], v142 offset:54272
	ds_read_b128 v[184:187], v142 offset:55296
	ds_read_b128 v[188:191], v142 offset:56320
	s_mov_b32 m0, s84
	v_lshl_add_u64 v[214:215], v[208:209], 0, s[26:27]
	global_load_lds_dwordx4 v[214:215], off
	s_mov_b32 m0, s85
	v_lshl_add_u64 v[216:217], v[208:209], 0, s[28:29]
	global_load_lds_dwordx4 v[216:217], off
	s_mov_b32 m0, s86
	v_lshl_add_u64 v[212:213], v[140:141], 0, s[30:31]
	global_load_lds_dwordx4 v[212:213], off
	s_mov_b32 m0, s87
	v_lshl_add_u64 v[214:215], v[140:141], 0, s[34:35]
	global_load_lds_dwordx4 v[214:215], off
	s_mov_b32 m0, s88
	v_lshl_add_u64 v[216:217], v[208:209], 0, s[36:37]
	global_load_lds_dwordx4 v[216:217], off
	s_mov_b32 m0, s89
	v_lshl_add_u64 v[212:213], v[208:209], 0, s[38:39]
	global_load_lds_dwordx4 v[212:213], off
	s_waitcnt vmcnt(6)
	s_waitcnt lgkmcnt(0)
	s_barrier
	s_setprio 1
	v_mfma_f32_16x16x32_bf16 v[60:63], v[160:163], v[136:139], v[60:63]
	v_mfma_f32_16x16x32_bf16 v[56:59], v[160:163], v[152:155], v[56:59]
	v_mfma_f32_16x16x32_bf16 v[52:55], v[168:171], v[136:139], v[52:55]
	v_mfma_f32_16x16x32_bf16 v[48:51], v[168:171], v[152:155], v[48:51]
	v_mfma_f32_16x16x32_bf16 v[44:47], v[176:179], v[136:139], v[44:47]
	v_mfma_f32_16x16x32_bf16 v[40:43], v[176:179], v[152:155], v[40:43]
	v_mfma_f32_16x16x32_bf16 v[36:39], v[184:187], v[136:139], v[36:39]
	v_mfma_f32_16x16x32_bf16 v[32:35], v[184:187], v[152:155], v[32:35]
	v_mfma_f32_16x16x32_bf16 v[60:63], v[164:167], v[148:151], v[60:63]
	v_mfma_f32_16x16x32_bf16 v[56:59], v[164:167], v[156:159], v[56:59]
	v_mfma_f32_16x16x32_bf16 v[52:55], v[172:175], v[148:151], v[52:55]
	v_mfma_f32_16x16x32_bf16 v[48:51], v[172:175], v[156:159], v[48:51]
	v_mfma_f32_16x16x32_bf16 v[44:47], v[180:183], v[148:151], v[44:47]
	v_mfma_f32_16x16x32_bf16 v[40:43], v[180:183], v[156:159], v[40:43]
	v_mfma_f32_16x16x32_bf16 v[36:39], v[188:191], v[148:151], v[36:39]
	v_mfma_f32_16x16x32_bf16 v[32:35], v[188:191], v[156:159], v[32:35]
	v_mfma_f32_16x16x32_bf16 v[28:31], v[160:163], v[192:195], v[28:31]
	v_mfma_f32_16x16x32_bf16 v[24:27], v[160:163], v[200:203], v[24:27]
	v_mfma_f32_16x16x32_bf16 v[20:23], v[168:171], v[192:195], v[20:23]
	v_mfma_f32_16x16x32_bf16 v[16:19], v[168:171], v[200:203], v[16:19]
	v_mfma_f32_16x16x32_bf16 v[12:15], v[176:179], v[192:195], v[12:15]
	v_mfma_f32_16x16x32_bf16 v[8:11], v[176:179], v[200:203], v[8:11]
	v_mfma_f32_16x16x32_bf16 v[4:7], v[184:187], v[192:195], v[4:7]
	v_mfma_f32_16x16x32_bf16 v[0:3], v[184:187], v[200:203], v[0:3]
	v_mfma_f32_16x16x32_bf16 v[28:31], v[164:167], v[196:199], v[28:31]
	v_mfma_f32_16x16x32_bf16 v[24:27], v[164:167], v[204:207], v[24:27]
	v_mfma_f32_16x16x32_bf16 v[20:23], v[172:175], v[196:199], v[20:23]
	v_mfma_f32_16x16x32_bf16 v[16:19], v[172:175], v[204:207], v[16:19]
	v_mfma_f32_16x16x32_bf16 v[12:15], v[180:183], v[196:199], v[12:15]
	v_mfma_f32_16x16x32_bf16 v[8:11], v[180:183], v[204:207], v[8:11]
	v_mfma_f32_16x16x32_bf16 v[4:7], v[188:191], v[196:199], v[4:7]
	v_mfma_f32_16x16x32_bf16 v[0:3], v[188:191], v[204:207], v[0:3]
	s_setprio 0
	s_add_i32 s1, s1, 2
	s_add_u32 s50, s50, 0x100
	s_addc_u32 s51, s51, 0
	s_add_u32 s52, s52, 0x100
	s_addc_u32 s53, s53, 0
	s_cmp_ge_i32 s1, s0
	s_barrier
	s_cbranch_scc0 .LBB0_1327

; #define WAIT_V(n) asm volatile("s_waitcnt vmcnt(" #n ")" ::: "memory")
; #define BAR __builtin_amdgcn_s_barrier()
; template <class Epi>
; __device__ __forceinline__ void gemm_phase(const bfr* __restrict__ A, int lda, const bfr* __restrict__ Bt, int K,
;                                            int nM, int nN, const Epi& epi, bfr* shm, int wv, int nMfull, int ksplit) {
;     ...
;     f32x4 acc[2][2][4][2];
; #pragma unroll
;     for (int a = 0; a < 2; a++)
; #pragma unroll
;       for (int b = 0; b < 2; b++)
; #pragma unroll
;         for (int m = 0; m < 4; m++)
; #pragma unroll
;           for (int n = 0; n < 2; n++) acc[a][b][m][n] = f32x4{0.f, 0.f, 0.f, 0.f};
;     bf16x8 At[4][2], B0[2][2], B1[2][2];
;     if (wr == 1) BAR;
;     WAIT_V(10); BAR;
;     WAIT_V(6); BAR;
;     for (int t = 0; t < nt - 2; t += 2) {
.LBB0_1366:
	s_waitcnt vmcnt(8)
	s_barrier
	s_waitcnt vmcnt(6)
	v_mov_b32_e32 v127, 0
	s_cmp_lt_u32 s56, 3
	v_mov_b32_e32 v126, v127
	v_mov_b32_e32 v125, v127
	v_mov_b32_e32 v124, v127
	v_mov_b32_e32 v123, v127
	v_mov_b32_e32 v122, v127
	v_mov_b32_e32 v121, v127
	v_mov_b32_e32 v120, v127
	v_mov_b32_e32 v119, v127
	v_mov_b32_e32 v118, v127
	v_mov_b32_e32 v117, v127
	v_mov_b32_e32 v116, v127
	v_mov_b32_e32 v115, v127
	v_mov_b32_e32 v114, v127
	v_mov_b32_e32 v113, v127
	v_mov_b32_e32 v112, v127
	v_mov_b32_e32 v111, v127
	v_mov_b32_e32 v110, v127
	v_mov_b32_e32 v109, v127
	v_mov_b32_e32 v108, v127
	v_mov_b32_e32 v107, v127
	v_mov_b32_e32 v106, v127
	v_mov_b32_e32 v105, v127
	v_mov_b32_e32 v104, v127
	v_mov_b32_e32 v103, v127
	v_mov_b32_e32 v102, v127
	v_mov_b32_e32 v101, v127
	v_mov_b32_e32 v100, v127
	v_mov_b32_e32 v99, v127
	v_mov_b32_e32 v98, v127
	v_mov_b32_e32 v97, v127
	v_mov_b32_e32 v96, v127
	v_mov_b32_e32 v95, v127
	v_mov_b32_e32 v94, v127
	v_mov_b32_e32 v93, v127
	v_mov_b32_e32 v92, v127
	v_mov_b32_e32 v91, v127
	v_mov_b32_e32 v90, v127
	v_mov_b32_e32 v89, v127
	v_mov_b32_e32 v88, v127
	v_mov_b32_e32 v87, v127
	v_mov_b32_e32 v86, v127
	v_mov_b32_e32 v85, v127
	v_mov_b32_e32 v84, v127
	v_mov_b32_e32 v83, v127
	v_mov_b32_e32 v82, v127
	v_mov_b32_e32 v81, v127
	v_mov_b32_e32 v80, v127
	v_mov_b32_e32 v79, v127
	v_mov_b32_e32 v78, v127
	v_mov_b32_e32 v77, v127
	v_mov_b32_e32 v76, v127
	v_mov_b32_e32 v75, v127
	v_mov_b32_e32 v74, v127
	v_mov_b32_e32 v73, v127
	v_mov_b32_e32 v72, v127
	v_mov_b32_e32 v71, v127
	v_mov_b32_e32 v70, v127
	v_mov_b32_e32 v69, v127
	v_mov_b32_e32 v68, v127
	v_mov_b32_e32 v67, v127
	v_mov_b32_e32 v66, v127
	v_mov_b32_e32 v65, v127
	v_mov_b32_e32 v64, v127
	v_mov_b32_e32 v63, v127
	v_mov_b32_e32 v62, v127
	v_mov_b32_e32 v61, v127
	v_mov_b32_e32 v60, v127
	v_mov_b32_e32 v59, v127
	v_mov_b32_e32 v58, v127
	v_mov_b32_e32 v57, v127
	v_mov_b32_e32 v56, v127
	v_mov_b32_e32 v55, v127
	v_mov_b32_e32 v54, v127
	v_mov_b32_e32 v53, v127
	v_mov_b32_e32 v52, v127
	v_mov_b32_e32 v51, v127
	v_mov_b32_e32 v50, v127
	v_mov_b32_e32 v49, v127
	v_mov_b32_e32 v48, v127
	v_mov_b32_e32 v47, v127
	v_mov_b32_e32 v46, v127
	v_mov_b32_e32 v45, v127
	v_mov_b32_e32 v44, v127
	v_mov_b32_e32 v43, v127
	v_mov_b32_e32 v42, v127
	v_mov_b32_e32 v41, v127
	v_mov_b32_e32 v40, v127
	v_mov_b32_e32 v39, v127
	v_mov_b32_e32 v38, v127
	v_mov_b32_e32 v37, v127
	v_mov_b32_e32 v36, v127
	v_mov_b32_e32 v35, v127
	v_mov_b32_e32 v34, v127
	v_mov_b32_e32 v33, v127
	v_mov_b32_e32 v32, v127
	v_mov_b32_e32 v31, v127
	v_mov_b32_e32 v30, v127
	v_mov_b32_e32 v29, v127
	v_mov_b32_e32 v28, v127
	v_mov_b32_e32 v27, v127
	v_mov_b32_e32 v26, v127
	v_mov_b32_e32 v25, v127
	v_mov_b32_e32 v24, v127
	v_mov_b32_e32 v23, v127
	v_mov_b32_e32 v22, v127
	v_mov_b32_e32 v21, v127
	v_mov_b32_e32 v20, v127
	v_mov_b32_e32 v19, v127
	v_mov_b32_e32 v18, v127
	v_mov_b32_e32 v17, v127
	v_mov_b32_e32 v16, v127
	v_mov_b32_e32 v15, v127
	v_mov_b32_e32 v14, v127
	v_mov_b32_e32 v13, v127
	v_mov_b32_e32 v12, v127
	v_mov_b32_e32 v11, v127
	v_mov_b32_e32 v10, v127
	v_mov_b32_e32 v9, v127
	v_mov_b32_e32 v8, v127
	v_mov_b32_e32 v7, v127
	v_mov_b32_e32 v6, v127
	v_mov_b32_e32 v5, v127
	v_mov_b32_e32 v4, v127
	v_mov_b32_e32 v3, v127
	v_mov_b32_e32 v2, v127
	v_mov_b32_e32 v1, v127
	v_mov_b32_e32 v0, v127
	s_barrier
	s_cbranch_scc1 .LBB0_1369
	s_mul_i32 s60, s58, 0xb00
	s_ashr_i32 s61, s60, 31
	v_readlane_b32 s76, v254, 54
	s_add_i32 s57, s56, -2
	s_lshl_b64 s[60:61], s[60:61], 1
	v_readlane_b32 s80, v254, 58
	v_readlane_b32 s77, v254, 55
	v_readlane_b32 s78, v254, 56
	v_readlane_b32 s79, v254, 57
	v_readlane_b32 s81, v254, 59
	v_readlane_b32 s82, v254, 60
	v_readlane_b32 s83, v254, 61
	v_readlane_b32 s84, v254, 62
	v_readlane_b32 s85, v254, 63
	v_readlane_b32 s86, v255, 0
	v_readlane_b32 s87, v255, 1
	v_readlane_b32 s88, v255, 2
	v_readlane_b32 s89, v255, 3
	v_readlane_b32 s90, v255, 4
	v_readlane_b32 s91, v255, 5
	s_add_u32 s60, s80, s60
	s_addc_u32 s61, s81, s61
	v_readlane_b32 s76, v255, 10
	s_mul_i32 s64, s94, 0x1600
	v_readlane_b32 s82, v255, 16
	s_mul_hi_i32 s59, s94, 0x1600
	v_readlane_b32 s83, v255, 17
	s_add_u32 s64, s82, s64
	v_mov_b32_e32 v0, 0
	s_addc_u32 s65, s83, s59
	s_mov_b32 s59, 0
	v_readlane_b32 s77, v255, 11
	v_readlane_b32 s78, v255, 12
	v_readlane_b32 s79, v255, 13
	v_readlane_b32 s80, v255, 14
	v_readlane_b32 s81, v255, 15
	v_readlane_b32 s84, v255, 18
	v_readlane_b32 s85, v255, 19
	v_readlane_b32 s86, v255, 20
	v_readlane_b32 s87, v255, 21
	v_readlane_b32 s88, v255, 22
	v_readlane_b32 s89, v255, 23
	v_readlane_b32 s90, v255, 24
	v_readlane_b32 s91, v255, 25
; #define STAGE(P, BASE, br, kt) do { const char* _g = (const char*)((BASE) + (size_t)(br) * K + (size_t)(kt) * G_BK); \
;     _Pragma("unroll") for (int _i = 0; _i < 2; ++_i) { \
;       __builtin_amdgcn_global_load_lds((const unsigned*)(_g + (size_t)_i * 128 * K + sg_off), (unsigned*)((char*)(P) + wid * 1024 + _i * 8192), 16, 0, 0); } } while (0)
; #define LDA(dst, b, h) _Pragma("unroll") for (int m = 0; m < 4; ++m) _Pragma("unroll") for (int k = 0; k < 2; ++k) \
;     dst[m][k] = *reinterpret_cast<const bf16x8*>((const char*)shm + aoff + (((b) * 2 + (h)) * 16384 + m * 2048 + k * 1024))
; #define LDB(dst, b, h) _Pragma("unroll") for (int n = 0; n < 2; ++n) _Pragma("unroll") for (int k = 0; k < 2; ++k) \
;     dst[n][k] = *reinterpret_cast<const bf16x8*>((const char*)shm + boff + (((b) * 2 + (h)) * 16384 + n * 2048 + k * 1024))
; #define MMA(ai, bj, At, Bt_) do { __builtin_amdgcn_s_setprio(1); \
;     _Pragma("unroll") for (int m = 0; m < 4; ++m) _Pragma("unroll") for (int n = 0; n < 2; ++n) _Pragma("unroll") for (int k = 0; k < 2; ++k) \
;       acc[ai][bj][m][n] = mfma16(At[m][k], Bt_[n][k], acc[ai][bj][m][n]); \
;     __builtin_amdgcn_s_setprio(0); } while (0)
; #define WAIT_V(n) asm volatile("s_waitcnt vmcnt(" #n ")" ::: "memory")
; #define WAIT_L(n) asm volatile("s_waitcnt lgkmcnt(" #n ")" ::: "memory")
; #define BAR __builtin_amdgcn_s_barrier()
; #define SCHED __builtin_amdgcn_sched_barrier(0)
; template <class Epi>
; __device__ __forceinline__ void gemm_phase(const bfr* __restrict__ A, int lda, const bfr* __restrict__ Bt, int K,
;                                            int nM, int nN, const Epi& epi, bfr* shm, int wv, int nMfull, int ksplit) {
;     ...
;       LDB(B0, 0, 0); SCHED; LDA(At, 0, 0); STAGE(SA(1, 1), Ak, brow + G_HALF, t + 1);
;       WAIT_L(8); BAR; WAIT_L(0); MMA(0, 0, At, B0); BAR; SCHED;
;       LDB(B1, 0, 1); STAGE(SB(0, 0), Bk, bcol, t + 2);
;       BAR; WAIT_L(0); MMA(0, 1, At, B1); BAR;
;       LDA(At, 0, 1); STAGE(SA(0, 0), Ak, brow, t + 2);
;       BAR; WAIT_L(0); MMA(1, 0, At, B0); BAR; SCHED;
;       STAGE(SB(0, 1), Bk, bcol + G_HALF, t + 2);
;       WAIT_V(6); BAR; MMA(1, 1, At, B1); BAR;
.LBB0_1368:
	ds_read_b128 v[136:139], v143
	ds_read_b128 v[148:151], v143 offset:1024
	ds_read_b128 v[152:155], v143 offset:2048
	ds_read_b128 v[156:159], v143 offset:3072
	ds_read_b128 v[160:163], v142
	ds_read_b128 v[164:167], v142 offset:1024
	ds_read_b128 v[168:171], v142 offset:2048
	ds_read_b128 v[172:175], v142 offset:3072
	ds_read_b128 v[176:179], v142 offset:4096
	ds_read_b128 v[180:183], v142 offset:5120
	ds_read_b128 v[184:187], v142 offset:6144
	ds_read_b128 v[188:191], v142 offset:7168
	ds_read_b128 v[192:195], v143 offset:16384
	ds_read_b128 v[196:199], v143 offset:17408
	ds_read_b128 v[200:203], v143 offset:18432
	ds_read_b128 v[204:207], v143 offset:19456
	v_lshl_add_u64 v[140:141], s[64:65], 0, v[134:135]
	v_lshl_add_u64 v[208:209], s[60:61], 0, v[134:135]
	s_mov_b32 m0, s47
	v_lshl_add_u64 v[212:213], v[140:141], 0, s[12:13]
	global_load_lds_dwordx4 v[212:213], off
	s_mov_b32 m0, s71
	v_lshl_add_u64 v[214:215], v[140:141], 0, s[14:15]
	global_load_lds_dwordx4 v[214:215], off
	s_waitcnt lgkmcnt(0)
	s_barrier
	s_setprio 1
	v_mfma_f32_16x16x32_bf16 v[124:127], v[160:163], v[136:139], v[124:127]
	v_mfma_f32_16x16x32_bf16 v[120:123], v[160:163], v[152:155], v[120:123]
	v_mfma_f32_16x16x32_bf16 v[116:119], v[168:171], v[136:139], v[116:119]
	v_mfma_f32_16x16x32_bf16 v[112:115], v[168:171], v[152:155], v[112:115]
	v_mfma_f32_16x16x32_bf16 v[108:111], v[176:179], v[136:139], v[108:111]
	v_mfma_f32_16x16x32_bf16 v[104:107], v[176:179], v[152:155], v[104:107]
	v_mfma_f32_16x16x32_bf16 v[100:103], v[184:187], v[136:139], v[100:103]
	v_mfma_f32_16x16x32_bf16 v[96:99], v[184:187], v[152:155], v[96:99]
	v_mfma_f32_16x16x32_bf16 v[124:127], v[164:167], v[148:151], v[124:127]
	v_mfma_f32_16x16x32_bf16 v[120:123], v[164:167], v[156:159], v[120:123]
	v_mfma_f32_16x16x32_bf16 v[116:119], v[172:175], v[148:151], v[116:119]
	v_mfma_f32_16x16x32_bf16 v[112:115], v[172:175], v[156:159], v[112:115]
	v_mfma_f32_16x16x32_bf16 v[108:111], v[180:183], v[148:151], v[108:111]
	v_mfma_f32_16x16x32_bf16 v[104:107], v[180:183], v[156:159], v[104:107]
	v_mfma_f32_16x16x32_bf16 v[100:103], v[188:191], v[148:151], v[100:103]
	v_mfma_f32_16x16x32_bf16 v[96:99], v[188:191], v[156:159], v[96:99]
	v_mfma_f32_16x16x32_bf16 v[92:95], v[160:163], v[192:195], v[92:95]
	v_mfma_f32_16x16x32_bf16 v[88:91], v[160:163], v[200:203], v[88:91]
	v_mfma_f32_16x16x32_bf16 v[84:87], v[168:171], v[192:195], v[84:87]
	v_mfma_f32_16x16x32_bf16 v[80:83], v[168:171], v[200:203], v[80:83]
	v_mfma_f32_16x16x32_bf16 v[76:79], v[176:179], v[192:195], v[76:79]
	v_mfma_f32_16x16x32_bf16 v[72:75], v[176:179], v[200:203], v[72:75]
	v_mfma_f32_16x16x32_bf16 v[68:71], v[184:187], v[192:195], v[68:71]
	v_mfma_f32_16x16x32_bf16 v[64:67], v[184:187], v[200:203], v[64:67]
	v_mfma_f32_16x16x32_bf16 v[92:95], v[164:167], v[196:199], v[92:95]
	v_mfma_f32_16x16x32_bf16 v[88:91], v[164:167], v[204:207], v[88:91]
	v_mfma_f32_16x16x32_bf16 v[84:87], v[172:175], v[196:199], v[84:87]
	v_mfma_f32_16x16x32_bf16 v[80:83], v[172:175], v[204:207], v[80:83]
	v_mfma_f32_16x16x32_bf16 v[76:79], v[180:183], v[196:199], v[76:79]
	v_mfma_f32_16x16x32_bf16 v[72:75], v[180:183], v[204:207], v[72:75]
	v_mfma_f32_16x16x32_bf16 v[68:71], v[188:191], v[196:199], v[68:71]
	v_mfma_f32_16x16x32_bf16 v[64:67], v[188:191], v[204:207], v[64:67]
	s_setprio 0
	s_barrier
	ds_read_b128 v[160:163], v142 offset:16384
	ds_read_b128 v[164:167], v142 offset:17408
	ds_read_b128 v[168:171], v142 offset:18432
	ds_read_b128 v[172:175], v142 offset:19456
	ds_read_b128 v[176:179], v142 offset:20480
	ds_read_b128 v[180:183], v142 offset:21504
	ds_read_b128 v[184:187], v142 offset:22528
	ds_read_b128 v[188:191], v142 offset:23552
	s_mov_b32 m0, s72
	s_mov_b64 s[96:97], 0x1080100
	v_lshl_add_u64 v[216:217], v[208:209], 0, s[96:97]
	global_load_lds_dwordx4 v[216:217], off
	s_mov_b32 m0, s73
	v_lshl_add_u64 v[212:213], v[208:209], 0, s[18:19]
	global_load_lds_dwordx4 v[212:213], off
	s_mov_b32 m0, s48
	v_lshl_add_u64 v[214:215], v[140:141], 0, s[24:25]
	global_load_lds_dwordx4 v[214:215], off
	s_mov_b32 m0, s74
	v_lshl_add_u64 v[216:217], v[140:141], 0, s[26:27]
	global_load_lds_dwordx4 v[216:217], off
	s_waitcnt vmcnt(6)
	s_waitcnt lgkmcnt(0)
	s_barrier
	s_setprio 1
	v_mfma_f32_16x16x32_bf16 v[60:63], v[160:163], v[136:139], v[60:63]
	v_mfma_f32_16x16x32_bf16 v[56:59], v[160:163], v[152:155], v[56:59]
	v_mfma_f32_16x16x32_bf16 v[52:55], v[168:171], v[136:139], v[52:55]
	v_mfma_f32_16x16x32_bf16 v[48:51], v[168:171], v[152:155], v[48:51]
	v_mfma_f32_16x16x32_bf16 v[44:47], v[176:179], v[136:139], v[44:47]
	v_mfma_f32_16x16x32_bf16 v[40:43], v[176:179], v[152:155], v[40:43]
	v_mfma_f32_16x16x32_bf16 v[36:39], v[184:187], v[136:139], v[36:39]
	v_mfma_f32_16x16x32_bf16 v[32:35], v[184:187], v[152:155], v[32:35]
	v_mfma_f32_16x16x32_bf16 v[60:63], v[164:167], v[148:151], v[60:63]
	v_mfma_f32_16x16x32_bf16 v[56:59], v[164:167], v[156:159], v[56:59]
	v_mfma_f32_16x16x32_bf16 v[52:55], v[172:175], v[148:151], v[52:55]
	v_mfma_f32_16x16x32_bf16 v[48:51], v[172:175], v[156:159], v[48:51]
	v_mfma_f32_16x16x32_bf16 v[44:47], v[180:183], v[148:151], v[44:47]
	v_mfma_f32_16x16x32_bf16 v[40:43], v[180:183], v[156:159], v[40:43]
	v_mfma_f32_16x16x32_bf16 v[36:39], v[188:191], v[148:151], v[36:39]
	v_mfma_f32_16x16x32_bf16 v[32:35], v[188:191], v[156:159], v[32:35]
	v_mfma_f32_16x16x32_bf16 v[28:31], v[160:163], v[192:195], v[28:31]
	v_mfma_f32_16x16x32_bf16 v[24:27], v[160:163], v[200:203], v[24:27]
	v_mfma_f32_16x16x32_bf16 v[20:23], v[168:171], v[192:195], v[20:23]
	v_mfma_f32_16x16x32_bf16 v[16:19], v[168:171], v[200:203], v[16:19]
	v_mfma_f32_16x16x32_bf16 v[12:15], v[176:179], v[192:195], v[12:15]
	v_mfma_f32_16x16x32_bf16 v[8:11], v[176:179], v[200:203], v[8:11]
	v_mfma_f32_16x16x32_bf16 v[4:7], v[184:187], v[192:195], v[4:7]
	v_mfma_f32_16x16x32_bf16 v[0:3], v[184:187], v[200:203], v[0:3]
	v_mfma_f32_16x16x32_bf16 v[28:31], v[164:167], v[196:199], v[28:31]
	v_mfma_f32_16x16x32_bf16 v[24:27], v[164:167], v[204:207], v[24:27]
	v_mfma_f32_16x16x32_bf16 v[20:23], v[172:175], v[196:199], v[20:23]
	v_mfma_f32_16x16x32_bf16 v[16:19], v[172:175], v[204:207], v[16:19]
	v_mfma_f32_16x16x32_bf16 v[12:15], v[180:183], v[196:199], v[12:15]
	v_mfma_f32_16x16x32_bf16 v[8:11], v[180:183], v[204:207], v[8:11]
	v_mfma_f32_16x16x32_bf16 v[4:7], v[188:191], v[196:199], v[4:7]
	v_mfma_f32_16x16x32_bf16 v[0:3], v[188:191], v[204:207], v[0:3]
	s_setprio 0
	s_barrier
; #define STAGE(P, BASE, br, kt) do { const char* _g = (const char*)((BASE) + (size_t)(br) * K + (size_t)(kt) * G_BK); \
;     _Pragma("unroll") for (int _i = 0; _i < 2; ++_i) { \
;       __builtin_amdgcn_global_load_lds((const unsigned*)(_g + (size_t)_i * 128 * K + sg_off), (unsigned*)((char*)(P) + wid * 1024 + _i * 8192), 16, 0, 0); } } while (0)
; #define LDA(dst, b, h) _Pragma("unroll") for (int m = 0; m < 4; ++m) _Pragma("unroll") for (int k = 0; k < 2; ++k) \
;     dst[m][k] = *reinterpret_cast<const bf16x8*>((const char*)shm + aoff + (((b) * 2 + (h)) * 16384 + m * 2048 + k * 1024))
; #define LDB(dst, b, h) _Pragma("unroll") for (int n = 0; n < 2; ++n) _Pragma("unroll") for (int k = 0; k < 2; ++k) \
;     dst[n][k] = *reinterpret_cast<const bf16x8*>((const char*)shm + boff + (((b) * 2 + (h)) * 16384 + n * 2048 + k * 1024))
; #define MMA(ai, bj, At, Bt_) do { __builtin_amdgcn_s_setprio(1); \
;     _Pragma("unroll") for (int m = 0; m < 4; ++m) _Pragma("unroll") for (int n = 0; n < 2; ++n) _Pragma("unroll") for (int k = 0; k < 2; ++k) \
;       acc[ai][bj][m][n] = mfma16(At[m][k], Bt_[n][k], acc[ai][bj][m][n]); \
;     __builtin_amdgcn_s_setprio(0); } while (0)
; #define WAIT_V(n) asm volatile("s_waitcnt vmcnt(" #n ")" ::: "memory")
; #define WAIT_L(n) asm volatile("s_waitcnt lgkmcnt(" #n ")" ::: "memory")
; #define BAR __builtin_amdgcn_s_barrier()
; #define SCHED __builtin_amdgcn_sched_barrier(0)
; template <class Epi>
; __device__ __forceinline__ void gemm_phase(const bfr* __restrict__ A, int lda, const bfr* __restrict__ Bt, int K,
;                                            int nM, int nN, const Epi& epi, bfr* shm, int wv, int nMfull, int ksplit) {
;     ...
;       LDB(B0, 1, 0); SCHED; LDA(At, 1, 0); STAGE(SA(0, 1), Ak, brow + G_HALF, t + 2);
;       WAIT_L(8); BAR; WAIT_L(0); MMA(0, 0, At, B0); BAR; SCHED;
;       LDB(B1, 1, 1); STAGE(SB(1, 0), Bk, bcol, t + 3);
;       BAR; WAIT_L(0); MMA(0, 1, At, B1); BAR;
;       LDA(At, 1, 1); STAGE(SA(1, 0), Ak, brow, t + 3);
;       BAR; WAIT_L(0); MMA(1, 0, At, B0); BAR; SCHED;
;       STAGE(SB(1, 1), Bk, bcol + G_HALF, t + 3);
;       WAIT_V(6); BAR; MMA(1, 1, At, B1); BAR;
;     }
	ds_read_b128 v[136:139], v143 offset:32768
	ds_read_b128 v[148:151], v143 offset:33792
	ds_read_b128 v[152:155], v143 offset:34816
	ds_read_b128 v[156:159], v143 offset:35840
	ds_read_b128 v[160:163], v142 offset:32768
	ds_read_b128 v[164:167], v142 offset:33792
	ds_read_b128 v[168:171], v142 offset:34816
	ds_read_b128 v[172:175], v142 offset:35840
	ds_read_b128 v[176:179], v142 offset:36864
	ds_read_b128 v[180:183], v142 offset:37888
	ds_read_b128 v[184:187], v142 offset:38912
	ds_read_b128 v[188:191], v142 offset:39936
	ds_read_b128 v[192:195], v143 offset:49152
	ds_read_b128 v[196:199], v143 offset:50176
	ds_read_b128 v[200:203], v143 offset:51200
	ds_read_b128 v[204:207], v143 offset:52224
	s_mov_b32 m0, s75
	v_lshl_add_u64 v[212:213], v[208:209], 0, s[28:29]
	global_load_lds_dwordx4 v[212:213], off
	s_mov_b32 m0, s62
	v_lshl_add_u64 v[214:215], v[208:209], 0, s[30:31]
	global_load_lds_dwordx4 v[214:215], off
	s_mov_b32 m0, s63
	v_lshl_add_u64 v[216:217], v[140:141], 0, s[8:9]
	global_load_lds_dwordx4 v[216:217], off
	s_mov_b32 m0, s66
	v_lshl_add_u64 v[212:213], v[140:141], 0, s[10:11]
	global_load_lds_dwordx4 v[212:213], off
	s_waitcnt vmcnt(8)
	s_waitcnt lgkmcnt(0)
	s_barrier
	s_setprio 1
	v_mfma_f32_16x16x32_bf16 v[124:127], v[160:163], v[136:139], v[124:127]
	v_mfma_f32_16x16x32_bf16 v[120:123], v[160:163], v[152:155], v[120:123]
	v_mfma_f32_16x16x32_bf16 v[116:119], v[168:171], v[136:139], v[116:119]
	v_mfma_f32_16x16x32_bf16 v[112:115], v[168:171], v[152:155], v[112:115]
	v_mfma_f32_16x16x32_bf16 v[108:111], v[176:179], v[136:139], v[108:111]
	v_mfma_f32_16x16x32_bf16 v[104:107], v[176:179], v[152:155], v[104:107]
	v_mfma_f32_16x16x32_bf16 v[100:103], v[184:187], v[136:139], v[100:103]
	v_mfma_f32_16x16x32_bf16 v[96:99], v[184:187], v[152:155], v[96:99]
	v_mfma_f32_16x16x32_bf16 v[124:127], v[164:167], v[148:151], v[124:127]
	v_mfma_f32_16x16x32_bf16 v[120:123], v[164:167], v[156:159], v[120:123]
	v_mfma_f32_16x16x32_bf16 v[116:119], v[172:175], v[148:151], v[116:119]
	v_mfma_f32_16x16x32_bf16 v[112:115], v[172:175], v[156:159], v[112:115]
	v_mfma_f32_16x16x32_bf16 v[108:111], v[180:183], v[148:151], v[108:111]
	v_mfma_f32_16x16x32_bf16 v[104:107], v[180:183], v[156:159], v[104:107]
	v_mfma_f32_16x16x32_bf16 v[100:103], v[188:191], v[148:151], v[100:103]
	v_mfma_f32_16x16x32_bf16 v[96:99], v[188:191], v[156:159], v[96:99]
	v_mfma_f32_16x16x32_bf16 v[92:95], v[160:163], v[192:195], v[92:95]
	v_mfma_f32_16x16x32_bf16 v[88:91], v[160:163], v[200:203], v[88:91]
	v_mfma_f32_16x16x32_bf16 v[84:87], v[168:171], v[192:195], v[84:87]
	v_mfma_f32_16x16x32_bf16 v[80:83], v[168:171], v[200:203], v[80:83]
	v_mfma_f32_16x16x32_bf16 v[76:79], v[176:179], v[192:195], v[76:79]
	v_mfma_f32_16x16x32_bf16 v[72:75], v[176:179], v[200:203], v[72:75]
	v_mfma_f32_16x16x32_bf16 v[68:71], v[184:187], v[192:195], v[68:71]
	v_mfma_f32_16x16x32_bf16 v[64:67], v[184:187], v[200:203], v[64:67]
	v_mfma_f32_16x16x32_bf16 v[92:95], v[164:167], v[196:199], v[92:95]
	v_mfma_f32_16x16x32_bf16 v[88:91], v[164:167], v[204:207], v[88:91]
	v_mfma_f32_16x16x32_bf16 v[84:87], v[172:175], v[196:199], v[84:87]
	v_mfma_f32_16x16x32_bf16 v[80:83], v[172:175], v[204:207], v[80:83]
	v_mfma_f32_16x16x32_bf16 v[76:79], v[180:183], v[196:199], v[76:79]
	v_mfma_f32_16x16x32_bf16 v[72:75], v[180:183], v[204:207], v[72:75]
	v_mfma_f32_16x16x32_bf16 v[68:71], v[188:191], v[196:199], v[68:71]
	v_mfma_f32_16x16x32_bf16 v[64:67], v[188:191], v[204:207], v[64:67]
	s_setprio 0
	s_barrier
	ds_read_b128 v[160:163], v142 offset:49152
	ds_read_b128 v[164:167], v142 offset:50176
	ds_read_b128 v[168:171], v142 offset:51200
	ds_read_b128 v[172:175], v142 offset:52224
	ds_read_b128 v[176:179], v142 offset:53248
	ds_read_b128 v[180:183], v142 offset:54272
	ds_read_b128 v[184:187], v142 offset:55296
	ds_read_b128 v[188:191], v142 offset:56320
	s_mov_b32 m0, s67
	v_lshl_add_u64 v[214:215], v[208:209], 0, s[34:35]
	global_load_lds_dwordx4 v[214:215], off
	s_mov_b32 m0, s4
	v_lshl_add_u64 v[216:217], v[208:209], 0, s[36:37]
	global_load_lds_dwordx4 v[216:217], off
	s_mov_b32 m0, s5
	v_lshl_add_u64 v[212:213], v[140:141], 0, s[38:39]
	global_load_lds_dwordx4 v[212:213], off
	s_mov_b32 m0, s6
	v_lshl_add_u64 v[214:215], v[140:141], 0, s[40:41]
	global_load_lds_dwordx4 v[214:215], off
	s_mov_b32 m0, s7
	v_lshl_add_u64 v[216:217], v[208:209], 0, s[42:43]
	global_load_lds_dwordx4 v[216:217], off
	s_mov_b32 m0, s46
	v_lshl_add_u64 v[212:213], v[208:209], 0, s[44:45]
	global_load_lds_dwordx4 v[212:213], off
	s_waitcnt vmcnt(6)
	s_waitcnt lgkmcnt(0)
	s_barrier
	s_setprio 1
	v_mfma_f32_16x16x32_bf16 v[60:63], v[160:163], v[136:139], v[60:63]
	v_mfma_f32_16x16x32_bf16 v[56:59], v[160:163], v[152:155], v[56:59]
	v_mfma_f32_16x16x32_bf16 v[52:55], v[168:171], v[136:139], v[52:55]
	v_mfma_f32_16x16x32_bf16 v[48:51], v[168:171], v[152:155], v[48:51]
	v_mfma_f32_16x16x32_bf16 v[44:47], v[176:179], v[136:139], v[44:47]
	v_mfma_f32_16x16x32_bf16 v[40:43], v[176:179], v[152:155], v[40:43]
	v_mfma_f32_16x16x32_bf16 v[36:39], v[184:187], v[136:139], v[36:39]
	v_mfma_f32_16x16x32_bf16 v[32:35], v[184:187], v[152:155], v[32:35]
	v_mfma_f32_16x16x32_bf16 v[60:63], v[164:167], v[148:151], v[60:63]
	v_mfma_f32_16x16x32_bf16 v[56:59], v[164:167], v[156:159], v[56:59]
	v_mfma_f32_16x16x32_bf16 v[52:55], v[172:175], v[148:151], v[52:55]
	v_mfma_f32_16x16x32_bf16 v[48:51], v[172:175], v[156:159], v[48:51]
	v_mfma_f32_16x16x32_bf16 v[44:47], v[180:183], v[148:151], v[44:47]
	v_mfma_f32_16x16x32_bf16 v[40:43], v[180:183], v[156:159], v[40:43]
	v_mfma_f32_16x16x32_bf16 v[36:39], v[188:191], v[148:151], v[36:39]
	v_mfma_f32_16x16x32_bf16 v[32:35], v[188:191], v[156:159], v[32:35]
	v_mfma_f32_16x16x32_bf16 v[28:31], v[160:163], v[192:195], v[28:31]
	v_mfma_f32_16x16x32_bf16 v[24:27], v[160:163], v[200:203], v[24:27]
	v_mfma_f32_16x16x32_bf16 v[20:23], v[168:171], v[192:195], v[20:23]
	v_mfma_f32_16x16x32_bf16 v[16:19], v[168:171], v[200:203], v[16:19]
	v_mfma_f32_16x16x32_bf16 v[12:15], v[176:179], v[192:195], v[12:15]
	v_mfma_f32_16x16x32_bf16 v[8:11], v[176:179], v[200:203], v[8:11]
	v_mfma_f32_16x16x32_bf16 v[4:7], v[184:187], v[192:195], v[4:7]
	v_mfma_f32_16x16x32_bf16 v[0:3], v[184:187], v[200:203], v[0:3]
	v_mfma_f32_16x16x32_bf16 v[28:31], v[164:167], v[196:199], v[28:31]
	v_mfma_f32_16x16x32_bf16 v[24:27], v[164:167], v[204:207], v[24:27]
	v_mfma_f32_16x16x32_bf16 v[20:23], v[172:175], v[196:199], v[20:23]
	v_mfma_f32_16x16x32_bf16 v[16:19], v[172:175], v[204:207], v[16:19]
	v_mfma_f32_16x16x32_bf16 v[12:15], v[180:183], v[196:199], v[12:15]
	v_mfma_f32_16x16x32_bf16 v[8:11], v[180:183], v[204:207], v[8:11]
	v_mfma_f32_16x16x32_bf16 v[4:7], v[188:191], v[196:199], v[4:7]
	v_mfma_f32_16x16x32_bf16 v[0:3], v[188:191], v[204:207], v[0:3]
	s_setprio 0
	s_add_i32 s59, s59, 2
	s_add_u32 s60, s60, 0x100
	s_addc_u32 s61, s61, 0
	s_add_u32 s64, s64, 0x100
	s_addc_u32 s65, s65, 0
	s_cmp_ge_i32 s59, s57
	s_barrier
	s_cbranch_scc0 .LBB0_1368
